# K-loop MFMA blocks: s_setprio 1 before the opening barrier, redundant lgkmcnt(0) after it dropped, closing barrier signalled before s_setprio 0; attention window loop: prefetch wait moved to loop entr
# speedup vs baseline: 1.0070x; 1.0026x over previous
.LBB0_169:
	v_cmp_gt_i32_e32 vcc, 1, v138
	s_cbranch_vccnz .LBB0_231
	v_lshl_add_u64 v[152:153], v[2:3], 0, s[22:23]
	v_add_u32_e32 v154, -2, v138
	s_waitcnt lgkmcnt(0)
	v_lshl_add_u64 v[150:151], v[4:5], 0, s[28:29]
	s_mov_b32 s7, 0
	s_nop 0
	v_readfirstlane_b32 s86, v152
	v_readfirstlane_b32 s87, v153
	v_readfirstlane_b32 s88, v150
	v_readfirstlane_b32 s89, v151
	v_readfirstlane_b32 s90, v146
	v_readfirstlane_b32 s91, v147
	v_readfirstlane_b32 s92, v148
	v_readfirstlane_b32 s93, v149
	v_readfirstlane_b32 s100, v154
	v_readfirstlane_b32 s101, v138
	v_add_u32_e32 v230, s76, v141
	v_add_u32_e32 v231, s77, v141
	v_add_u32_e32 v232, 0x18000, v141
	v_add_u32_e32 v233, 0x1c000, v141
	s_add_u32 s98, s86, 0xfffc0080
	s_addc_u32 s99, s87, -1
	s_cmp_eq_u32 s7, s100
	s_cselect_b64 s[94:95], s[90:91], s[98:99]
	s_cselect_b64 s[96:97], s[92:93], s[88:89]
	s_add_i32 s51, s7, 2
	s_nop 0
	s_mov_b32 m0, s78
	s_nop 0
	global_load_lds_dwordx4 v144, s[86:87]
	s_mov_b32 m0, s79
	s_nop 0
	global_load_lds_dwordx4 v142, s[86:87]
	ds_read_b128 v[164:167], v230
	ds_read_b128 v[168:171], v230 offset:1024
	ds_read_b128 v[172:175], v230 offset:2048
	ds_read_b128 v[176:179], v230 offset:3072
	ds_read_b128 v[180:183], v231
	ds_read_b128 v[184:187], v231 offset:1024
	ds_read_b128 v[188:191], v231 offset:2048
	ds_read_b128 v[192:195], v231 offset:3072
	ds_read_b128 v[196:199], v160
	ds_read_b128 v[200:203], v160 offset:1024
	ds_read_b128 v[204:207], v160 offset:2048
	ds_read_b128 v[208:211], v160 offset:3072
	ds_read_b128 v[212:215], v160 offset:4096
	ds_read_b128 v[216:219], v160 offset:5120
	ds_read_b128 v[220:223], v160 offset:6144
	ds_read_b128 v[224:227], v160 offset:7168
	s_waitcnt vmcnt(8)
	s_waitcnt lgkmcnt(0)
	s_setprio 1
	s_barrier
	v_mfma_f32_16x16x32_bf16 v[122:125], v[164:167], v[196:199], 0
	v_mfma_f32_16x16x32_bf16 v[118:121], v[172:175], v[196:199], 0
	v_mfma_f32_16x16x32_bf16 v[110:113], v[164:167], v[204:207], 0
	v_mfma_f32_16x16x32_bf16 v[102:105], v[172:175], v[204:207], 0
	v_mfma_f32_16x16x32_bf16 v[94:97], v[164:167], v[212:215], 0
	v_mfma_f32_16x16x32_bf16 v[86:89], v[172:175], v[212:215], 0
	v_mfma_f32_16x16x32_bf16 v[78:81], v[164:167], v[220:223], 0
	v_mfma_f32_16x16x32_bf16 v[70:73], v[172:175], v[220:223], 0
	v_mfma_f32_16x16x32_bf16 v[122:125], v[168:171], v[200:203], v[122:125]
	v_mfma_f32_16x16x32_bf16 v[118:121], v[176:179], v[200:203], v[118:121]
	v_mfma_f32_16x16x32_bf16 v[110:113], v[168:171], v[208:211], v[110:113]
	v_mfma_f32_16x16x32_bf16 v[102:105], v[176:179], v[208:211], v[102:105]
	v_mfma_f32_16x16x32_bf16 v[94:97], v[168:171], v[216:219], v[94:97]
	v_mfma_f32_16x16x32_bf16 v[86:89], v[176:179], v[216:219], v[86:89]
	v_mfma_f32_16x16x32_bf16 v[78:81], v[168:171], v[224:227], v[78:81]
	v_mfma_f32_16x16x32_bf16 v[70:73], v[176:179], v[224:227], v[70:73]
	s_setprio 0
	s_setprio 1
	v_mfma_f32_16x16x32_bf16 v[126:129], v[180:183], v[196:199], 0
	v_mfma_f32_16x16x32_bf16 v[114:117], v[188:191], v[196:199], 0
	v_mfma_f32_16x16x32_bf16 v[106:109], v[180:183], v[204:207], 0
	v_mfma_f32_16x16x32_bf16 v[98:101], v[188:191], v[204:207], 0
	v_mfma_f32_16x16x32_bf16 v[90:93], v[180:183], v[212:215], 0
	v_mfma_f32_16x16x32_bf16 v[82:85], v[188:191], v[212:215], 0
	v_mfma_f32_16x16x32_bf16 v[74:77], v[180:183], v[220:223], 0
	v_mfma_f32_16x16x32_bf16 v[66:69], v[188:191], v[220:223], 0
	v_mfma_f32_16x16x32_bf16 v[126:129], v[184:187], v[200:203], v[126:129]
	v_mfma_f32_16x16x32_bf16 v[114:117], v[192:195], v[200:203], v[114:117]
	v_mfma_f32_16x16x32_bf16 v[106:109], v[184:187], v[208:211], v[106:109]
	v_mfma_f32_16x16x32_bf16 v[98:101], v[192:195], v[208:211], v[98:101]
	v_mfma_f32_16x16x32_bf16 v[90:93], v[184:187], v[216:219], v[90:93]
	v_mfma_f32_16x16x32_bf16 v[82:85], v[192:195], v[216:219], v[82:85]
	v_mfma_f32_16x16x32_bf16 v[74:77], v[184:187], v[224:227], v[74:77]
	v_mfma_f32_16x16x32_bf16 v[66:69], v[192:195], v[224:227], v[66:69]
	s_barrier
	s_setprio 0
	s_add_u32 s98, s96, 0x40000
	s_addc_u32 s99, s97, 0
	s_mov_b32 m0, s80
	s_nop 0
	global_load_lds_dwordx4 v132, s[96:97]
	s_mov_b32 m0, s81
	s_add_i32 s7, s77, s47
	global_load_lds_dwordx4 v136, s[96:97]
	s_mov_b32 m0, s7
	s_nop 0
	global_load_lds_dwordx4 v132, s[98:99]
	s_add_i32 m0, s7, 0x2000
	s_nop 0
	global_load_lds_dwordx4 v136, s[98:99]
	s_mov_b32 m0, s57
	s_nop 0
	global_load_lds_dwordx4 v130, s[94:95]
	s_mov_b32 m0, s62
	s_nop 0
	global_load_lds_dwordx4 v134, s[94:95]
	ds_read_b128 v[196:199], v160 offset:16384
	ds_read_b128 v[200:203], v160 offset:17408
	ds_read_b128 v[204:207], v160 offset:18432
	ds_read_b128 v[208:211], v160 offset:19456
	ds_read_b128 v[212:215], v160 offset:20480
	ds_read_b128 v[216:219], v160 offset:21504
	ds_read_b128 v[220:223], v160 offset:22528
	ds_read_b128 v[224:227], v160 offset:23552
	s_waitcnt vmcnt(8)
	s_waitcnt lgkmcnt(0)
	s_setprio 1
	s_barrier
	v_mfma_f32_16x16x32_bf16 v[62:65], v[164:167], v[196:199], 0
	v_mfma_f32_16x16x32_bf16 v[54:57], v[172:175], v[196:199], 0
	v_mfma_f32_16x16x32_bf16 v[46:49], v[164:167], v[204:207], 0
	v_mfma_f32_16x16x32_bf16 v[38:41], v[172:175], v[204:207], 0
	v_mfma_f32_16x16x32_bf16 v[30:33], v[164:167], v[212:215], 0
	v_mfma_f32_16x16x32_bf16 v[22:25], v[172:175], v[212:215], 0
	v_mfma_f32_16x16x32_bf16 v[14:17], v[164:167], v[220:223], 0
	v_mfma_f32_16x16x32_bf16 v[6:9], v[172:175], v[220:223], 0
	v_mfma_f32_16x16x32_bf16 v[62:65], v[168:171], v[200:203], v[62:65]
	v_mfma_f32_16x16x32_bf16 v[54:57], v[176:179], v[200:203], v[54:57]
	v_mfma_f32_16x16x32_bf16 v[46:49], v[168:171], v[208:211], v[46:49]
	v_mfma_f32_16x16x32_bf16 v[38:41], v[176:179], v[208:211], v[38:41]
	v_mfma_f32_16x16x32_bf16 v[30:33], v[168:171], v[216:219], v[30:33]
	v_mfma_f32_16x16x32_bf16 v[22:25], v[176:179], v[216:219], v[22:25]
	v_mfma_f32_16x16x32_bf16 v[14:17], v[168:171], v[224:227], v[14:17]
	v_mfma_f32_16x16x32_bf16 v[6:9], v[176:179], v[224:227], v[6:9]
	s_setprio 0
	s_setprio 1
	v_mfma_f32_16x16x32_bf16 v[58:61], v[180:183], v[196:199], 0
	v_mfma_f32_16x16x32_bf16 v[50:53], v[188:191], v[196:199], 0
	v_mfma_f32_16x16x32_bf16 v[42:45], v[180:183], v[204:207], 0
	v_mfma_f32_16x16x32_bf16 v[34:37], v[188:191], v[204:207], 0
	v_mfma_f32_16x16x32_bf16 v[26:29], v[180:183], v[212:215], 0
	v_mfma_f32_16x16x32_bf16 v[18:21], v[188:191], v[212:215], 0
	v_mfma_f32_16x16x32_bf16 v[10:13], v[180:183], v[220:223], 0
	v_mfma_f32_16x16x32_bf16 v[2:5], v[188:191], v[220:223], 0
	v_mfma_f32_16x16x32_bf16 v[58:61], v[184:187], v[200:203], v[58:61]
	v_mfma_f32_16x16x32_bf16 v[50:53], v[192:195], v[200:203], v[50:53]
	v_mfma_f32_16x16x32_bf16 v[42:45], v[184:187], v[208:211], v[42:45]
	v_mfma_f32_16x16x32_bf16 v[34:37], v[192:195], v[208:211], v[34:37]
	v_mfma_f32_16x16x32_bf16 v[26:29], v[184:187], v[216:219], v[26:29]
	v_mfma_f32_16x16x32_bf16 v[18:21], v[192:195], v[216:219], v[18:21]
	v_mfma_f32_16x16x32_bf16 v[10:13], v[184:187], v[224:227], v[10:13]
	v_mfma_f32_16x16x32_bf16 v[2:5], v[192:195], v[224:227], v[2:5]
	s_barrier
	s_setprio 0
	s_add_u32 s98, s94, 0x40000
	s_addc_u32 s99, s95, 0
	s_add_i32 s7, 0, 0x18000
	s_add_i32 s55, 0, 0x1c000
	s_mov_b32 m0, s63
	s_nop 0
	global_load_lds_dwordx4 v130, s[98:99]
	s_mov_b32 m0, s64
	s_nop 0
	global_load_lds_dwordx4 v134, s[98:99]
	ds_read_b128 v[164:167], v232
	ds_read_b128 v[168:171], v232 offset:1024
	ds_read_b128 v[172:175], v232 offset:2048
	ds_read_b128 v[176:179], v232 offset:3072
	ds_read_b128 v[180:183], v233
	ds_read_b128 v[184:187], v233 offset:1024
	ds_read_b128 v[188:191], v233 offset:2048
	ds_read_b128 v[192:195], v233 offset:3072
	ds_read_b128 v[196:199], v160 offset:32768
	ds_read_b128 v[200:203], v160 offset:33792
	ds_read_b128 v[204:207], v160 offset:34816
	ds_read_b128 v[208:211], v160 offset:35840
	ds_read_b128 v[212:215], v160 offset:36864
	ds_read_b128 v[216:219], v160 offset:37888
	ds_read_b128 v[220:223], v160 offset:38912
	ds_read_b128 v[224:227], v160 offset:39936
	s_waitcnt vmcnt(8)
	s_waitcnt lgkmcnt(0)
	s_setprio 1
	s_barrier
	v_mfma_f32_16x16x32_bf16 v[122:125], v[164:167], v[196:199], v[122:125]
	v_mfma_f32_16x16x32_bf16 v[118:121], v[172:175], v[196:199], v[118:121]
	v_mfma_f32_16x16x32_bf16 v[110:113], v[164:167], v[204:207], v[110:113]
	v_mfma_f32_16x16x32_bf16 v[102:105], v[172:175], v[204:207], v[102:105]
	v_mfma_f32_16x16x32_bf16 v[94:97], v[164:167], v[212:215], v[94:97]
	v_mfma_f32_16x16x32_bf16 v[86:89], v[172:175], v[212:215], v[86:89]
	v_mfma_f32_16x16x32_bf16 v[78:81], v[164:167], v[220:223], v[78:81]
	v_mfma_f32_16x16x32_bf16 v[70:73], v[172:175], v[220:223], v[70:73]
	v_mfma_f32_16x16x32_bf16 v[122:125], v[168:171], v[200:203], v[122:125]
	v_mfma_f32_16x16x32_bf16 v[118:121], v[176:179], v[200:203], v[118:121]
	v_mfma_f32_16x16x32_bf16 v[110:113], v[168:171], v[208:211], v[110:113]
	v_mfma_f32_16x16x32_bf16 v[102:105], v[176:179], v[208:211], v[102:105]
	v_mfma_f32_16x16x32_bf16 v[94:97], v[168:171], v[216:219], v[94:97]
	v_mfma_f32_16x16x32_bf16 v[86:89], v[176:179], v[216:219], v[86:89]
	v_mfma_f32_16x16x32_bf16 v[78:81], v[168:171], v[224:227], v[78:81]
	v_mfma_f32_16x16x32_bf16 v[70:73], v[176:179], v[224:227], v[70:73]
	s_setprio 0
	s_setprio 1
	v_mfma_f32_16x16x32_bf16 v[126:129], v[180:183], v[196:199], v[126:129]
	v_mfma_f32_16x16x32_bf16 v[114:117], v[188:191], v[196:199], v[114:117]
	v_mfma_f32_16x16x32_bf16 v[106:109], v[180:183], v[204:207], v[106:109]
	v_mfma_f32_16x16x32_bf16 v[98:101], v[188:191], v[204:207], v[98:101]
	v_mfma_f32_16x16x32_bf16 v[90:93], v[180:183], v[212:215], v[90:93]
	v_mfma_f32_16x16x32_bf16 v[82:85], v[188:191], v[212:215], v[82:85]
	v_mfma_f32_16x16x32_bf16 v[74:77], v[180:183], v[220:223], v[74:77]
	v_mfma_f32_16x16x32_bf16 v[66:69], v[188:191], v[220:223], v[66:69]
	v_mfma_f32_16x16x32_bf16 v[126:129], v[184:187], v[200:203], v[126:129]
	v_mfma_f32_16x16x32_bf16 v[114:117], v[192:195], v[200:203], v[114:117]
	v_mfma_f32_16x16x32_bf16 v[106:109], v[184:187], v[208:211], v[106:109]
	v_mfma_f32_16x16x32_bf16 v[98:101], v[192:195], v[208:211], v[98:101]
	v_mfma_f32_16x16x32_bf16 v[90:93], v[184:187], v[216:219], v[90:93]
	v_mfma_f32_16x16x32_bf16 v[82:85], v[192:195], v[216:219], v[82:85]
	v_mfma_f32_16x16x32_bf16 v[74:77], v[184:187], v[224:227], v[74:77]
	v_mfma_f32_16x16x32_bf16 v[66:69], v[192:195], v[224:227], v[66:69]
	s_barrier
	s_setprio 0
	s_add_u32 s96, s96, 0x80
	s_addc_u32 s97, s97, 0
	s_add_u32 s98, s96, 0x40000
	s_addc_u32 s99, s97, 0
	s_add_u32 s94, s94, 0x80
	s_addc_u32 s95, s95, 0
	s_add_i32 s7, s7, s47
	s_mov_b32 m0, s7
	s_nop 0
	global_load_lds_dwordx4 v132, s[96:97]
	s_add_i32 m0, s7, 0x2000
	s_add_i32 s7, s55, s47
	global_load_lds_dwordx4 v136, s[96:97]
	s_mov_b32 m0, s7
	s_nop 0
	global_load_lds_dwordx4 v132, s[98:99]
	s_add_i32 m0, s7, 0x2000
	s_nop 0
	global_load_lds_dwordx4 v136, s[98:99]
	s_mov_b32 m0, s65
	s_nop 0
	global_load_lds_dwordx4 v130, s[94:95]
	s_mov_b32 m0, s66
	s_nop 0
	global_load_lds_dwordx4 v134, s[94:95]
	ds_read_b128 v[196:199], v160 offset:49152
	ds_read_b128 v[200:203], v160 offset:50176
	ds_read_b128 v[204:207], v160 offset:51200
	ds_read_b128 v[208:211], v160 offset:52224
	ds_read_b128 v[212:215], v160 offset:53248
	ds_read_b128 v[216:219], v160 offset:54272
	ds_read_b128 v[220:223], v160 offset:55296
	ds_read_b128 v[224:227], v160 offset:56320
	s_waitcnt vmcnt(8)
	s_waitcnt lgkmcnt(0)
	s_setprio 1
	s_barrier
	v_mfma_f32_16x16x32_bf16 v[62:65], v[164:167], v[196:199], v[62:65]
	v_mfma_f32_16x16x32_bf16 v[54:57], v[172:175], v[196:199], v[54:57]
	v_mfma_f32_16x16x32_bf16 v[46:49], v[164:167], v[204:207], v[46:49]
	v_mfma_f32_16x16x32_bf16 v[38:41], v[172:175], v[204:207], v[38:41]
	v_mfma_f32_16x16x32_bf16 v[30:33], v[164:167], v[212:215], v[30:33]
	v_mfma_f32_16x16x32_bf16 v[22:25], v[172:175], v[212:215], v[22:25]
	v_mfma_f32_16x16x32_bf16 v[14:17], v[164:167], v[220:223], v[14:17]
	v_mfma_f32_16x16x32_bf16 v[6:9], v[172:175], v[220:223], v[6:9]
	v_mfma_f32_16x16x32_bf16 v[62:65], v[168:171], v[200:203], v[62:65]
	v_mfma_f32_16x16x32_bf16 v[54:57], v[176:179], v[200:203], v[54:57]
	v_mfma_f32_16x16x32_bf16 v[46:49], v[168:171], v[208:211], v[46:49]
	v_mfma_f32_16x16x32_bf16 v[38:41], v[176:179], v[208:211], v[38:41]
	v_mfma_f32_16x16x32_bf16 v[30:33], v[168:171], v[216:219], v[30:33]
	v_mfma_f32_16x16x32_bf16 v[22:25], v[176:179], v[216:219], v[22:25]
	v_mfma_f32_16x16x32_bf16 v[14:17], v[168:171], v[224:227], v[14:17]
	v_mfma_f32_16x16x32_bf16 v[6:9], v[176:179], v[224:227], v[6:9]
	s_setprio 0
	s_setprio 1
	v_mfma_f32_16x16x32_bf16 v[58:61], v[180:183], v[196:199], v[58:61]
	v_mfma_f32_16x16x32_bf16 v[50:53], v[188:191], v[196:199], v[50:53]
	v_mfma_f32_16x16x32_bf16 v[42:45], v[180:183], v[204:207], v[42:45]
	v_mfma_f32_16x16x32_bf16 v[34:37], v[188:191], v[204:207], v[34:37]
	v_mfma_f32_16x16x32_bf16 v[26:29], v[180:183], v[212:215], v[26:29]
	v_mfma_f32_16x16x32_bf16 v[18:21], v[188:191], v[212:215], v[18:21]
	v_mfma_f32_16x16x32_bf16 v[10:13], v[180:183], v[220:223], v[10:13]
	v_mfma_f32_16x16x32_bf16 v[2:5], v[188:191], v[220:223], v[2:5]
	v_mfma_f32_16x16x32_bf16 v[58:61], v[184:187], v[200:203], v[58:61]
	v_mfma_f32_16x16x32_bf16 v[50:53], v[192:195], v[200:203], v[50:53]
	v_mfma_f32_16x16x32_bf16 v[42:45], v[184:187], v[208:211], v[42:45]
	v_mfma_f32_16x16x32_bf16 v[34:37], v[192:195], v[208:211], v[34:37]
	v_mfma_f32_16x16x32_bf16 v[26:29], v[184:187], v[216:219], v[26:29]
	v_mfma_f32_16x16x32_bf16 v[18:21], v[192:195], v[216:219], v[18:21]
	v_mfma_f32_16x16x32_bf16 v[10:13], v[184:187], v[224:227], v[10:13]
	v_mfma_f32_16x16x32_bf16 v[2:5], v[192:195], v[224:227], v[2:5]
	s_barrier
	s_setprio 0
	s_mov_b32 s7, s51
	s_add_u32 s88, s88, 0x100
	s_addc_u32 s89, s89, 0
	s_add_u32 s86, s86, 0x100
	s_addc_u32 s87, s87, 0
	s_cmp_ge_i32 s51, s101
	s_cbranch_scc1 .Lmy_kexit_0
.LBB0_171:
	s_add_u32 s98, s86, 0xfffc0080
	s_addc_u32 s99, s87, -1
	s_cmp_eq_u32 s7, s100
	s_cselect_b64 s[94:95], s[90:91], s[98:99]
	s_cselect_b64 s[96:97], s[92:93], s[88:89]
	s_add_i32 s51, s7, 2
	s_nop 0
	s_mov_b32 m0, s78
	s_nop 0
	global_load_lds_dwordx4 v144, s[86:87]
	s_mov_b32 m0, s79
	s_nop 0
	global_load_lds_dwordx4 v142, s[86:87]
	ds_read_b128 v[164:167], v230
	ds_read_b128 v[168:171], v230 offset:1024
	ds_read_b128 v[172:175], v230 offset:2048
	ds_read_b128 v[176:179], v230 offset:3072
	ds_read_b128 v[180:183], v231
	ds_read_b128 v[184:187], v231 offset:1024
	ds_read_b128 v[188:191], v231 offset:2048
	ds_read_b128 v[192:195], v231 offset:3072
	ds_read_b128 v[196:199], v160
	ds_read_b128 v[200:203], v160 offset:1024
	ds_read_b128 v[204:207], v160 offset:2048
	ds_read_b128 v[208:211], v160 offset:3072
	ds_read_b128 v[212:215], v160 offset:4096
	ds_read_b128 v[216:219], v160 offset:5120
	ds_read_b128 v[220:223], v160 offset:6144
	ds_read_b128 v[224:227], v160 offset:7168
	s_waitcnt vmcnt(8)
	s_waitcnt lgkmcnt(0)
	s_setprio 1
	s_barrier
	v_mfma_f32_16x16x32_bf16 v[122:125], v[164:167], v[196:199], v[122:125]
	v_mfma_f32_16x16x32_bf16 v[118:121], v[172:175], v[196:199], v[118:121]
	v_mfma_f32_16x16x32_bf16 v[110:113], v[164:167], v[204:207], v[110:113]
	v_mfma_f32_16x16x32_bf16 v[102:105], v[172:175], v[204:207], v[102:105]
	v_mfma_f32_16x16x32_bf16 v[94:97], v[164:167], v[212:215], v[94:97]
	v_mfma_f32_16x16x32_bf16 v[86:89], v[172:175], v[212:215], v[86:89]
	v_mfma_f32_16x16x32_bf16 v[78:81], v[164:167], v[220:223], v[78:81]
	v_mfma_f32_16x16x32_bf16 v[70:73], v[172:175], v[220:223], v[70:73]
	v_mfma_f32_16x16x32_bf16 v[122:125], v[168:171], v[200:203], v[122:125]
	v_mfma_f32_16x16x32_bf16 v[118:121], v[176:179], v[200:203], v[118:121]
	v_mfma_f32_16x16x32_bf16 v[110:113], v[168:171], v[208:211], v[110:113]
	v_mfma_f32_16x16x32_bf16 v[102:105], v[176:179], v[208:211], v[102:105]
	v_mfma_f32_16x16x32_bf16 v[94:97], v[168:171], v[216:219], v[94:97]
	v_mfma_f32_16x16x32_bf16 v[86:89], v[176:179], v[216:219], v[86:89]
	v_mfma_f32_16x16x32_bf16 v[78:81], v[168:171], v[224:227], v[78:81]
	v_mfma_f32_16x16x32_bf16 v[70:73], v[176:179], v[224:227], v[70:73]
	s_setprio 0
	s_setprio 1
	v_mfma_f32_16x16x32_bf16 v[126:129], v[180:183], v[196:199], v[126:129]
	v_mfma_f32_16x16x32_bf16 v[114:117], v[188:191], v[196:199], v[114:117]
	v_mfma_f32_16x16x32_bf16 v[106:109], v[180:183], v[204:207], v[106:109]
	v_mfma_f32_16x16x32_bf16 v[98:101], v[188:191], v[204:207], v[98:101]
	v_mfma_f32_16x16x32_bf16 v[90:93], v[180:183], v[212:215], v[90:93]
	v_mfma_f32_16x16x32_bf16 v[82:85], v[188:191], v[212:215], v[82:85]
	v_mfma_f32_16x16x32_bf16 v[74:77], v[180:183], v[220:223], v[74:77]
	v_mfma_f32_16x16x32_bf16 v[66:69], v[188:191], v[220:223], v[66:69]
	v_mfma_f32_16x16x32_bf16 v[126:129], v[184:187], v[200:203], v[126:129]
	v_mfma_f32_16x16x32_bf16 v[114:117], v[192:195], v[200:203], v[114:117]
	v_mfma_f32_16x16x32_bf16 v[106:109], v[184:187], v[208:211], v[106:109]
	v_mfma_f32_16x16x32_bf16 v[98:101], v[192:195], v[208:211], v[98:101]
	v_mfma_f32_16x16x32_bf16 v[90:93], v[184:187], v[216:219], v[90:93]
	v_mfma_f32_16x16x32_bf16 v[82:85], v[192:195], v[216:219], v[82:85]
	v_mfma_f32_16x16x32_bf16 v[74:77], v[184:187], v[224:227], v[74:77]
	v_mfma_f32_16x16x32_bf16 v[66:69], v[192:195], v[224:227], v[66:69]
	s_barrier
	s_setprio 0
	s_add_u32 s98, s96, 0x40000
	s_addc_u32 s99, s97, 0
	s_mov_b32 m0, s80
	s_nop 0
	global_load_lds_dwordx4 v132, s[96:97]
	s_mov_b32 m0, s81
	s_add_i32 s7, s77, s47
	global_load_lds_dwordx4 v136, s[96:97]
	s_mov_b32 m0, s7
	s_nop 0
	global_load_lds_dwordx4 v132, s[98:99]
	s_add_i32 m0, s7, 0x2000
	s_nop 0
	global_load_lds_dwordx4 v136, s[98:99]
	s_mov_b32 m0, s57
	s_nop 0
	global_load_lds_dwordx4 v130, s[94:95]
	s_mov_b32 m0, s62
	s_nop 0
	global_load_lds_dwordx4 v134, s[94:95]
	ds_read_b128 v[196:199], v160 offset:16384
	ds_read_b128 v[200:203], v160 offset:17408
	ds_read_b128 v[204:207], v160 offset:18432
	ds_read_b128 v[208:211], v160 offset:19456
	ds_read_b128 v[212:215], v160 offset:20480
	ds_read_b128 v[216:219], v160 offset:21504
	ds_read_b128 v[220:223], v160 offset:22528
	ds_read_b128 v[224:227], v160 offset:23552
	s_waitcnt vmcnt(8)
	s_waitcnt lgkmcnt(0)
	s_setprio 1
	s_barrier
	v_mfma_f32_16x16x32_bf16 v[62:65], v[164:167], v[196:199], v[62:65]
	v_mfma_f32_16x16x32_bf16 v[54:57], v[172:175], v[196:199], v[54:57]
	v_mfma_f32_16x16x32_bf16 v[46:49], v[164:167], v[204:207], v[46:49]
	v_mfma_f32_16x16x32_bf16 v[38:41], v[172:175], v[204:207], v[38:41]
	v_mfma_f32_16x16x32_bf16 v[30:33], v[164:167], v[212:215], v[30:33]
	v_mfma_f32_16x16x32_bf16 v[22:25], v[172:175], v[212:215], v[22:25]
	v_mfma_f32_16x16x32_bf16 v[14:17], v[164:167], v[220:223], v[14:17]
	v_mfma_f32_16x16x32_bf16 v[6:9], v[172:175], v[220:223], v[6:9]
	v_mfma_f32_16x16x32_bf16 v[62:65], v[168:171], v[200:203], v[62:65]
	v_mfma_f32_16x16x32_bf16 v[54:57], v[176:179], v[200:203], v[54:57]
	v_mfma_f32_16x16x32_bf16 v[46:49], v[168:171], v[208:211], v[46:49]
	v_mfma_f32_16x16x32_bf16 v[38:41], v[176:179], v[208:211], v[38:41]
	v_mfma_f32_16x16x32_bf16 v[30:33], v[168:171], v[216:219], v[30:33]
	v_mfma_f32_16x16x32_bf16 v[22:25], v[176:179], v[216:219], v[22:25]
	v_mfma_f32_16x16x32_bf16 v[14:17], v[168:171], v[224:227], v[14:17]
	v_mfma_f32_16x16x32_bf16 v[6:9], v[176:179], v[224:227], v[6:9]
	s_setprio 0
	s_setprio 1
	v_mfma_f32_16x16x32_bf16 v[58:61], v[180:183], v[196:199], v[58:61]
	v_mfma_f32_16x16x32_bf16 v[50:53], v[188:191], v[196:199], v[50:53]
	v_mfma_f32_16x16x32_bf16 v[42:45], v[180:183], v[204:207], v[42:45]
	v_mfma_f32_16x16x32_bf16 v[34:37], v[188:191], v[204:207], v[34:37]
	v_mfma_f32_16x16x32_bf16 v[26:29], v[180:183], v[212:215], v[26:29]
	v_mfma_f32_16x16x32_bf16 v[18:21], v[188:191], v[212:215], v[18:21]
	v_mfma_f32_16x16x32_bf16 v[10:13], v[180:183], v[220:223], v[10:13]
	v_mfma_f32_16x16x32_bf16 v[2:5], v[188:191], v[220:223], v[2:5]
	v_mfma_f32_16x16x32_bf16 v[58:61], v[184:187], v[200:203], v[58:61]
	v_mfma_f32_16x16x32_bf16 v[50:53], v[192:195], v[200:203], v[50:53]
	v_mfma_f32_16x16x32_bf16 v[42:45], v[184:187], v[208:211], v[42:45]
	v_mfma_f32_16x16x32_bf16 v[34:37], v[192:195], v[208:211], v[34:37]
	v_mfma_f32_16x16x32_bf16 v[26:29], v[184:187], v[216:219], v[26:29]
	v_mfma_f32_16x16x32_bf16 v[18:21], v[192:195], v[216:219], v[18:21]
	v_mfma_f32_16x16x32_bf16 v[10:13], v[184:187], v[224:227], v[10:13]
	v_mfma_f32_16x16x32_bf16 v[2:5], v[192:195], v[224:227], v[2:5]
	s_barrier
	s_setprio 0
	s_add_u32 s98, s94, 0x40000
	s_addc_u32 s99, s95, 0
	s_add_i32 s7, 0, 0x18000
	s_add_i32 s55, 0, 0x1c000
	s_mov_b32 m0, s63
	s_nop 0
	global_load_lds_dwordx4 v130, s[98:99]
	s_mov_b32 m0, s64
	s_nop 0
	global_load_lds_dwordx4 v134, s[98:99]
	ds_read_b128 v[164:167], v232
	ds_read_b128 v[168:171], v232 offset:1024
	ds_read_b128 v[172:175], v232 offset:2048
	ds_read_b128 v[176:179], v232 offset:3072
	ds_read_b128 v[180:183], v233
	ds_read_b128 v[184:187], v233 offset:1024
	ds_read_b128 v[188:191], v233 offset:2048
	ds_read_b128 v[192:195], v233 offset:3072
	ds_read_b128 v[196:199], v160 offset:32768
	ds_read_b128 v[200:203], v160 offset:33792
	ds_read_b128 v[204:207], v160 offset:34816
	ds_read_b128 v[208:211], v160 offset:35840
	ds_read_b128 v[212:215], v160 offset:36864
	ds_read_b128 v[216:219], v160 offset:37888
	ds_read_b128 v[220:223], v160 offset:38912
	ds_read_b128 v[224:227], v160 offset:39936
	s_waitcnt vmcnt(8)
	s_waitcnt lgkmcnt(0)
	s_setprio 1
	s_barrier
	v_mfma_f32_16x16x32_bf16 v[122:125], v[164:167], v[196:199], v[122:125]
	v_mfma_f32_16x16x32_bf16 v[118:121], v[172:175], v[196:199], v[118:121]
	v_mfma_f32_16x16x32_bf16 v[110:113], v[164:167], v[204:207], v[110:113]
	v_mfma_f32_16x16x32_bf16 v[102:105], v[172:175], v[204:207], v[102:105]
	v_mfma_f32_16x16x32_bf16 v[94:97], v[164:167], v[212:215], v[94:97]
	v_mfma_f32_16x16x32_bf16 v[86:89], v[172:175], v[212:215], v[86:89]
	v_mfma_f32_16x16x32_bf16 v[78:81], v[164:167], v[220:223], v[78:81]
	v_mfma_f32_16x16x32_bf16 v[70:73], v[172:175], v[220:223], v[70:73]
	v_mfma_f32_16x16x32_bf16 v[122:125], v[168:171], v[200:203], v[122:125]
	v_mfma_f32_16x16x32_bf16 v[118:121], v[176:179], v[200:203], v[118:121]
	v_mfma_f32_16x16x32_bf16 v[110:113], v[168:171], v[208:211], v[110:113]
	v_mfma_f32_16x16x32_bf16 v[102:105], v[176:179], v[208:211], v[102:105]
	v_mfma_f32_16x16x32_bf16 v[94:97], v[168:171], v[216:219], v[94:97]
	v_mfma_f32_16x16x32_bf16 v[86:89], v[176:179], v[216:219], v[86:89]
	v_mfma_f32_16x16x32_bf16 v[78:81], v[168:171], v[224:227], v[78:81]
	v_mfma_f32_16x16x32_bf16 v[70:73], v[176:179], v[224:227], v[70:73]
	s_setprio 0
	s_setprio 1
	v_mfma_f32_16x16x32_bf16 v[126:129], v[180:183], v[196:199], v[126:129]
	v_mfma_f32_16x16x32_bf16 v[114:117], v[188:191], v[196:199], v[114:117]
	v_mfma_f32_16x16x32_bf16 v[106:109], v[180:183], v[204:207], v[106:109]
	v_mfma_f32_16x16x32_bf16 v[98:101], v[188:191], v[204:207], v[98:101]
	v_mfma_f32_16x16x32_bf16 v[90:93], v[180:183], v[212:215], v[90:93]
	v_mfma_f32_16x16x32_bf16 v[82:85], v[188:191], v[212:215], v[82:85]
	v_mfma_f32_16x16x32_bf16 v[74:77], v[180:183], v[220:223], v[74:77]
	v_mfma_f32_16x16x32_bf16 v[66:69], v[188:191], v[220:223], v[66:69]
	v_mfma_f32_16x16x32_bf16 v[126:129], v[184:187], v[200:203], v[126:129]
	v_mfma_f32_16x16x32_bf16 v[114:117], v[192:195], v[200:203], v[114:117]
	v_mfma_f32_16x16x32_bf16 v[106:109], v[184:187], v[208:211], v[106:109]
	v_mfma_f32_16x16x32_bf16 v[98:101], v[192:195], v[208:211], v[98:101]
	v_mfma_f32_16x16x32_bf16 v[90:93], v[184:187], v[216:219], v[90:93]
	v_mfma_f32_16x16x32_bf16 v[82:85], v[192:195], v[216:219], v[82:85]
	v_mfma_f32_16x16x32_bf16 v[74:77], v[184:187], v[224:227], v[74:77]
	v_mfma_f32_16x16x32_bf16 v[66:69], v[192:195], v[224:227], v[66:69]
	s_barrier
	s_setprio 0
	s_add_u32 s96, s96, 0x80
	s_addc_u32 s97, s97, 0
	s_add_u32 s98, s96, 0x40000
	s_addc_u32 s99, s97, 0
	s_add_u32 s94, s94, 0x80
	s_addc_u32 s95, s95, 0
	s_add_i32 s7, s7, s47
	s_mov_b32 m0, s7
	s_nop 0
	global_load_lds_dwordx4 v132, s[96:97]
	s_add_i32 m0, s7, 0x2000
	s_add_i32 s7, s55, s47
	global_load_lds_dwordx4 v136, s[96:97]
	s_mov_b32 m0, s7
	s_nop 0
	global_load_lds_dwordx4 v132, s[98:99]
	s_add_i32 m0, s7, 0x2000
	s_nop 0
	global_load_lds_dwordx4 v136, s[98:99]
	s_mov_b32 m0, s65
	s_nop 0
	global_load_lds_dwordx4 v130, s[94:95]
	s_mov_b32 m0, s66
	s_nop 0
	global_load_lds_dwordx4 v134, s[94:95]
	ds_read_b128 v[196:199], v160 offset:49152
	ds_read_b128 v[200:203], v160 offset:50176
	ds_read_b128 v[204:207], v160 offset:51200
	ds_read_b128 v[208:211], v160 offset:52224
	ds_read_b128 v[212:215], v160 offset:53248
	ds_read_b128 v[216:219], v160 offset:54272
	ds_read_b128 v[220:223], v160 offset:55296
	ds_read_b128 v[224:227], v160 offset:56320
	s_waitcnt vmcnt(8)
	s_waitcnt lgkmcnt(0)
	s_setprio 1
	s_barrier
	v_mfma_f32_16x16x32_bf16 v[62:65], v[164:167], v[196:199], v[62:65]
	v_mfma_f32_16x16x32_bf16 v[54:57], v[172:175], v[196:199], v[54:57]
	v_mfma_f32_16x16x32_bf16 v[46:49], v[164:167], v[204:207], v[46:49]
	v_mfma_f32_16x16x32_bf16 v[38:41], v[172:175], v[204:207], v[38:41]
	v_mfma_f32_16x16x32_bf16 v[30:33], v[164:167], v[212:215], v[30:33]
	v_mfma_f32_16x16x32_bf16 v[22:25], v[172:175], v[212:215], v[22:25]
	v_mfma_f32_16x16x32_bf16 v[14:17], v[164:167], v[220:223], v[14:17]
	v_mfma_f32_16x16x32_bf16 v[6:9], v[172:175], v[220:223], v[6:9]
	v_mfma_f32_16x16x32_bf16 v[62:65], v[168:171], v[200:203], v[62:65]
	v_mfma_f32_16x16x32_bf16 v[54:57], v[176:179], v[200:203], v[54:57]
	v_mfma_f32_16x16x32_bf16 v[46:49], v[168:171], v[208:211], v[46:49]
	v_mfma_f32_16x16x32_bf16 v[38:41], v[176:179], v[208:211], v[38:41]
	v_mfma_f32_16x16x32_bf16 v[30:33], v[168:171], v[216:219], v[30:33]
	v_mfma_f32_16x16x32_bf16 v[22:25], v[176:179], v[216:219], v[22:25]
	v_mfma_f32_16x16x32_bf16 v[14:17], v[168:171], v[224:227], v[14:17]
	v_mfma_f32_16x16x32_bf16 v[6:9], v[176:179], v[224:227], v[6:9]
	s_setprio 0
	s_setprio 1
	v_mfma_f32_16x16x32_bf16 v[58:61], v[180:183], v[196:199], v[58:61]
	v_mfma_f32_16x16x32_bf16 v[50:53], v[188:191], v[196:199], v[50:53]
	v_mfma_f32_16x16x32_bf16 v[42:45], v[180:183], v[204:207], v[42:45]
	v_mfma_f32_16x16x32_bf16 v[34:37], v[188:191], v[204:207], v[34:37]
	v_mfma_f32_16x16x32_bf16 v[26:29], v[180:183], v[212:215], v[26:29]
	v_mfma_f32_16x16x32_bf16 v[18:21], v[188:191], v[212:215], v[18:21]
	v_mfma_f32_16x16x32_bf16 v[10:13], v[180:183], v[220:223], v[10:13]
	v_mfma_f32_16x16x32_bf16 v[2:5], v[188:191], v[220:223], v[2:5]
	v_mfma_f32_16x16x32_bf16 v[58:61], v[184:187], v[200:203], v[58:61]
	v_mfma_f32_16x16x32_bf16 v[50:53], v[192:195], v[200:203], v[50:53]
	v_mfma_f32_16x16x32_bf16 v[42:45], v[184:187], v[208:211], v[42:45]
	v_mfma_f32_16x16x32_bf16 v[34:37], v[192:195], v[208:211], v[34:37]
	v_mfma_f32_16x16x32_bf16 v[26:29], v[184:187], v[216:219], v[26:29]
	v_mfma_f32_16x16x32_bf16 v[18:21], v[192:195], v[216:219], v[18:21]
	v_mfma_f32_16x16x32_bf16 v[10:13], v[184:187], v[224:227], v[10:13]
	v_mfma_f32_16x16x32_bf16 v[2:5], v[192:195], v[224:227], v[2:5]
	s_barrier
	s_setprio 0
	s_mov_b32 s7, s51
	s_add_u32 s88, s88, 0x100
	s_addc_u32 s89, s89, 0
	s_add_u32 s86, s86, 0x100
	s_addc_u32 s87, s87, 0
	s_cmp_ge_i32 s51, s101
	s_cbranch_scc0 .LBB0_171

.LBB0_308:
	v_cmp_gt_i32_e32 vcc, 1, v141
	s_cbranch_vccnz .LBB0_370
	v_lshl_add_u64 v[154:155], v[2:3], 0, s[28:29]
	v_add_u32_e32 v138, -2, v141
	s_mov_b32 s8, 0
	s_nop 0
	v_readfirstlane_b32 s86, v152
	v_readfirstlane_b32 s87, v153
	v_readfirstlane_b32 s88, v154
	v_readfirstlane_b32 s89, v155
	v_readfirstlane_b32 s90, v148
	v_readfirstlane_b32 s91, v149
	v_readfirstlane_b32 s92, v150
	v_readfirstlane_b32 s93, v151
	v_readfirstlane_b32 s100, v138
	v_readfirstlane_b32 s101, v141
	v_add_u32_e32 v230, s69, v160
	v_add_u32_e32 v231, s72, v160
	v_add_u32_e32 v232, 0x18000, v160
	v_add_u32_e32 v233, 0x1c000, v160
	s_add_u32 s98, s86, 0x100
	s_addc_u32 s99, s87, 0
	s_cmp_eq_u32 s8, s100
	s_cselect_b64 s[94:95], s[90:91], s[98:99]
	s_cselect_b64 s[96:97], s[92:93], s[88:89]
	s_add_i32 s9, s8, 2
	s_nop 0
	s_add_i32 m0, s55, 0xc000
	s_nop 0
	global_load_lds_dwordx4 v144, s[86:87]
	s_add_i32 m0, s55, 0xe000
	s_nop 0
	global_load_lds_dwordx4 v142, s[86:87]
	ds_read_b128 v[166:169], v230
	ds_read_b128 v[170:173], v230 offset:1024
	ds_read_b128 v[174:177], v230 offset:2048
	ds_read_b128 v[178:181], v230 offset:3072
	ds_read_b128 v[182:185], v231
	ds_read_b128 v[186:189], v231 offset:1024
	ds_read_b128 v[190:193], v231 offset:2048
	ds_read_b128 v[194:197], v231 offset:3072
	ds_read_b128 v[198:201], v163
	ds_read_b128 v[202:205], v163 offset:1024
	ds_read_b128 v[206:209], v163 offset:2048
	ds_read_b128 v[210:213], v163 offset:3072
	ds_read_b128 v[214:217], v163 offset:4096
	ds_read_b128 v[218:221], v163 offset:5120
	ds_read_b128 v[222:225], v163 offset:6144
	ds_read_b128 v[226:229], v163 offset:7168
	s_waitcnt vmcnt(8)
	s_waitcnt lgkmcnt(0)
	s_setprio 1
	s_barrier
	v_mfma_f32_16x16x32_bf16 v[122:125], v[166:169], v[198:201], 0
	v_mfma_f32_16x16x32_bf16 v[118:121], v[174:177], v[198:201], 0
	v_mfma_f32_16x16x32_bf16 v[110:113], v[166:169], v[206:209], 0
	v_mfma_f32_16x16x32_bf16 v[102:105], v[174:177], v[206:209], 0
	v_mfma_f32_16x16x32_bf16 v[94:97], v[166:169], v[214:217], 0
	v_mfma_f32_16x16x32_bf16 v[86:89], v[174:177], v[214:217], 0
	v_mfma_f32_16x16x32_bf16 v[78:81], v[166:169], v[222:225], 0
	v_mfma_f32_16x16x32_bf16 v[70:73], v[174:177], v[222:225], 0
	v_mfma_f32_16x16x32_bf16 v[122:125], v[170:173], v[202:205], v[122:125]
	v_mfma_f32_16x16x32_bf16 v[118:121], v[178:181], v[202:205], v[118:121]
	v_mfma_f32_16x16x32_bf16 v[110:113], v[170:173], v[210:213], v[110:113]
	v_mfma_f32_16x16x32_bf16 v[102:105], v[178:181], v[210:213], v[102:105]
	v_mfma_f32_16x16x32_bf16 v[94:97], v[170:173], v[218:221], v[94:97]
	v_mfma_f32_16x16x32_bf16 v[86:89], v[178:181], v[218:221], v[86:89]
	v_mfma_f32_16x16x32_bf16 v[78:81], v[170:173], v[226:229], v[78:81]
	v_mfma_f32_16x16x32_bf16 v[70:73], v[178:181], v[226:229], v[70:73]
	s_setprio 0
	s_setprio 1
	v_mfma_f32_16x16x32_bf16 v[126:129], v[182:185], v[198:201], 0
	v_mfma_f32_16x16x32_bf16 v[114:117], v[190:193], v[198:201], 0
	v_mfma_f32_16x16x32_bf16 v[106:109], v[182:185], v[206:209], 0
	v_mfma_f32_16x16x32_bf16 v[98:101], v[190:193], v[206:209], 0
	v_mfma_f32_16x16x32_bf16 v[90:93], v[182:185], v[214:217], 0
	v_mfma_f32_16x16x32_bf16 v[82:85], v[190:193], v[214:217], 0
	v_mfma_f32_16x16x32_bf16 v[74:77], v[182:185], v[222:225], 0
	v_mfma_f32_16x16x32_bf16 v[66:69], v[190:193], v[222:225], 0
	v_mfma_f32_16x16x32_bf16 v[126:129], v[186:189], v[202:205], v[126:129]
	v_mfma_f32_16x16x32_bf16 v[114:117], v[194:197], v[202:205], v[114:117]
	v_mfma_f32_16x16x32_bf16 v[106:109], v[186:189], v[210:213], v[106:109]
	v_mfma_f32_16x16x32_bf16 v[98:101], v[194:197], v[210:213], v[98:101]
	v_mfma_f32_16x16x32_bf16 v[90:93], v[186:189], v[218:221], v[90:93]
	v_mfma_f32_16x16x32_bf16 v[82:85], v[194:197], v[218:221], v[82:85]
	v_mfma_f32_16x16x32_bf16 v[74:77], v[186:189], v[226:229], v[74:77]
	v_mfma_f32_16x16x32_bf16 v[66:69], v[194:197], v[226:229], v[66:69]
	s_barrier
	s_setprio 0
	s_add_u32 s98, s96, 0xb0000
	s_addc_u32 s99, s97, 0
	s_add_i32 s8, s69, s54
	s_mov_b32 m0, s8
	s_nop 0
	global_load_lds_dwordx4 v132, s[96:97]
	s_add_i32 m0, s8, 0x2000
	s_add_i32 s8, s72, s54
	global_load_lds_dwordx4 v136, s[96:97]
	s_mov_b32 m0, s8
	s_nop 0
	global_load_lds_dwordx4 v132, s[98:99]
	s_add_i32 m0, s8, 0x2000
	s_nop 0
	global_load_lds_dwordx4 v136, s[98:99]
	s_mov_b32 m0, s55
	s_nop 0
	global_load_lds_dwordx4 v130, s[94:95]
	s_mov_b32 m0, s56
	s_nop 0
	global_load_lds_dwordx4 v134, s[94:95]
	ds_read_b128 v[198:201], v163 offset:16384
	ds_read_b128 v[202:205], v163 offset:17408
	ds_read_b128 v[206:209], v163 offset:18432
	ds_read_b128 v[210:213], v163 offset:19456
	ds_read_b128 v[214:217], v163 offset:20480
	ds_read_b128 v[218:221], v163 offset:21504
	ds_read_b128 v[222:225], v163 offset:22528
	ds_read_b128 v[226:229], v163 offset:23552
	s_waitcnt vmcnt(8)
	s_waitcnt lgkmcnt(0)
	s_setprio 1
	s_barrier
	v_mfma_f32_16x16x32_bf16 v[62:65], v[166:169], v[198:201], 0
	v_mfma_f32_16x16x32_bf16 v[54:57], v[174:177], v[198:201], 0
	v_mfma_f32_16x16x32_bf16 v[46:49], v[166:169], v[206:209], 0
	v_mfma_f32_16x16x32_bf16 v[38:41], v[174:177], v[206:209], 0
	v_mfma_f32_16x16x32_bf16 v[30:33], v[166:169], v[214:217], 0
	v_mfma_f32_16x16x32_bf16 v[22:25], v[174:177], v[214:217], 0
	v_mfma_f32_16x16x32_bf16 v[14:17], v[166:169], v[222:225], 0
	v_mfma_f32_16x16x32_bf16 v[6:9], v[174:177], v[222:225], 0
	v_mfma_f32_16x16x32_bf16 v[62:65], v[170:173], v[202:205], v[62:65]
	v_mfma_f32_16x16x32_bf16 v[54:57], v[178:181], v[202:205], v[54:57]
	v_mfma_f32_16x16x32_bf16 v[46:49], v[170:173], v[210:213], v[46:49]
	v_mfma_f32_16x16x32_bf16 v[38:41], v[178:181], v[210:213], v[38:41]
	v_mfma_f32_16x16x32_bf16 v[30:33], v[170:173], v[218:221], v[30:33]
	v_mfma_f32_16x16x32_bf16 v[22:25], v[178:181], v[218:221], v[22:25]
	v_mfma_f32_16x16x32_bf16 v[14:17], v[170:173], v[226:229], v[14:17]
	v_mfma_f32_16x16x32_bf16 v[6:9], v[178:181], v[226:229], v[6:9]
	s_setprio 0
	s_setprio 1
	v_mfma_f32_16x16x32_bf16 v[58:61], v[182:185], v[198:201], 0
	v_mfma_f32_16x16x32_bf16 v[50:53], v[190:193], v[198:201], 0
	v_mfma_f32_16x16x32_bf16 v[42:45], v[182:185], v[206:209], 0
	v_mfma_f32_16x16x32_bf16 v[34:37], v[190:193], v[206:209], 0
	v_mfma_f32_16x16x32_bf16 v[26:29], v[182:185], v[214:217], 0
	v_mfma_f32_16x16x32_bf16 v[18:21], v[190:193], v[214:217], 0
	v_mfma_f32_16x16x32_bf16 v[10:13], v[182:185], v[222:225], 0
	v_mfma_f32_16x16x32_bf16 v[2:5], v[190:193], v[222:225], 0
	v_mfma_f32_16x16x32_bf16 v[58:61], v[186:189], v[202:205], v[58:61]
	v_mfma_f32_16x16x32_bf16 v[50:53], v[194:197], v[202:205], v[50:53]
	v_mfma_f32_16x16x32_bf16 v[42:45], v[186:189], v[210:213], v[42:45]
	v_mfma_f32_16x16x32_bf16 v[34:37], v[194:197], v[210:213], v[34:37]
	v_mfma_f32_16x16x32_bf16 v[26:29], v[186:189], v[218:221], v[26:29]
	v_mfma_f32_16x16x32_bf16 v[18:21], v[194:197], v[218:221], v[18:21]
	v_mfma_f32_16x16x32_bf16 v[10:13], v[186:189], v[226:229], v[10:13]
	v_mfma_f32_16x16x32_bf16 v[2:5], v[194:197], v[226:229], v[2:5]
	s_barrier
	s_setprio 0
	s_add_u32 s98, s94, 0xb0000
	s_addc_u32 s99, s95, 0
	s_add_i32 s8, 0, 0x18000
	s_add_i32 s50, 0, 0x1c000
	s_mov_b32 m0, s57
	s_nop 0
	global_load_lds_dwordx4 v130, s[98:99]
	s_mov_b32 m0, s58
	s_nop 0
	global_load_lds_dwordx4 v134, s[98:99]
	ds_read_b128 v[166:169], v232
	ds_read_b128 v[170:173], v232 offset:1024
	ds_read_b128 v[174:177], v232 offset:2048
	ds_read_b128 v[178:181], v232 offset:3072
	ds_read_b128 v[182:185], v233
	ds_read_b128 v[186:189], v233 offset:1024
	ds_read_b128 v[190:193], v233 offset:2048
	ds_read_b128 v[194:197], v233 offset:3072
	ds_read_b128 v[198:201], v163 offset:32768
	ds_read_b128 v[202:205], v163 offset:33792
	ds_read_b128 v[206:209], v163 offset:34816
	ds_read_b128 v[210:213], v163 offset:35840
	ds_read_b128 v[214:217], v163 offset:36864
	ds_read_b128 v[218:221], v163 offset:37888
	ds_read_b128 v[222:225], v163 offset:38912
	ds_read_b128 v[226:229], v163 offset:39936
	s_waitcnt vmcnt(8)
	s_waitcnt lgkmcnt(0)
	s_setprio 1
	s_barrier
	v_mfma_f32_16x16x32_bf16 v[122:125], v[166:169], v[198:201], v[122:125]
	v_mfma_f32_16x16x32_bf16 v[118:121], v[174:177], v[198:201], v[118:121]
	v_mfma_f32_16x16x32_bf16 v[110:113], v[166:169], v[206:209], v[110:113]
	v_mfma_f32_16x16x32_bf16 v[102:105], v[174:177], v[206:209], v[102:105]
	v_mfma_f32_16x16x32_bf16 v[94:97], v[166:169], v[214:217], v[94:97]
	v_mfma_f32_16x16x32_bf16 v[86:89], v[174:177], v[214:217], v[86:89]
	v_mfma_f32_16x16x32_bf16 v[78:81], v[166:169], v[222:225], v[78:81]
	v_mfma_f32_16x16x32_bf16 v[70:73], v[174:177], v[222:225], v[70:73]
	v_mfma_f32_16x16x32_bf16 v[122:125], v[170:173], v[202:205], v[122:125]
	v_mfma_f32_16x16x32_bf16 v[118:121], v[178:181], v[202:205], v[118:121]
	v_mfma_f32_16x16x32_bf16 v[110:113], v[170:173], v[210:213], v[110:113]
	v_mfma_f32_16x16x32_bf16 v[102:105], v[178:181], v[210:213], v[102:105]
	v_mfma_f32_16x16x32_bf16 v[94:97], v[170:173], v[218:221], v[94:97]
	v_mfma_f32_16x16x32_bf16 v[86:89], v[178:181], v[218:221], v[86:89]
	v_mfma_f32_16x16x32_bf16 v[78:81], v[170:173], v[226:229], v[78:81]
	v_mfma_f32_16x16x32_bf16 v[70:73], v[178:181], v[226:229], v[70:73]
	s_setprio 0
	s_setprio 1
	v_mfma_f32_16x16x32_bf16 v[126:129], v[182:185], v[198:201], v[126:129]
	v_mfma_f32_16x16x32_bf16 v[114:117], v[190:193], v[198:201], v[114:117]
	v_mfma_f32_16x16x32_bf16 v[106:109], v[182:185], v[206:209], v[106:109]
	v_mfma_f32_16x16x32_bf16 v[98:101], v[190:193], v[206:209], v[98:101]
	v_mfma_f32_16x16x32_bf16 v[90:93], v[182:185], v[214:217], v[90:93]
	v_mfma_f32_16x16x32_bf16 v[82:85], v[190:193], v[214:217], v[82:85]
	v_mfma_f32_16x16x32_bf16 v[74:77], v[182:185], v[222:225], v[74:77]
	v_mfma_f32_16x16x32_bf16 v[66:69], v[190:193], v[222:225], v[66:69]
	v_mfma_f32_16x16x32_bf16 v[126:129], v[186:189], v[202:205], v[126:129]
	v_mfma_f32_16x16x32_bf16 v[114:117], v[194:197], v[202:205], v[114:117]
	v_mfma_f32_16x16x32_bf16 v[106:109], v[186:189], v[210:213], v[106:109]
	v_mfma_f32_16x16x32_bf16 v[98:101], v[194:197], v[210:213], v[98:101]
	v_mfma_f32_16x16x32_bf16 v[90:93], v[186:189], v[218:221], v[90:93]
	v_mfma_f32_16x16x32_bf16 v[82:85], v[194:197], v[218:221], v[82:85]
	v_mfma_f32_16x16x32_bf16 v[74:77], v[186:189], v[226:229], v[74:77]
	v_mfma_f32_16x16x32_bf16 v[66:69], v[194:197], v[226:229], v[66:69]
	s_barrier
	s_setprio 0
	s_add_u32 s96, s96, 0x80
	s_addc_u32 s97, s97, 0
	s_add_u32 s98, s96, 0xb0000
	s_addc_u32 s99, s97, 0
	s_add_u32 s94, s94, 0x80
	s_addc_u32 s95, s95, 0
	s_add_i32 s8, s8, s54
	s_mov_b32 m0, s8
	s_nop 0
	global_load_lds_dwordx4 v132, s[96:97]
	s_add_i32 m0, s8, 0x2000
	s_add_i32 s8, s50, s54
	global_load_lds_dwordx4 v136, s[96:97]
	s_mov_b32 m0, s8
	s_nop 0
	global_load_lds_dwordx4 v132, s[98:99]
	s_add_i32 m0, s8, 0x2000
	s_nop 0
	global_load_lds_dwordx4 v136, s[98:99]
	s_mov_b32 m0, s64
	s_nop 0
	global_load_lds_dwordx4 v130, s[94:95]
	s_mov_b32 m0, s65
	s_nop 0
	global_load_lds_dwordx4 v134, s[94:95]
	ds_read_b128 v[198:201], v163 offset:49152
	ds_read_b128 v[202:205], v163 offset:50176
	ds_read_b128 v[206:209], v163 offset:51200
	ds_read_b128 v[210:213], v163 offset:52224
	ds_read_b128 v[214:217], v163 offset:53248
	ds_read_b128 v[218:221], v163 offset:54272
	ds_read_b128 v[222:225], v163 offset:55296
	ds_read_b128 v[226:229], v163 offset:56320
	s_waitcnt vmcnt(8)
	s_waitcnt lgkmcnt(0)
	s_setprio 1
	s_barrier
	v_mfma_f32_16x16x32_bf16 v[62:65], v[166:169], v[198:201], v[62:65]
	v_mfma_f32_16x16x32_bf16 v[54:57], v[174:177], v[198:201], v[54:57]
	v_mfma_f32_16x16x32_bf16 v[46:49], v[166:169], v[206:209], v[46:49]
	v_mfma_f32_16x16x32_bf16 v[38:41], v[174:177], v[206:209], v[38:41]
	v_mfma_f32_16x16x32_bf16 v[30:33], v[166:169], v[214:217], v[30:33]
	v_mfma_f32_16x16x32_bf16 v[22:25], v[174:177], v[214:217], v[22:25]
	v_mfma_f32_16x16x32_bf16 v[14:17], v[166:169], v[222:225], v[14:17]
	v_mfma_f32_16x16x32_bf16 v[6:9], v[174:177], v[222:225], v[6:9]
	v_mfma_f32_16x16x32_bf16 v[62:65], v[170:173], v[202:205], v[62:65]
	v_mfma_f32_16x16x32_bf16 v[54:57], v[178:181], v[202:205], v[54:57]
	v_mfma_f32_16x16x32_bf16 v[46:49], v[170:173], v[210:213], v[46:49]
	v_mfma_f32_16x16x32_bf16 v[38:41], v[178:181], v[210:213], v[38:41]
	v_mfma_f32_16x16x32_bf16 v[30:33], v[170:173], v[218:221], v[30:33]
	v_mfma_f32_16x16x32_bf16 v[22:25], v[178:181], v[218:221], v[22:25]
	v_mfma_f32_16x16x32_bf16 v[14:17], v[170:173], v[226:229], v[14:17]
	v_mfma_f32_16x16x32_bf16 v[6:9], v[178:181], v[226:229], v[6:9]
	s_setprio 0
	s_setprio 1
	v_mfma_f32_16x16x32_bf16 v[58:61], v[182:185], v[198:201], v[58:61]
	v_mfma_f32_16x16x32_bf16 v[50:53], v[190:193], v[198:201], v[50:53]
	v_mfma_f32_16x16x32_bf16 v[42:45], v[182:185], v[206:209], v[42:45]
	v_mfma_f32_16x16x32_bf16 v[34:37], v[190:193], v[206:209], v[34:37]
	v_mfma_f32_16x16x32_bf16 v[26:29], v[182:185], v[214:217], v[26:29]
	v_mfma_f32_16x16x32_bf16 v[18:21], v[190:193], v[214:217], v[18:21]
	v_mfma_f32_16x16x32_bf16 v[10:13], v[182:185], v[222:225], v[10:13]
	v_mfma_f32_16x16x32_bf16 v[2:5], v[190:193], v[222:225], v[2:5]
	v_mfma_f32_16x16x32_bf16 v[58:61], v[186:189], v[202:205], v[58:61]
	v_mfma_f32_16x16x32_bf16 v[50:53], v[194:197], v[202:205], v[50:53]
	v_mfma_f32_16x16x32_bf16 v[42:45], v[186:189], v[210:213], v[42:45]
	v_mfma_f32_16x16x32_bf16 v[34:37], v[194:197], v[210:213], v[34:37]
	v_mfma_f32_16x16x32_bf16 v[26:29], v[186:189], v[218:221], v[26:29]
	v_mfma_f32_16x16x32_bf16 v[18:21], v[194:197], v[218:221], v[18:21]
	v_mfma_f32_16x16x32_bf16 v[10:13], v[186:189], v[226:229], v[10:13]
	v_mfma_f32_16x16x32_bf16 v[2:5], v[194:197], v[226:229], v[2:5]
	s_barrier
	s_setprio 0
	s_mov_b32 s8, s9
	s_add_u32 s88, s88, 0x100
	s_addc_u32 s89, s89, 0
	s_add_u32 s86, s86, 0x100
	s_addc_u32 s87, s87, 0
	s_cmp_ge_i32 s9, s101
	s_cbranch_scc1 .Lmy_kexit_1
.LBB0_310:
	s_add_u32 s98, s86, 0x100
	s_addc_u32 s99, s87, 0
	s_cmp_eq_u32 s8, s100
	s_cselect_b64 s[94:95], s[90:91], s[98:99]
	s_cselect_b64 s[96:97], s[92:93], s[88:89]
	s_add_i32 s9, s8, 2
	s_nop 0
	s_add_i32 m0, s55, 0xc000
	s_nop 0
	global_load_lds_dwordx4 v144, s[86:87]
	s_add_i32 m0, s55, 0xe000
	s_nop 0
	global_load_lds_dwordx4 v142, s[86:87]
	ds_read_b128 v[166:169], v230
	ds_read_b128 v[170:173], v230 offset:1024
	ds_read_b128 v[174:177], v230 offset:2048
	ds_read_b128 v[178:181], v230 offset:3072
	ds_read_b128 v[182:185], v231
	ds_read_b128 v[186:189], v231 offset:1024
	ds_read_b128 v[190:193], v231 offset:2048
	ds_read_b128 v[194:197], v231 offset:3072
	ds_read_b128 v[198:201], v163
	ds_read_b128 v[202:205], v163 offset:1024
	ds_read_b128 v[206:209], v163 offset:2048
	ds_read_b128 v[210:213], v163 offset:3072
	ds_read_b128 v[214:217], v163 offset:4096
	ds_read_b128 v[218:221], v163 offset:5120
	ds_read_b128 v[222:225], v163 offset:6144
	ds_read_b128 v[226:229], v163 offset:7168
	s_waitcnt vmcnt(8)
	s_waitcnt lgkmcnt(0)
	s_setprio 1
	s_barrier
	v_mfma_f32_16x16x32_bf16 v[122:125], v[166:169], v[198:201], v[122:125]
	v_mfma_f32_16x16x32_bf16 v[118:121], v[174:177], v[198:201], v[118:121]
	v_mfma_f32_16x16x32_bf16 v[110:113], v[166:169], v[206:209], v[110:113]
	v_mfma_f32_16x16x32_bf16 v[102:105], v[174:177], v[206:209], v[102:105]
	v_mfma_f32_16x16x32_bf16 v[94:97], v[166:169], v[214:217], v[94:97]
	v_mfma_f32_16x16x32_bf16 v[86:89], v[174:177], v[214:217], v[86:89]
	v_mfma_f32_16x16x32_bf16 v[78:81], v[166:169], v[222:225], v[78:81]
	v_mfma_f32_16x16x32_bf16 v[70:73], v[174:177], v[222:225], v[70:73]
	v_mfma_f32_16x16x32_bf16 v[122:125], v[170:173], v[202:205], v[122:125]
	v_mfma_f32_16x16x32_bf16 v[118:121], v[178:181], v[202:205], v[118:121]
	v_mfma_f32_16x16x32_bf16 v[110:113], v[170:173], v[210:213], v[110:113]
	v_mfma_f32_16x16x32_bf16 v[102:105], v[178:181], v[210:213], v[102:105]
	v_mfma_f32_16x16x32_bf16 v[94:97], v[170:173], v[218:221], v[94:97]
	v_mfma_f32_16x16x32_bf16 v[86:89], v[178:181], v[218:221], v[86:89]
	v_mfma_f32_16x16x32_bf16 v[78:81], v[170:173], v[226:229], v[78:81]
	v_mfma_f32_16x16x32_bf16 v[70:73], v[178:181], v[226:229], v[70:73]
	s_setprio 0
	s_setprio 1
	v_mfma_f32_16x16x32_bf16 v[126:129], v[182:185], v[198:201], v[126:129]
	v_mfma_f32_16x16x32_bf16 v[114:117], v[190:193], v[198:201], v[114:117]
	v_mfma_f32_16x16x32_bf16 v[106:109], v[182:185], v[206:209], v[106:109]
	v_mfma_f32_16x16x32_bf16 v[98:101], v[190:193], v[206:209], v[98:101]
	v_mfma_f32_16x16x32_bf16 v[90:93], v[182:185], v[214:217], v[90:93]
	v_mfma_f32_16x16x32_bf16 v[82:85], v[190:193], v[214:217], v[82:85]
	v_mfma_f32_16x16x32_bf16 v[74:77], v[182:185], v[222:225], v[74:77]
	v_mfma_f32_16x16x32_bf16 v[66:69], v[190:193], v[222:225], v[66:69]
	v_mfma_f32_16x16x32_bf16 v[126:129], v[186:189], v[202:205], v[126:129]
	v_mfma_f32_16x16x32_bf16 v[114:117], v[194:197], v[202:205], v[114:117]
	v_mfma_f32_16x16x32_bf16 v[106:109], v[186:189], v[210:213], v[106:109]
	v_mfma_f32_16x16x32_bf16 v[98:101], v[194:197], v[210:213], v[98:101]
	v_mfma_f32_16x16x32_bf16 v[90:93], v[186:189], v[218:221], v[90:93]
	v_mfma_f32_16x16x32_bf16 v[82:85], v[194:197], v[218:221], v[82:85]
	v_mfma_f32_16x16x32_bf16 v[74:77], v[186:189], v[226:229], v[74:77]
	v_mfma_f32_16x16x32_bf16 v[66:69], v[194:197], v[226:229], v[66:69]
	s_barrier
	s_setprio 0
	s_add_u32 s98, s96, 0xb0000
	s_addc_u32 s99, s97, 0
	s_add_i32 s8, s69, s54
	s_mov_b32 m0, s8
	s_nop 0
	global_load_lds_dwordx4 v132, s[96:97]
	s_add_i32 m0, s8, 0x2000
	s_add_i32 s8, s72, s54
	global_load_lds_dwordx4 v136, s[96:97]
	s_mov_b32 m0, s8
	s_nop 0
	global_load_lds_dwordx4 v132, s[98:99]
	s_add_i32 m0, s8, 0x2000
	s_nop 0
	global_load_lds_dwordx4 v136, s[98:99]
	s_mov_b32 m0, s55
	s_nop 0
	global_load_lds_dwordx4 v130, s[94:95]
	s_mov_b32 m0, s56
	s_nop 0
	global_load_lds_dwordx4 v134, s[94:95]
	ds_read_b128 v[198:201], v163 offset:16384
	ds_read_b128 v[202:205], v163 offset:17408
	ds_read_b128 v[206:209], v163 offset:18432
	ds_read_b128 v[210:213], v163 offset:19456
	ds_read_b128 v[214:217], v163 offset:20480
	ds_read_b128 v[218:221], v163 offset:21504
	ds_read_b128 v[222:225], v163 offset:22528
	ds_read_b128 v[226:229], v163 offset:23552
	s_waitcnt vmcnt(8)
	s_waitcnt lgkmcnt(0)
	s_setprio 1
	s_barrier
	v_mfma_f32_16x16x32_bf16 v[62:65], v[166:169], v[198:201], v[62:65]
	v_mfma_f32_16x16x32_bf16 v[54:57], v[174:177], v[198:201], v[54:57]
	v_mfma_f32_16x16x32_bf16 v[46:49], v[166:169], v[206:209], v[46:49]
	v_mfma_f32_16x16x32_bf16 v[38:41], v[174:177], v[206:209], v[38:41]
	v_mfma_f32_16x16x32_bf16 v[30:33], v[166:169], v[214:217], v[30:33]
	v_mfma_f32_16x16x32_bf16 v[22:25], v[174:177], v[214:217], v[22:25]
	v_mfma_f32_16x16x32_bf16 v[14:17], v[166:169], v[222:225], v[14:17]
	v_mfma_f32_16x16x32_bf16 v[6:9], v[174:177], v[222:225], v[6:9]
	v_mfma_f32_16x16x32_bf16 v[62:65], v[170:173], v[202:205], v[62:65]
	v_mfma_f32_16x16x32_bf16 v[54:57], v[178:181], v[202:205], v[54:57]
	v_mfma_f32_16x16x32_bf16 v[46:49], v[170:173], v[210:213], v[46:49]
	v_mfma_f32_16x16x32_bf16 v[38:41], v[178:181], v[210:213], v[38:41]
	v_mfma_f32_16x16x32_bf16 v[30:33], v[170:173], v[218:221], v[30:33]
	v_mfma_f32_16x16x32_bf16 v[22:25], v[178:181], v[218:221], v[22:25]
	v_mfma_f32_16x16x32_bf16 v[14:17], v[170:173], v[226:229], v[14:17]
	v_mfma_f32_16x16x32_bf16 v[6:9], v[178:181], v[226:229], v[6:9]
	s_setprio 0
	s_setprio 1
	v_mfma_f32_16x16x32_bf16 v[58:61], v[182:185], v[198:201], v[58:61]
	v_mfma_f32_16x16x32_bf16 v[50:53], v[190:193], v[198:201], v[50:53]
	v_mfma_f32_16x16x32_bf16 v[42:45], v[182:185], v[206:209], v[42:45]
	v_mfma_f32_16x16x32_bf16 v[34:37], v[190:193], v[206:209], v[34:37]
	v_mfma_f32_16x16x32_bf16 v[26:29], v[182:185], v[214:217], v[26:29]
	v_mfma_f32_16x16x32_bf16 v[18:21], v[190:193], v[214:217], v[18:21]
	v_mfma_f32_16x16x32_bf16 v[10:13], v[182:185], v[222:225], v[10:13]
	v_mfma_f32_16x16x32_bf16 v[2:5], v[190:193], v[222:225], v[2:5]
	v_mfma_f32_16x16x32_bf16 v[58:61], v[186:189], v[202:205], v[58:61]
	v_mfma_f32_16x16x32_bf16 v[50:53], v[194:197], v[202:205], v[50:53]
	v_mfma_f32_16x16x32_bf16 v[42:45], v[186:189], v[210:213], v[42:45]
	v_mfma_f32_16x16x32_bf16 v[34:37], v[194:197], v[210:213], v[34:37]
	v_mfma_f32_16x16x32_bf16 v[26:29], v[186:189], v[218:221], v[26:29]
	v_mfma_f32_16x16x32_bf16 v[18:21], v[194:197], v[218:221], v[18:21]
	v_mfma_f32_16x16x32_bf16 v[10:13], v[186:189], v[226:229], v[10:13]
	v_mfma_f32_16x16x32_bf16 v[2:5], v[194:197], v[226:229], v[2:5]
	s_barrier
	s_setprio 0
	s_add_u32 s98, s94, 0xb0000
	s_addc_u32 s99, s95, 0
	s_add_i32 s8, 0, 0x18000
	s_add_i32 s50, 0, 0x1c000
	s_mov_b32 m0, s57
	s_nop 0
	global_load_lds_dwordx4 v130, s[98:99]
	s_mov_b32 m0, s58
	s_nop 0
	global_load_lds_dwordx4 v134, s[98:99]
	ds_read_b128 v[166:169], v232
	ds_read_b128 v[170:173], v232 offset:1024
	ds_read_b128 v[174:177], v232 offset:2048
	ds_read_b128 v[178:181], v232 offset:3072
	ds_read_b128 v[182:185], v233
	ds_read_b128 v[186:189], v233 offset:1024
	ds_read_b128 v[190:193], v233 offset:2048
	ds_read_b128 v[194:197], v233 offset:3072
	ds_read_b128 v[198:201], v163 offset:32768
	ds_read_b128 v[202:205], v163 offset:33792
	ds_read_b128 v[206:209], v163 offset:34816
	ds_read_b128 v[210:213], v163 offset:35840
	ds_read_b128 v[214:217], v163 offset:36864
	ds_read_b128 v[218:221], v163 offset:37888
	ds_read_b128 v[222:225], v163 offset:38912
	ds_read_b128 v[226:229], v163 offset:39936
	s_waitcnt vmcnt(8)
	s_waitcnt lgkmcnt(0)
	s_setprio 1
	s_barrier
	v_mfma_f32_16x16x32_bf16 v[122:125], v[166:169], v[198:201], v[122:125]
	v_mfma_f32_16x16x32_bf16 v[118:121], v[174:177], v[198:201], v[118:121]
	v_mfma_f32_16x16x32_bf16 v[110:113], v[166:169], v[206:209], v[110:113]
	v_mfma_f32_16x16x32_bf16 v[102:105], v[174:177], v[206:209], v[102:105]
	v_mfma_f32_16x16x32_bf16 v[94:97], v[166:169], v[214:217], v[94:97]
	v_mfma_f32_16x16x32_bf16 v[86:89], v[174:177], v[214:217], v[86:89]
	v_mfma_f32_16x16x32_bf16 v[78:81], v[166:169], v[222:225], v[78:81]
	v_mfma_f32_16x16x32_bf16 v[70:73], v[174:177], v[222:225], v[70:73]
	v_mfma_f32_16x16x32_bf16 v[122:125], v[170:173], v[202:205], v[122:125]
	v_mfma_f32_16x16x32_bf16 v[118:121], v[178:181], v[202:205], v[118:121]
	v_mfma_f32_16x16x32_bf16 v[110:113], v[170:173], v[210:213], v[110:113]
	v_mfma_f32_16x16x32_bf16 v[102:105], v[178:181], v[210:213], v[102:105]
	v_mfma_f32_16x16x32_bf16 v[94:97], v[170:173], v[218:221], v[94:97]
	v_mfma_f32_16x16x32_bf16 v[86:89], v[178:181], v[218:221], v[86:89]
	v_mfma_f32_16x16x32_bf16 v[78:81], v[170:173], v[226:229], v[78:81]
	v_mfma_f32_16x16x32_bf16 v[70:73], v[178:181], v[226:229], v[70:73]
	s_setprio 0
	s_setprio 1
	v_mfma_f32_16x16x32_bf16 v[126:129], v[182:185], v[198:201], v[126:129]
	v_mfma_f32_16x16x32_bf16 v[114:117], v[190:193], v[198:201], v[114:117]
	v_mfma_f32_16x16x32_bf16 v[106:109], v[182:185], v[206:209], v[106:109]
	v_mfma_f32_16x16x32_bf16 v[98:101], v[190:193], v[206:209], v[98:101]
	v_mfma_f32_16x16x32_bf16 v[90:93], v[182:185], v[214:217], v[90:93]
	v_mfma_f32_16x16x32_bf16 v[82:85], v[190:193], v[214:217], v[82:85]
	v_mfma_f32_16x16x32_bf16 v[74:77], v[182:185], v[222:225], v[74:77]
	v_mfma_f32_16x16x32_bf16 v[66:69], v[190:193], v[222:225], v[66:69]
	v_mfma_f32_16x16x32_bf16 v[126:129], v[186:189], v[202:205], v[126:129]
	v_mfma_f32_16x16x32_bf16 v[114:117], v[194:197], v[202:205], v[114:117]
	v_mfma_f32_16x16x32_bf16 v[106:109], v[186:189], v[210:213], v[106:109]
	v_mfma_f32_16x16x32_bf16 v[98:101], v[194:197], v[210:213], v[98:101]
	v_mfma_f32_16x16x32_bf16 v[90:93], v[186:189], v[218:221], v[90:93]
	v_mfma_f32_16x16x32_bf16 v[82:85], v[194:197], v[218:221], v[82:85]
	v_mfma_f32_16x16x32_bf16 v[74:77], v[186:189], v[226:229], v[74:77]
	v_mfma_f32_16x16x32_bf16 v[66:69], v[194:197], v[226:229], v[66:69]
	s_barrier
	s_setprio 0
	s_add_u32 s96, s96, 0x80
	s_addc_u32 s97, s97, 0
	s_add_u32 s98, s96, 0xb0000
	s_addc_u32 s99, s97, 0
	s_add_u32 s94, s94, 0x80
	s_addc_u32 s95, s95, 0
	s_add_i32 s8, s8, s54
	s_mov_b32 m0, s8
	s_nop 0
	global_load_lds_dwordx4 v132, s[96:97]
	s_add_i32 m0, s8, 0x2000
	s_add_i32 s8, s50, s54
	global_load_lds_dwordx4 v136, s[96:97]
	s_mov_b32 m0, s8
	s_nop 0
	global_load_lds_dwordx4 v132, s[98:99]
	s_add_i32 m0, s8, 0x2000
	s_nop 0
	global_load_lds_dwordx4 v136, s[98:99]
	s_mov_b32 m0, s64
	s_nop 0
	global_load_lds_dwordx4 v130, s[94:95]
	s_mov_b32 m0, s65
	s_nop 0
	global_load_lds_dwordx4 v134, s[94:95]
	ds_read_b128 v[198:201], v163 offset:49152
	ds_read_b128 v[202:205], v163 offset:50176
	ds_read_b128 v[206:209], v163 offset:51200
	ds_read_b128 v[210:213], v163 offset:52224
	ds_read_b128 v[214:217], v163 offset:53248
	ds_read_b128 v[218:221], v163 offset:54272
	ds_read_b128 v[222:225], v163 offset:55296
	ds_read_b128 v[226:229], v163 offset:56320
	s_waitcnt vmcnt(8)
	s_waitcnt lgkmcnt(0)
	s_setprio 1
	s_barrier
	v_mfma_f32_16x16x32_bf16 v[62:65], v[166:169], v[198:201], v[62:65]
	v_mfma_f32_16x16x32_bf16 v[54:57], v[174:177], v[198:201], v[54:57]
	v_mfma_f32_16x16x32_bf16 v[46:49], v[166:169], v[206:209], v[46:49]
	v_mfma_f32_16x16x32_bf16 v[38:41], v[174:177], v[206:209], v[38:41]
	v_mfma_f32_16x16x32_bf16 v[30:33], v[166:169], v[214:217], v[30:33]
	v_mfma_f32_16x16x32_bf16 v[22:25], v[174:177], v[214:217], v[22:25]
	v_mfma_f32_16x16x32_bf16 v[14:17], v[166:169], v[222:225], v[14:17]
	v_mfma_f32_16x16x32_bf16 v[6:9], v[174:177], v[222:225], v[6:9]
	v_mfma_f32_16x16x32_bf16 v[62:65], v[170:173], v[202:205], v[62:65]
	v_mfma_f32_16x16x32_bf16 v[54:57], v[178:181], v[202:205], v[54:57]
	v_mfma_f32_16x16x32_bf16 v[46:49], v[170:173], v[210:213], v[46:49]
	v_mfma_f32_16x16x32_bf16 v[38:41], v[178:181], v[210:213], v[38:41]
	v_mfma_f32_16x16x32_bf16 v[30:33], v[170:173], v[218:221], v[30:33]
	v_mfma_f32_16x16x32_bf16 v[22:25], v[178:181], v[218:221], v[22:25]
	v_mfma_f32_16x16x32_bf16 v[14:17], v[170:173], v[226:229], v[14:17]
	v_mfma_f32_16x16x32_bf16 v[6:9], v[178:181], v[226:229], v[6:9]
	s_setprio 0
	s_setprio 1
	v_mfma_f32_16x16x32_bf16 v[58:61], v[182:185], v[198:201], v[58:61]
	v_mfma_f32_16x16x32_bf16 v[50:53], v[190:193], v[198:201], v[50:53]
	v_mfma_f32_16x16x32_bf16 v[42:45], v[182:185], v[206:209], v[42:45]
	v_mfma_f32_16x16x32_bf16 v[34:37], v[190:193], v[206:209], v[34:37]
	v_mfma_f32_16x16x32_bf16 v[26:29], v[182:185], v[214:217], v[26:29]
	v_mfma_f32_16x16x32_bf16 v[18:21], v[190:193], v[214:217], v[18:21]
	v_mfma_f32_16x16x32_bf16 v[10:13], v[182:185], v[222:225], v[10:13]
	v_mfma_f32_16x16x32_bf16 v[2:5], v[190:193], v[222:225], v[2:5]
	v_mfma_f32_16x16x32_bf16 v[58:61], v[186:189], v[202:205], v[58:61]
	v_mfma_f32_16x16x32_bf16 v[50:53], v[194:197], v[202:205], v[50:53]
	v_mfma_f32_16x16x32_bf16 v[42:45], v[186:189], v[210:213], v[42:45]
	v_mfma_f32_16x16x32_bf16 v[34:37], v[194:197], v[210:213], v[34:37]
	v_mfma_f32_16x16x32_bf16 v[26:29], v[186:189], v[218:221], v[26:29]
	v_mfma_f32_16x16x32_bf16 v[18:21], v[194:197], v[218:221], v[18:21]
	v_mfma_f32_16x16x32_bf16 v[10:13], v[186:189], v[226:229], v[10:13]
	v_mfma_f32_16x16x32_bf16 v[2:5], v[194:197], v[226:229], v[2:5]
	s_barrier
	s_setprio 0
	s_mov_b32 s8, s9
	s_add_u32 s88, s88, 0x100
	s_addc_u32 s89, s89, 0
	s_add_u32 s86, s86, 0x100
	s_addc_u32 s87, s87, 0
	s_cmp_ge_i32 s9, s101
	s_cbranch_scc0 .LBB0_310

.LBB0_497:
	v_cmp_gt_i32_e32 vcc, 1, v141
	s_cbranch_vccnz .LBB0_559
	v_lshl_add_u64 v[154:155], v[2:3], 0, s[16:17]
	v_add_u32_e32 v138, -2, v141
	v_lshl_add_u64 v[152:153], v[4:5], 0, s[20:21]
	s_mov_b32 s7, 0
	s_nop 0
	v_readfirstlane_b32 s86, v154
	v_readfirstlane_b32 s87, v155
	v_readfirstlane_b32 s88, v152
	v_readfirstlane_b32 s89, v153
	v_readfirstlane_b32 s90, v148
	v_readfirstlane_b32 s91, v149
	v_readfirstlane_b32 s92, v150
	v_readfirstlane_b32 s93, v151
	v_readfirstlane_b32 s100, v138
	v_readfirstlane_b32 s101, v141
	v_add_u32_e32 v230, s77, v160
	v_add_u32_e32 v231, s78, v160
	v_add_u32_e32 v232, 0x18000, v160
	v_add_u32_e32 v233, 0x1c000, v160
	s_add_u32 s98, s86, 0xfffc0080
	s_addc_u32 s99, s87, -1
	s_cmp_eq_u32 s7, s100
	s_cselect_b64 s[94:95], s[90:91], s[98:99]
	s_cselect_b64 s[96:97], s[92:93], s[88:89]
	s_add_i32 s45, s7, 2
	s_nop 0
	s_add_i32 m0, s49, 0xc000
	s_nop 0
	global_load_lds_dwordx4 v144, s[86:87]
	s_add_i32 m0, s49, 0xe000
	s_nop 0
	global_load_lds_dwordx4 v142, s[86:87]
	ds_read_b128 v[156:159], v230
	ds_read_b128 v[166:169], v230 offset:1024
	ds_read_b128 v[170:173], v230 offset:2048
	ds_read_b128 v[174:177], v230 offset:3072
	ds_read_b128 v[178:181], v231
	ds_read_b128 v[182:185], v231 offset:1024
	ds_read_b128 v[186:189], v231 offset:2048
	ds_read_b128 v[190:193], v231 offset:3072
	ds_read_b128 v[194:197], v163
	ds_read_b128 v[198:201], v163 offset:1024
	ds_read_b128 v[202:205], v163 offset:2048
	ds_read_b128 v[206:209], v163 offset:3072
	ds_read_b128 v[210:213], v163 offset:4096
	ds_read_b128 v[214:217], v163 offset:5120
	ds_read_b128 v[218:221], v163 offset:6144
	ds_read_b128 v[222:225], v163 offset:7168
	s_waitcnt vmcnt(8)
	s_waitcnt lgkmcnt(0)
	s_setprio 1
	s_barrier
	v_mfma_f32_16x16x32_bf16 v[122:125], v[156:159], v[194:197], 0
	v_mfma_f32_16x16x32_bf16 v[118:121], v[170:173], v[194:197], 0
	v_mfma_f32_16x16x32_bf16 v[110:113], v[156:159], v[202:205], 0
	v_mfma_f32_16x16x32_bf16 v[102:105], v[170:173], v[202:205], 0
	v_mfma_f32_16x16x32_bf16 v[94:97], v[156:159], v[210:213], 0
	v_mfma_f32_16x16x32_bf16 v[86:89], v[170:173], v[210:213], 0
	v_mfma_f32_16x16x32_bf16 v[78:81], v[156:159], v[218:221], 0
	v_mfma_f32_16x16x32_bf16 v[70:73], v[170:173], v[218:221], 0
	v_mfma_f32_16x16x32_bf16 v[122:125], v[166:169], v[198:201], v[122:125]
	v_mfma_f32_16x16x32_bf16 v[118:121], v[174:177], v[198:201], v[118:121]
	v_mfma_f32_16x16x32_bf16 v[110:113], v[166:169], v[206:209], v[110:113]
	v_mfma_f32_16x16x32_bf16 v[102:105], v[174:177], v[206:209], v[102:105]
	v_mfma_f32_16x16x32_bf16 v[94:97], v[166:169], v[214:217], v[94:97]
	v_mfma_f32_16x16x32_bf16 v[86:89], v[174:177], v[214:217], v[86:89]
	v_mfma_f32_16x16x32_bf16 v[78:81], v[166:169], v[222:225], v[78:81]
	v_mfma_f32_16x16x32_bf16 v[70:73], v[174:177], v[222:225], v[70:73]
	s_setprio 0
	s_setprio 1
	v_mfma_f32_16x16x32_bf16 v[126:129], v[178:181], v[194:197], 0
	v_mfma_f32_16x16x32_bf16 v[114:117], v[186:189], v[194:197], 0
	v_mfma_f32_16x16x32_bf16 v[106:109], v[178:181], v[202:205], 0
	v_mfma_f32_16x16x32_bf16 v[98:101], v[186:189], v[202:205], 0
	v_mfma_f32_16x16x32_bf16 v[90:93], v[178:181], v[210:213], 0
	v_mfma_f32_16x16x32_bf16 v[82:85], v[186:189], v[210:213], 0
	v_mfma_f32_16x16x32_bf16 v[74:77], v[178:181], v[218:221], 0
	v_mfma_f32_16x16x32_bf16 v[66:69], v[186:189], v[218:221], 0
	v_mfma_f32_16x16x32_bf16 v[126:129], v[182:185], v[198:201], v[126:129]
	v_mfma_f32_16x16x32_bf16 v[114:117], v[190:193], v[198:201], v[114:117]
	v_mfma_f32_16x16x32_bf16 v[106:109], v[182:185], v[206:209], v[106:109]
	v_mfma_f32_16x16x32_bf16 v[98:101], v[190:193], v[206:209], v[98:101]
	v_mfma_f32_16x16x32_bf16 v[90:93], v[182:185], v[214:217], v[90:93]
	v_mfma_f32_16x16x32_bf16 v[82:85], v[190:193], v[214:217], v[82:85]
	v_mfma_f32_16x16x32_bf16 v[74:77], v[182:185], v[222:225], v[74:77]
	v_mfma_f32_16x16x32_bf16 v[66:69], v[190:193], v[222:225], v[66:69]
	s_barrier
	s_setprio 0
	s_add_u32 s98, s96, 0x40000
	s_addc_u32 s99, s97, 0
	s_add_i32 s7, s77, s25
	s_mov_b32 m0, s7
	s_nop 0
	global_load_lds_dwordx4 v132, s[96:97]
	s_add_i32 m0, s7, 0x2000
	s_add_i32 s7, s78, s25
	global_load_lds_dwordx4 v136, s[96:97]
	s_mov_b32 m0, s7
	s_nop 0
	global_load_lds_dwordx4 v132, s[98:99]
	s_add_i32 m0, s7, 0x2000
	s_nop 0
	global_load_lds_dwordx4 v136, s[98:99]
	s_mov_b32 m0, s49
	s_nop 0
	global_load_lds_dwordx4 v130, s[94:95]
	s_mov_b32 m0, s58
	s_nop 0
	global_load_lds_dwordx4 v134, s[94:95]
	ds_read_b128 v[194:197], v163 offset:16384
	ds_read_b128 v[198:201], v163 offset:17408
	ds_read_b128 v[202:205], v163 offset:18432
	ds_read_b128 v[206:209], v163 offset:19456
	ds_read_b128 v[210:213], v163 offset:20480
	ds_read_b128 v[214:217], v163 offset:21504
	ds_read_b128 v[218:221], v163 offset:22528
	ds_read_b128 v[222:225], v163 offset:23552
	s_waitcnt vmcnt(8)
	s_waitcnt lgkmcnt(0)
	s_setprio 1
	s_barrier
	v_mfma_f32_16x16x32_bf16 v[62:65], v[156:159], v[194:197], 0
	v_mfma_f32_16x16x32_bf16 v[54:57], v[170:173], v[194:197], 0
	v_mfma_f32_16x16x32_bf16 v[46:49], v[156:159], v[202:205], 0
	v_mfma_f32_16x16x32_bf16 v[38:41], v[170:173], v[202:205], 0
	v_mfma_f32_16x16x32_bf16 v[30:33], v[156:159], v[210:213], 0
	v_mfma_f32_16x16x32_bf16 v[22:25], v[170:173], v[210:213], 0
	v_mfma_f32_16x16x32_bf16 v[14:17], v[156:159], v[218:221], 0
	v_mfma_f32_16x16x32_bf16 v[6:9], v[170:173], v[218:221], 0
	v_mfma_f32_16x16x32_bf16 v[62:65], v[166:169], v[198:201], v[62:65]
	v_mfma_f32_16x16x32_bf16 v[54:57], v[174:177], v[198:201], v[54:57]
	v_mfma_f32_16x16x32_bf16 v[46:49], v[166:169], v[206:209], v[46:49]
	v_mfma_f32_16x16x32_bf16 v[38:41], v[174:177], v[206:209], v[38:41]
	v_mfma_f32_16x16x32_bf16 v[30:33], v[166:169], v[214:217], v[30:33]
	v_mfma_f32_16x16x32_bf16 v[22:25], v[174:177], v[214:217], v[22:25]
	v_mfma_f32_16x16x32_bf16 v[14:17], v[166:169], v[222:225], v[14:17]
	v_mfma_f32_16x16x32_bf16 v[6:9], v[174:177], v[222:225], v[6:9]
	s_setprio 0
	s_setprio 1
	v_mfma_f32_16x16x32_bf16 v[58:61], v[178:181], v[194:197], 0
	v_mfma_f32_16x16x32_bf16 v[50:53], v[186:189], v[194:197], 0
	v_mfma_f32_16x16x32_bf16 v[42:45], v[178:181], v[202:205], 0
	v_mfma_f32_16x16x32_bf16 v[34:37], v[186:189], v[202:205], 0
	v_mfma_f32_16x16x32_bf16 v[26:29], v[178:181], v[210:213], 0
	v_mfma_f32_16x16x32_bf16 v[18:21], v[186:189], v[210:213], 0
	v_mfma_f32_16x16x32_bf16 v[10:13], v[178:181], v[218:221], 0
	v_mfma_f32_16x16x32_bf16 v[2:5], v[186:189], v[218:221], 0
	v_mfma_f32_16x16x32_bf16 v[58:61], v[182:185], v[198:201], v[58:61]
	v_mfma_f32_16x16x32_bf16 v[50:53], v[190:193], v[198:201], v[50:53]
	v_mfma_f32_16x16x32_bf16 v[42:45], v[182:185], v[206:209], v[42:45]
	v_mfma_f32_16x16x32_bf16 v[34:37], v[190:193], v[206:209], v[34:37]
	v_mfma_f32_16x16x32_bf16 v[26:29], v[182:185], v[214:217], v[26:29]
	v_mfma_f32_16x16x32_bf16 v[18:21], v[190:193], v[214:217], v[18:21]
	v_mfma_f32_16x16x32_bf16 v[10:13], v[182:185], v[222:225], v[10:13]
	v_mfma_f32_16x16x32_bf16 v[2:5], v[190:193], v[222:225], v[2:5]
	s_barrier
	s_setprio 0
	s_add_u32 s98, s94, 0x40000
	s_addc_u32 s99, s95, 0
	s_add_i32 s7, 0, 0x18000
	s_add_i32 s47, 0, 0x1c000
	s_mov_b32 m0, s59
	s_nop 0
	global_load_lds_dwordx4 v130, s[98:99]
	s_mov_b32 m0, s60
	s_nop 0
	global_load_lds_dwordx4 v134, s[98:99]
	ds_read_b128 v[156:159], v232
	ds_read_b128 v[166:169], v232 offset:1024
	ds_read_b128 v[170:173], v232 offset:2048
	ds_read_b128 v[174:177], v232 offset:3072
	ds_read_b128 v[178:181], v233
	ds_read_b128 v[182:185], v233 offset:1024
	ds_read_b128 v[186:189], v233 offset:2048
	ds_read_b128 v[190:193], v233 offset:3072
	ds_read_b128 v[194:197], v163 offset:32768
	ds_read_b128 v[198:201], v163 offset:33792
	ds_read_b128 v[202:205], v163 offset:34816
	ds_read_b128 v[206:209], v163 offset:35840
	ds_read_b128 v[210:213], v163 offset:36864
	ds_read_b128 v[214:217], v163 offset:37888
	ds_read_b128 v[218:221], v163 offset:38912
	ds_read_b128 v[222:225], v163 offset:39936
	s_waitcnt vmcnt(8)
	s_waitcnt lgkmcnt(0)
	s_setprio 1
	s_barrier
	v_mfma_f32_16x16x32_bf16 v[122:125], v[156:159], v[194:197], v[122:125]
	v_mfma_f32_16x16x32_bf16 v[118:121], v[170:173], v[194:197], v[118:121]
	v_mfma_f32_16x16x32_bf16 v[110:113], v[156:159], v[202:205], v[110:113]
	v_mfma_f32_16x16x32_bf16 v[102:105], v[170:173], v[202:205], v[102:105]
	v_mfma_f32_16x16x32_bf16 v[94:97], v[156:159], v[210:213], v[94:97]
	v_mfma_f32_16x16x32_bf16 v[86:89], v[170:173], v[210:213], v[86:89]
	v_mfma_f32_16x16x32_bf16 v[78:81], v[156:159], v[218:221], v[78:81]
	v_mfma_f32_16x16x32_bf16 v[70:73], v[170:173], v[218:221], v[70:73]
	v_mfma_f32_16x16x32_bf16 v[122:125], v[166:169], v[198:201], v[122:125]
	v_mfma_f32_16x16x32_bf16 v[118:121], v[174:177], v[198:201], v[118:121]
	v_mfma_f32_16x16x32_bf16 v[110:113], v[166:169], v[206:209], v[110:113]
	v_mfma_f32_16x16x32_bf16 v[102:105], v[174:177], v[206:209], v[102:105]
	v_mfma_f32_16x16x32_bf16 v[94:97], v[166:169], v[214:217], v[94:97]
	v_mfma_f32_16x16x32_bf16 v[86:89], v[174:177], v[214:217], v[86:89]
	v_mfma_f32_16x16x32_bf16 v[78:81], v[166:169], v[222:225], v[78:81]
	v_mfma_f32_16x16x32_bf16 v[70:73], v[174:177], v[222:225], v[70:73]
	s_setprio 0
	s_setprio 1
	v_mfma_f32_16x16x32_bf16 v[126:129], v[178:181], v[194:197], v[126:129]
	v_mfma_f32_16x16x32_bf16 v[114:117], v[186:189], v[194:197], v[114:117]
	v_mfma_f32_16x16x32_bf16 v[106:109], v[178:181], v[202:205], v[106:109]
	v_mfma_f32_16x16x32_bf16 v[98:101], v[186:189], v[202:205], v[98:101]
	v_mfma_f32_16x16x32_bf16 v[90:93], v[178:181], v[210:213], v[90:93]
	v_mfma_f32_16x16x32_bf16 v[82:85], v[186:189], v[210:213], v[82:85]
	v_mfma_f32_16x16x32_bf16 v[74:77], v[178:181], v[218:221], v[74:77]
	v_mfma_f32_16x16x32_bf16 v[66:69], v[186:189], v[218:221], v[66:69]
	v_mfma_f32_16x16x32_bf16 v[126:129], v[182:185], v[198:201], v[126:129]
	v_mfma_f32_16x16x32_bf16 v[114:117], v[190:193], v[198:201], v[114:117]
	v_mfma_f32_16x16x32_bf16 v[106:109], v[182:185], v[206:209], v[106:109]
	v_mfma_f32_16x16x32_bf16 v[98:101], v[190:193], v[206:209], v[98:101]
	v_mfma_f32_16x16x32_bf16 v[90:93], v[182:185], v[214:217], v[90:93]
	v_mfma_f32_16x16x32_bf16 v[82:85], v[190:193], v[214:217], v[82:85]
	v_mfma_f32_16x16x32_bf16 v[74:77], v[182:185], v[222:225], v[74:77]
	v_mfma_f32_16x16x32_bf16 v[66:69], v[190:193], v[222:225], v[66:69]
	s_barrier
	s_setprio 0
	s_add_u32 s96, s96, 0x80
	s_addc_u32 s97, s97, 0
	s_add_u32 s98, s96, 0x40000
	s_addc_u32 s99, s97, 0
	s_add_u32 s94, s94, 0x80
	s_addc_u32 s95, s95, 0
	s_add_i32 s7, s7, s25
	s_mov_b32 m0, s7
	s_nop 0
	global_load_lds_dwordx4 v132, s[96:97]
	s_add_i32 m0, s7, 0x2000
	s_add_i32 s7, s47, s25
	global_load_lds_dwordx4 v136, s[96:97]
	s_mov_b32 m0, s7
	s_nop 0
	global_load_lds_dwordx4 v132, s[98:99]
	s_add_i32 m0, s7, 0x2000
	s_nop 0
	global_load_lds_dwordx4 v136, s[98:99]
	s_mov_b32 m0, s66
	s_nop 0
	global_load_lds_dwordx4 v130, s[94:95]
	s_mov_b32 m0, s67
	s_nop 0
	global_load_lds_dwordx4 v134, s[94:95]
	ds_read_b128 v[194:197], v163 offset:49152
	ds_read_b128 v[198:201], v163 offset:50176
	ds_read_b128 v[202:205], v163 offset:51200
	ds_read_b128 v[206:209], v163 offset:52224
	ds_read_b128 v[210:213], v163 offset:53248
	ds_read_b128 v[214:217], v163 offset:54272
	ds_read_b128 v[218:221], v163 offset:55296
	ds_read_b128 v[222:225], v163 offset:56320
	s_waitcnt vmcnt(8)
	s_waitcnt lgkmcnt(0)
	s_setprio 1
	s_barrier
	v_mfma_f32_16x16x32_bf16 v[62:65], v[156:159], v[194:197], v[62:65]
	v_mfma_f32_16x16x32_bf16 v[54:57], v[170:173], v[194:197], v[54:57]
	v_mfma_f32_16x16x32_bf16 v[46:49], v[156:159], v[202:205], v[46:49]
	v_mfma_f32_16x16x32_bf16 v[38:41], v[170:173], v[202:205], v[38:41]
	v_mfma_f32_16x16x32_bf16 v[30:33], v[156:159], v[210:213], v[30:33]
	v_mfma_f32_16x16x32_bf16 v[22:25], v[170:173], v[210:213], v[22:25]
	v_mfma_f32_16x16x32_bf16 v[14:17], v[156:159], v[218:221], v[14:17]
	v_mfma_f32_16x16x32_bf16 v[6:9], v[170:173], v[218:221], v[6:9]
	v_mfma_f32_16x16x32_bf16 v[62:65], v[166:169], v[198:201], v[62:65]
	v_mfma_f32_16x16x32_bf16 v[54:57], v[174:177], v[198:201], v[54:57]
	v_mfma_f32_16x16x32_bf16 v[46:49], v[166:169], v[206:209], v[46:49]
	v_mfma_f32_16x16x32_bf16 v[38:41], v[174:177], v[206:209], v[38:41]
	v_mfma_f32_16x16x32_bf16 v[30:33], v[166:169], v[214:217], v[30:33]
	v_mfma_f32_16x16x32_bf16 v[22:25], v[174:177], v[214:217], v[22:25]
	v_mfma_f32_16x16x32_bf16 v[14:17], v[166:169], v[222:225], v[14:17]
	v_mfma_f32_16x16x32_bf16 v[6:9], v[174:177], v[222:225], v[6:9]
	s_setprio 0
	s_setprio 1
	v_mfma_f32_16x16x32_bf16 v[58:61], v[178:181], v[194:197], v[58:61]
	v_mfma_f32_16x16x32_bf16 v[50:53], v[186:189], v[194:197], v[50:53]
	v_mfma_f32_16x16x32_bf16 v[42:45], v[178:181], v[202:205], v[42:45]
	v_mfma_f32_16x16x32_bf16 v[34:37], v[186:189], v[202:205], v[34:37]
	v_mfma_f32_16x16x32_bf16 v[26:29], v[178:181], v[210:213], v[26:29]
	v_mfma_f32_16x16x32_bf16 v[18:21], v[186:189], v[210:213], v[18:21]
	v_mfma_f32_16x16x32_bf16 v[10:13], v[178:181], v[218:221], v[10:13]
	v_mfma_f32_16x16x32_bf16 v[2:5], v[186:189], v[218:221], v[2:5]
	v_mfma_f32_16x16x32_bf16 v[58:61], v[182:185], v[198:201], v[58:61]
	v_mfma_f32_16x16x32_bf16 v[50:53], v[190:193], v[198:201], v[50:53]
	v_mfma_f32_16x16x32_bf16 v[42:45], v[182:185], v[206:209], v[42:45]
	v_mfma_f32_16x16x32_bf16 v[34:37], v[190:193], v[206:209], v[34:37]
	v_mfma_f32_16x16x32_bf16 v[26:29], v[182:185], v[214:217], v[26:29]
	v_mfma_f32_16x16x32_bf16 v[18:21], v[190:193], v[214:217], v[18:21]
	v_mfma_f32_16x16x32_bf16 v[10:13], v[182:185], v[222:225], v[10:13]
	v_mfma_f32_16x16x32_bf16 v[2:5], v[190:193], v[222:225], v[2:5]
	s_barrier
	s_setprio 0
	s_mov_b32 s7, s45
	s_add_u32 s88, s88, 0x100
	s_addc_u32 s89, s89, 0
	s_add_u32 s86, s86, 0x100
	s_addc_u32 s87, s87, 0
	s_cmp_ge_i32 s45, s101
	s_cbranch_scc1 .Lmy_kexit_2
.LBB0_499:
	s_add_u32 s98, s86, 0xfffc0080
	s_addc_u32 s99, s87, -1
	s_cmp_eq_u32 s7, s100
	s_cselect_b64 s[94:95], s[90:91], s[98:99]
	s_cselect_b64 s[96:97], s[92:93], s[88:89]
	s_add_i32 s45, s7, 2
	s_nop 0
	s_add_i32 m0, s49, 0xc000
	s_nop 0
	global_load_lds_dwordx4 v144, s[86:87]
	s_add_i32 m0, s49, 0xe000
	s_nop 0
	global_load_lds_dwordx4 v142, s[86:87]
	ds_read_b128 v[156:159], v230
	ds_read_b128 v[166:169], v230 offset:1024
	ds_read_b128 v[170:173], v230 offset:2048
	ds_read_b128 v[174:177], v230 offset:3072
	ds_read_b128 v[178:181], v231
	ds_read_b128 v[182:185], v231 offset:1024
	ds_read_b128 v[186:189], v231 offset:2048
	ds_read_b128 v[190:193], v231 offset:3072
	ds_read_b128 v[194:197], v163
	ds_read_b128 v[198:201], v163 offset:1024
	ds_read_b128 v[202:205], v163 offset:2048
	ds_read_b128 v[206:209], v163 offset:3072
	ds_read_b128 v[210:213], v163 offset:4096
	ds_read_b128 v[214:217], v163 offset:5120
	ds_read_b128 v[218:221], v163 offset:6144
	ds_read_b128 v[222:225], v163 offset:7168
	s_waitcnt vmcnt(8)
	s_waitcnt lgkmcnt(0)
	s_setprio 1
	s_barrier
	v_mfma_f32_16x16x32_bf16 v[122:125], v[156:159], v[194:197], v[122:125]
	v_mfma_f32_16x16x32_bf16 v[118:121], v[170:173], v[194:197], v[118:121]
	v_mfma_f32_16x16x32_bf16 v[110:113], v[156:159], v[202:205], v[110:113]
	v_mfma_f32_16x16x32_bf16 v[102:105], v[170:173], v[202:205], v[102:105]
	v_mfma_f32_16x16x32_bf16 v[94:97], v[156:159], v[210:213], v[94:97]
	v_mfma_f32_16x16x32_bf16 v[86:89], v[170:173], v[210:213], v[86:89]
	v_mfma_f32_16x16x32_bf16 v[78:81], v[156:159], v[218:221], v[78:81]
	v_mfma_f32_16x16x32_bf16 v[70:73], v[170:173], v[218:221], v[70:73]
	v_mfma_f32_16x16x32_bf16 v[122:125], v[166:169], v[198:201], v[122:125]
	v_mfma_f32_16x16x32_bf16 v[118:121], v[174:177], v[198:201], v[118:121]
	v_mfma_f32_16x16x32_bf16 v[110:113], v[166:169], v[206:209], v[110:113]
	v_mfma_f32_16x16x32_bf16 v[102:105], v[174:177], v[206:209], v[102:105]
	v_mfma_f32_16x16x32_bf16 v[94:97], v[166:169], v[214:217], v[94:97]
	v_mfma_f32_16x16x32_bf16 v[86:89], v[174:177], v[214:217], v[86:89]
	v_mfma_f32_16x16x32_bf16 v[78:81], v[166:169], v[222:225], v[78:81]
	v_mfma_f32_16x16x32_bf16 v[70:73], v[174:177], v[222:225], v[70:73]
	s_setprio 0
	s_setprio 1
	v_mfma_f32_16x16x32_bf16 v[126:129], v[178:181], v[194:197], v[126:129]
	v_mfma_f32_16x16x32_bf16 v[114:117], v[186:189], v[194:197], v[114:117]
	v_mfma_f32_16x16x32_bf16 v[106:109], v[178:181], v[202:205], v[106:109]
	v_mfma_f32_16x16x32_bf16 v[98:101], v[186:189], v[202:205], v[98:101]
	v_mfma_f32_16x16x32_bf16 v[90:93], v[178:181], v[210:213], v[90:93]
	v_mfma_f32_16x16x32_bf16 v[82:85], v[186:189], v[210:213], v[82:85]
	v_mfma_f32_16x16x32_bf16 v[74:77], v[178:181], v[218:221], v[74:77]
	v_mfma_f32_16x16x32_bf16 v[66:69], v[186:189], v[218:221], v[66:69]
	v_mfma_f32_16x16x32_bf16 v[126:129], v[182:185], v[198:201], v[126:129]
	v_mfma_f32_16x16x32_bf16 v[114:117], v[190:193], v[198:201], v[114:117]
	v_mfma_f32_16x16x32_bf16 v[106:109], v[182:185], v[206:209], v[106:109]
	v_mfma_f32_16x16x32_bf16 v[98:101], v[190:193], v[206:209], v[98:101]
	v_mfma_f32_16x16x32_bf16 v[90:93], v[182:185], v[214:217], v[90:93]
	v_mfma_f32_16x16x32_bf16 v[82:85], v[190:193], v[214:217], v[82:85]
	v_mfma_f32_16x16x32_bf16 v[74:77], v[182:185], v[222:225], v[74:77]
	v_mfma_f32_16x16x32_bf16 v[66:69], v[190:193], v[222:225], v[66:69]
	s_barrier
	s_setprio 0
	s_add_u32 s98, s96, 0x40000
	s_addc_u32 s99, s97, 0
	s_add_i32 s7, s77, s25
	s_mov_b32 m0, s7
	s_nop 0
	global_load_lds_dwordx4 v132, s[96:97]
	s_add_i32 m0, s7, 0x2000
	s_add_i32 s7, s78, s25
	global_load_lds_dwordx4 v136, s[96:97]
	s_mov_b32 m0, s7
	s_nop 0
	global_load_lds_dwordx4 v132, s[98:99]
	s_add_i32 m0, s7, 0x2000
	s_nop 0
	global_load_lds_dwordx4 v136, s[98:99]
	s_mov_b32 m0, s49
	s_nop 0
	global_load_lds_dwordx4 v130, s[94:95]
	s_mov_b32 m0, s58
	s_nop 0
	global_load_lds_dwordx4 v134, s[94:95]
	ds_read_b128 v[194:197], v163 offset:16384
	ds_read_b128 v[198:201], v163 offset:17408
	ds_read_b128 v[202:205], v163 offset:18432
	ds_read_b128 v[206:209], v163 offset:19456
	ds_read_b128 v[210:213], v163 offset:20480
	ds_read_b128 v[214:217], v163 offset:21504
	ds_read_b128 v[218:221], v163 offset:22528
	ds_read_b128 v[222:225], v163 offset:23552
	s_waitcnt vmcnt(8)
	s_waitcnt lgkmcnt(0)
	s_setprio 1
	s_barrier
	v_mfma_f32_16x16x32_bf16 v[62:65], v[156:159], v[194:197], v[62:65]
	v_mfma_f32_16x16x32_bf16 v[54:57], v[170:173], v[194:197], v[54:57]
	v_mfma_f32_16x16x32_bf16 v[46:49], v[156:159], v[202:205], v[46:49]
	v_mfma_f32_16x16x32_bf16 v[38:41], v[170:173], v[202:205], v[38:41]
	v_mfma_f32_16x16x32_bf16 v[30:33], v[156:159], v[210:213], v[30:33]
	v_mfma_f32_16x16x32_bf16 v[22:25], v[170:173], v[210:213], v[22:25]
	v_mfma_f32_16x16x32_bf16 v[14:17], v[156:159], v[218:221], v[14:17]
	v_mfma_f32_16x16x32_bf16 v[6:9], v[170:173], v[218:221], v[6:9]
	v_mfma_f32_16x16x32_bf16 v[62:65], v[166:169], v[198:201], v[62:65]
	v_mfma_f32_16x16x32_bf16 v[54:57], v[174:177], v[198:201], v[54:57]
	v_mfma_f32_16x16x32_bf16 v[46:49], v[166:169], v[206:209], v[46:49]
	v_mfma_f32_16x16x32_bf16 v[38:41], v[174:177], v[206:209], v[38:41]
	v_mfma_f32_16x16x32_bf16 v[30:33], v[166:169], v[214:217], v[30:33]
	v_mfma_f32_16x16x32_bf16 v[22:25], v[174:177], v[214:217], v[22:25]
	v_mfma_f32_16x16x32_bf16 v[14:17], v[166:169], v[222:225], v[14:17]
	v_mfma_f32_16x16x32_bf16 v[6:9], v[174:177], v[222:225], v[6:9]
	s_setprio 0
	s_setprio 1
	v_mfma_f32_16x16x32_bf16 v[58:61], v[178:181], v[194:197], v[58:61]
	v_mfma_f32_16x16x32_bf16 v[50:53], v[186:189], v[194:197], v[50:53]
	v_mfma_f32_16x16x32_bf16 v[42:45], v[178:181], v[202:205], v[42:45]
	v_mfma_f32_16x16x32_bf16 v[34:37], v[186:189], v[202:205], v[34:37]
	v_mfma_f32_16x16x32_bf16 v[26:29], v[178:181], v[210:213], v[26:29]
	v_mfma_f32_16x16x32_bf16 v[18:21], v[186:189], v[210:213], v[18:21]
	v_mfma_f32_16x16x32_bf16 v[10:13], v[178:181], v[218:221], v[10:13]
	v_mfma_f32_16x16x32_bf16 v[2:5], v[186:189], v[218:221], v[2:5]
	v_mfma_f32_16x16x32_bf16 v[58:61], v[182:185], v[198:201], v[58:61]
	v_mfma_f32_16x16x32_bf16 v[50:53], v[190:193], v[198:201], v[50:53]
	v_mfma_f32_16x16x32_bf16 v[42:45], v[182:185], v[206:209], v[42:45]
	v_mfma_f32_16x16x32_bf16 v[34:37], v[190:193], v[206:209], v[34:37]
	v_mfma_f32_16x16x32_bf16 v[26:29], v[182:185], v[214:217], v[26:29]
	v_mfma_f32_16x16x32_bf16 v[18:21], v[190:193], v[214:217], v[18:21]
	v_mfma_f32_16x16x32_bf16 v[10:13], v[182:185], v[222:225], v[10:13]
	v_mfma_f32_16x16x32_bf16 v[2:5], v[190:193], v[222:225], v[2:5]
	s_barrier
	s_setprio 0
	s_add_u32 s98, s94, 0x40000
	s_addc_u32 s99, s95, 0
	s_add_i32 s7, 0, 0x18000
	s_add_i32 s47, 0, 0x1c000
	s_mov_b32 m0, s59
	s_nop 0
	global_load_lds_dwordx4 v130, s[98:99]
	s_mov_b32 m0, s60
	s_nop 0
	global_load_lds_dwordx4 v134, s[98:99]
	ds_read_b128 v[156:159], v232
	ds_read_b128 v[166:169], v232 offset:1024
	ds_read_b128 v[170:173], v232 offset:2048
	ds_read_b128 v[174:177], v232 offset:3072
	ds_read_b128 v[178:181], v233
	ds_read_b128 v[182:185], v233 offset:1024
	ds_read_b128 v[186:189], v233 offset:2048
	ds_read_b128 v[190:193], v233 offset:3072
	ds_read_b128 v[194:197], v163 offset:32768
	ds_read_b128 v[198:201], v163 offset:33792
	ds_read_b128 v[202:205], v163 offset:34816
	ds_read_b128 v[206:209], v163 offset:35840
	ds_read_b128 v[210:213], v163 offset:36864
	ds_read_b128 v[214:217], v163 offset:37888
	ds_read_b128 v[218:221], v163 offset:38912
	ds_read_b128 v[222:225], v163 offset:39936
	s_waitcnt vmcnt(8)
	s_waitcnt lgkmcnt(0)
	s_setprio 1
	s_barrier
	v_mfma_f32_16x16x32_bf16 v[122:125], v[156:159], v[194:197], v[122:125]
	v_mfma_f32_16x16x32_bf16 v[118:121], v[170:173], v[194:197], v[118:121]
	v_mfma_f32_16x16x32_bf16 v[110:113], v[156:159], v[202:205], v[110:113]
	v_mfma_f32_16x16x32_bf16 v[102:105], v[170:173], v[202:205], v[102:105]
	v_mfma_f32_16x16x32_bf16 v[94:97], v[156:159], v[210:213], v[94:97]
	v_mfma_f32_16x16x32_bf16 v[86:89], v[170:173], v[210:213], v[86:89]
	v_mfma_f32_16x16x32_bf16 v[78:81], v[156:159], v[218:221], v[78:81]
	v_mfma_f32_16x16x32_bf16 v[70:73], v[170:173], v[218:221], v[70:73]
	v_mfma_f32_16x16x32_bf16 v[122:125], v[166:169], v[198:201], v[122:125]
	v_mfma_f32_16x16x32_bf16 v[118:121], v[174:177], v[198:201], v[118:121]
	v_mfma_f32_16x16x32_bf16 v[110:113], v[166:169], v[206:209], v[110:113]
	v_mfma_f32_16x16x32_bf16 v[102:105], v[174:177], v[206:209], v[102:105]
	v_mfma_f32_16x16x32_bf16 v[94:97], v[166:169], v[214:217], v[94:97]
	v_mfma_f32_16x16x32_bf16 v[86:89], v[174:177], v[214:217], v[86:89]
	v_mfma_f32_16x16x32_bf16 v[78:81], v[166:169], v[222:225], v[78:81]
	v_mfma_f32_16x16x32_bf16 v[70:73], v[174:177], v[222:225], v[70:73]
	s_setprio 0
	s_setprio 1
	v_mfma_f32_16x16x32_bf16 v[126:129], v[178:181], v[194:197], v[126:129]
	v_mfma_f32_16x16x32_bf16 v[114:117], v[186:189], v[194:197], v[114:117]
	v_mfma_f32_16x16x32_bf16 v[106:109], v[178:181], v[202:205], v[106:109]
	v_mfma_f32_16x16x32_bf16 v[98:101], v[186:189], v[202:205], v[98:101]
	v_mfma_f32_16x16x32_bf16 v[90:93], v[178:181], v[210:213], v[90:93]
	v_mfma_f32_16x16x32_bf16 v[82:85], v[186:189], v[210:213], v[82:85]
	v_mfma_f32_16x16x32_bf16 v[74:77], v[178:181], v[218:221], v[74:77]
	v_mfma_f32_16x16x32_bf16 v[66:69], v[186:189], v[218:221], v[66:69]
	v_mfma_f32_16x16x32_bf16 v[126:129], v[182:185], v[198:201], v[126:129]
	v_mfma_f32_16x16x32_bf16 v[114:117], v[190:193], v[198:201], v[114:117]
	v_mfma_f32_16x16x32_bf16 v[106:109], v[182:185], v[206:209], v[106:109]
	v_mfma_f32_16x16x32_bf16 v[98:101], v[190:193], v[206:209], v[98:101]
	v_mfma_f32_16x16x32_bf16 v[90:93], v[182:185], v[214:217], v[90:93]
	v_mfma_f32_16x16x32_bf16 v[82:85], v[190:193], v[214:217], v[82:85]
	v_mfma_f32_16x16x32_bf16 v[74:77], v[182:185], v[222:225], v[74:77]
	v_mfma_f32_16x16x32_bf16 v[66:69], v[190:193], v[222:225], v[66:69]
	s_barrier
	s_setprio 0
	s_add_u32 s96, s96, 0x80
	s_addc_u32 s97, s97, 0
	s_add_u32 s98, s96, 0x40000
	s_addc_u32 s99, s97, 0
	s_add_u32 s94, s94, 0x80
	s_addc_u32 s95, s95, 0
	s_add_i32 s7, s7, s25
	s_mov_b32 m0, s7
	s_nop 0
	global_load_lds_dwordx4 v132, s[96:97]
	s_add_i32 m0, s7, 0x2000
	s_add_i32 s7, s47, s25
	global_load_lds_dwordx4 v136, s[96:97]
	s_mov_b32 m0, s7
	s_nop 0
	global_load_lds_dwordx4 v132, s[98:99]
	s_add_i32 m0, s7, 0x2000
	s_nop 0
	global_load_lds_dwordx4 v136, s[98:99]
	s_mov_b32 m0, s66
	s_nop 0
	global_load_lds_dwordx4 v130, s[94:95]
	s_mov_b32 m0, s67
	s_nop 0
	global_load_lds_dwordx4 v134, s[94:95]
	ds_read_b128 v[194:197], v163 offset:49152
	ds_read_b128 v[198:201], v163 offset:50176
	ds_read_b128 v[202:205], v163 offset:51200
	ds_read_b128 v[206:209], v163 offset:52224
	ds_read_b128 v[210:213], v163 offset:53248
	ds_read_b128 v[214:217], v163 offset:54272
	ds_read_b128 v[218:221], v163 offset:55296
	ds_read_b128 v[222:225], v163 offset:56320
	s_waitcnt vmcnt(8)
	s_waitcnt lgkmcnt(0)
	s_setprio 1
	s_barrier
	v_mfma_f32_16x16x32_bf16 v[62:65], v[156:159], v[194:197], v[62:65]
	v_mfma_f32_16x16x32_bf16 v[54:57], v[170:173], v[194:197], v[54:57]
	v_mfma_f32_16x16x32_bf16 v[46:49], v[156:159], v[202:205], v[46:49]
	v_mfma_f32_16x16x32_bf16 v[38:41], v[170:173], v[202:205], v[38:41]
	v_mfma_f32_16x16x32_bf16 v[30:33], v[156:159], v[210:213], v[30:33]
	v_mfma_f32_16x16x32_bf16 v[22:25], v[170:173], v[210:213], v[22:25]
	v_mfma_f32_16x16x32_bf16 v[14:17], v[156:159], v[218:221], v[14:17]
	v_mfma_f32_16x16x32_bf16 v[6:9], v[170:173], v[218:221], v[6:9]
	v_mfma_f32_16x16x32_bf16 v[62:65], v[166:169], v[198:201], v[62:65]
	v_mfma_f32_16x16x32_bf16 v[54:57], v[174:177], v[198:201], v[54:57]
	v_mfma_f32_16x16x32_bf16 v[46:49], v[166:169], v[206:209], v[46:49]
	v_mfma_f32_16x16x32_bf16 v[38:41], v[174:177], v[206:209], v[38:41]
	v_mfma_f32_16x16x32_bf16 v[30:33], v[166:169], v[214:217], v[30:33]
	v_mfma_f32_16x16x32_bf16 v[22:25], v[174:177], v[214:217], v[22:25]
	v_mfma_f32_16x16x32_bf16 v[14:17], v[166:169], v[222:225], v[14:17]
	v_mfma_f32_16x16x32_bf16 v[6:9], v[174:177], v[222:225], v[6:9]
	s_setprio 0
	s_setprio 1
	v_mfma_f32_16x16x32_bf16 v[58:61], v[178:181], v[194:197], v[58:61]
	v_mfma_f32_16x16x32_bf16 v[50:53], v[186:189], v[194:197], v[50:53]
	v_mfma_f32_16x16x32_bf16 v[42:45], v[178:181], v[202:205], v[42:45]
	v_mfma_f32_16x16x32_bf16 v[34:37], v[186:189], v[202:205], v[34:37]
	v_mfma_f32_16x16x32_bf16 v[26:29], v[178:181], v[210:213], v[26:29]
	v_mfma_f32_16x16x32_bf16 v[18:21], v[186:189], v[210:213], v[18:21]
	v_mfma_f32_16x16x32_bf16 v[10:13], v[178:181], v[218:221], v[10:13]
	v_mfma_f32_16x16x32_bf16 v[2:5], v[186:189], v[218:221], v[2:5]
	v_mfma_f32_16x16x32_bf16 v[58:61], v[182:185], v[198:201], v[58:61]
	v_mfma_f32_16x16x32_bf16 v[50:53], v[190:193], v[198:201], v[50:53]
	v_mfma_f32_16x16x32_bf16 v[42:45], v[182:185], v[206:209], v[42:45]
	v_mfma_f32_16x16x32_bf16 v[34:37], v[190:193], v[206:209], v[34:37]
	v_mfma_f32_16x16x32_bf16 v[26:29], v[182:185], v[214:217], v[26:29]
	v_mfma_f32_16x16x32_bf16 v[18:21], v[190:193], v[214:217], v[18:21]
	v_mfma_f32_16x16x32_bf16 v[10:13], v[182:185], v[222:225], v[10:13]
	v_mfma_f32_16x16x32_bf16 v[2:5], v[190:193], v[222:225], v[2:5]
	s_barrier
	s_setprio 0
	s_mov_b32 s7, s45
	s_add_u32 s88, s88, 0x100
	s_addc_u32 s89, s89, 0
	s_add_u32 s86, s86, 0x100
	s_addc_u32 s87, s87, 0
	s_cmp_ge_i32 s45, s101
	s_cbranch_scc0 .LBB0_499

.LBB0_689:
	s_waitcnt vmcnt(1)
	v_add_u32_e32 v2, -8, v126
	v_min_u32_e32 v2, 32, v2
	v_cmp_ne_u32_e32 vcc, 0, v126
	v_add_u32_e32 v3, -8, v113
	v_min_u32_e32 v3, 48, v3
	v_cndmask_b32_e32 v2, 0, v2, vcc
	v_lshl_add_u32 v4, v99, 2, v2
	v_cmp_lt_u32_e32 vcc, 7, v113
	v_sub_u32_e32 v5, v4, v113
	v_add_u32_e32 v6, 15, v5
	v_cndmask_b32_e32 v3, 0, v3, vcc
	v_min_u32_e32 v6, 30, v6
	v_cmp_lt_i32_e32 vcc, -16, v5
	v_sub_u32_e32 v5, v4, v3
	s_lshl_b32 s6, s85, 19
	v_cndmask_b32_e32 v158, 0, v6, vcc
	v_cmp_gt_u32_e32 vcc, 16, v5
	v_or_b32_e32 v5, 1, v4
	v_sub_u32_e32 v6, v5, v113
	v_add_u32_e32 v7, 15, v6
	v_cndmask_b32_e64 v54, v149, 0, vcc
	v_min_u32_e32 v7, 30, v7
	v_cmp_lt_i32_e32 vcc, -16, v6
	v_sub_u32_e32 v5, v5, v3
	s_add_u32 s4, s25, s6
	v_cndmask_b32_e32 v159, 0, v7, vcc
	v_cmp_gt_u32_e32 vcc, 16, v5
	v_or_b32_e32 v5, 2, v4
	v_sub_u32_e32 v6, v5, v113
	v_add_u32_e32 v7, 15, v6
	v_cndmask_b32_e64 v55, v149, 0, vcc
	v_min_u32_e32 v7, 30, v7
	v_cmp_lt_i32_e32 vcc, -16, v6
	v_sub_u32_e32 v5, v5, v3
	s_addc_u32 s5, s62, 0
	v_cndmask_b32_e32 v160, 0, v7, vcc
	v_cmp_gt_u32_e32 vcc, 16, v5
	v_or_b32_e32 v5, 3, v4
	v_sub_u32_e32 v6, v5, v113
	v_add_u32_e32 v7, 15, v6
	v_cndmask_b32_e64 v56, v149, 0, vcc
	v_min_u32_e32 v7, 30, v7
	v_cmp_lt_i32_e32 vcc, -16, v6
	v_sub_u32_e32 v5, v5, v3
	s_add_u32 s6, s65, s6
	v_cndmask_b32_e32 v161, 0, v7, vcc
	v_cmp_gt_u32_e32 vcc, 16, v5
	v_add_u32_e32 v5, 16, v4
	v_sub_u32_e32 v6, v5, v113
	v_add_u32_e32 v7, 15, v6
	v_cndmask_b32_e64 v57, v149, 0, vcc
	v_min_u32_e32 v7, 30, v7
	v_cmp_lt_i32_e32 vcc, -16, v6
	v_sub_u32_e32 v5, v5, v3
	s_addc_u32 s7, s66, 0
	v_cndmask_b32_e32 v162, 0, v7, vcc
	v_cmp_gt_u32_e32 vcc, 16, v5
	v_add_u32_e32 v5, 17, v4
	v_sub_u32_e32 v6, v5, v113
	v_add_u32_e32 v7, 15, v6
	v_cndmask_b32_e64 v58, v149, 0, vcc
	v_min_u32_e32 v7, 30, v7
	v_cmp_lt_i32_e32 vcc, -16, v6
	v_sub_u32_e32 v5, v5, v3
	s_add_i32 s8, 0, 0x12000
	v_cndmask_b32_e32 v163, 0, v7, vcc
	v_cmp_gt_u32_e32 vcc, 16, v5
	v_add_u32_e32 v5, 18, v4
	v_sub_u32_e32 v6, v5, v113
	v_add_u32_e32 v7, 15, v6
	v_cndmask_b32_e64 v59, v149, 0, vcc
	v_min_u32_e32 v7, 30, v7
	v_cmp_lt_i32_e32 vcc, -16, v6
	v_sub_u32_e32 v5, v5, v3
	v_add_u32_e32 v2, v2, v95
	v_cndmask_b32_e32 v164, 0, v7, vcc
	v_cmp_gt_u32_e32 vcc, 16, v5
	v_add_u32_e32 v5, 19, v4
	v_sub_u32_e32 v6, v5, v113
	v_add_u32_e32 v7, 15, v6
	v_cndmask_b32_e64 v60, v149, 0, vcc
	v_min_u32_e32 v7, 30, v7
	v_cmp_lt_i32_e32 vcc, -16, v6
	v_sub_u32_e32 v3, v5, v3
	s_lshl_b32 s61, s84, 4
	v_cndmask_b32_e32 v165, 0, v7, vcc
	v_cmp_gt_u32_e32 vcc, 16, v3
	v_lshlrev_b32_e32 v3, 4, v4
	v_lshlrev_b32_e32 v4, 2, v4
	v_and_b32_e32 v3, 0x700, v3
	v_and_b32_e32 v4, 48, v4
	v_or3_b32 v3, v3, v4, v95
	v_lshl_add_u32 v166, v3, 3, s8
	v_lshlrev_b32_e32 v3, 4, v94
	v_add_u32_e32 v167, 0, v3
	v_add_u32_e32 v168, s8, v3
	v_lshlrev_b32_e32 v3, 3, v2
	v_and_b32_e32 v4, 0x380, v3
	v_add_u32_e32 v3, 0x80, v3
	v_and_b32_e32 v2, 15, v2
	v_and_b32_e32 v3, 0x780, v3
	v_or3_b32 v4, v98, v4, v2
	v_or3_b32 v2, v98, v3, v2
	v_lshlrev_b32_e32 v170, 4, v2
	v_lshl_add_u64 v[2:3], s[16:17], 0, v[104:105]
	v_lshl_add_u64 v[2:3], v[2:3], 0, v[102:103]
	v_lshl_add_u64 v[64:65], s[14:15], 0, v[2:3]
	v_lshl_add_u64 v[2:3], s[58:59], 0, v[106:107]
	v_lshl_add_u64 v[2:3], v[2:3], 0, v[102:103]
	v_lshl_add_u64 v[66:67], s[18:19], 0, v[2:3]
	v_lshlrev_b32_e32 v2, 6, v96
	v_lshl_add_u32 v2, s84, 10, v2
	v_ashrrev_i32_e32 v3, 31, v2
	v_lshl_add_u64 v[2:3], v[2:3], 0, v[100:101]
	v_lshlrev_b64 v[2:3], 11, v[2:3]
	v_or_b32_e32 v2, s50, v2
	v_lshlrev_b32_e32 v62, 3, v94
	v_lshl_add_u64 v[2:3], v[2:3], 0, v[88:89]
	v_add_u32_e32 v88, s61, v96
	s_mov_b32 s60, 2
	v_cndmask_b32_e64 v61, v149, 0, vcc
	v_ashrrev_i32_e32 v63, 31, v62
	v_lshlrev_b32_e32 v169, 4, v4
	v_lshl_add_u64 v[68:69], s[20:21], 0, v[2:3]
	v_sub_u32_e32 v171, 0, v88
	s_waitcnt lgkmcnt(0)
	s_barrier
	s_waitcnt vmcnt(0)
	s_branch .LBB0_691

.LBB0_695:
	v_add_u32_e32 v26, s60, v88
	v_add_u32_e32 v27, -2, v26
	v_add_u32_e32 v26, -6, v26
	v_min_u32_e32 v26, 56, v26
	v_cmp_lt_i32_e32 vcc, 3, v27
	s_and_b64 s[50:51], s[50:51], exec
	s_cselect_b32 s50, 0, s60
	v_cndmask_b32_e32 v106, 0, v26, vcc
	v_mul_lo_u16_e32 v26, 57, v106
	v_lshrrev_b16_e32 v26, 9, v26
	v_mul_lo_u16_e32 v26, 9, v26
	v_sub_u16_e32 v26, v106, v26
	v_lshlrev_b32_sdwa v179, v150, v26 dst_sel:DWORD dst_unused:UNUSED_PAD src0_sel:DWORD src1_sel:BYTE_0
	v_add_u32_e32 v30, 0, v179
	v_add_u32_e32 v31, v30, v169
	ds_read_b128 v[26:29], v31
	v_add_u32_e32 v38, v30, v170
	ds_read_b128 v[30:33], v31 offset:1024
	v_mad_legacy_u16 v42, v106, 57, 57
	v_lshrrev_b16_e32 v42, 9, v42
	s_waitcnt lgkmcnt(1)
	v_mfma_f32_16x16x32_bf16 v[26:29], v[26:29], v[22:25], 0
	v_mul_lo_u16_e32 v42, 9, v42
	v_sub_u16_e32 v42, v106, v42
	ds_read_b128 v[34:37], v38
	s_waitcnt lgkmcnt(1)
	v_mfma_f32_16x16x32_bf16 v[70:73], v[30:33], v[18:21], v[26:29]
	s_add_i32 s51, 0, 0x24000
	s_nop 1
	v_add_u16_e32 v26, 1, v42
	v_lshlrev_b32_sdwa v178, v150, v26 dst_sel:DWORD dst_unused:UNUSED_PAD src0_sel:DWORD src1_sel:BYTE_0
	v_add_u32_e32 v42, 0, v178
	v_add_u32_e32 v30, v42, v169
	ds_read_b128 v[26:29], v30
	ds_read_b128 v[38:41], v38 offset:1024
	ds_read_b128 v[30:33], v30 offset:1024
	s_waitcnt lgkmcnt(3)
	v_mfma_f32_16x16x32_bf16 v[34:37], v[34:37], v[22:25], 0
	s_waitcnt lgkmcnt(2)
	v_mfma_f32_16x16x32_bf16 v[26:29], v[26:29], v[22:25], 0
	s_waitcnt lgkmcnt(1)
	v_mfma_f32_16x16x32_bf16 v[74:77], v[38:41], v[18:21], v[34:37]
	s_nop 3
	v_mad_legacy_u16 v34, v106, 57, v151
	v_lshrrev_b16_e32 v34, 9, v34
	v_mul_lo_u16_e32 v34, 9, v34
	s_waitcnt lgkmcnt(0)
	v_mfma_f32_16x16x32_bf16 v[82:85], v[30:33], v[18:21], v[26:29]
	v_add_u32_e32 v30, v42, v170
	v_sub_u16_e32 v34, v106, v34
	s_nop 0
	ds_read_b128 v[26:29], v30
	ds_read_b128 v[30:33], v30 offset:1024
	v_add_u16_e32 v34, 2, v34
	v_lshlrev_b32_sdwa v177, v150, v34 dst_sel:DWORD dst_unused:UNUSED_PAD src0_sel:DWORD src1_sel:BYTE_0
	v_add_u32_e32 v38, 0, v177
	v_add_u32_e32 v39, v38, v169
	s_waitcnt lgkmcnt(1)
	v_mfma_f32_16x16x32_bf16 v[26:29], v[26:29], v[22:25], 0
	ds_read_b128 v[34:37], v39
	s_waitcnt lgkmcnt(1)
	v_mfma_f32_16x16x32_bf16 v[94:97], v[30:33], v[18:21], v[26:29]
	s_nop 4
	ds_read_b128 v[26:29], v39 offset:1024
	s_waitcnt lgkmcnt(1)
	v_mfma_f32_16x16x32_bf16 v[30:33], v[34:37], v[22:25], 0
	v_mad_legacy_u16 v34, v106, 57, v152
	v_lshrrev_b16_e32 v34, 9, v34
	v_mul_lo_u16_e32 v34, 9, v34
	s_waitcnt lgkmcnt(0)
	v_mfma_f32_16x16x32_bf16 v[102:105], v[26:29], v[18:21], v[30:33]
	s_nop 2
	v_add_u32_e32 v30, v38, v170
	v_sub_u16_e32 v34, v106, v34
	ds_read_b128 v[26:29], v30
	ds_read_b128 v[30:33], v30 offset:1024
	v_add_u16_e32 v34, 3, v34
	v_lshlrev_b32_sdwa v176, v150, v34 dst_sel:DWORD dst_unused:UNUSED_PAD src0_sel:DWORD src1_sel:BYTE_0
	v_add_u32_e32 v38, 0, v176
	v_add_u32_e32 v39, v38, v169
	s_waitcnt lgkmcnt(1)
	v_mfma_f32_16x16x32_bf16 v[26:29], v[26:29], v[22:25], 0
	ds_read_b128 v[34:37], v39
	s_waitcnt lgkmcnt(1)
	v_mfma_f32_16x16x32_bf16 v[108:111], v[30:33], v[18:21], v[26:29]
	s_nop 4
	ds_read_b128 v[26:29], v39 offset:1024
	s_waitcnt lgkmcnt(1)
	v_mfma_f32_16x16x32_bf16 v[30:33], v[34:37], v[22:25], 0
	v_mad_legacy_u16 v34, v106, 57, v153
	v_lshrrev_b16_e32 v34, 9, v34
	v_mul_lo_u16_e32 v34, 9, v34
	s_waitcnt lgkmcnt(0)
	v_mfma_f32_16x16x32_bf16 v[112:115], v[26:29], v[18:21], v[30:33]
	s_nop 2
	v_add_u32_e32 v30, v38, v170
	v_sub_u16_e32 v34, v106, v34
	ds_read_b128 v[26:29], v30
	ds_read_b128 v[30:33], v30 offset:1024
	v_add_u16_e32 v34, 4, v34
	v_lshlrev_b32_sdwa v175, v150, v34 dst_sel:DWORD dst_unused:UNUSED_PAD src0_sel:DWORD src1_sel:BYTE_0
	v_add_u32_e32 v38, 0, v175
	v_add_u32_e32 v39, v38, v169
	s_waitcnt lgkmcnt(1)
	v_mfma_f32_16x16x32_bf16 v[26:29], v[26:29], v[22:25], 0
	ds_read_b128 v[34:37], v39
	s_waitcnt lgkmcnt(1)
	v_mfma_f32_16x16x32_bf16 v[116:119], v[30:33], v[18:21], v[26:29]
	s_nop 4
	ds_read_b128 v[26:29], v39 offset:1024
	s_waitcnt lgkmcnt(1)
	v_mfma_f32_16x16x32_bf16 v[30:33], v[34:37], v[22:25], 0
	v_mad_legacy_u16 v34, v106, 57, v154
	v_lshrrev_b16_e32 v34, 9, v34
	v_mul_lo_u16_e32 v34, 9, v34
	s_waitcnt lgkmcnt(0)
	v_mfma_f32_16x16x32_bf16 v[50:53], v[26:29], v[18:21], v[30:33]
	s_nop 2
	v_add_u32_e32 v30, v38, v170
	v_sub_u16_e32 v34, v106, v34
	ds_read_b128 v[26:29], v30
	ds_read_b128 v[30:33], v30 offset:1024
	v_add_u16_e32 v34, 5, v34
	v_lshlrev_b32_sdwa v174, v150, v34 dst_sel:DWORD dst_unused:UNUSED_PAD src0_sel:DWORD src1_sel:BYTE_0
	v_add_u32_e32 v42, 0, v174
	v_add_u32_e32 v38, v42, v169
	s_waitcnt lgkmcnt(1)
	v_mfma_f32_16x16x32_bf16 v[26:29], v[26:29], v[22:25], 0
	ds_read_b128 v[34:37], v38
	s_waitcnt lgkmcnt(1)
	v_mfma_f32_16x16x32_bf16 v[46:49], v[30:33], v[18:21], v[26:29]
	s_nop 4
	ds_read_b128 v[26:29], v38 offset:1024
	s_waitcnt lgkmcnt(1)
	v_mfma_f32_16x16x32_bf16 v[30:33], v[34:37], v[22:25], 0
	v_mad_legacy_u16 v34, v106, 57, v155
	v_lshrrev_b16_e32 v34, 9, v34
	v_mul_lo_u16_e32 v34, 9, v34
	s_waitcnt lgkmcnt(0)
	v_mfma_f32_16x16x32_bf16 v[38:41], v[26:29], v[18:21], v[30:33]
	s_nop 2
	v_add_u32_e32 v30, v42, v170
	v_sub_u16_e32 v34, v106, v34
	ds_read_b128 v[26:29], v30
	ds_read_b128 v[30:33], v30 offset:1024
	v_add_u16_e32 v34, 6, v34
	v_lshlrev_b32_sdwa v173, v150, v34 dst_sel:DWORD dst_unused:UNUSED_PAD src0_sel:DWORD src1_sel:BYTE_0
	v_add_u32_e32 v78, 0, v173
	v_add_u32_e32 v79, v78, v169
	s_waitcnt lgkmcnt(1)
	v_mfma_f32_16x16x32_bf16 v[26:29], v[26:29], v[22:25], 0
	ds_read_b128 v[34:37], v79
	s_waitcnt lgkmcnt(1)
	v_mfma_f32_16x16x32_bf16 v[42:45], v[30:33], v[18:21], v[26:29]
	s_nop 4
	ds_read_b128 v[26:29], v79 offset:1024
	s_waitcnt lgkmcnt(1)
	v_mfma_f32_16x16x32_bf16 v[30:33], v[34:37], v[22:25], 0
	s_waitcnt lgkmcnt(0)
	v_mfma_f32_16x16x32_bf16 v[34:37], v[26:29], v[18:21], v[30:33]
	s_nop 5
	v_add_u32_e32 v30, v78, v170
	v_mad_legacy_u16 v78, v106, 57, v156
	v_lshrrev_b16_e32 v78, 9, v78
	v_mul_lo_u16_e32 v78, 9, v78
	v_sub_u16_e32 v78, v106, v78
	ds_read_b128 v[26:29], v30
	ds_read_b128 v[30:33], v30 offset:1024
	v_add_u16_e32 v78, 7, v78
	v_lshlrev_b32_sdwa v172, v150, v78 dst_sel:DWORD dst_unused:UNUSED_PAD src0_sel:DWORD src1_sel:BYTE_0
	v_add_u32_e32 v98, 0, v172
	v_add_u32_e32 v99, v98, v169
	s_waitcnt lgkmcnt(1)
	v_mfma_f32_16x16x32_bf16 v[26:29], v[26:29], v[22:25], 0
	ds_read_b128 v[78:81], v99
	v_add_u32_e32 v107, v98, v170
	s_waitcnt lgkmcnt(1)
	v_mfma_f32_16x16x32_bf16 v[30:33], v[30:33], v[18:21], v[26:29]
	s_nop 3
	ds_read_b128 v[26:29], v99 offset:1024
	s_waitcnt lgkmcnt(1)
	v_mfma_f32_16x16x32_bf16 v[78:81], v[78:81], v[22:25], 0
	ds_read_b128 v[98:101], v107
	s_waitcnt lgkmcnt(1)
	v_mfma_f32_16x16x32_bf16 v[26:29], v[26:29], v[18:21], v[78:81]
	s_nop 4
	ds_read_b128 v[78:81], v107 offset:1024
	s_waitcnt lgkmcnt(1)
	v_mfma_f32_16x16x32_bf16 v[22:25], v[98:101], v[22:25], 0
	s_waitcnt lgkmcnt(0)
	v_mfma_f32_16x16x32_bf16 v[18:21], v[78:81], v[18:21], v[22:25]
	s_nop 5
	v_add_u32_e32 v22, v106, v171
	v_mul_lo_u32 v22, v22, s80
	v_add_u32_e32 v98, s51, v22
	v_lshl_add_u32 v126, v158, 2, v98
	v_lshl_add_u32 v127, v159, 2, v98
	v_lshl_add_u32 v128, v160, 2, v98
	v_lshl_add_u32 v129, v161, 2, v98
	ds_read2_b32 v[22:23], v126 offset0:217 offset1:248
	ds_read2_b32 v[24:25], v127 offset0:217 offset1:248
	ds_read2_b32 v[106:107], v128 offset0:217 offset1:248
	ds_read2_b32 v[120:121], v129 offset0:217 offset1:248
	v_lshl_add_u32 v130, v163, 2, v98
	s_waitcnt lgkmcnt(3)
	v_mov_b32_e32 v78, v22
	s_waitcnt lgkmcnt(2)
	v_mov_b32_e32 v79, v24
	s_waitcnt lgkmcnt(1)
	v_mov_b32_e32 v80, v106
	s_waitcnt lgkmcnt(0)
	v_mov_b32_e32 v81, v120
	v_pk_add_f32 v[78:79], v[54:55], v[78:79]
	v_pk_add_f32 v[80:81], v[56:57], v[80:81]
	v_lshl_add_u32 v106, v162, 2, v98
	v_lshl_add_u32 v131, v164, 2, v98
	v_lshl_add_u32 v132, v165, 2, v98
	v_pk_fma_f32 v[80:81], v[72:73], s[24:25], v[80:81] op_sel_hi:[1,0,1]
	v_pk_fma_f32 v[78:79], v[70:71], s[24:25], v[78:79] op_sel_hi:[1,0,1]
	ds_read2_b32 v[70:71], v106 offset0:217 offset1:248
	ds_read2_b32 v[72:73], v130 offset0:217 offset1:248
	ds_read2_b32 v[122:123], v131 offset0:217 offset1:248
	ds_read2_b32 v[124:125], v132 offset0:217 offset1:248
	v_mov_b32_e32 v24, v23
	s_waitcnt lgkmcnt(3)
	v_mov_b32_e32 v98, v70
	s_waitcnt lgkmcnt(2)
	v_mov_b32_e32 v99, v72
	s_waitcnt lgkmcnt(1)
	v_mov_b32_e32 v100, v122
	s_waitcnt lgkmcnt(0)
	v_mov_b32_e32 v101, v124
	v_mov_b32_e32 v120, v107
	v_pk_add_f32 v[98:99], v[58:59], v[98:99]
	v_pk_add_f32 v[100:101], v[60:61], v[100:101]
	v_pk_add_f32 v[22:23], v[54:55], v[24:25]
	v_pk_add_f32 v[24:25], v[56:57], v[120:121]
	v_mov_b32_e32 v72, v71
	v_mov_b32_e32 v124, v123
	v_pk_fma_f32 v[100:101], v[76:77], s[24:25], v[100:101] op_sel_hi:[1,0,1]
	v_pk_fma_f32 v[98:99], v[74:75], s[24:25], v[98:99] op_sel_hi:[1,0,1]
	v_pk_fma_f32 v[84:85], v[84:85], s[24:25], v[24:25] op_sel_hi:[1,0,1]
	v_pk_fma_f32 v[82:83], v[82:83], s[24:25], v[22:23] op_sel_hi:[1,0,1]
	v_pk_add_f32 v[22:23], v[58:59], v[72:73]
	v_pk_add_f32 v[24:25], v[60:61], v[124:125]
	v_max3_f32 v74, v80, s79, v100
	v_max3_f32 v75, v81, s79, v101
	v_max3_f32 v76, v78, s79, v98
	v_max3_f32 v77, v79, s79, v99
	v_pk_fma_f32 v[72:73], v[96:97], s[24:25], v[24:25] op_sel_hi:[1,0,1]
	v_pk_fma_f32 v[70:71], v[94:95], s[24:25], v[22:23] op_sel_hi:[1,0,1]
	v_add_u32_e32 v138, 0x400, v128
	v_add_u32_e32 v139, 0x400, v129
	v_max3_f32 v124, v75, v85, v73
	v_max3_f32 v125, v74, v84, v72
	v_max3_f32 v133, v77, v83, v71
	v_max3_f32 v134, v76, v82, v70
	ds_read2_b32 v[74:75], v138 offset0:23 offset1:54
	ds_read2_b32 v[76:77], v139 offset0:23 offset1:54
	v_add_u32_e32 v136, 0x400, v126
	v_add_u32_e32 v137, 0x400, v127
	ds_read2_b32 v[22:23], v136 offset0:23 offset1:54
	ds_read2_b32 v[24:25], v137 offset0:23 offset1:54
	s_waitcnt lgkmcnt(3)
	v_mov_b32_e32 v96, v74
	s_waitcnt lgkmcnt(2)
	v_mov_b32_e32 v97, v76
	v_add_u32_e32 v182, 0x400, v131
	v_add_u32_e32 v183, 0x400, v132
	v_pk_add_f32 v[96:97], v[56:57], v[96:97]
	v_add_u32_e32 v180, 0x400, v106
	v_add_u32_e32 v181, 0x400, v130
	ds_read2_b32 v[122:123], v182 offset0:23 offset1:54
	ds_read2_b32 v[126:127], v183 offset0:23 offset1:54
	v_pk_fma_f32 v[96:97], v[104:105], s[24:25], v[96:97] op_sel_hi:[1,0,1]
	ds_read2_b32 v[104:105], v180 offset0:23 offset1:54
	ds_read2_b32 v[120:121], v181 offset0:23 offset1:54
	s_waitcnt lgkmcnt(5)
	v_mov_b32_e32 v94, v22
	s_waitcnt lgkmcnt(4)
	v_mov_b32_e32 v95, v24
	v_pk_add_f32 v[94:95], v[54:55], v[94:95]
	s_waitcnt lgkmcnt(3)
	v_mov_b32_e32 v106, v122
	s_waitcnt lgkmcnt(2)
	v_mov_b32_e32 v107, v126
	v_pk_fma_f32 v[94:95], v[102:103], s[24:25], v[94:95] op_sel_hi:[1,0,1]
	s_waitcnt lgkmcnt(1)
	v_mov_b32_e32 v102, v104
	s_waitcnt lgkmcnt(0)
	v_mov_b32_e32 v103, v120
	v_pk_add_f32 v[106:107], v[60:61], v[106:107]
	v_mov_b32_e32 v24, v23
	v_mov_b32_e32 v76, v75
	v_pk_add_f32 v[102:103], v[58:59], v[102:103]
	v_pk_fma_f32 v[106:107], v[110:111], s[24:25], v[106:107] op_sel_hi:[1,0,1]
	v_pk_add_f32 v[22:23], v[54:55], v[24:25]
	v_pk_add_f32 v[24:25], v[56:57], v[76:77]
	v_mov_b32_e32 v120, v105
	v_mov_b32_e32 v126, v123
	v_pk_fma_f32 v[102:103], v[108:109], s[24:25], v[102:103] op_sel_hi:[1,0,1]
	v_max3_f32 v104, v125, v96, v106
	v_max3_f32 v108, v124, v97, v107
	v_pk_fma_f32 v[128:129], v[114:115], s[24:25], v[24:25] op_sel_hi:[1,0,1]
	v_pk_fma_f32 v[124:125], v[112:113], s[24:25], v[22:23] op_sel_hi:[1,0,1]
	v_pk_add_f32 v[22:23], v[58:59], v[120:121]
	v_pk_add_f32 v[24:25], v[60:61], v[126:127]
	v_max3_f32 v109, v134, v94, v102
	v_pk_fma_f32 v[76:77], v[118:119], s[24:25], v[24:25] op_sel_hi:[1,0,1]
	v_pk_fma_f32 v[74:75], v[116:117], s[24:25], v[22:23] op_sel_hi:[1,0,1]
	v_max3_f32 v118, v108, v129, v77
	v_max3_f32 v119, v104, v128, v76
	ds_read2_b32 v[22:23], v136 offset0:85 offset1:116
	ds_read2_b32 v[24:25], v137 offset0:85 offset1:116
	v_max3_f32 v121, v109, v124, v74
	ds_read2_b32 v[104:105], v138 offset0:85 offset1:116
	ds_read2_b32 v[108:109], v139 offset0:85 offset1:116
	v_max3_f32 v110, v133, v95, v103
	v_max3_f32 v120, v110, v125, v75
	s_waitcnt lgkmcnt(3)
	v_mov_b32_e32 v110, v22
	s_waitcnt lgkmcnt(1)
	v_mov_b32_e32 v112, v104
	s_waitcnt lgkmcnt(0)
	v_mov_b32_e32 v113, v108
	v_mov_b32_e32 v111, v24
	v_pk_add_f32 v[112:113], v[56:57], v[112:113]
	v_pk_add_f32 v[110:111], v[54:55], v[110:111]
	v_pk_fma_f32 v[126:127], v[52:53], s[24:25], v[112:113] op_sel_hi:[1,0,1]
	ds_read2_b32 v[112:113], v180 offset0:85 offset1:116
	ds_read2_b32 v[114:115], v181 offset0:85 offset1:116
	v_pk_fma_f32 v[134:135], v[50:51], s[24:25], v[110:111] op_sel_hi:[1,0,1]
	ds_read2_b32 v[50:51], v182 offset0:85 offset1:116
	ds_read2_b32 v[110:111], v183 offset0:85 offset1:116
	v_mov_b32_e32 v24, v23
	s_waitcnt lgkmcnt(3)
	v_mov_b32_e32 v52, v112
	s_waitcnt lgkmcnt(2)
	v_mov_b32_e32 v53, v114
	v_mov_b32_e32 v108, v105
	v_pk_add_f32 v[52:53], v[58:59], v[52:53]
	s_waitcnt lgkmcnt(0)
	v_mov_b32_e32 v117, v110
	v_pk_add_f32 v[22:23], v[54:55], v[24:25]
	v_pk_add_f32 v[24:25], v[56:57], v[108:109]
	v_mov_b32_e32 v114, v113
	v_mov_b32_e32 v110, v51
	v_pk_fma_f32 v[130:131], v[46:47], s[24:25], v[52:53] op_sel_hi:[1,0,1]
	v_pk_fma_f32 v[122:123], v[40:41], s[24:25], v[24:25] op_sel_hi:[1,0,1]
	v_pk_fma_f32 v[52:53], v[38:39], s[24:25], v[22:23] op_sel_hi:[1,0,1]
	v_pk_add_f32 v[22:23], v[58:59], v[114:115]
	v_pk_add_f32 v[24:25], v[60:61], v[110:111]
	v_pk_fma_f32 v[110:111], v[42:43], s[24:25], v[22:23] op_sel_hi:[1,0,1]
	v_pk_fma_f32 v[112:113], v[44:45], s[24:25], v[24:25] op_sel_hi:[1,0,1]
	ds_read2_b32 v[22:23], v136 offset0:147 offset1:178
	ds_read2_b32 v[24:25], v137 offset0:147 offset1:178
	ds_read2_b32 v[38:39], v138 offset0:147 offset1:178
	ds_read2_b32 v[40:41], v139 offset0:147 offset1:178
	v_mov_b32_e32 v116, v50
	v_pk_add_f32 v[116:117], v[60:61], v[116:117]
	s_waitcnt lgkmcnt(3)
	v_mov_b32_e32 v42, v22
	s_waitcnt lgkmcnt(2)
	v_mov_b32_e32 v43, v24
	s_waitcnt lgkmcnt(1)
	v_mov_b32_e32 v44, v38
	s_waitcnt lgkmcnt(0)
	v_mov_b32_e32 v45, v40
	v_pk_fma_f32 v[132:133], v[48:49], s[24:25], v[116:117] op_sel_hi:[1,0,1]
	v_max3_f32 v48, v121, v134, v130
	v_max3_f32 v49, v120, v135, v131
	v_pk_add_f32 v[42:43], v[54:55], v[42:43]
	v_pk_add_f32 v[44:45], v[56:57], v[44:45]
	v_max3_f32 v116, v49, v53, v111
	v_max3_f32 v117, v48, v52, v110
	v_pk_fma_f32 v[50:51], v[36:37], s[24:25], v[44:45] op_sel_hi:[1,0,1]
	ds_read2_b32 v[36:37], v180 offset0:147 offset1:178
	ds_read2_b32 v[104:105], v181 offset0:147 offset1:178
	v_pk_fma_f32 v[48:49], v[34:35], s[24:25], v[42:43] op_sel_hi:[1,0,1]
	ds_read2_b32 v[34:35], v182 offset0:147 offset1:178
	ds_read2_b32 v[108:109], v183 offset0:147 offset1:178
	v_mov_b32_e32 v24, v23
	s_waitcnt lgkmcnt(3)
	v_mov_b32_e32 v42, v36
	s_waitcnt lgkmcnt(2)
	v_mov_b32_e32 v43, v104
	s_waitcnt lgkmcnt(1)
	v_mov_b32_e32 v44, v34
	s_waitcnt lgkmcnt(0)
	v_mov_b32_e32 v45, v108
	v_mov_b32_e32 v40, v39
	v_max3_f32 v46, v119, v126, v132
	v_max3_f32 v47, v118, v127, v133
	v_pk_add_f32 v[42:43], v[58:59], v[42:43]
	v_pk_add_f32 v[44:45], v[60:61], v[44:45]
	v_pk_add_f32 v[22:23], v[54:55], v[24:25]
	v_pk_add_f32 v[24:25], v[56:57], v[40:41]
	v_mov_b32_e32 v108, v35
	v_max3_f32 v114, v47, v123, v113
	v_max3_f32 v115, v46, v122, v112
	v_pk_fma_f32 v[46:47], v[32:33], s[24:25], v[44:45] op_sel_hi:[1,0,1]
	v_pk_fma_f32 v[44:45], v[30:31], s[24:25], v[42:43] op_sel_hi:[1,0,1]
	v_pk_fma_f32 v[42:43], v[28:29], s[24:25], v[24:25] op_sel_hi:[1,0,1]
	v_mov_b32_e32 v104, v37
	v_pk_add_f32 v[24:25], v[60:61], v[108:109]
	v_max3_f32 v30, v115, v50, v46
	v_max3_f32 v31, v114, v51, v47
	v_pk_fma_f32 v[40:41], v[26:27], s[24:25], v[22:23] op_sel_hi:[1,0,1]
	v_pk_add_f32 v[22:23], v[58:59], v[104:105]
	v_pk_fma_f32 v[38:39], v[20:21], s[24:25], v[24:25] op_sel_hi:[1,0,1]
	v_max3_f32 v32, v117, v48, v44
	v_max3_f32 v33, v116, v49, v45
	v_pk_fma_f32 v[36:37], v[18:19], s[24:25], v[22:23] op_sel_hi:[1,0,1]
	v_max3_f32 v18, v31, v43, v39
	v_max3_f32 v19, v30, v42, v38
	v_max3_f32 v20, v33, v41, v37
	v_max3_f32 v21, v32, v40, v36
	v_max_f32_e32 v18, v19, v18
	v_max3_f32 v20, v21, v20, v18
	ds_bpermute_b32 v21, v93, v20
	v_add_u32_e32 v18, s50, v92
	v_ashrrev_i32_e32 v19, 31, v18
	v_lshlrev_b64 v[18:19], 17, v[18:19]
	v_lshl_add_u64 v[18:19], v[90:91], 0, v[18:19]
	s_waitcnt lgkmcnt(0)
	v_max_f32_e32 v21, v21, v21
	v_max_f32_e32 v26, v20, v21
	ds_bpermute_b32 v27, v157, v26
	global_load_dwordx4 v[22:25], v[18:19], off
	s_nop 0
	global_load_dwordx4 v[18:21], v[18:19], off offset:64
	s_waitcnt lgkmcnt(0)
	v_max_f32_e32 v27, v27, v27
	v_max_f32_e32 v180, v26, v27
	v_sub_f32_e32 v28, v79, v180
	v_sub_f32_e32 v29, v78, v180
	v_exp_f32_e32 v114, v29
	v_exp_f32_e32 v115, v28
	v_sub_f32_e32 v99, v99, v180
	v_sub_f32_e32 v98, v98, v180
	v_exp_f32_e32 v136, v98
	v_exp_f32_e32 v137, v99
	v_sub_f32_e32 v83, v83, v180
	v_sub_f32_e32 v82, v82, v180
	v_sub_f32_e32 v26, v81, v180
	v_sub_f32_e32 v27, v80, v180
	v_exp_f32_e32 v104, v82
	v_exp_f32_e32 v105, v83
	v_sub_f32_e32 v71, v71, v180
	v_sub_f32_e32 v70, v70, v180
	v_exp_f32_e32 v118, v27
	v_exp_f32_e32 v119, v26
	v_sub_f32_e32 v101, v101, v180
	v_sub_f32_e32 v100, v100, v180
	v_exp_f32_e32 v116, v70
	v_exp_f32_e32 v117, v71
	v_pk_add_f32 v[78:79], v[114:115], 0 op_sel_hi:[1,0]
	v_exp_f32_e32 v138, v100
	v_exp_f32_e32 v139, v101
	v_sub_f32_e32 v85, v85, v180
	v_sub_f32_e32 v84, v84, v180
	v_exp_f32_e32 v108, v84
	v_exp_f32_e32 v109, v85
	v_pk_add_f32 v[78:79], v[136:137], v[78:79]
	v_sub_f32_e32 v73, v73, v180
	v_sub_f32_e32 v72, v72, v180
	v_pk_add_f32 v[78:79], v[104:105], v[78:79]
	v_exp_f32_e32 v120, v72
	v_exp_f32_e32 v121, v73
	v_sub_f32_e32 v70, v97, v180
	v_sub_f32_e32 v71, v96, v180
	v_sub_f32_e32 v72, v95, v180
	v_sub_f32_e32 v73, v94, v180
	v_pk_add_f32 v[80:81], v[118:119], 0 op_sel_hi:[1,0]
	v_exp_f32_e32 v96, v73
	v_exp_f32_e32 v97, v72
	v_exp_f32_e32 v100, v71
	v_exp_f32_e32 v101, v70
	v_pk_add_f32 v[72:73], v[116:117], v[78:79]
	v_sub_f32_e32 v78, v107, v180
	v_sub_f32_e32 v79, v106, v180
	v_pk_add_f32 v[80:81], v[138:139], v[80:81]
	v_exp_f32_e32 v106, v79
	v_exp_f32_e32 v107, v78
	v_sub_f32_e32 v78, v129, v180
	v_sub_f32_e32 v79, v128, v180
	v_pk_add_f32 v[80:81], v[108:109], v[80:81]
	v_exp_f32_e32 v84, v79
	v_exp_f32_e32 v85, v78
	v_sub_f32_e32 v77, v77, v180
	v_sub_f32_e32 v76, v76, v180
	v_pk_add_f32 v[70:71], v[120:121], v[80:81]
	v_sub_f32_e32 v80, v103, v180
	v_sub_f32_e32 v81, v102, v180
	v_exp_f32_e32 v98, v76
	v_exp_f32_e32 v99, v77
	v_sub_f32_e32 v77, v127, v180
	v_sub_f32_e32 v76, v126, v180
	v_pk_add_f32 v[70:71], v[100:101], v[70:71]
	v_exp_f32_e32 v102, v81
	v_exp_f32_e32 v103, v80
	v_sub_f32_e32 v81, v125, v180
	v_sub_f32_e32 v80, v124, v180
	v_exp_f32_e32 v76, v76
	v_exp_f32_e32 v77, v77
	v_exp_f32_e32 v80, v80
	v_exp_f32_e32 v81, v81
	v_pk_add_f32 v[70:71], v[106:107], v[70:71]
	v_sub_f32_e32 v75, v75, v180
	v_sub_f32_e32 v74, v74, v180
	v_pk_add_f32 v[70:71], v[84:85], v[70:71]
	v_exp_f32_e32 v94, v74
	v_exp_f32_e32 v95, v75
	v_sub_f32_e32 v75, v135, v180
	v_sub_f32_e32 v74, v134, v180
	v_pk_add_f32 v[72:73], v[96:97], v[72:73]
	v_exp_f32_e32 v74, v74
	v_exp_f32_e32 v75, v75
	v_pk_add_f32 v[70:71], v[98:99], v[70:71]
	v_sub_f32_e32 v79, v131, v180
	v_sub_f32_e32 v78, v130, v180
	v_pk_add_f32 v[72:73], v[102:103], v[72:73]
	v_pk_add_f32 v[124:125], v[76:77], v[70:71]
	v_sub_f32_e32 v70, v133, v180
	v_sub_f32_e32 v71, v132, v180
	v_exp_f32_e32 v78, v78
	v_exp_f32_e32 v79, v79
	v_sub_f32_e32 v53, v53, v180
	v_sub_f32_e32 v52, v52, v180
	v_pk_add_f32 v[72:73], v[80:81], v[72:73]
	v_exp_f32_e32 v82, v71
	v_exp_f32_e32 v83, v70
	v_sub_f32_e32 v71, v123, v180
	v_sub_f32_e32 v70, v122, v180
	v_exp_f32_e32 v52, v52
	v_exp_f32_e32 v53, v53
	v_pk_add_f32 v[72:73], v[94:95], v[72:73]
	v_exp_f32_e32 v70, v70
	v_exp_f32_e32 v71, v71
	v_pk_add_f32 v[72:73], v[74:75], v[72:73]
	global_load_dwordx2 v[32:33], v[66:67], off offset:-1024
	global_load_dwordx2 v[30:31], v[66:67], off offset:-512
	global_load_dwordx2 v[28:29], v[66:67], off
	global_load_dwordx2 v[26:27], v[66:67], off offset:512
	global_load_dwordx2 v[34:35], v[64:65], off
	v_pk_add_f32 v[72:73], v[78:79], v[72:73]
	v_pk_add_f32 v[122:123], v[82:83], v[124:125]
	v_pk_add_f32 v[186:187], v[52:53], v[72:73]
	v_sub_f32_e32 v126, v113, v180
	v_sub_f32_e32 v127, v112, v180
	v_sub_f32_e32 v73, v111, v180
	v_sub_f32_e32 v72, v110, v180
	v_cvt_pk_bf16_f32 v112, v114, v115
	v_cvt_pk_bf16_f32 v113, v118, v119
	v_add_u32_e32 v118, v166, v179
	v_pk_add_f32 v[188:189], v[70:71], v[122:123]
	v_exp_f32_e32 v72, v72
	v_exp_f32_e32 v73, v73
	v_cvt_pk_bf16_f32 v114, v136, v137
	v_cvt_pk_bf16_f32 v115, v138, v139
	ds_read2st64_b64 v[122:125], v118 offset1:1
	v_exp_f32_e32 v110, v127
	v_exp_f32_e32 v111, v126
	ds_read2st64_b64 v[126:129], v118 offset0:4 offset1:5
	ds_read2st64_b64 v[130:133], v118 offset0:2 offset1:3
	ds_read2st64_b64 v[182:185], v118 offset0:6 offset1:7
	v_pk_add_f32 v[138:139], v[72:73], v[186:187]
	v_cvt_pk_bf16_f32 v186, v104, v105
	v_add_u32_e32 v104, v166, v178
	s_waitcnt lgkmcnt(3)
	v_mov_b32_e32 v134, v122
	v_mov_b32_e32 v135, v123
	s_waitcnt lgkmcnt(2)
	v_mov_b32_e32 v136, v126
	v_mov_b32_e32 v137, v127
	v_pk_add_f32 v[202:203], v[110:111], v[188:189]
	v_mov_b32_e32 v126, v124
	v_mov_b32_e32 v127, v125
	s_waitcnt lgkmcnt(1)
	v_mov_b32_e32 v122, v130
	v_mov_b32_e32 v123, v131
	s_waitcnt lgkmcnt(0)
	v_mov_b32_e32 v124, v182
	v_mov_b32_e32 v125, v183
	v_cvt_pk_bf16_f32 v187, v108, v109
	v_cvt_pk_bf16_f32 v188, v116, v117
	v_cvt_pk_bf16_f32 v189, v120, v121
	ds_read2st64_b64 v[116:119], v104 offset1:1
	v_mov_b32_e32 v182, v132
	v_mov_b32_e32 v183, v133
	ds_read2st64_b64 v[130:133], v104 offset0:4 offset1:5
	ds_read2st64_b64 v[190:193], v104 offset0:2 offset1:3
	ds_read2st64_b64 v[198:201], v104 offset0:6 offset1:7
	v_sub_f32_e32 v49, v49, v180
	v_sub_f32_e32 v48, v48, v180
	v_exp_f32_e32 v48, v48
	s_waitcnt lgkmcnt(3)
	v_mov_b32_e32 v194, v116
	v_mov_b32_e32 v195, v117
	s_waitcnt lgkmcnt(2)
	v_mov_b32_e32 v196, v130
	v_mov_b32_e32 v197, v131
	v_exp_f32_e32 v49, v49
	v_mov_b32_e32 v130, v118
	v_mov_b32_e32 v131, v119
	s_waitcnt lgkmcnt(1)
	v_mov_b32_e32 v116, v190
	v_mov_b32_e32 v117, v191
	s_waitcnt lgkmcnt(0)
	v_mov_b32_e32 v118, v198
	v_mov_b32_e32 v119, v199
	v_mfma_f32_16x16x32_bf16 v[126:129], v[126:129], v[112:115], 0
	v_sub_f32_e32 v51, v51, v180
	v_sub_f32_e32 v50, v50, v180
	v_exp_f32_e32 v108, v50
	v_mfma_f32_16x16x32_bf16 v[122:125], v[122:125], v[112:115], 0
	v_exp_f32_e32 v109, v51
	v_pk_add_f32 v[50:51], v[48:49], v[138:139]
	v_sub_f32_e32 v139, v46, v180
	v_add_u32_e32 v46, v166, v177
	v_mfma_f32_16x16x32_bf16 v[126:129], v[130:133], v[186:189], v[126:129]
	v_cvt_pk_bf16_f32 v120, v96, v97
	v_cvt_pk_bf16_f32 v121, v100, v101
	v_mov_b32_e32 v198, v192
	v_mfma_f32_16x16x32_bf16 v[116:119], v[116:119], v[186:189], v[122:125]
	v_cvt_pk_bf16_f32 v122, v102, v103
	v_cvt_pk_bf16_f32 v123, v106, v107
	ds_read2st64_b64 v[100:103], v46 offset1:1
	v_mov_b32_e32 v199, v193
	ds_read2st64_b64 v[104:107], v46 offset0:4 offset1:5
	ds_read2st64_b64 v[130:133], v46 offset0:2 offset1:3
	ds_read2st64_b64 v[190:193], v46 offset0:6 offset1:7
	v_mfma_f32_16x16x32_bf16 v[134:137], v[134:137], v[112:115], 0
	v_sub_f32_e32 v138, v47, v180
	v_sub_f32_e32 v96, v45, v180
	v_sub_f32_e32 v44, v44, v180
	v_mfma_f32_16x16x32_bf16 v[112:115], v[182:185], v[112:115], 0
	s_waitcnt lgkmcnt(3)
	v_mov_b32_e32 v182, v100
	v_mov_b32_e32 v183, v101
	s_waitcnt lgkmcnt(2)
	v_mov_b32_e32 v184, v104
	v_mov_b32_e32 v185, v105
	v_mov_b32_e32 v104, v102
	v_mov_b32_e32 v105, v103
	s_waitcnt lgkmcnt(1)
	v_mov_b32_e32 v100, v130
	v_mov_b32_e32 v101, v131
	s_waitcnt lgkmcnt(0)
	v_mov_b32_e32 v102, v190
	v_mov_b32_e32 v103, v191
	v_mfma_f32_16x16x32_bf16 v[134:137], v[194:197], v[186:189], v[134:137]
	v_exp_f32_e32 v178, v44
	v_exp_f32_e32 v179, v96
	v_mov_b32_e32 v190, v132
	v_mfma_f32_16x16x32_bf16 v[100:103], v[100:103], v[120:123], v[116:119]
	v_cvt_pk_bf16_f32 v116, v80, v81
	v_add_u32_e32 v80, v166, v176
	v_cvt_pk_bf16_f32 v117, v84, v85
	v_mfma_f32_16x16x32_bf16 v[44:47], v[182:185], v[120:123], v[134:137]
	v_exp_f32_e32 v182, v139
	v_exp_f32_e32 v183, v138
	v_cvt_pk_bf16_f32 v118, v94, v95
	v_mfma_f32_16x16x32_bf16 v[104:107], v[104:107], v[120:123], v[126:129]
	v_cvt_pk_bf16_f32 v119, v98, v99
	ds_read2st64_b64 v[94:97], v80 offset1:1
	s_nop 1
	ds_read2st64_b64 v[124:127], v80 offset0:4 offset1:5
	ds_read2st64_b64 v[128:131], v80 offset0:2 offset1:3
	ds_read2st64_b64 v[136:139], v80 offset0:6 offset1:7
	v_mov_b32_e32 v191, v133
	v_pk_add_f32 v[80:81], v[108:109], v[202:203]
	s_waitcnt lgkmcnt(3)
	v_mov_b32_e32 v132, v94
	v_mov_b32_e32 v133, v95
	s_waitcnt lgkmcnt(2)
	v_mov_b32_e32 v134, v124
	v_mov_b32_e32 v135, v125
	v_mov_b32_e32 v124, v96
	v_mov_b32_e32 v125, v97
	s_waitcnt lgkmcnt(1)
	v_mov_b32_e32 v94, v128
	v_mov_b32_e32 v95, v129
	s_waitcnt lgkmcnt(0)
	v_mov_b32_e32 v96, v136
	v_mov_b32_e32 v97, v137
	v_sub_f32_e32 v129, v42, v180
	v_add_u32_e32 v42, v166, v175
	v_pk_add_f32 v[176:177], v[182:183], v[80:81]
	v_cvt_pk_bf16_f32 v74, v74, v75
	v_cvt_pk_bf16_f32 v75, v76, v77
	v_cvt_pk_bf16_f32 v76, v78, v79
	v_cvt_pk_bf16_f32 v77, v82, v83
	ds_read2st64_b64 v[78:81], v42 offset1:1
	v_mfma_f32_16x16x32_bf16 v[112:115], v[198:201], v[186:189], v[112:115]
	v_mov_b32_e32 v136, v130
	v_mov_b32_e32 v137, v131
	v_sub_f32_e32 v41, v41, v180
	v_mfma_f32_16x16x32_bf16 v[94:97], v[94:97], v[116:119], v[100:103]
	ds_read2st64_b64 v[82:85], v42 offset0:4 offset1:5
	s_nop 1
	ds_read2st64_b64 v[98:101], v42 offset0:2 offset1:3
	v_sub_f32_e32 v40, v40, v180
	v_sub_f32_e32 v128, v43, v180
	v_mfma_f32_16x16x32_bf16 v[112:115], v[190:193], v[120:123], v[112:115]
	s_waitcnt lgkmcnt(2)
	v_mov_b32_e32 v120, v78
	v_mov_b32_e32 v121, v79
	s_waitcnt lgkmcnt(1)
	v_mov_b32_e32 v122, v82
	v_mfma_f32_16x16x32_bf16 v[104:107], v[124:127], v[116:119], v[104:107]
	ds_read2st64_b64 v[124:127], v42 offset0:6 offset1:7
	v_mov_b32_e32 v123, v83
	v_mov_b32_e32 v82, v80
	v_mfma_f32_16x16x32_bf16 v[44:47], v[132:135], v[116:119], v[44:47]
	v_mov_b32_e32 v83, v81
	v_pk_add_f32 v[50:51], v[178:179], v[50:51]
	v_add_u32_e32 v102, v166, v174
	v_mfma_f32_16x16x32_bf16 v[112:115], v[136:139], v[116:119], v[112:115]
	v_exp_f32_e32 v116, v40
	v_exp_f32_e32 v117, v41
	v_sub_f32_e32 v36, v36, v180
	v_mfma_f32_16x16x32_bf16 v[40:43], v[120:123], v[74:77], v[44:47]
	v_sub_f32_e32 v37, v37, v180
	v_pk_add_f32 v[120:121], v[116:117], v[50:51]
	v_cvt_pk_bf16_f32 v50, v52, v53
	v_mfma_f32_16x16x32_bf16 v[78:81], v[82:85], v[74:77], v[104:107]
	s_waitcnt lgkmcnt(1)
	v_mov_b32_e32 v44, v98
	v_mov_b32_e32 v45, v99
	s_waitcnt lgkmcnt(0)
	v_mov_b32_e32 v46, v124
	v_mov_b32_e32 v47, v125
	v_cvt_pk_bf16_f32 v51, v70, v71
	v_cvt_pk_bf16_f32 v52, v72, v73
	v_cvt_pk_bf16_f32 v53, v110, v111
	ds_read2st64_b64 v[70:73], v102 offset1:1
	v_mov_b32_e32 v124, v100
	v_mfma_f32_16x16x32_bf16 v[44:47], v[44:47], v[74:77], v[94:97]
	ds_read2st64_b64 v[82:85], v102 offset0:4 offset1:5
	s_nop 1
	ds_read2st64_b64 v[94:97], v102 offset0:2 offset1:3
	ds_read2st64_b64 v[102:105], v102 offset0:6 offset1:7
	v_mov_b32_e32 v125, v101
	s_waitcnt lgkmcnt(3)
	v_mov_b32_e32 v98, v70
	v_mov_b32_e32 v99, v71
	s_waitcnt lgkmcnt(2)
	v_mov_b32_e32 v100, v82
	v_mov_b32_e32 v101, v83
	v_mov_b32_e32 v82, v72
	v_mov_b32_e32 v83, v73
	s_waitcnt lgkmcnt(1)
	v_mov_b32_e32 v70, v94
	v_mov_b32_e32 v71, v95
	s_waitcnt lgkmcnt(0)
	v_mov_b32_e32 v72, v102
	v_mov_b32_e32 v73, v103
	v_mfma_f32_16x16x32_bf16 v[74:77], v[124:127], v[74:77], v[112:115]
	v_mov_b32_e32 v102, v96
	v_mov_b32_e32 v103, v97
	v_exp_f32_e32 v118, v129
	v_exp_f32_e32 v112, v36
	v_add_u32_e32 v36, v166, v173
	v_sub_f32_e32 v114, v39, v180
	v_sub_f32_e32 v115, v38, v180
	v_mfma_f32_16x16x32_bf16 v[38:41], v[98:101], v[50:53], v[40:43]
	v_exp_f32_e32 v113, v37
	v_exp_f32_e32 v119, v128
	v_mfma_f32_16x16x32_bf16 v[78:81], v[82:85], v[50:53], v[78:81]
	v_add_f32_e64 v110, v118, v176
	v_add_f32_e64 v111, v119, v177
	v_mfma_f32_16x16x32_bf16 v[42:45], v[70:73], v[50:53], v[44:47]
	v_cvt_pk_bf16_f32 v46, v48, v49
	v_cvt_pk_bf16_f32 v47, v108, v109
	v_cvt_pk_bf16_f32 v48, v178, v179
	v_cvt_pk_bf16_f32 v49, v182, v183
	ds_read2st64_b64 v[70:73], v36 offset1:1
	ds_read2st64_b64 v[82:85], v36 offset0:4 offset1:5
	ds_read2st64_b64 v[94:97], v36 offset0:2 offset1:3
	ds_read2st64_b64 v[106:109], v36 offset0:6 offset1:7
	v_mfma_f32_16x16x32_bf16 v[50:53], v[102:105], v[50:53], v[74:77]
	v_exp_f32_e32 v102, v115
	s_waitcnt lgkmcnt(3)
	v_mov_b32_e32 v98, v70
	v_mov_b32_e32 v99, v71
	s_waitcnt lgkmcnt(2)
	v_mov_b32_e32 v100, v82
	v_mov_b32_e32 v101, v83
	v_mov_b32_e32 v82, v72
	v_mov_b32_e32 v83, v73
	s_waitcnt lgkmcnt(1)
	v_mov_b32_e32 v70, v94
	v_mov_b32_e32 v71, v95
	s_waitcnt lgkmcnt(0)
	v_mov_b32_e32 v72, v106
	v_mov_b32_e32 v73, v107
	v_mfma_f32_16x16x32_bf16 v[36:39], v[98:101], v[46:49], v[38:41]
	v_exp_f32_e32 v103, v114
	v_mov_b32_e32 v106, v96
	v_mov_b32_e32 v107, v97
	v_mfma_f32_16x16x32_bf16 v[40:43], v[70:73], v[46:49], v[42:45]
	v_cvt_pk_bf16_f32 v70, v116, v117
	v_cvt_pk_bf16_f32 v71, v118, v119
	v_cvt_pk_bf16_f32 v72, v112, v113
	v_mfma_f32_16x16x32_bf16 v[74:77], v[82:85], v[46:49], v[78:81]
	v_cvt_pk_bf16_f32 v73, v102, v103
	s_nop 1
	v_add_u32_e32 v44, v166, v172
	v_pk_add_f32 v[110:111], v[102:103], v[110:111]
	v_pk_add_f32 v[114:115], v[112:113], v[120:121]
	ds_read2st64_b64 v[78:81], v44 offset1:1
	ds_read2st64_b64 v[82:85], v44 offset0:4 offset1:5
	ds_read2st64_b64 v[94:97], v44 offset0:2 offset1:3
	ds_read2st64_b64 v[102:105], v44 offset0:6 offset1:7
	v_pk_mov_b32 v[120:121], v[114:115], v[110:111] op_sel:[1,0]
	v_mov_b32_e32 v115, v111
	s_waitcnt lgkmcnt(2)
	v_mov_b32_e32 v100, v82
	v_mov_b32_e32 v101, v83
	v_mov_b32_e32 v82, v80
	v_mov_b32_e32 v83, v81
	v_mfma_f32_16x16x32_bf16 v[44:47], v[106:109], v[46:49], v[50:53]
	v_add_f32_e64 v48, v120, v114
	v_add_f32_e64 v49, v121, v115
	v_mov_b32_e32 v98, v78
	v_mov_b32_e32 v99, v79
	v_add_f32_e32 v52, v48, v49
	ds_bpermute_b32 v53, v93, v52
	v_mfma_f32_16x16x32_bf16 v[48:51], v[82:85], v[70:73], v[74:77]
	s_waitcnt lgkmcnt(0)
	v_add_f32_e32 v52, v52, v53
	s_nop 0
	v_mov_b32_e32 v74, v94
	v_mov_b32_e32 v75, v95
	v_mov_b32_e32 v76, v102
	v_mov_b32_e32 v77, v103
	s_waitcnt vmcnt(0)
	v_max_f32_e32 v53, v34, v34
	ds_bpermute_b32 v78, v157, v52
	v_mfma_f32_16x16x32_bf16 v[40:43], v[74:77], v[70:73], v[40:43]
	v_max_f32_e32 v74, v180, v53
	v_sub_f32_e32 v53, v180, v74
	v_sub_f32_e32 v34, v34, v74
	v_exp_f32_e32 v53, v53
	v_exp_f32_e32 v74, v34
	s_waitcnt lgkmcnt(0)
	v_add_f32_e32 v75, v52, v78
	v_mov_b32_e32 v52, v35
	v_mov_b32_e32 v102, v96
	v_pk_mul_f32 v[34:35], v[52:53], v[74:75]
	v_mov_b32_e32 v103, v97
	v_add_f32_e32 v35, v34, v35
	v_div_scale_f32 v52, s[50:51], v35, v35, 1.0
	v_rcp_f32_e32 v74, v52
	v_mfma_f32_16x16x32_bf16 v[36:39], v[98:101], v[70:73], v[36:39]
	v_mfma_f32_16x16x32_bf16 v[44:47], v[102:105], v[70:73], v[44:47]
	v_fma_f32 v70, -v52, v74, 1.0
	v_fmac_f32_e32 v74, v70, v74
	v_div_scale_f32 v70, vcc, 1.0, v35, 1.0
	v_mul_f32_e32 v71, v70, v74
	v_fma_f32 v72, -v52, v71, v70
	v_fmac_f32_e32 v71, v72, v74
	v_fma_f32 v52, -v52, v71, v70
	v_div_fmas_f32 v52, v52, v74, v71
	v_div_fixup_f32 v52, v52, v35, 1.0
	v_mov_b32_e32 v35, v53
	v_lshlrev_b32_e32 v70, 16, v32
	v_and_b32_e32 v72, 0xffff0000, v32
	v_pk_mul_f32 v[34:35], v[34:35], v[52:53] op_sel_hi:[1,0]
	v_mov_b32_e32 v71, v36
	v_mov_b32_e32 v73, v37
	v_pk_mul_f32 v[52:53], v[34:35], v[70:71]
	v_pk_mul_f32 v[36:37], v[34:35], v[72:73]
	v_lshlrev_b32_e32 v74, 16, v33
	v_add_f32_e32 v32, v52, v53
	v_add_f32_e32 v36, v36, v37
	v_mov_b32_e32 v75, v38
	v_cvt_pk_bf16_f32 v32, v32, v36
	v_pk_mul_f32 v[36:37], v[34:35], v[74:75]
	v_and_b32_e32 v38, 0xffff0000, v33
	v_add_f32_e32 v52, v36, v37
	v_pk_mul_f32 v[36:37], v[34:35], v[38:39]
	s_andn2_b64 vcc, exec, s[8:9]
	v_add_f32_e32 v33, v36, v37
	v_cvt_pk_bf16_f32 v33, v52, v33
	global_store_dwordx2 v[68:69], v[32:33], off
	v_lshlrev_b32_e32 v32, 16, v30
	v_mov_b32_e32 v33, v48
	v_pk_mul_f32 v[32:33], v[34:35], v[32:33]
	v_and_b32_e32 v48, 0xffff0000, v30
	v_add_f32_e32 v36, v32, v33
	v_pk_mul_f32 v[32:33], v[34:35], v[48:49]
	s_nop 0
	v_add_f32_e32 v30, v32, v33
	v_lshlrev_b32_e32 v32, 16, v31
	v_mov_b32_e32 v33, v50
	v_pk_mul_f32 v[32:33], v[34:35], v[32:33]
	v_and_b32_e32 v50, 0xffff0000, v31
	v_cvt_pk_bf16_f32 v30, v36, v30
	v_add_f32_e32 v36, v32, v33
	v_pk_mul_f32 v[32:33], v[34:35], v[50:51]
	s_nop 0
	v_add_f32_e32 v31, v32, v33
	v_cvt_pk_bf16_f32 v31, v36, v31
	global_store_dwordx2 v[68:69], v[30:31], off offset:32
	v_lshlrev_b32_e32 v30, 16, v28
	v_mov_b32_e32 v31, v40
	v_pk_mul_f32 v[30:31], v[34:35], v[30:31]
	v_and_b32_e32 v40, 0xffff0000, v28
	v_add_f32_e32 v32, v30, v31
	v_pk_mul_f32 v[30:31], v[34:35], v[40:41]
	s_nop 0
	v_add_f32_e32 v28, v30, v31
	v_lshlrev_b32_e32 v30, 16, v29
	v_mov_b32_e32 v31, v42
	v_pk_mul_f32 v[30:31], v[34:35], v[30:31]
	v_and_b32_e32 v42, 0xffff0000, v29
	v_cvt_pk_bf16_f32 v28, v32, v28
	v_add_f32_e32 v32, v30, v31
	v_pk_mul_f32 v[30:31], v[34:35], v[42:43]
	s_nop 0
	v_add_f32_e32 v29, v30, v31
	v_cvt_pk_bf16_f32 v29, v32, v29
	global_store_dwordx2 v[68:69], v[28:29], off offset:64
	v_lshlrev_b32_e32 v28, 16, v26
	v_mov_b32_e32 v29, v44
	v_pk_mul_f32 v[28:29], v[34:35], v[28:29]
	v_and_b32_e32 v44, 0xffff0000, v26
	v_add_f32_e32 v30, v28, v29
	v_pk_mul_f32 v[28:29], v[34:35], v[44:45]
	s_nop 0
	v_add_f32_e32 v26, v28, v29
	v_lshlrev_b32_e32 v28, 16, v27
	v_mov_b32_e32 v29, v46
	v_pk_mul_f32 v[28:29], v[34:35], v[28:29]
	v_and_b32_e32 v46, 0xffff0000, v27
	v_cvt_pk_bf16_f32 v26, v30, v26
	v_add_f32_e32 v30, v28, v29
	v_pk_mul_f32 v[28:29], v[34:35], v[46:47]
	s_nop 0
	v_add_f32_e32 v27, v28, v29
	v_cvt_pk_bf16_f32 v27, v30, v27
	global_store_dwordx2 v[68:69], v[26:27], off offset:96
	s_barrier
	s_cbranch_vccnz .LBB0_697
	s_mul_hi_u32 s8, s16, 0x38e38e39
	s_lshr_b32 s8, s8, 1
	s_mul_i32 s8, s8, 9
	s_sub_i32 s8, s16, s8
	s_lshl_b32 s8, s8, 13
	v_add_u32_e32 v26, s8, v167
	ds_write_b128 v26, v[2:5]
	v_add_u32_e32 v26, s8, v168
	ds_write_b128 v26, v[10:13]

.LBB0_766:
	v_cmp_gt_i32_e32 vcc, 1, v138
	s_cbranch_vccnz .LBB0_828
	v_lshl_add_u64 v[152:153], v[2:3], 0, s[16:17]
	v_add_u32_e32 v154, -2, v138
	s_waitcnt lgkmcnt(0)
	v_lshl_add_u64 v[150:151], v[4:5], 0, s[20:21]
	s_mov_b32 s7, 0
	s_nop 0
	v_readfirstlane_b32 s86, v152
	v_readfirstlane_b32 s87, v153
	v_readfirstlane_b32 s88, v150
	v_readfirstlane_b32 s89, v151
	v_readfirstlane_b32 s90, v146
	v_readfirstlane_b32 s91, v147
	v_readfirstlane_b32 s92, v148
	v_readfirstlane_b32 s93, v149
	v_readfirstlane_b32 s100, v154
	v_readfirstlane_b32 s101, v138
	v_add_u32_e32 v230, s76, v141
	v_add_u32_e32 v231, s77, v141
	v_add_u32_e32 v232, 0x18000, v141
	v_add_u32_e32 v233, 0x1c000, v141
	s_add_u32 s98, s86, 0xfffc0080
	s_addc_u32 s99, s87, -1
	s_cmp_eq_u32 s7, s100
	s_cselect_b64 s[94:95], s[90:91], s[98:99]
	s_cselect_b64 s[96:97], s[92:93], s[88:89]
	s_add_i32 s45, s7, 2
	s_nop 0
	s_add_i32 m0, s49, 0xc000
	s_nop 0
	global_load_lds_dwordx4 v144, s[86:87]
	s_add_i32 m0, s49, 0xe000
	s_nop 0
	global_load_lds_dwordx4 v142, s[86:87]
	ds_read_b128 v[164:167], v230
	ds_read_b128 v[168:171], v230 offset:1024
	ds_read_b128 v[172:175], v230 offset:2048
	ds_read_b128 v[176:179], v230 offset:3072
	ds_read_b128 v[180:183], v231
	ds_read_b128 v[184:187], v231 offset:1024
	ds_read_b128 v[188:191], v231 offset:2048
	ds_read_b128 v[192:195], v231 offset:3072
	ds_read_b128 v[196:199], v160
	ds_read_b128 v[200:203], v160 offset:1024
	ds_read_b128 v[204:207], v160 offset:2048
	ds_read_b128 v[208:211], v160 offset:3072
	ds_read_b128 v[212:215], v160 offset:4096
	ds_read_b128 v[216:219], v160 offset:5120
	ds_read_b128 v[220:223], v160 offset:6144
	ds_read_b128 v[224:227], v160 offset:7168
	s_waitcnt vmcnt(8)
	s_waitcnt lgkmcnt(0)
	s_setprio 1
	s_barrier
	v_mfma_f32_16x16x32_bf16 v[122:125], v[164:167], v[196:199], 0
	v_mfma_f32_16x16x32_bf16 v[118:121], v[172:175], v[196:199], 0
	v_mfma_f32_16x16x32_bf16 v[110:113], v[164:167], v[204:207], 0
	v_mfma_f32_16x16x32_bf16 v[102:105], v[172:175], v[204:207], 0
	v_mfma_f32_16x16x32_bf16 v[94:97], v[164:167], v[212:215], 0
	v_mfma_f32_16x16x32_bf16 v[86:89], v[172:175], v[212:215], 0
	v_mfma_f32_16x16x32_bf16 v[78:81], v[164:167], v[220:223], 0
	v_mfma_f32_16x16x32_bf16 v[70:73], v[172:175], v[220:223], 0
	v_mfma_f32_16x16x32_bf16 v[122:125], v[168:171], v[200:203], v[122:125]
	v_mfma_f32_16x16x32_bf16 v[118:121], v[176:179], v[200:203], v[118:121]
	v_mfma_f32_16x16x32_bf16 v[110:113], v[168:171], v[208:211], v[110:113]
	v_mfma_f32_16x16x32_bf16 v[102:105], v[176:179], v[208:211], v[102:105]
	v_mfma_f32_16x16x32_bf16 v[94:97], v[168:171], v[216:219], v[94:97]
	v_mfma_f32_16x16x32_bf16 v[86:89], v[176:179], v[216:219], v[86:89]
	v_mfma_f32_16x16x32_bf16 v[78:81], v[168:171], v[224:227], v[78:81]
	v_mfma_f32_16x16x32_bf16 v[70:73], v[176:179], v[224:227], v[70:73]
	s_setprio 0
	s_setprio 1
	v_mfma_f32_16x16x32_bf16 v[126:129], v[180:183], v[196:199], 0
	v_mfma_f32_16x16x32_bf16 v[114:117], v[188:191], v[196:199], 0
	v_mfma_f32_16x16x32_bf16 v[106:109], v[180:183], v[204:207], 0
	v_mfma_f32_16x16x32_bf16 v[98:101], v[188:191], v[204:207], 0
	v_mfma_f32_16x16x32_bf16 v[90:93], v[180:183], v[212:215], 0
	v_mfma_f32_16x16x32_bf16 v[82:85], v[188:191], v[212:215], 0
	v_mfma_f32_16x16x32_bf16 v[74:77], v[180:183], v[220:223], 0
	v_mfma_f32_16x16x32_bf16 v[66:69], v[188:191], v[220:223], 0
	v_mfma_f32_16x16x32_bf16 v[126:129], v[184:187], v[200:203], v[126:129]
	v_mfma_f32_16x16x32_bf16 v[114:117], v[192:195], v[200:203], v[114:117]
	v_mfma_f32_16x16x32_bf16 v[106:109], v[184:187], v[208:211], v[106:109]
	v_mfma_f32_16x16x32_bf16 v[98:101], v[192:195], v[208:211], v[98:101]
	v_mfma_f32_16x16x32_bf16 v[90:93], v[184:187], v[216:219], v[90:93]
	v_mfma_f32_16x16x32_bf16 v[82:85], v[192:195], v[216:219], v[82:85]
	v_mfma_f32_16x16x32_bf16 v[74:77], v[184:187], v[224:227], v[74:77]
	v_mfma_f32_16x16x32_bf16 v[66:69], v[192:195], v[224:227], v[66:69]
	s_barrier
	s_setprio 0
	s_add_u32 s98, s96, 0x40000
	s_addc_u32 s99, s97, 0
	s_add_i32 s7, s76, s25
	s_mov_b32 m0, s7
	s_nop 0
	global_load_lds_dwordx4 v132, s[96:97]
	s_add_i32 m0, s7, 0x2000
	s_add_i32 s7, s77, s25
	global_load_lds_dwordx4 v136, s[96:97]
	s_mov_b32 m0, s7
	s_nop 0
	global_load_lds_dwordx4 v132, s[98:99]
	s_add_i32 m0, s7, 0x2000
	s_nop 0
	global_load_lds_dwordx4 v136, s[98:99]
	s_mov_b32 m0, s49
	s_nop 0
	global_load_lds_dwordx4 v130, s[94:95]
	s_mov_b32 m0, s58
	s_nop 0
	global_load_lds_dwordx4 v134, s[94:95]
	ds_read_b128 v[196:199], v160 offset:16384
	ds_read_b128 v[200:203], v160 offset:17408
	ds_read_b128 v[204:207], v160 offset:18432
	ds_read_b128 v[208:211], v160 offset:19456
	ds_read_b128 v[212:215], v160 offset:20480
	ds_read_b128 v[216:219], v160 offset:21504
	ds_read_b128 v[220:223], v160 offset:22528
	ds_read_b128 v[224:227], v160 offset:23552
	s_waitcnt vmcnt(8)
	s_waitcnt lgkmcnt(0)
	s_setprio 1
	s_barrier
	v_mfma_f32_16x16x32_bf16 v[62:65], v[164:167], v[196:199], 0
	v_mfma_f32_16x16x32_bf16 v[54:57], v[172:175], v[196:199], 0
	v_mfma_f32_16x16x32_bf16 v[46:49], v[164:167], v[204:207], 0
	v_mfma_f32_16x16x32_bf16 v[38:41], v[172:175], v[204:207], 0
	v_mfma_f32_16x16x32_bf16 v[30:33], v[164:167], v[212:215], 0
	v_mfma_f32_16x16x32_bf16 v[22:25], v[172:175], v[212:215], 0
	v_mfma_f32_16x16x32_bf16 v[14:17], v[164:167], v[220:223], 0
	v_mfma_f32_16x16x32_bf16 v[6:9], v[172:175], v[220:223], 0
	v_mfma_f32_16x16x32_bf16 v[62:65], v[168:171], v[200:203], v[62:65]
	v_mfma_f32_16x16x32_bf16 v[54:57], v[176:179], v[200:203], v[54:57]
	v_mfma_f32_16x16x32_bf16 v[46:49], v[168:171], v[208:211], v[46:49]
	v_mfma_f32_16x16x32_bf16 v[38:41], v[176:179], v[208:211], v[38:41]
	v_mfma_f32_16x16x32_bf16 v[30:33], v[168:171], v[216:219], v[30:33]
	v_mfma_f32_16x16x32_bf16 v[22:25], v[176:179], v[216:219], v[22:25]
	v_mfma_f32_16x16x32_bf16 v[14:17], v[168:171], v[224:227], v[14:17]
	v_mfma_f32_16x16x32_bf16 v[6:9], v[176:179], v[224:227], v[6:9]
	s_setprio 0
	s_setprio 1
	v_mfma_f32_16x16x32_bf16 v[58:61], v[180:183], v[196:199], 0
	v_mfma_f32_16x16x32_bf16 v[50:53], v[188:191], v[196:199], 0
	v_mfma_f32_16x16x32_bf16 v[42:45], v[180:183], v[204:207], 0
	v_mfma_f32_16x16x32_bf16 v[34:37], v[188:191], v[204:207], 0
	v_mfma_f32_16x16x32_bf16 v[26:29], v[180:183], v[212:215], 0
	v_mfma_f32_16x16x32_bf16 v[18:21], v[188:191], v[212:215], 0
	v_mfma_f32_16x16x32_bf16 v[10:13], v[180:183], v[220:223], 0
	v_mfma_f32_16x16x32_bf16 v[2:5], v[188:191], v[220:223], 0
	v_mfma_f32_16x16x32_bf16 v[58:61], v[184:187], v[200:203], v[58:61]
	v_mfma_f32_16x16x32_bf16 v[50:53], v[192:195], v[200:203], v[50:53]
	v_mfma_f32_16x16x32_bf16 v[42:45], v[184:187], v[208:211], v[42:45]
	v_mfma_f32_16x16x32_bf16 v[34:37], v[192:195], v[208:211], v[34:37]
	v_mfma_f32_16x16x32_bf16 v[26:29], v[184:187], v[216:219], v[26:29]
	v_mfma_f32_16x16x32_bf16 v[18:21], v[192:195], v[216:219], v[18:21]
	v_mfma_f32_16x16x32_bf16 v[10:13], v[184:187], v[224:227], v[10:13]
	v_mfma_f32_16x16x32_bf16 v[2:5], v[192:195], v[224:227], v[2:5]
	s_barrier
	s_setprio 0
	s_add_u32 s98, s94, 0x40000
	s_addc_u32 s99, s95, 0
	s_add_i32 s7, 0, 0x18000
	s_add_i32 s47, 0, 0x1c000
	s_mov_b32 m0, s59
	s_nop 0
	global_load_lds_dwordx4 v130, s[98:99]
	s_mov_b32 m0, s60
	s_nop 0
	global_load_lds_dwordx4 v134, s[98:99]
	ds_read_b128 v[164:167], v232
	ds_read_b128 v[168:171], v232 offset:1024
	ds_read_b128 v[172:175], v232 offset:2048
	ds_read_b128 v[176:179], v232 offset:3072
	ds_read_b128 v[180:183], v233
	ds_read_b128 v[184:187], v233 offset:1024
	ds_read_b128 v[188:191], v233 offset:2048
	ds_read_b128 v[192:195], v233 offset:3072
	ds_read_b128 v[196:199], v160 offset:32768
	ds_read_b128 v[200:203], v160 offset:33792
	ds_read_b128 v[204:207], v160 offset:34816
	ds_read_b128 v[208:211], v160 offset:35840
	ds_read_b128 v[212:215], v160 offset:36864
	ds_read_b128 v[216:219], v160 offset:37888
	ds_read_b128 v[220:223], v160 offset:38912
	ds_read_b128 v[224:227], v160 offset:39936
	s_waitcnt vmcnt(8)
	s_waitcnt lgkmcnt(0)
	s_setprio 1
	s_barrier
	v_mfma_f32_16x16x32_bf16 v[122:125], v[164:167], v[196:199], v[122:125]
	v_mfma_f32_16x16x32_bf16 v[118:121], v[172:175], v[196:199], v[118:121]
	v_mfma_f32_16x16x32_bf16 v[110:113], v[164:167], v[204:207], v[110:113]
	v_mfma_f32_16x16x32_bf16 v[102:105], v[172:175], v[204:207], v[102:105]
	v_mfma_f32_16x16x32_bf16 v[94:97], v[164:167], v[212:215], v[94:97]
	v_mfma_f32_16x16x32_bf16 v[86:89], v[172:175], v[212:215], v[86:89]
	v_mfma_f32_16x16x32_bf16 v[78:81], v[164:167], v[220:223], v[78:81]
	v_mfma_f32_16x16x32_bf16 v[70:73], v[172:175], v[220:223], v[70:73]
	v_mfma_f32_16x16x32_bf16 v[122:125], v[168:171], v[200:203], v[122:125]
	v_mfma_f32_16x16x32_bf16 v[118:121], v[176:179], v[200:203], v[118:121]
	v_mfma_f32_16x16x32_bf16 v[110:113], v[168:171], v[208:211], v[110:113]
	v_mfma_f32_16x16x32_bf16 v[102:105], v[176:179], v[208:211], v[102:105]
	v_mfma_f32_16x16x32_bf16 v[94:97], v[168:171], v[216:219], v[94:97]
	v_mfma_f32_16x16x32_bf16 v[86:89], v[176:179], v[216:219], v[86:89]
	v_mfma_f32_16x16x32_bf16 v[78:81], v[168:171], v[224:227], v[78:81]
	v_mfma_f32_16x16x32_bf16 v[70:73], v[176:179], v[224:227], v[70:73]
	s_setprio 0
	s_setprio 1
	v_mfma_f32_16x16x32_bf16 v[126:129], v[180:183], v[196:199], v[126:129]
	v_mfma_f32_16x16x32_bf16 v[114:117], v[188:191], v[196:199], v[114:117]
	v_mfma_f32_16x16x32_bf16 v[106:109], v[180:183], v[204:207], v[106:109]
	v_mfma_f32_16x16x32_bf16 v[98:101], v[188:191], v[204:207], v[98:101]
	v_mfma_f32_16x16x32_bf16 v[90:93], v[180:183], v[212:215], v[90:93]
	v_mfma_f32_16x16x32_bf16 v[82:85], v[188:191], v[212:215], v[82:85]
	v_mfma_f32_16x16x32_bf16 v[74:77], v[180:183], v[220:223], v[74:77]
	v_mfma_f32_16x16x32_bf16 v[66:69], v[188:191], v[220:223], v[66:69]
	v_mfma_f32_16x16x32_bf16 v[126:129], v[184:187], v[200:203], v[126:129]
	v_mfma_f32_16x16x32_bf16 v[114:117], v[192:195], v[200:203], v[114:117]
	v_mfma_f32_16x16x32_bf16 v[106:109], v[184:187], v[208:211], v[106:109]
	v_mfma_f32_16x16x32_bf16 v[98:101], v[192:195], v[208:211], v[98:101]
	v_mfma_f32_16x16x32_bf16 v[90:93], v[184:187], v[216:219], v[90:93]
	v_mfma_f32_16x16x32_bf16 v[82:85], v[192:195], v[216:219], v[82:85]
	v_mfma_f32_16x16x32_bf16 v[74:77], v[184:187], v[224:227], v[74:77]
	v_mfma_f32_16x16x32_bf16 v[66:69], v[192:195], v[224:227], v[66:69]
	s_barrier
	s_setprio 0
	s_add_u32 s96, s96, 0x80
	s_addc_u32 s97, s97, 0
	s_add_u32 s98, s96, 0x40000
	s_addc_u32 s99, s97, 0
	s_add_u32 s94, s94, 0x80
	s_addc_u32 s95, s95, 0
	s_add_i32 s7, s7, s25
	s_mov_b32 m0, s7
	s_nop 0
	global_load_lds_dwordx4 v132, s[96:97]
	s_add_i32 m0, s7, 0x2000
	s_add_i32 s7, s47, s25
	global_load_lds_dwordx4 v136, s[96:97]
	s_mov_b32 m0, s7
	s_nop 0
	global_load_lds_dwordx4 v132, s[98:99]
	s_add_i32 m0, s7, 0x2000
	s_nop 0
	global_load_lds_dwordx4 v136, s[98:99]
	s_mov_b32 m0, s66
	s_nop 0
	global_load_lds_dwordx4 v130, s[94:95]
	s_mov_b32 m0, s67
	s_nop 0
	global_load_lds_dwordx4 v134, s[94:95]
	ds_read_b128 v[196:199], v160 offset:49152
	ds_read_b128 v[200:203], v160 offset:50176
	ds_read_b128 v[204:207], v160 offset:51200
	ds_read_b128 v[208:211], v160 offset:52224
	ds_read_b128 v[212:215], v160 offset:53248
	ds_read_b128 v[216:219], v160 offset:54272
	ds_read_b128 v[220:223], v160 offset:55296
	ds_read_b128 v[224:227], v160 offset:56320
	s_waitcnt vmcnt(8)
	s_waitcnt lgkmcnt(0)
	s_setprio 1
	s_barrier
	v_mfma_f32_16x16x32_bf16 v[62:65], v[164:167], v[196:199], v[62:65]
	v_mfma_f32_16x16x32_bf16 v[54:57], v[172:175], v[196:199], v[54:57]
	v_mfma_f32_16x16x32_bf16 v[46:49], v[164:167], v[204:207], v[46:49]
	v_mfma_f32_16x16x32_bf16 v[38:41], v[172:175], v[204:207], v[38:41]
	v_mfma_f32_16x16x32_bf16 v[30:33], v[164:167], v[212:215], v[30:33]
	v_mfma_f32_16x16x32_bf16 v[22:25], v[172:175], v[212:215], v[22:25]
	v_mfma_f32_16x16x32_bf16 v[14:17], v[164:167], v[220:223], v[14:17]
	v_mfma_f32_16x16x32_bf16 v[6:9], v[172:175], v[220:223], v[6:9]
	v_mfma_f32_16x16x32_bf16 v[62:65], v[168:171], v[200:203], v[62:65]
	v_mfma_f32_16x16x32_bf16 v[54:57], v[176:179], v[200:203], v[54:57]
	v_mfma_f32_16x16x32_bf16 v[46:49], v[168:171], v[208:211], v[46:49]
	v_mfma_f32_16x16x32_bf16 v[38:41], v[176:179], v[208:211], v[38:41]
	v_mfma_f32_16x16x32_bf16 v[30:33], v[168:171], v[216:219], v[30:33]
	v_mfma_f32_16x16x32_bf16 v[22:25], v[176:179], v[216:219], v[22:25]
	v_mfma_f32_16x16x32_bf16 v[14:17], v[168:171], v[224:227], v[14:17]
	v_mfma_f32_16x16x32_bf16 v[6:9], v[176:179], v[224:227], v[6:9]
	s_setprio 0
	s_setprio 1
	v_mfma_f32_16x16x32_bf16 v[58:61], v[180:183], v[196:199], v[58:61]
	v_mfma_f32_16x16x32_bf16 v[50:53], v[188:191], v[196:199], v[50:53]
	v_mfma_f32_16x16x32_bf16 v[42:45], v[180:183], v[204:207], v[42:45]
	v_mfma_f32_16x16x32_bf16 v[34:37], v[188:191], v[204:207], v[34:37]
	v_mfma_f32_16x16x32_bf16 v[26:29], v[180:183], v[212:215], v[26:29]
	v_mfma_f32_16x16x32_bf16 v[18:21], v[188:191], v[212:215], v[18:21]
	v_mfma_f32_16x16x32_bf16 v[10:13], v[180:183], v[220:223], v[10:13]
	v_mfma_f32_16x16x32_bf16 v[2:5], v[188:191], v[220:223], v[2:5]
	v_mfma_f32_16x16x32_bf16 v[58:61], v[184:187], v[200:203], v[58:61]
	v_mfma_f32_16x16x32_bf16 v[50:53], v[192:195], v[200:203], v[50:53]
	v_mfma_f32_16x16x32_bf16 v[42:45], v[184:187], v[208:211], v[42:45]
	v_mfma_f32_16x16x32_bf16 v[34:37], v[192:195], v[208:211], v[34:37]
	v_mfma_f32_16x16x32_bf16 v[26:29], v[184:187], v[216:219], v[26:29]
	v_mfma_f32_16x16x32_bf16 v[18:21], v[192:195], v[216:219], v[18:21]
	v_mfma_f32_16x16x32_bf16 v[10:13], v[184:187], v[224:227], v[10:13]
	v_mfma_f32_16x16x32_bf16 v[2:5], v[192:195], v[224:227], v[2:5]
	s_barrier
	s_setprio 0
	s_mov_b32 s7, s45
	s_add_u32 s88, s88, 0x100
	s_addc_u32 s89, s89, 0
	s_add_u32 s86, s86, 0x100
	s_addc_u32 s87, s87, 0
	s_cmp_ge_i32 s45, s101
	s_cbranch_scc1 .Lmy_kexit_3
.LBB0_768:
	s_add_u32 s98, s86, 0xfffc0080
	s_addc_u32 s99, s87, -1
	s_cmp_eq_u32 s7, s100
	s_cselect_b64 s[94:95], s[90:91], s[98:99]
	s_cselect_b64 s[96:97], s[92:93], s[88:89]
	s_add_i32 s45, s7, 2
	s_nop 0
	s_add_i32 m0, s49, 0xc000
	s_nop 0
	global_load_lds_dwordx4 v144, s[86:87]
	s_add_i32 m0, s49, 0xe000
	s_nop 0
	global_load_lds_dwordx4 v142, s[86:87]
	ds_read_b128 v[164:167], v230
	ds_read_b128 v[168:171], v230 offset:1024
	ds_read_b128 v[172:175], v230 offset:2048
	ds_read_b128 v[176:179], v230 offset:3072
	ds_read_b128 v[180:183], v231
	ds_read_b128 v[184:187], v231 offset:1024
	ds_read_b128 v[188:191], v231 offset:2048
	ds_read_b128 v[192:195], v231 offset:3072
	ds_read_b128 v[196:199], v160
	ds_read_b128 v[200:203], v160 offset:1024
	ds_read_b128 v[204:207], v160 offset:2048
	ds_read_b128 v[208:211], v160 offset:3072
	ds_read_b128 v[212:215], v160 offset:4096
	ds_read_b128 v[216:219], v160 offset:5120
	ds_read_b128 v[220:223], v160 offset:6144
	ds_read_b128 v[224:227], v160 offset:7168
	s_waitcnt vmcnt(8)
	s_waitcnt lgkmcnt(0)
	s_setprio 1
	s_barrier
	v_mfma_f32_16x16x32_bf16 v[122:125], v[164:167], v[196:199], v[122:125]
	v_mfma_f32_16x16x32_bf16 v[118:121], v[172:175], v[196:199], v[118:121]
	v_mfma_f32_16x16x32_bf16 v[110:113], v[164:167], v[204:207], v[110:113]
	v_mfma_f32_16x16x32_bf16 v[102:105], v[172:175], v[204:207], v[102:105]
	v_mfma_f32_16x16x32_bf16 v[94:97], v[164:167], v[212:215], v[94:97]
	v_mfma_f32_16x16x32_bf16 v[86:89], v[172:175], v[212:215], v[86:89]
	v_mfma_f32_16x16x32_bf16 v[78:81], v[164:167], v[220:223], v[78:81]
	v_mfma_f32_16x16x32_bf16 v[70:73], v[172:175], v[220:223], v[70:73]
	v_mfma_f32_16x16x32_bf16 v[122:125], v[168:171], v[200:203], v[122:125]
	v_mfma_f32_16x16x32_bf16 v[118:121], v[176:179], v[200:203], v[118:121]
	v_mfma_f32_16x16x32_bf16 v[110:113], v[168:171], v[208:211], v[110:113]
	v_mfma_f32_16x16x32_bf16 v[102:105], v[176:179], v[208:211], v[102:105]
	v_mfma_f32_16x16x32_bf16 v[94:97], v[168:171], v[216:219], v[94:97]
	v_mfma_f32_16x16x32_bf16 v[86:89], v[176:179], v[216:219], v[86:89]
	v_mfma_f32_16x16x32_bf16 v[78:81], v[168:171], v[224:227], v[78:81]
	v_mfma_f32_16x16x32_bf16 v[70:73], v[176:179], v[224:227], v[70:73]
	s_setprio 0
	s_setprio 1
	v_mfma_f32_16x16x32_bf16 v[126:129], v[180:183], v[196:199], v[126:129]
	v_mfma_f32_16x16x32_bf16 v[114:117], v[188:191], v[196:199], v[114:117]
	v_mfma_f32_16x16x32_bf16 v[106:109], v[180:183], v[204:207], v[106:109]
	v_mfma_f32_16x16x32_bf16 v[98:101], v[188:191], v[204:207], v[98:101]
	v_mfma_f32_16x16x32_bf16 v[90:93], v[180:183], v[212:215], v[90:93]
	v_mfma_f32_16x16x32_bf16 v[82:85], v[188:191], v[212:215], v[82:85]
	v_mfma_f32_16x16x32_bf16 v[74:77], v[180:183], v[220:223], v[74:77]
	v_mfma_f32_16x16x32_bf16 v[66:69], v[188:191], v[220:223], v[66:69]
	v_mfma_f32_16x16x32_bf16 v[126:129], v[184:187], v[200:203], v[126:129]
	v_mfma_f32_16x16x32_bf16 v[114:117], v[192:195], v[200:203], v[114:117]
	v_mfma_f32_16x16x32_bf16 v[106:109], v[184:187], v[208:211], v[106:109]
	v_mfma_f32_16x16x32_bf16 v[98:101], v[192:195], v[208:211], v[98:101]
	v_mfma_f32_16x16x32_bf16 v[90:93], v[184:187], v[216:219], v[90:93]
	v_mfma_f32_16x16x32_bf16 v[82:85], v[192:195], v[216:219], v[82:85]
	v_mfma_f32_16x16x32_bf16 v[74:77], v[184:187], v[224:227], v[74:77]
	v_mfma_f32_16x16x32_bf16 v[66:69], v[192:195], v[224:227], v[66:69]
	s_barrier
	s_setprio 0
	s_add_u32 s98, s96, 0x40000
	s_addc_u32 s99, s97, 0
	s_add_i32 s7, s76, s25
	s_mov_b32 m0, s7
	s_nop 0
	global_load_lds_dwordx4 v132, s[96:97]
	s_add_i32 m0, s7, 0x2000
	s_add_i32 s7, s77, s25
	global_load_lds_dwordx4 v136, s[96:97]
	s_mov_b32 m0, s7
	s_nop 0
	global_load_lds_dwordx4 v132, s[98:99]
	s_add_i32 m0, s7, 0x2000
	s_nop 0
	global_load_lds_dwordx4 v136, s[98:99]
	s_mov_b32 m0, s49
	s_nop 0
	global_load_lds_dwordx4 v130, s[94:95]
	s_mov_b32 m0, s58
	s_nop 0
	global_load_lds_dwordx4 v134, s[94:95]
	ds_read_b128 v[196:199], v160 offset:16384
	ds_read_b128 v[200:203], v160 offset:17408
	ds_read_b128 v[204:207], v160 offset:18432
	ds_read_b128 v[208:211], v160 offset:19456
	ds_read_b128 v[212:215], v160 offset:20480
	ds_read_b128 v[216:219], v160 offset:21504
	ds_read_b128 v[220:223], v160 offset:22528
	ds_read_b128 v[224:227], v160 offset:23552
	s_waitcnt vmcnt(8)
	s_waitcnt lgkmcnt(0)
	s_setprio 1
	s_barrier
	v_mfma_f32_16x16x32_bf16 v[62:65], v[164:167], v[196:199], v[62:65]
	v_mfma_f32_16x16x32_bf16 v[54:57], v[172:175], v[196:199], v[54:57]
	v_mfma_f32_16x16x32_bf16 v[46:49], v[164:167], v[204:207], v[46:49]
	v_mfma_f32_16x16x32_bf16 v[38:41], v[172:175], v[204:207], v[38:41]
	v_mfma_f32_16x16x32_bf16 v[30:33], v[164:167], v[212:215], v[30:33]
	v_mfma_f32_16x16x32_bf16 v[22:25], v[172:175], v[212:215], v[22:25]
	v_mfma_f32_16x16x32_bf16 v[14:17], v[164:167], v[220:223], v[14:17]
	v_mfma_f32_16x16x32_bf16 v[6:9], v[172:175], v[220:223], v[6:9]
	v_mfma_f32_16x16x32_bf16 v[62:65], v[168:171], v[200:203], v[62:65]
	v_mfma_f32_16x16x32_bf16 v[54:57], v[176:179], v[200:203], v[54:57]
	v_mfma_f32_16x16x32_bf16 v[46:49], v[168:171], v[208:211], v[46:49]
	v_mfma_f32_16x16x32_bf16 v[38:41], v[176:179], v[208:211], v[38:41]
	v_mfma_f32_16x16x32_bf16 v[30:33], v[168:171], v[216:219], v[30:33]
	v_mfma_f32_16x16x32_bf16 v[22:25], v[176:179], v[216:219], v[22:25]
	v_mfma_f32_16x16x32_bf16 v[14:17], v[168:171], v[224:227], v[14:17]
	v_mfma_f32_16x16x32_bf16 v[6:9], v[176:179], v[224:227], v[6:9]
	s_setprio 0
	s_setprio 1
	v_mfma_f32_16x16x32_bf16 v[58:61], v[180:183], v[196:199], v[58:61]
	v_mfma_f32_16x16x32_bf16 v[50:53], v[188:191], v[196:199], v[50:53]
	v_mfma_f32_16x16x32_bf16 v[42:45], v[180:183], v[204:207], v[42:45]
	v_mfma_f32_16x16x32_bf16 v[34:37], v[188:191], v[204:207], v[34:37]
	v_mfma_f32_16x16x32_bf16 v[26:29], v[180:183], v[212:215], v[26:29]
	v_mfma_f32_16x16x32_bf16 v[18:21], v[188:191], v[212:215], v[18:21]
	v_mfma_f32_16x16x32_bf16 v[10:13], v[180:183], v[220:223], v[10:13]
	v_mfma_f32_16x16x32_bf16 v[2:5], v[188:191], v[220:223], v[2:5]
	v_mfma_f32_16x16x32_bf16 v[58:61], v[184:187], v[200:203], v[58:61]
	v_mfma_f32_16x16x32_bf16 v[50:53], v[192:195], v[200:203], v[50:53]
	v_mfma_f32_16x16x32_bf16 v[42:45], v[184:187], v[208:211], v[42:45]
	v_mfma_f32_16x16x32_bf16 v[34:37], v[192:195], v[208:211], v[34:37]
	v_mfma_f32_16x16x32_bf16 v[26:29], v[184:187], v[216:219], v[26:29]
	v_mfma_f32_16x16x32_bf16 v[18:21], v[192:195], v[216:219], v[18:21]
	v_mfma_f32_16x16x32_bf16 v[10:13], v[184:187], v[224:227], v[10:13]
	v_mfma_f32_16x16x32_bf16 v[2:5], v[192:195], v[224:227], v[2:5]
	s_barrier
	s_setprio 0
	s_add_u32 s98, s94, 0x40000
	s_addc_u32 s99, s95, 0
	s_add_i32 s7, 0, 0x18000
	s_add_i32 s47, 0, 0x1c000
	s_mov_b32 m0, s59
	s_nop 0
	global_load_lds_dwordx4 v130, s[98:99]
	s_mov_b32 m0, s60
	s_nop 0
	global_load_lds_dwordx4 v134, s[98:99]
	ds_read_b128 v[164:167], v232
	ds_read_b128 v[168:171], v232 offset:1024
	ds_read_b128 v[172:175], v232 offset:2048
	ds_read_b128 v[176:179], v232 offset:3072
	ds_read_b128 v[180:183], v233
	ds_read_b128 v[184:187], v233 offset:1024
	ds_read_b128 v[188:191], v233 offset:2048
	ds_read_b128 v[192:195], v233 offset:3072
	ds_read_b128 v[196:199], v160 offset:32768
	ds_read_b128 v[200:203], v160 offset:33792
	ds_read_b128 v[204:207], v160 offset:34816
	ds_read_b128 v[208:211], v160 offset:35840
	ds_read_b128 v[212:215], v160 offset:36864
	ds_read_b128 v[216:219], v160 offset:37888
	ds_read_b128 v[220:223], v160 offset:38912
	ds_read_b128 v[224:227], v160 offset:39936
	s_waitcnt vmcnt(8)
	s_waitcnt lgkmcnt(0)
	s_setprio 1
	s_barrier
	v_mfma_f32_16x16x32_bf16 v[122:125], v[164:167], v[196:199], v[122:125]
	v_mfma_f32_16x16x32_bf16 v[118:121], v[172:175], v[196:199], v[118:121]
	v_mfma_f32_16x16x32_bf16 v[110:113], v[164:167], v[204:207], v[110:113]
	v_mfma_f32_16x16x32_bf16 v[102:105], v[172:175], v[204:207], v[102:105]
	v_mfma_f32_16x16x32_bf16 v[94:97], v[164:167], v[212:215], v[94:97]
	v_mfma_f32_16x16x32_bf16 v[86:89], v[172:175], v[212:215], v[86:89]
	v_mfma_f32_16x16x32_bf16 v[78:81], v[164:167], v[220:223], v[78:81]
	v_mfma_f32_16x16x32_bf16 v[70:73], v[172:175], v[220:223], v[70:73]
	v_mfma_f32_16x16x32_bf16 v[122:125], v[168:171], v[200:203], v[122:125]
	v_mfma_f32_16x16x32_bf16 v[118:121], v[176:179], v[200:203], v[118:121]
	v_mfma_f32_16x16x32_bf16 v[110:113], v[168:171], v[208:211], v[110:113]
	v_mfma_f32_16x16x32_bf16 v[102:105], v[176:179], v[208:211], v[102:105]
	v_mfma_f32_16x16x32_bf16 v[94:97], v[168:171], v[216:219], v[94:97]
	v_mfma_f32_16x16x32_bf16 v[86:89], v[176:179], v[216:219], v[86:89]
	v_mfma_f32_16x16x32_bf16 v[78:81], v[168:171], v[224:227], v[78:81]
	v_mfma_f32_16x16x32_bf16 v[70:73], v[176:179], v[224:227], v[70:73]
	s_setprio 0
	s_setprio 1
	v_mfma_f32_16x16x32_bf16 v[126:129], v[180:183], v[196:199], v[126:129]
	v_mfma_f32_16x16x32_bf16 v[114:117], v[188:191], v[196:199], v[114:117]
	v_mfma_f32_16x16x32_bf16 v[106:109], v[180:183], v[204:207], v[106:109]
	v_mfma_f32_16x16x32_bf16 v[98:101], v[188:191], v[204:207], v[98:101]
	v_mfma_f32_16x16x32_bf16 v[90:93], v[180:183], v[212:215], v[90:93]
	v_mfma_f32_16x16x32_bf16 v[82:85], v[188:191], v[212:215], v[82:85]
	v_mfma_f32_16x16x32_bf16 v[74:77], v[180:183], v[220:223], v[74:77]
	v_mfma_f32_16x16x32_bf16 v[66:69], v[188:191], v[220:223], v[66:69]
	v_mfma_f32_16x16x32_bf16 v[126:129], v[184:187], v[200:203], v[126:129]
	v_mfma_f32_16x16x32_bf16 v[114:117], v[192:195], v[200:203], v[114:117]
	v_mfma_f32_16x16x32_bf16 v[106:109], v[184:187], v[208:211], v[106:109]
	v_mfma_f32_16x16x32_bf16 v[98:101], v[192:195], v[208:211], v[98:101]
	v_mfma_f32_16x16x32_bf16 v[90:93], v[184:187], v[216:219], v[90:93]
	v_mfma_f32_16x16x32_bf16 v[82:85], v[192:195], v[216:219], v[82:85]
	v_mfma_f32_16x16x32_bf16 v[74:77], v[184:187], v[224:227], v[74:77]
	v_mfma_f32_16x16x32_bf16 v[66:69], v[192:195], v[224:227], v[66:69]
	s_barrier
	s_setprio 0
	s_add_u32 s96, s96, 0x80
	s_addc_u32 s97, s97, 0
	s_add_u32 s98, s96, 0x40000
	s_addc_u32 s99, s97, 0
	s_add_u32 s94, s94, 0x80
	s_addc_u32 s95, s95, 0
	s_add_i32 s7, s7, s25
	s_mov_b32 m0, s7
	s_nop 0
	global_load_lds_dwordx4 v132, s[96:97]
	s_add_i32 m0, s7, 0x2000
	s_add_i32 s7, s47, s25
	global_load_lds_dwordx4 v136, s[96:97]
	s_mov_b32 m0, s7
	s_nop 0
	global_load_lds_dwordx4 v132, s[98:99]
	s_add_i32 m0, s7, 0x2000
	s_nop 0
	global_load_lds_dwordx4 v136, s[98:99]
	s_mov_b32 m0, s66
	s_nop 0
	global_load_lds_dwordx4 v130, s[94:95]
	s_mov_b32 m0, s67
	s_nop 0
	global_load_lds_dwordx4 v134, s[94:95]
	ds_read_b128 v[196:199], v160 offset:49152
	ds_read_b128 v[200:203], v160 offset:50176
	ds_read_b128 v[204:207], v160 offset:51200
	ds_read_b128 v[208:211], v160 offset:52224
	ds_read_b128 v[212:215], v160 offset:53248
	ds_read_b128 v[216:219], v160 offset:54272
	ds_read_b128 v[220:223], v160 offset:55296
	ds_read_b128 v[224:227], v160 offset:56320
	s_waitcnt vmcnt(8)
	s_waitcnt lgkmcnt(0)
	s_setprio 1
	s_barrier
	v_mfma_f32_16x16x32_bf16 v[62:65], v[164:167], v[196:199], v[62:65]
	v_mfma_f32_16x16x32_bf16 v[54:57], v[172:175], v[196:199], v[54:57]
	v_mfma_f32_16x16x32_bf16 v[46:49], v[164:167], v[204:207], v[46:49]
	v_mfma_f32_16x16x32_bf16 v[38:41], v[172:175], v[204:207], v[38:41]
	v_mfma_f32_16x16x32_bf16 v[30:33], v[164:167], v[212:215], v[30:33]
	v_mfma_f32_16x16x32_bf16 v[22:25], v[172:175], v[212:215], v[22:25]
	v_mfma_f32_16x16x32_bf16 v[14:17], v[164:167], v[220:223], v[14:17]
	v_mfma_f32_16x16x32_bf16 v[6:9], v[172:175], v[220:223], v[6:9]
	v_mfma_f32_16x16x32_bf16 v[62:65], v[168:171], v[200:203], v[62:65]
	v_mfma_f32_16x16x32_bf16 v[54:57], v[176:179], v[200:203], v[54:57]
	v_mfma_f32_16x16x32_bf16 v[46:49], v[168:171], v[208:211], v[46:49]
	v_mfma_f32_16x16x32_bf16 v[38:41], v[176:179], v[208:211], v[38:41]
	v_mfma_f32_16x16x32_bf16 v[30:33], v[168:171], v[216:219], v[30:33]
	v_mfma_f32_16x16x32_bf16 v[22:25], v[176:179], v[216:219], v[22:25]
	v_mfma_f32_16x16x32_bf16 v[14:17], v[168:171], v[224:227], v[14:17]
	v_mfma_f32_16x16x32_bf16 v[6:9], v[176:179], v[224:227], v[6:9]
	s_setprio 0
	s_setprio 1
	v_mfma_f32_16x16x32_bf16 v[58:61], v[180:183], v[196:199], v[58:61]
	v_mfma_f32_16x16x32_bf16 v[50:53], v[188:191], v[196:199], v[50:53]
	v_mfma_f32_16x16x32_bf16 v[42:45], v[180:183], v[204:207], v[42:45]
	v_mfma_f32_16x16x32_bf16 v[34:37], v[188:191], v[204:207], v[34:37]
	v_mfma_f32_16x16x32_bf16 v[26:29], v[180:183], v[212:215], v[26:29]
	v_mfma_f32_16x16x32_bf16 v[18:21], v[188:191], v[212:215], v[18:21]
	v_mfma_f32_16x16x32_bf16 v[10:13], v[180:183], v[220:223], v[10:13]
	v_mfma_f32_16x16x32_bf16 v[2:5], v[188:191], v[220:223], v[2:5]
	v_mfma_f32_16x16x32_bf16 v[58:61], v[184:187], v[200:203], v[58:61]
	v_mfma_f32_16x16x32_bf16 v[50:53], v[192:195], v[200:203], v[50:53]
	v_mfma_f32_16x16x32_bf16 v[42:45], v[184:187], v[208:211], v[42:45]
	v_mfma_f32_16x16x32_bf16 v[34:37], v[192:195], v[208:211], v[34:37]
	v_mfma_f32_16x16x32_bf16 v[26:29], v[184:187], v[216:219], v[26:29]
	v_mfma_f32_16x16x32_bf16 v[18:21], v[192:195], v[216:219], v[18:21]
	v_mfma_f32_16x16x32_bf16 v[10:13], v[184:187], v[224:227], v[10:13]
	v_mfma_f32_16x16x32_bf16 v[2:5], v[192:195], v[224:227], v[2:5]
	s_barrier
	s_setprio 0
	s_mov_b32 s7, s45
	s_add_u32 s88, s88, 0x100
	s_addc_u32 s89, s89, 0
	s_add_u32 s86, s86, 0x100
	s_addc_u32 s87, s87, 0
	s_cmp_ge_i32 s45, s101
	s_cbranch_scc0 .LBB0_768

.LBB0_947:
	v_cmp_gt_i32_e32 vcc, 1, v138
	s_cbranch_vccnz .LBB0_1009
	v_lshl_add_u64 v[152:153], v[2:3], 0, s[18:19]
	v_add_u32_e32 v154, -2, v138
	s_waitcnt lgkmcnt(0)
	v_lshl_add_u64 v[150:151], v[4:5], 0, s[22:23]
	s_mov_b32 s7, 0
	s_nop 0
	v_readfirstlane_b32 s86, v152
	v_readfirstlane_b32 s87, v153
	v_readfirstlane_b32 s88, v150
	v_readfirstlane_b32 s89, v151
	v_readfirstlane_b32 s90, v146
	v_readfirstlane_b32 s91, v147
	v_readfirstlane_b32 s92, v148
	v_readfirstlane_b32 s93, v149
	v_readfirstlane_b32 s100, v154
	v_readfirstlane_b32 s101, v138
	v_add_u32_e32 v230, s74, v141
	v_add_u32_e32 v231, s75, v141
	v_add_u32_e32 v232, 0x18000, v141
	v_add_u32_e32 v233, 0x1c000, v141
	s_add_u32 s98, s86, 0xfffc0080
	s_addc_u32 s99, s87, -1
	s_cmp_eq_u32 s7, s100
	s_cselect_b64 s[94:95], s[90:91], s[98:99]
	s_cselect_b64 s[96:97], s[92:93], s[88:89]
	s_add_i32 s47, s7, 2
	s_nop 0
	s_mov_b32 m0, s76
	s_nop 0
	global_load_lds_dwordx4 v144, s[86:87]
	s_mov_b32 m0, s77
	s_nop 0
	global_load_lds_dwordx4 v142, s[86:87]
	ds_read_b128 v[164:167], v230
	ds_read_b128 v[168:171], v230 offset:1024
	ds_read_b128 v[172:175], v230 offset:2048
	ds_read_b128 v[176:179], v230 offset:3072
	ds_read_b128 v[180:183], v231
	ds_read_b128 v[184:187], v231 offset:1024
	ds_read_b128 v[188:191], v231 offset:2048
	ds_read_b128 v[192:195], v231 offset:3072
	ds_read_b128 v[196:199], v160
	ds_read_b128 v[200:203], v160 offset:1024
	ds_read_b128 v[204:207], v160 offset:2048
	ds_read_b128 v[208:211], v160 offset:3072
	ds_read_b128 v[212:215], v160 offset:4096
	ds_read_b128 v[216:219], v160 offset:5120
	ds_read_b128 v[220:223], v160 offset:6144
	ds_read_b128 v[224:227], v160 offset:7168
	s_waitcnt vmcnt(8)
	s_waitcnt lgkmcnt(0)
	s_setprio 1
	s_barrier
	v_mfma_f32_16x16x32_bf16 v[122:125], v[164:167], v[196:199], 0
	v_mfma_f32_16x16x32_bf16 v[118:121], v[172:175], v[196:199], 0
	v_mfma_f32_16x16x32_bf16 v[110:113], v[164:167], v[204:207], 0
	v_mfma_f32_16x16x32_bf16 v[102:105], v[172:175], v[204:207], 0
	v_mfma_f32_16x16x32_bf16 v[94:97], v[164:167], v[212:215], 0
	v_mfma_f32_16x16x32_bf16 v[86:89], v[172:175], v[212:215], 0
	v_mfma_f32_16x16x32_bf16 v[78:81], v[164:167], v[220:223], 0
	v_mfma_f32_16x16x32_bf16 v[70:73], v[172:175], v[220:223], 0
	v_mfma_f32_16x16x32_bf16 v[122:125], v[168:171], v[200:203], v[122:125]
	v_mfma_f32_16x16x32_bf16 v[118:121], v[176:179], v[200:203], v[118:121]
	v_mfma_f32_16x16x32_bf16 v[110:113], v[168:171], v[208:211], v[110:113]
	v_mfma_f32_16x16x32_bf16 v[102:105], v[176:179], v[208:211], v[102:105]
	v_mfma_f32_16x16x32_bf16 v[94:97], v[168:171], v[216:219], v[94:97]
	v_mfma_f32_16x16x32_bf16 v[86:89], v[176:179], v[216:219], v[86:89]
	v_mfma_f32_16x16x32_bf16 v[78:81], v[168:171], v[224:227], v[78:81]
	v_mfma_f32_16x16x32_bf16 v[70:73], v[176:179], v[224:227], v[70:73]
	s_setprio 0
	s_setprio 1
	v_mfma_f32_16x16x32_bf16 v[126:129], v[180:183], v[196:199], 0
	v_mfma_f32_16x16x32_bf16 v[114:117], v[188:191], v[196:199], 0
	v_mfma_f32_16x16x32_bf16 v[106:109], v[180:183], v[204:207], 0
	v_mfma_f32_16x16x32_bf16 v[98:101], v[188:191], v[204:207], 0
	v_mfma_f32_16x16x32_bf16 v[90:93], v[180:183], v[212:215], 0
	v_mfma_f32_16x16x32_bf16 v[82:85], v[188:191], v[212:215], 0
	v_mfma_f32_16x16x32_bf16 v[74:77], v[180:183], v[220:223], 0
	v_mfma_f32_16x16x32_bf16 v[66:69], v[188:191], v[220:223], 0
	v_mfma_f32_16x16x32_bf16 v[126:129], v[184:187], v[200:203], v[126:129]
	v_mfma_f32_16x16x32_bf16 v[114:117], v[192:195], v[200:203], v[114:117]
	v_mfma_f32_16x16x32_bf16 v[106:109], v[184:187], v[208:211], v[106:109]
	v_mfma_f32_16x16x32_bf16 v[98:101], v[192:195], v[208:211], v[98:101]
	v_mfma_f32_16x16x32_bf16 v[90:93], v[184:187], v[216:219], v[90:93]
	v_mfma_f32_16x16x32_bf16 v[82:85], v[192:195], v[216:219], v[82:85]
	v_mfma_f32_16x16x32_bf16 v[74:77], v[184:187], v[224:227], v[74:77]
	v_mfma_f32_16x16x32_bf16 v[66:69], v[192:195], v[224:227], v[66:69]
	s_barrier
	s_setprio 0
	s_add_u32 s98, s96, 0x40000
	s_addc_u32 s99, s97, 0
	s_mov_b32 m0, s78
	s_nop 0
	global_load_lds_dwordx4 v132, s[96:97]
	s_mov_b32 m0, s79
	s_add_i32 s7, s75, s29
	global_load_lds_dwordx4 v136, s[96:97]
	s_mov_b32 m0, s7
	s_nop 0
	global_load_lds_dwordx4 v132, s[98:99]
	s_add_i32 m0, s7, 0x2000
	s_nop 0
	global_load_lds_dwordx4 v136, s[98:99]
	s_mov_b32 m0, s51
	s_nop 0
	global_load_lds_dwordx4 v130, s[94:95]
	s_mov_b32 m0, s60
	s_nop 0
	global_load_lds_dwordx4 v134, s[94:95]
	ds_read_b128 v[196:199], v160 offset:16384
	ds_read_b128 v[200:203], v160 offset:17408
	ds_read_b128 v[204:207], v160 offset:18432
	ds_read_b128 v[208:211], v160 offset:19456
	ds_read_b128 v[212:215], v160 offset:20480
	ds_read_b128 v[216:219], v160 offset:21504
	ds_read_b128 v[220:223], v160 offset:22528
	ds_read_b128 v[224:227], v160 offset:23552
	s_waitcnt vmcnt(8)
	s_waitcnt lgkmcnt(0)
	s_setprio 1
	s_barrier
	v_mfma_f32_16x16x32_bf16 v[62:65], v[164:167], v[196:199], 0
	v_mfma_f32_16x16x32_bf16 v[54:57], v[172:175], v[196:199], 0
	v_mfma_f32_16x16x32_bf16 v[46:49], v[164:167], v[204:207], 0
	v_mfma_f32_16x16x32_bf16 v[38:41], v[172:175], v[204:207], 0
	v_mfma_f32_16x16x32_bf16 v[30:33], v[164:167], v[212:215], 0
	v_mfma_f32_16x16x32_bf16 v[22:25], v[172:175], v[212:215], 0
	v_mfma_f32_16x16x32_bf16 v[14:17], v[164:167], v[220:223], 0
	v_mfma_f32_16x16x32_bf16 v[6:9], v[172:175], v[220:223], 0
	v_mfma_f32_16x16x32_bf16 v[62:65], v[168:171], v[200:203], v[62:65]
	v_mfma_f32_16x16x32_bf16 v[54:57], v[176:179], v[200:203], v[54:57]
	v_mfma_f32_16x16x32_bf16 v[46:49], v[168:171], v[208:211], v[46:49]
	v_mfma_f32_16x16x32_bf16 v[38:41], v[176:179], v[208:211], v[38:41]
	v_mfma_f32_16x16x32_bf16 v[30:33], v[168:171], v[216:219], v[30:33]
	v_mfma_f32_16x16x32_bf16 v[22:25], v[176:179], v[216:219], v[22:25]
	v_mfma_f32_16x16x32_bf16 v[14:17], v[168:171], v[224:227], v[14:17]
	v_mfma_f32_16x16x32_bf16 v[6:9], v[176:179], v[224:227], v[6:9]
	s_setprio 0
	s_setprio 1
	v_mfma_f32_16x16x32_bf16 v[58:61], v[180:183], v[196:199], 0
	v_mfma_f32_16x16x32_bf16 v[50:53], v[188:191], v[196:199], 0
	v_mfma_f32_16x16x32_bf16 v[42:45], v[180:183], v[204:207], 0
	v_mfma_f32_16x16x32_bf16 v[34:37], v[188:191], v[204:207], 0
	v_mfma_f32_16x16x32_bf16 v[26:29], v[180:183], v[212:215], 0
	v_mfma_f32_16x16x32_bf16 v[18:21], v[188:191], v[212:215], 0
	v_mfma_f32_16x16x32_bf16 v[10:13], v[180:183], v[220:223], 0
	v_mfma_f32_16x16x32_bf16 v[2:5], v[188:191], v[220:223], 0
	v_mfma_f32_16x16x32_bf16 v[58:61], v[184:187], v[200:203], v[58:61]
	v_mfma_f32_16x16x32_bf16 v[50:53], v[192:195], v[200:203], v[50:53]
	v_mfma_f32_16x16x32_bf16 v[42:45], v[184:187], v[208:211], v[42:45]
	v_mfma_f32_16x16x32_bf16 v[34:37], v[192:195], v[208:211], v[34:37]
	v_mfma_f32_16x16x32_bf16 v[26:29], v[184:187], v[216:219], v[26:29]
	v_mfma_f32_16x16x32_bf16 v[18:21], v[192:195], v[216:219], v[18:21]
	v_mfma_f32_16x16x32_bf16 v[10:13], v[184:187], v[224:227], v[10:13]
	v_mfma_f32_16x16x32_bf16 v[2:5], v[192:195], v[224:227], v[2:5]
	s_barrier
	s_setprio 0
	s_add_u32 s98, s94, 0x40000
	s_addc_u32 s99, s95, 0
	s_add_i32 s7, 0, 0x18000
	s_add_i32 s49, 0, 0x1c000
	s_mov_b32 m0, s61
	s_nop 0
	global_load_lds_dwordx4 v130, s[98:99]
	s_mov_b32 m0, s62
	s_nop 0
	global_load_lds_dwordx4 v134, s[98:99]
	ds_read_b128 v[164:167], v232
	ds_read_b128 v[168:171], v232 offset:1024
	ds_read_b128 v[172:175], v232 offset:2048
	ds_read_b128 v[176:179], v232 offset:3072
	ds_read_b128 v[180:183], v233
	ds_read_b128 v[184:187], v233 offset:1024
	ds_read_b128 v[188:191], v233 offset:2048
	ds_read_b128 v[192:195], v233 offset:3072
	ds_read_b128 v[196:199], v160 offset:32768
	ds_read_b128 v[200:203], v160 offset:33792
	ds_read_b128 v[204:207], v160 offset:34816
	ds_read_b128 v[208:211], v160 offset:35840
	ds_read_b128 v[212:215], v160 offset:36864
	ds_read_b128 v[216:219], v160 offset:37888
	ds_read_b128 v[220:223], v160 offset:38912
	ds_read_b128 v[224:227], v160 offset:39936
	s_waitcnt vmcnt(8)
	s_waitcnt lgkmcnt(0)
	s_setprio 1
	s_barrier
	v_mfma_f32_16x16x32_bf16 v[122:125], v[164:167], v[196:199], v[122:125]
	v_mfma_f32_16x16x32_bf16 v[118:121], v[172:175], v[196:199], v[118:121]
	v_mfma_f32_16x16x32_bf16 v[110:113], v[164:167], v[204:207], v[110:113]
	v_mfma_f32_16x16x32_bf16 v[102:105], v[172:175], v[204:207], v[102:105]
	v_mfma_f32_16x16x32_bf16 v[94:97], v[164:167], v[212:215], v[94:97]
	v_mfma_f32_16x16x32_bf16 v[86:89], v[172:175], v[212:215], v[86:89]
	v_mfma_f32_16x16x32_bf16 v[78:81], v[164:167], v[220:223], v[78:81]
	v_mfma_f32_16x16x32_bf16 v[70:73], v[172:175], v[220:223], v[70:73]
	v_mfma_f32_16x16x32_bf16 v[122:125], v[168:171], v[200:203], v[122:125]
	v_mfma_f32_16x16x32_bf16 v[118:121], v[176:179], v[200:203], v[118:121]
	v_mfma_f32_16x16x32_bf16 v[110:113], v[168:171], v[208:211], v[110:113]
	v_mfma_f32_16x16x32_bf16 v[102:105], v[176:179], v[208:211], v[102:105]
	v_mfma_f32_16x16x32_bf16 v[94:97], v[168:171], v[216:219], v[94:97]
	v_mfma_f32_16x16x32_bf16 v[86:89], v[176:179], v[216:219], v[86:89]
	v_mfma_f32_16x16x32_bf16 v[78:81], v[168:171], v[224:227], v[78:81]
	v_mfma_f32_16x16x32_bf16 v[70:73], v[176:179], v[224:227], v[70:73]
	s_setprio 0
	s_setprio 1
	v_mfma_f32_16x16x32_bf16 v[126:129], v[180:183], v[196:199], v[126:129]
	v_mfma_f32_16x16x32_bf16 v[114:117], v[188:191], v[196:199], v[114:117]
	v_mfma_f32_16x16x32_bf16 v[106:109], v[180:183], v[204:207], v[106:109]
	v_mfma_f32_16x16x32_bf16 v[98:101], v[188:191], v[204:207], v[98:101]
	v_mfma_f32_16x16x32_bf16 v[90:93], v[180:183], v[212:215], v[90:93]
	v_mfma_f32_16x16x32_bf16 v[82:85], v[188:191], v[212:215], v[82:85]
	v_mfma_f32_16x16x32_bf16 v[74:77], v[180:183], v[220:223], v[74:77]
	v_mfma_f32_16x16x32_bf16 v[66:69], v[188:191], v[220:223], v[66:69]
	v_mfma_f32_16x16x32_bf16 v[126:129], v[184:187], v[200:203], v[126:129]
	v_mfma_f32_16x16x32_bf16 v[114:117], v[192:195], v[200:203], v[114:117]
	v_mfma_f32_16x16x32_bf16 v[106:109], v[184:187], v[208:211], v[106:109]
	v_mfma_f32_16x16x32_bf16 v[98:101], v[192:195], v[208:211], v[98:101]
	v_mfma_f32_16x16x32_bf16 v[90:93], v[184:187], v[216:219], v[90:93]
	v_mfma_f32_16x16x32_bf16 v[82:85], v[192:195], v[216:219], v[82:85]
	v_mfma_f32_16x16x32_bf16 v[74:77], v[184:187], v[224:227], v[74:77]
	v_mfma_f32_16x16x32_bf16 v[66:69], v[192:195], v[224:227], v[66:69]
	s_barrier
	s_setprio 0
	s_add_u32 s96, s96, 0x80
	s_addc_u32 s97, s97, 0
	s_add_u32 s98, s96, 0x40000
	s_addc_u32 s99, s97, 0
	s_add_u32 s94, s94, 0x80
	s_addc_u32 s95, s95, 0
	s_add_i32 s7, s7, s29
	s_mov_b32 m0, s7
	s_nop 0
	global_load_lds_dwordx4 v132, s[96:97]
	s_add_i32 m0, s7, 0x2000
	s_add_i32 s7, s49, s29
	global_load_lds_dwordx4 v136, s[96:97]
	s_mov_b32 m0, s7
	s_nop 0
	global_load_lds_dwordx4 v132, s[98:99]
	s_add_i32 m0, s7, 0x2000
	s_nop 0
	global_load_lds_dwordx4 v136, s[98:99]
	s_mov_b32 m0, s63
	s_nop 0
	global_load_lds_dwordx4 v130, s[94:95]
	s_mov_b32 m0, s64
	s_nop 0
	global_load_lds_dwordx4 v134, s[94:95]
	ds_read_b128 v[196:199], v160 offset:49152
	ds_read_b128 v[200:203], v160 offset:50176
	ds_read_b128 v[204:207], v160 offset:51200
	ds_read_b128 v[208:211], v160 offset:52224
	ds_read_b128 v[212:215], v160 offset:53248
	ds_read_b128 v[216:219], v160 offset:54272
	ds_read_b128 v[220:223], v160 offset:55296
	ds_read_b128 v[224:227], v160 offset:56320
	s_waitcnt vmcnt(8)
	s_waitcnt lgkmcnt(0)
	s_setprio 1
	s_barrier
	v_mfma_f32_16x16x32_bf16 v[62:65], v[164:167], v[196:199], v[62:65]
	v_mfma_f32_16x16x32_bf16 v[54:57], v[172:175], v[196:199], v[54:57]
	v_mfma_f32_16x16x32_bf16 v[46:49], v[164:167], v[204:207], v[46:49]
	v_mfma_f32_16x16x32_bf16 v[38:41], v[172:175], v[204:207], v[38:41]
	v_mfma_f32_16x16x32_bf16 v[30:33], v[164:167], v[212:215], v[30:33]
	v_mfma_f32_16x16x32_bf16 v[22:25], v[172:175], v[212:215], v[22:25]
	v_mfma_f32_16x16x32_bf16 v[14:17], v[164:167], v[220:223], v[14:17]
	v_mfma_f32_16x16x32_bf16 v[6:9], v[172:175], v[220:223], v[6:9]
	v_mfma_f32_16x16x32_bf16 v[62:65], v[168:171], v[200:203], v[62:65]
	v_mfma_f32_16x16x32_bf16 v[54:57], v[176:179], v[200:203], v[54:57]
	v_mfma_f32_16x16x32_bf16 v[46:49], v[168:171], v[208:211], v[46:49]
	v_mfma_f32_16x16x32_bf16 v[38:41], v[176:179], v[208:211], v[38:41]
	v_mfma_f32_16x16x32_bf16 v[30:33], v[168:171], v[216:219], v[30:33]
	v_mfma_f32_16x16x32_bf16 v[22:25], v[176:179], v[216:219], v[22:25]
	v_mfma_f32_16x16x32_bf16 v[14:17], v[168:171], v[224:227], v[14:17]
	v_mfma_f32_16x16x32_bf16 v[6:9], v[176:179], v[224:227], v[6:9]
	s_setprio 0
	s_setprio 1
	v_mfma_f32_16x16x32_bf16 v[58:61], v[180:183], v[196:199], v[58:61]
	v_mfma_f32_16x16x32_bf16 v[50:53], v[188:191], v[196:199], v[50:53]
	v_mfma_f32_16x16x32_bf16 v[42:45], v[180:183], v[204:207], v[42:45]
	v_mfma_f32_16x16x32_bf16 v[34:37], v[188:191], v[204:207], v[34:37]
	v_mfma_f32_16x16x32_bf16 v[26:29], v[180:183], v[212:215], v[26:29]
	v_mfma_f32_16x16x32_bf16 v[18:21], v[188:191], v[212:215], v[18:21]
	v_mfma_f32_16x16x32_bf16 v[10:13], v[180:183], v[220:223], v[10:13]
	v_mfma_f32_16x16x32_bf16 v[2:5], v[188:191], v[220:223], v[2:5]
	v_mfma_f32_16x16x32_bf16 v[58:61], v[184:187], v[200:203], v[58:61]
	v_mfma_f32_16x16x32_bf16 v[50:53], v[192:195], v[200:203], v[50:53]
	v_mfma_f32_16x16x32_bf16 v[42:45], v[184:187], v[208:211], v[42:45]
	v_mfma_f32_16x16x32_bf16 v[34:37], v[192:195], v[208:211], v[34:37]
	v_mfma_f32_16x16x32_bf16 v[26:29], v[184:187], v[216:219], v[26:29]
	v_mfma_f32_16x16x32_bf16 v[18:21], v[192:195], v[216:219], v[18:21]
	v_mfma_f32_16x16x32_bf16 v[10:13], v[184:187], v[224:227], v[10:13]
	v_mfma_f32_16x16x32_bf16 v[2:5], v[192:195], v[224:227], v[2:5]
	s_barrier
	s_setprio 0
	s_mov_b32 s7, s47
	s_add_u32 s88, s88, 0x100
	s_addc_u32 s89, s89, 0
	s_add_u32 s86, s86, 0x100
	s_addc_u32 s87, s87, 0
	s_cmp_ge_i32 s47, s101
	s_cbranch_scc1 .Lmy_kexit_4
.LBB0_949:
	s_add_u32 s98, s86, 0xfffc0080
	s_addc_u32 s99, s87, -1
	s_cmp_eq_u32 s7, s100
	s_cselect_b64 s[94:95], s[90:91], s[98:99]
	s_cselect_b64 s[96:97], s[92:93], s[88:89]
	s_add_i32 s47, s7, 2
	s_nop 0
	s_mov_b32 m0, s76
	s_nop 0
	global_load_lds_dwordx4 v144, s[86:87]
	s_mov_b32 m0, s77
	s_nop 0
	global_load_lds_dwordx4 v142, s[86:87]
	ds_read_b128 v[164:167], v230
	ds_read_b128 v[168:171], v230 offset:1024
	ds_read_b128 v[172:175], v230 offset:2048
	ds_read_b128 v[176:179], v230 offset:3072
	ds_read_b128 v[180:183], v231
	ds_read_b128 v[184:187], v231 offset:1024
	ds_read_b128 v[188:191], v231 offset:2048
	ds_read_b128 v[192:195], v231 offset:3072
	ds_read_b128 v[196:199], v160
	ds_read_b128 v[200:203], v160 offset:1024
	ds_read_b128 v[204:207], v160 offset:2048
	ds_read_b128 v[208:211], v160 offset:3072
	ds_read_b128 v[212:215], v160 offset:4096
	ds_read_b128 v[216:219], v160 offset:5120
	ds_read_b128 v[220:223], v160 offset:6144
	ds_read_b128 v[224:227], v160 offset:7168
	s_waitcnt vmcnt(8)
	s_waitcnt lgkmcnt(0)
	s_setprio 1
	s_barrier
	v_mfma_f32_16x16x32_bf16 v[122:125], v[164:167], v[196:199], v[122:125]
	v_mfma_f32_16x16x32_bf16 v[118:121], v[172:175], v[196:199], v[118:121]
	v_mfma_f32_16x16x32_bf16 v[110:113], v[164:167], v[204:207], v[110:113]
	v_mfma_f32_16x16x32_bf16 v[102:105], v[172:175], v[204:207], v[102:105]
	v_mfma_f32_16x16x32_bf16 v[94:97], v[164:167], v[212:215], v[94:97]
	v_mfma_f32_16x16x32_bf16 v[86:89], v[172:175], v[212:215], v[86:89]
	v_mfma_f32_16x16x32_bf16 v[78:81], v[164:167], v[220:223], v[78:81]
	v_mfma_f32_16x16x32_bf16 v[70:73], v[172:175], v[220:223], v[70:73]
	v_mfma_f32_16x16x32_bf16 v[122:125], v[168:171], v[200:203], v[122:125]
	v_mfma_f32_16x16x32_bf16 v[118:121], v[176:179], v[200:203], v[118:121]
	v_mfma_f32_16x16x32_bf16 v[110:113], v[168:171], v[208:211], v[110:113]
	v_mfma_f32_16x16x32_bf16 v[102:105], v[176:179], v[208:211], v[102:105]
	v_mfma_f32_16x16x32_bf16 v[94:97], v[168:171], v[216:219], v[94:97]
	v_mfma_f32_16x16x32_bf16 v[86:89], v[176:179], v[216:219], v[86:89]
	v_mfma_f32_16x16x32_bf16 v[78:81], v[168:171], v[224:227], v[78:81]
	v_mfma_f32_16x16x32_bf16 v[70:73], v[176:179], v[224:227], v[70:73]
	s_setprio 0
	s_setprio 1
	v_mfma_f32_16x16x32_bf16 v[126:129], v[180:183], v[196:199], v[126:129]
	v_mfma_f32_16x16x32_bf16 v[114:117], v[188:191], v[196:199], v[114:117]
	v_mfma_f32_16x16x32_bf16 v[106:109], v[180:183], v[204:207], v[106:109]
	v_mfma_f32_16x16x32_bf16 v[98:101], v[188:191], v[204:207], v[98:101]
	v_mfma_f32_16x16x32_bf16 v[90:93], v[180:183], v[212:215], v[90:93]
	v_mfma_f32_16x16x32_bf16 v[82:85], v[188:191], v[212:215], v[82:85]
	v_mfma_f32_16x16x32_bf16 v[74:77], v[180:183], v[220:223], v[74:77]
	v_mfma_f32_16x16x32_bf16 v[66:69], v[188:191], v[220:223], v[66:69]
	v_mfma_f32_16x16x32_bf16 v[126:129], v[184:187], v[200:203], v[126:129]
	v_mfma_f32_16x16x32_bf16 v[114:117], v[192:195], v[200:203], v[114:117]
	v_mfma_f32_16x16x32_bf16 v[106:109], v[184:187], v[208:211], v[106:109]
	v_mfma_f32_16x16x32_bf16 v[98:101], v[192:195], v[208:211], v[98:101]
	v_mfma_f32_16x16x32_bf16 v[90:93], v[184:187], v[216:219], v[90:93]
	v_mfma_f32_16x16x32_bf16 v[82:85], v[192:195], v[216:219], v[82:85]
	v_mfma_f32_16x16x32_bf16 v[74:77], v[184:187], v[224:227], v[74:77]
	v_mfma_f32_16x16x32_bf16 v[66:69], v[192:195], v[224:227], v[66:69]
	s_barrier
	s_setprio 0
	s_add_u32 s98, s96, 0x40000
	s_addc_u32 s99, s97, 0
	s_mov_b32 m0, s78
	s_nop 0
	global_load_lds_dwordx4 v132, s[96:97]
	s_mov_b32 m0, s79
	s_add_i32 s7, s75, s29
	global_load_lds_dwordx4 v136, s[96:97]
	s_mov_b32 m0, s7
	s_nop 0
	global_load_lds_dwordx4 v132, s[98:99]
	s_add_i32 m0, s7, 0x2000
	s_nop 0
	global_load_lds_dwordx4 v136, s[98:99]
	s_mov_b32 m0, s51
	s_nop 0
	global_load_lds_dwordx4 v130, s[94:95]
	s_mov_b32 m0, s60
	s_nop 0
	global_load_lds_dwordx4 v134, s[94:95]
	ds_read_b128 v[196:199], v160 offset:16384
	ds_read_b128 v[200:203], v160 offset:17408
	ds_read_b128 v[204:207], v160 offset:18432
	ds_read_b128 v[208:211], v160 offset:19456
	ds_read_b128 v[212:215], v160 offset:20480
	ds_read_b128 v[216:219], v160 offset:21504
	ds_read_b128 v[220:223], v160 offset:22528
	ds_read_b128 v[224:227], v160 offset:23552
	s_waitcnt vmcnt(8)
	s_waitcnt lgkmcnt(0)
	s_setprio 1
	s_barrier
	v_mfma_f32_16x16x32_bf16 v[62:65], v[164:167], v[196:199], v[62:65]
	v_mfma_f32_16x16x32_bf16 v[54:57], v[172:175], v[196:199], v[54:57]
	v_mfma_f32_16x16x32_bf16 v[46:49], v[164:167], v[204:207], v[46:49]
	v_mfma_f32_16x16x32_bf16 v[38:41], v[172:175], v[204:207], v[38:41]
	v_mfma_f32_16x16x32_bf16 v[30:33], v[164:167], v[212:215], v[30:33]
	v_mfma_f32_16x16x32_bf16 v[22:25], v[172:175], v[212:215], v[22:25]
	v_mfma_f32_16x16x32_bf16 v[14:17], v[164:167], v[220:223], v[14:17]
	v_mfma_f32_16x16x32_bf16 v[6:9], v[172:175], v[220:223], v[6:9]
	v_mfma_f32_16x16x32_bf16 v[62:65], v[168:171], v[200:203], v[62:65]
	v_mfma_f32_16x16x32_bf16 v[54:57], v[176:179], v[200:203], v[54:57]
	v_mfma_f32_16x16x32_bf16 v[46:49], v[168:171], v[208:211], v[46:49]
	v_mfma_f32_16x16x32_bf16 v[38:41], v[176:179], v[208:211], v[38:41]
	v_mfma_f32_16x16x32_bf16 v[30:33], v[168:171], v[216:219], v[30:33]
	v_mfma_f32_16x16x32_bf16 v[22:25], v[176:179], v[216:219], v[22:25]
	v_mfma_f32_16x16x32_bf16 v[14:17], v[168:171], v[224:227], v[14:17]
	v_mfma_f32_16x16x32_bf16 v[6:9], v[176:179], v[224:227], v[6:9]
	s_setprio 0
	s_setprio 1
	v_mfma_f32_16x16x32_bf16 v[58:61], v[180:183], v[196:199], v[58:61]
	v_mfma_f32_16x16x32_bf16 v[50:53], v[188:191], v[196:199], v[50:53]
	v_mfma_f32_16x16x32_bf16 v[42:45], v[180:183], v[204:207], v[42:45]
	v_mfma_f32_16x16x32_bf16 v[34:37], v[188:191], v[204:207], v[34:37]
	v_mfma_f32_16x16x32_bf16 v[26:29], v[180:183], v[212:215], v[26:29]
	v_mfma_f32_16x16x32_bf16 v[18:21], v[188:191], v[212:215], v[18:21]
	v_mfma_f32_16x16x32_bf16 v[10:13], v[180:183], v[220:223], v[10:13]
	v_mfma_f32_16x16x32_bf16 v[2:5], v[188:191], v[220:223], v[2:5]
	v_mfma_f32_16x16x32_bf16 v[58:61], v[184:187], v[200:203], v[58:61]
	v_mfma_f32_16x16x32_bf16 v[50:53], v[192:195], v[200:203], v[50:53]
	v_mfma_f32_16x16x32_bf16 v[42:45], v[184:187], v[208:211], v[42:45]
	v_mfma_f32_16x16x32_bf16 v[34:37], v[192:195], v[208:211], v[34:37]
	v_mfma_f32_16x16x32_bf16 v[26:29], v[184:187], v[216:219], v[26:29]
	v_mfma_f32_16x16x32_bf16 v[18:21], v[192:195], v[216:219], v[18:21]
	v_mfma_f32_16x16x32_bf16 v[10:13], v[184:187], v[224:227], v[10:13]
	v_mfma_f32_16x16x32_bf16 v[2:5], v[192:195], v[224:227], v[2:5]
	s_barrier
	s_setprio 0
	s_add_u32 s98, s94, 0x40000
	s_addc_u32 s99, s95, 0
	s_add_i32 s7, 0, 0x18000
	s_add_i32 s49, 0, 0x1c000
	s_mov_b32 m0, s61
	s_nop 0
	global_load_lds_dwordx4 v130, s[98:99]
	s_mov_b32 m0, s62
	s_nop 0
	global_load_lds_dwordx4 v134, s[98:99]
	ds_read_b128 v[164:167], v232
	ds_read_b128 v[168:171], v232 offset:1024
	ds_read_b128 v[172:175], v232 offset:2048
	ds_read_b128 v[176:179], v232 offset:3072
	ds_read_b128 v[180:183], v233
	ds_read_b128 v[184:187], v233 offset:1024
	ds_read_b128 v[188:191], v233 offset:2048
	ds_read_b128 v[192:195], v233 offset:3072
	ds_read_b128 v[196:199], v160 offset:32768
	ds_read_b128 v[200:203], v160 offset:33792
	ds_read_b128 v[204:207], v160 offset:34816
	ds_read_b128 v[208:211], v160 offset:35840
	ds_read_b128 v[212:215], v160 offset:36864
	ds_read_b128 v[216:219], v160 offset:37888
	ds_read_b128 v[220:223], v160 offset:38912
	ds_read_b128 v[224:227], v160 offset:39936
	s_waitcnt vmcnt(8)
	s_waitcnt lgkmcnt(0)
	s_setprio 1
	s_barrier
	v_mfma_f32_16x16x32_bf16 v[122:125], v[164:167], v[196:199], v[122:125]
	v_mfma_f32_16x16x32_bf16 v[118:121], v[172:175], v[196:199], v[118:121]
	v_mfma_f32_16x16x32_bf16 v[110:113], v[164:167], v[204:207], v[110:113]
	v_mfma_f32_16x16x32_bf16 v[102:105], v[172:175], v[204:207], v[102:105]
	v_mfma_f32_16x16x32_bf16 v[94:97], v[164:167], v[212:215], v[94:97]
	v_mfma_f32_16x16x32_bf16 v[86:89], v[172:175], v[212:215], v[86:89]
	v_mfma_f32_16x16x32_bf16 v[78:81], v[164:167], v[220:223], v[78:81]
	v_mfma_f32_16x16x32_bf16 v[70:73], v[172:175], v[220:223], v[70:73]
	v_mfma_f32_16x16x32_bf16 v[122:125], v[168:171], v[200:203], v[122:125]
	v_mfma_f32_16x16x32_bf16 v[118:121], v[176:179], v[200:203], v[118:121]
	v_mfma_f32_16x16x32_bf16 v[110:113], v[168:171], v[208:211], v[110:113]
	v_mfma_f32_16x16x32_bf16 v[102:105], v[176:179], v[208:211], v[102:105]
	v_mfma_f32_16x16x32_bf16 v[94:97], v[168:171], v[216:219], v[94:97]
	v_mfma_f32_16x16x32_bf16 v[86:89], v[176:179], v[216:219], v[86:89]
	v_mfma_f32_16x16x32_bf16 v[78:81], v[168:171], v[224:227], v[78:81]
	v_mfma_f32_16x16x32_bf16 v[70:73], v[176:179], v[224:227], v[70:73]
	s_setprio 0
	s_setprio 1
	v_mfma_f32_16x16x32_bf16 v[126:129], v[180:183], v[196:199], v[126:129]
	v_mfma_f32_16x16x32_bf16 v[114:117], v[188:191], v[196:199], v[114:117]
	v_mfma_f32_16x16x32_bf16 v[106:109], v[180:183], v[204:207], v[106:109]
	v_mfma_f32_16x16x32_bf16 v[98:101], v[188:191], v[204:207], v[98:101]
	v_mfma_f32_16x16x32_bf16 v[90:93], v[180:183], v[212:215], v[90:93]
	v_mfma_f32_16x16x32_bf16 v[82:85], v[188:191], v[212:215], v[82:85]
	v_mfma_f32_16x16x32_bf16 v[74:77], v[180:183], v[220:223], v[74:77]
	v_mfma_f32_16x16x32_bf16 v[66:69], v[188:191], v[220:223], v[66:69]
	v_mfma_f32_16x16x32_bf16 v[126:129], v[184:187], v[200:203], v[126:129]
	v_mfma_f32_16x16x32_bf16 v[114:117], v[192:195], v[200:203], v[114:117]
	v_mfma_f32_16x16x32_bf16 v[106:109], v[184:187], v[208:211], v[106:109]
	v_mfma_f32_16x16x32_bf16 v[98:101], v[192:195], v[208:211], v[98:101]
	v_mfma_f32_16x16x32_bf16 v[90:93], v[184:187], v[216:219], v[90:93]
	v_mfma_f32_16x16x32_bf16 v[82:85], v[192:195], v[216:219], v[82:85]
	v_mfma_f32_16x16x32_bf16 v[74:77], v[184:187], v[224:227], v[74:77]
	v_mfma_f32_16x16x32_bf16 v[66:69], v[192:195], v[224:227], v[66:69]
	s_barrier
	s_setprio 0
	s_add_u32 s96, s96, 0x80
	s_addc_u32 s97, s97, 0
	s_add_u32 s98, s96, 0x40000
	s_addc_u32 s99, s97, 0
	s_add_u32 s94, s94, 0x80
	s_addc_u32 s95, s95, 0
	s_add_i32 s7, s7, s29
	s_mov_b32 m0, s7
	s_nop 0
	global_load_lds_dwordx4 v132, s[96:97]
	s_add_i32 m0, s7, 0x2000
	s_add_i32 s7, s49, s29
	global_load_lds_dwordx4 v136, s[96:97]
	s_mov_b32 m0, s7
	s_nop 0
	global_load_lds_dwordx4 v132, s[98:99]
	s_add_i32 m0, s7, 0x2000
	s_nop 0
	global_load_lds_dwordx4 v136, s[98:99]
	s_mov_b32 m0, s63
	s_nop 0
	global_load_lds_dwordx4 v130, s[94:95]
	s_mov_b32 m0, s64
	s_nop 0
	global_load_lds_dwordx4 v134, s[94:95]
	ds_read_b128 v[196:199], v160 offset:49152
	ds_read_b128 v[200:203], v160 offset:50176
	ds_read_b128 v[204:207], v160 offset:51200
	ds_read_b128 v[208:211], v160 offset:52224
	ds_read_b128 v[212:215], v160 offset:53248
	ds_read_b128 v[216:219], v160 offset:54272
	ds_read_b128 v[220:223], v160 offset:55296
	ds_read_b128 v[224:227], v160 offset:56320
	s_waitcnt vmcnt(8)
	s_waitcnt lgkmcnt(0)
	s_setprio 1
	s_barrier
	v_mfma_f32_16x16x32_bf16 v[62:65], v[164:167], v[196:199], v[62:65]
	v_mfma_f32_16x16x32_bf16 v[54:57], v[172:175], v[196:199], v[54:57]
	v_mfma_f32_16x16x32_bf16 v[46:49], v[164:167], v[204:207], v[46:49]
	v_mfma_f32_16x16x32_bf16 v[38:41], v[172:175], v[204:207], v[38:41]
	v_mfma_f32_16x16x32_bf16 v[30:33], v[164:167], v[212:215], v[30:33]
	v_mfma_f32_16x16x32_bf16 v[22:25], v[172:175], v[212:215], v[22:25]
	v_mfma_f32_16x16x32_bf16 v[14:17], v[164:167], v[220:223], v[14:17]
	v_mfma_f32_16x16x32_bf16 v[6:9], v[172:175], v[220:223], v[6:9]
	v_mfma_f32_16x16x32_bf16 v[62:65], v[168:171], v[200:203], v[62:65]
	v_mfma_f32_16x16x32_bf16 v[54:57], v[176:179], v[200:203], v[54:57]
	v_mfma_f32_16x16x32_bf16 v[46:49], v[168:171], v[208:211], v[46:49]
	v_mfma_f32_16x16x32_bf16 v[38:41], v[176:179], v[208:211], v[38:41]
	v_mfma_f32_16x16x32_bf16 v[30:33], v[168:171], v[216:219], v[30:33]
	v_mfma_f32_16x16x32_bf16 v[22:25], v[176:179], v[216:219], v[22:25]
	v_mfma_f32_16x16x32_bf16 v[14:17], v[168:171], v[224:227], v[14:17]
	v_mfma_f32_16x16x32_bf16 v[6:9], v[176:179], v[224:227], v[6:9]
	s_setprio 0
	s_setprio 1
	v_mfma_f32_16x16x32_bf16 v[58:61], v[180:183], v[196:199], v[58:61]
	v_mfma_f32_16x16x32_bf16 v[50:53], v[188:191], v[196:199], v[50:53]
	v_mfma_f32_16x16x32_bf16 v[42:45], v[180:183], v[204:207], v[42:45]
	v_mfma_f32_16x16x32_bf16 v[34:37], v[188:191], v[204:207], v[34:37]
	v_mfma_f32_16x16x32_bf16 v[26:29], v[180:183], v[212:215], v[26:29]
	v_mfma_f32_16x16x32_bf16 v[18:21], v[188:191], v[212:215], v[18:21]
	v_mfma_f32_16x16x32_bf16 v[10:13], v[180:183], v[220:223], v[10:13]
	v_mfma_f32_16x16x32_bf16 v[2:5], v[188:191], v[220:223], v[2:5]
	v_mfma_f32_16x16x32_bf16 v[58:61], v[184:187], v[200:203], v[58:61]
	v_mfma_f32_16x16x32_bf16 v[50:53], v[192:195], v[200:203], v[50:53]
	v_mfma_f32_16x16x32_bf16 v[42:45], v[184:187], v[208:211], v[42:45]
	v_mfma_f32_16x16x32_bf16 v[34:37], v[192:195], v[208:211], v[34:37]
	v_mfma_f32_16x16x32_bf16 v[26:29], v[184:187], v[216:219], v[26:29]
	v_mfma_f32_16x16x32_bf16 v[18:21], v[192:195], v[216:219], v[18:21]
	v_mfma_f32_16x16x32_bf16 v[10:13], v[184:187], v[224:227], v[10:13]
	v_mfma_f32_16x16x32_bf16 v[2:5], v[192:195], v[224:227], v[2:5]
	s_barrier
	s_setprio 0
	s_mov_b32 s7, s47
	s_add_u32 s88, s88, 0x100
	s_addc_u32 s89, s89, 0
	s_add_u32 s86, s86, 0x100
	s_addc_u32 s87, s87, 0
	s_cmp_ge_i32 s47, s101
	s_cbranch_scc0 .LBB0_949

.LBB0_1078:
	v_cmp_gt_i32_e32 vcc, 1, v156
	s_cbranch_vccnz .LBB0_1140
	v_lshl_add_u64 v[152:153], v[2:3], 0, s[20:21]
	v_add_u32_e32 v138, -2, v156
	s_mov_b32 s6, 0
	s_nop 0
	v_readfirstlane_b32 s86, v150
	v_readfirstlane_b32 s87, v151
	v_readfirstlane_b32 s88, v152
	v_readfirstlane_b32 s89, v153
	v_readfirstlane_b32 s90, v146
	v_readfirstlane_b32 s91, v147
	v_readfirstlane_b32 s92, v148
	v_readfirstlane_b32 s93, v149
	v_readfirstlane_b32 s100, v138
	v_readfirstlane_b32 s101, v156
	v_add_u32_e32 v230, s67, v141
	v_add_u32_e32 v231, s68, v141
	v_add_u32_e32 v232, 0x18000, v141
	v_add_u32_e32 v233, 0x1c000, v141
	s_add_u32 s98, s86, 0x100
	s_addc_u32 s99, s87, 0
	s_cmp_eq_u32 s6, s100
	s_cselect_b64 s[94:95], s[90:91], s[98:99]
	s_cselect_b64 s[96:97], s[92:93], s[88:89]
	s_add_i32 s7, s6, 2
	s_nop 0
	s_add_i32 m0, s46, 0xc000
	s_nop 0
	global_load_lds_dwordx4 v144, s[86:87]
	s_add_i32 m0, s46, 0xe000
	s_nop 0
	global_load_lds_dwordx4 v142, s[86:87]
	ds_read_b128 v[164:167], v230
	ds_read_b128 v[168:171], v230 offset:1024
	ds_read_b128 v[172:175], v230 offset:2048
	ds_read_b128 v[176:179], v230 offset:3072
	ds_read_b128 v[180:183], v231
	ds_read_b128 v[184:187], v231 offset:1024
	ds_read_b128 v[188:191], v231 offset:2048
	ds_read_b128 v[192:195], v231 offset:3072
	ds_read_b128 v[196:199], v160
	ds_read_b128 v[200:203], v160 offset:1024
	ds_read_b128 v[204:207], v160 offset:2048
	ds_read_b128 v[208:211], v160 offset:3072
	ds_read_b128 v[212:215], v160 offset:4096
	ds_read_b128 v[216:219], v160 offset:5120
	ds_read_b128 v[220:223], v160 offset:6144
	ds_read_b128 v[224:227], v160 offset:7168
	s_waitcnt vmcnt(8)
	s_waitcnt lgkmcnt(0)
	s_setprio 1
	s_barrier
	v_mfma_f32_16x16x32_bf16 v[122:125], v[164:167], v[196:199], 0
	v_mfma_f32_16x16x32_bf16 v[118:121], v[172:175], v[196:199], 0
	v_mfma_f32_16x16x32_bf16 v[110:113], v[164:167], v[204:207], 0
	v_mfma_f32_16x16x32_bf16 v[102:105], v[172:175], v[204:207], 0
	v_mfma_f32_16x16x32_bf16 v[94:97], v[164:167], v[212:215], 0
	v_mfma_f32_16x16x32_bf16 v[86:89], v[172:175], v[212:215], 0
	v_mfma_f32_16x16x32_bf16 v[78:81], v[164:167], v[220:223], 0
	v_mfma_f32_16x16x32_bf16 v[70:73], v[172:175], v[220:223], 0
	v_mfma_f32_16x16x32_bf16 v[122:125], v[168:171], v[200:203], v[122:125]
	v_mfma_f32_16x16x32_bf16 v[118:121], v[176:179], v[200:203], v[118:121]
	v_mfma_f32_16x16x32_bf16 v[110:113], v[168:171], v[208:211], v[110:113]
	v_mfma_f32_16x16x32_bf16 v[102:105], v[176:179], v[208:211], v[102:105]
	v_mfma_f32_16x16x32_bf16 v[94:97], v[168:171], v[216:219], v[94:97]
	v_mfma_f32_16x16x32_bf16 v[86:89], v[176:179], v[216:219], v[86:89]
	v_mfma_f32_16x16x32_bf16 v[78:81], v[168:171], v[224:227], v[78:81]
	v_mfma_f32_16x16x32_bf16 v[70:73], v[176:179], v[224:227], v[70:73]
	s_setprio 0
	s_setprio 1
	v_mfma_f32_16x16x32_bf16 v[126:129], v[180:183], v[196:199], 0
	v_mfma_f32_16x16x32_bf16 v[114:117], v[188:191], v[196:199], 0
	v_mfma_f32_16x16x32_bf16 v[106:109], v[180:183], v[204:207], 0
	v_mfma_f32_16x16x32_bf16 v[98:101], v[188:191], v[204:207], 0
	v_mfma_f32_16x16x32_bf16 v[90:93], v[180:183], v[212:215], 0
	v_mfma_f32_16x16x32_bf16 v[82:85], v[188:191], v[212:215], 0
	v_mfma_f32_16x16x32_bf16 v[74:77], v[180:183], v[220:223], 0
	v_mfma_f32_16x16x32_bf16 v[66:69], v[188:191], v[220:223], 0
	v_mfma_f32_16x16x32_bf16 v[126:129], v[184:187], v[200:203], v[126:129]
	v_mfma_f32_16x16x32_bf16 v[114:117], v[192:195], v[200:203], v[114:117]
	v_mfma_f32_16x16x32_bf16 v[106:109], v[184:187], v[208:211], v[106:109]
	v_mfma_f32_16x16x32_bf16 v[98:101], v[192:195], v[208:211], v[98:101]
	v_mfma_f32_16x16x32_bf16 v[90:93], v[184:187], v[216:219], v[90:93]
	v_mfma_f32_16x16x32_bf16 v[82:85], v[192:195], v[216:219], v[82:85]
	v_mfma_f32_16x16x32_bf16 v[74:77], v[184:187], v[224:227], v[74:77]
	v_mfma_f32_16x16x32_bf16 v[66:69], v[192:195], v[224:227], v[66:69]
	s_barrier
	s_setprio 0
	s_add_u32 s98, s96, 0xb0000
	s_addc_u32 s99, s97, 0
	s_add_i32 s6, s67, s23
	s_mov_b32 m0, s6
	s_nop 0
	global_load_lds_dwordx4 v132, s[96:97]
	s_add_i32 m0, s6, 0x2000
	s_add_i32 s6, s68, s23
	global_load_lds_dwordx4 v136, s[96:97]
	s_mov_b32 m0, s6
	s_nop 0
	global_load_lds_dwordx4 v132, s[98:99]
	s_add_i32 m0, s6, 0x2000
	s_nop 0
	global_load_lds_dwordx4 v136, s[98:99]
	s_mov_b32 m0, s46
	s_nop 0
	global_load_lds_dwordx4 v130, s[94:95]
	s_mov_b32 m0, s47
	s_nop 0
	global_load_lds_dwordx4 v134, s[94:95]
	ds_read_b128 v[196:199], v160 offset:16384
	ds_read_b128 v[200:203], v160 offset:17408
	ds_read_b128 v[204:207], v160 offset:18432
	ds_read_b128 v[208:211], v160 offset:19456
	ds_read_b128 v[212:215], v160 offset:20480
	ds_read_b128 v[216:219], v160 offset:21504
	ds_read_b128 v[220:223], v160 offset:22528
	ds_read_b128 v[224:227], v160 offset:23552
	s_waitcnt vmcnt(8)
	s_waitcnt lgkmcnt(0)
	s_setprio 1
	s_barrier
	v_mfma_f32_16x16x32_bf16 v[62:65], v[164:167], v[196:199], 0
	v_mfma_f32_16x16x32_bf16 v[54:57], v[172:175], v[196:199], 0
	v_mfma_f32_16x16x32_bf16 v[46:49], v[164:167], v[204:207], 0
	v_mfma_f32_16x16x32_bf16 v[38:41], v[172:175], v[204:207], 0
	v_mfma_f32_16x16x32_bf16 v[30:33], v[164:167], v[212:215], 0
	v_mfma_f32_16x16x32_bf16 v[22:25], v[172:175], v[212:215], 0
	v_mfma_f32_16x16x32_bf16 v[14:17], v[164:167], v[220:223], 0
	v_mfma_f32_16x16x32_bf16 v[6:9], v[172:175], v[220:223], 0
	v_mfma_f32_16x16x32_bf16 v[62:65], v[168:171], v[200:203], v[62:65]
	v_mfma_f32_16x16x32_bf16 v[54:57], v[176:179], v[200:203], v[54:57]
	v_mfma_f32_16x16x32_bf16 v[46:49], v[168:171], v[208:211], v[46:49]
	v_mfma_f32_16x16x32_bf16 v[38:41], v[176:179], v[208:211], v[38:41]
	v_mfma_f32_16x16x32_bf16 v[30:33], v[168:171], v[216:219], v[30:33]
	v_mfma_f32_16x16x32_bf16 v[22:25], v[176:179], v[216:219], v[22:25]
	v_mfma_f32_16x16x32_bf16 v[14:17], v[168:171], v[224:227], v[14:17]
	v_mfma_f32_16x16x32_bf16 v[6:9], v[176:179], v[224:227], v[6:9]
	s_setprio 0
	s_setprio 1
	v_mfma_f32_16x16x32_bf16 v[58:61], v[180:183], v[196:199], 0
	v_mfma_f32_16x16x32_bf16 v[50:53], v[188:191], v[196:199], 0
	v_mfma_f32_16x16x32_bf16 v[42:45], v[180:183], v[204:207], 0
	v_mfma_f32_16x16x32_bf16 v[34:37], v[188:191], v[204:207], 0
	v_mfma_f32_16x16x32_bf16 v[26:29], v[180:183], v[212:215], 0
	v_mfma_f32_16x16x32_bf16 v[18:21], v[188:191], v[212:215], 0
	v_mfma_f32_16x16x32_bf16 v[10:13], v[180:183], v[220:223], 0
	v_mfma_f32_16x16x32_bf16 v[2:5], v[188:191], v[220:223], 0
	v_mfma_f32_16x16x32_bf16 v[58:61], v[184:187], v[200:203], v[58:61]
	v_mfma_f32_16x16x32_bf16 v[50:53], v[192:195], v[200:203], v[50:53]
	v_mfma_f32_16x16x32_bf16 v[42:45], v[184:187], v[208:211], v[42:45]
	v_mfma_f32_16x16x32_bf16 v[34:37], v[192:195], v[208:211], v[34:37]
	v_mfma_f32_16x16x32_bf16 v[26:29], v[184:187], v[216:219], v[26:29]
	v_mfma_f32_16x16x32_bf16 v[18:21], v[192:195], v[216:219], v[18:21]
	v_mfma_f32_16x16x32_bf16 v[10:13], v[184:187], v[224:227], v[10:13]
	v_mfma_f32_16x16x32_bf16 v[2:5], v[192:195], v[224:227], v[2:5]
	s_barrier
	s_setprio 0
	s_add_u32 s98, s94, 0xb0000
	s_addc_u32 s99, s95, 0
	s_add_i32 s6, 0, 0x18000
	s_add_i32 s29, 0, 0x1c000
	s_mov_b32 m0, s48
	s_nop 0
	global_load_lds_dwordx4 v130, s[98:99]
	s_mov_b32 m0, s49
	s_nop 0
	global_load_lds_dwordx4 v134, s[98:99]
	ds_read_b128 v[164:167], v232
	ds_read_b128 v[168:171], v232 offset:1024
	ds_read_b128 v[172:175], v232 offset:2048
	ds_read_b128 v[176:179], v232 offset:3072
	ds_read_b128 v[180:183], v233
	ds_read_b128 v[184:187], v233 offset:1024
	ds_read_b128 v[188:191], v233 offset:2048
	ds_read_b128 v[192:195], v233 offset:3072
	ds_read_b128 v[196:199], v160 offset:32768
	ds_read_b128 v[200:203], v160 offset:33792
	ds_read_b128 v[204:207], v160 offset:34816
	ds_read_b128 v[208:211], v160 offset:35840
	ds_read_b128 v[212:215], v160 offset:36864
	ds_read_b128 v[216:219], v160 offset:37888
	ds_read_b128 v[220:223], v160 offset:38912
	ds_read_b128 v[224:227], v160 offset:39936
	s_waitcnt vmcnt(8)
	s_waitcnt lgkmcnt(0)
	s_setprio 1
	s_barrier
	v_mfma_f32_16x16x32_bf16 v[122:125], v[164:167], v[196:199], v[122:125]
	v_mfma_f32_16x16x32_bf16 v[118:121], v[172:175], v[196:199], v[118:121]
	v_mfma_f32_16x16x32_bf16 v[110:113], v[164:167], v[204:207], v[110:113]
	v_mfma_f32_16x16x32_bf16 v[102:105], v[172:175], v[204:207], v[102:105]
	v_mfma_f32_16x16x32_bf16 v[94:97], v[164:167], v[212:215], v[94:97]
	v_mfma_f32_16x16x32_bf16 v[86:89], v[172:175], v[212:215], v[86:89]
	v_mfma_f32_16x16x32_bf16 v[78:81], v[164:167], v[220:223], v[78:81]
	v_mfma_f32_16x16x32_bf16 v[70:73], v[172:175], v[220:223], v[70:73]
	v_mfma_f32_16x16x32_bf16 v[122:125], v[168:171], v[200:203], v[122:125]
	v_mfma_f32_16x16x32_bf16 v[118:121], v[176:179], v[200:203], v[118:121]
	v_mfma_f32_16x16x32_bf16 v[110:113], v[168:171], v[208:211], v[110:113]
	v_mfma_f32_16x16x32_bf16 v[102:105], v[176:179], v[208:211], v[102:105]
	v_mfma_f32_16x16x32_bf16 v[94:97], v[168:171], v[216:219], v[94:97]
	v_mfma_f32_16x16x32_bf16 v[86:89], v[176:179], v[216:219], v[86:89]
	v_mfma_f32_16x16x32_bf16 v[78:81], v[168:171], v[224:227], v[78:81]
	v_mfma_f32_16x16x32_bf16 v[70:73], v[176:179], v[224:227], v[70:73]
	s_setprio 0
	s_setprio 1
	v_mfma_f32_16x16x32_bf16 v[126:129], v[180:183], v[196:199], v[126:129]
	v_mfma_f32_16x16x32_bf16 v[114:117], v[188:191], v[196:199], v[114:117]
	v_mfma_f32_16x16x32_bf16 v[106:109], v[180:183], v[204:207], v[106:109]
	v_mfma_f32_16x16x32_bf16 v[98:101], v[188:191], v[204:207], v[98:101]
	v_mfma_f32_16x16x32_bf16 v[90:93], v[180:183], v[212:215], v[90:93]
	v_mfma_f32_16x16x32_bf16 v[82:85], v[188:191], v[212:215], v[82:85]
	v_mfma_f32_16x16x32_bf16 v[74:77], v[180:183], v[220:223], v[74:77]
	v_mfma_f32_16x16x32_bf16 v[66:69], v[188:191], v[220:223], v[66:69]
	v_mfma_f32_16x16x32_bf16 v[126:129], v[184:187], v[200:203], v[126:129]
	v_mfma_f32_16x16x32_bf16 v[114:117], v[192:195], v[200:203], v[114:117]
	v_mfma_f32_16x16x32_bf16 v[106:109], v[184:187], v[208:211], v[106:109]
	v_mfma_f32_16x16x32_bf16 v[98:101], v[192:195], v[208:211], v[98:101]
	v_mfma_f32_16x16x32_bf16 v[90:93], v[184:187], v[216:219], v[90:93]
	v_mfma_f32_16x16x32_bf16 v[82:85], v[192:195], v[216:219], v[82:85]
	v_mfma_f32_16x16x32_bf16 v[74:77], v[184:187], v[224:227], v[74:77]
	v_mfma_f32_16x16x32_bf16 v[66:69], v[192:195], v[224:227], v[66:69]
	s_barrier
	s_setprio 0
	s_add_u32 s96, s96, 0x80
	s_addc_u32 s97, s97, 0
	s_add_u32 s98, s96, 0xb0000
	s_addc_u32 s99, s97, 0
	s_add_u32 s94, s94, 0x80
	s_addc_u32 s95, s95, 0
	s_add_i32 s6, s6, s23
	s_mov_b32 m0, s6
	s_nop 0
	global_load_lds_dwordx4 v132, s[96:97]
	s_add_i32 m0, s6, 0x2000
	s_add_i32 s6, s29, s23
	global_load_lds_dwordx4 v136, s[96:97]
	s_mov_b32 m0, s6
	s_nop 0
	global_load_lds_dwordx4 v132, s[98:99]
	s_add_i32 m0, s6, 0x2000
	s_nop 0
	global_load_lds_dwordx4 v136, s[98:99]
	s_mov_b32 m0, s59
	s_nop 0
	global_load_lds_dwordx4 v130, s[94:95]
	s_mov_b32 m0, s60
	s_nop 0
	global_load_lds_dwordx4 v134, s[94:95]
	ds_read_b128 v[196:199], v160 offset:49152
	ds_read_b128 v[200:203], v160 offset:50176
	ds_read_b128 v[204:207], v160 offset:51200
	ds_read_b128 v[208:211], v160 offset:52224
	ds_read_b128 v[212:215], v160 offset:53248
	ds_read_b128 v[216:219], v160 offset:54272
	ds_read_b128 v[220:223], v160 offset:55296
	ds_read_b128 v[224:227], v160 offset:56320
	s_waitcnt vmcnt(8)
	s_waitcnt lgkmcnt(0)
	s_setprio 1
	s_barrier
	v_mfma_f32_16x16x32_bf16 v[62:65], v[164:167], v[196:199], v[62:65]
	v_mfma_f32_16x16x32_bf16 v[54:57], v[172:175], v[196:199], v[54:57]
	v_mfma_f32_16x16x32_bf16 v[46:49], v[164:167], v[204:207], v[46:49]
	v_mfma_f32_16x16x32_bf16 v[38:41], v[172:175], v[204:207], v[38:41]
	v_mfma_f32_16x16x32_bf16 v[30:33], v[164:167], v[212:215], v[30:33]
	v_mfma_f32_16x16x32_bf16 v[22:25], v[172:175], v[212:215], v[22:25]
	v_mfma_f32_16x16x32_bf16 v[14:17], v[164:167], v[220:223], v[14:17]
	v_mfma_f32_16x16x32_bf16 v[6:9], v[172:175], v[220:223], v[6:9]
	v_mfma_f32_16x16x32_bf16 v[62:65], v[168:171], v[200:203], v[62:65]
	v_mfma_f32_16x16x32_bf16 v[54:57], v[176:179], v[200:203], v[54:57]
	v_mfma_f32_16x16x32_bf16 v[46:49], v[168:171], v[208:211], v[46:49]
	v_mfma_f32_16x16x32_bf16 v[38:41], v[176:179], v[208:211], v[38:41]
	v_mfma_f32_16x16x32_bf16 v[30:33], v[168:171], v[216:219], v[30:33]
	v_mfma_f32_16x16x32_bf16 v[22:25], v[176:179], v[216:219], v[22:25]
	v_mfma_f32_16x16x32_bf16 v[14:17], v[168:171], v[224:227], v[14:17]
	v_mfma_f32_16x16x32_bf16 v[6:9], v[176:179], v[224:227], v[6:9]
	s_setprio 0
	s_setprio 1
	v_mfma_f32_16x16x32_bf16 v[58:61], v[180:183], v[196:199], v[58:61]
	v_mfma_f32_16x16x32_bf16 v[50:53], v[188:191], v[196:199], v[50:53]
	v_mfma_f32_16x16x32_bf16 v[42:45], v[180:183], v[204:207], v[42:45]
	v_mfma_f32_16x16x32_bf16 v[34:37], v[188:191], v[204:207], v[34:37]
	v_mfma_f32_16x16x32_bf16 v[26:29], v[180:183], v[212:215], v[26:29]
	v_mfma_f32_16x16x32_bf16 v[18:21], v[188:191], v[212:215], v[18:21]
	v_mfma_f32_16x16x32_bf16 v[10:13], v[180:183], v[220:223], v[10:13]
	v_mfma_f32_16x16x32_bf16 v[2:5], v[188:191], v[220:223], v[2:5]
	v_mfma_f32_16x16x32_bf16 v[58:61], v[184:187], v[200:203], v[58:61]
	v_mfma_f32_16x16x32_bf16 v[50:53], v[192:195], v[200:203], v[50:53]
	v_mfma_f32_16x16x32_bf16 v[42:45], v[184:187], v[208:211], v[42:45]
	v_mfma_f32_16x16x32_bf16 v[34:37], v[192:195], v[208:211], v[34:37]
	v_mfma_f32_16x16x32_bf16 v[26:29], v[184:187], v[216:219], v[26:29]
	v_mfma_f32_16x16x32_bf16 v[18:21], v[192:195], v[216:219], v[18:21]
	v_mfma_f32_16x16x32_bf16 v[10:13], v[184:187], v[224:227], v[10:13]
	v_mfma_f32_16x16x32_bf16 v[2:5], v[192:195], v[224:227], v[2:5]
	s_barrier
	s_setprio 0
	s_mov_b32 s6, s7
	s_add_u32 s88, s88, 0x100
	s_addc_u32 s89, s89, 0
	s_add_u32 s86, s86, 0x100
	s_addc_u32 s87, s87, 0
	s_cmp_ge_i32 s7, s101
	s_cbranch_scc1 .Lmy_kexit_5
.LBB0_1080:
	s_add_u32 s98, s86, 0x100
	s_addc_u32 s99, s87, 0
	s_cmp_eq_u32 s6, s100
	s_cselect_b64 s[94:95], s[90:91], s[98:99]
	s_cselect_b64 s[96:97], s[92:93], s[88:89]
	s_add_i32 s7, s6, 2
	s_nop 0
	s_add_i32 m0, s46, 0xc000
	s_nop 0
	global_load_lds_dwordx4 v144, s[86:87]
	s_add_i32 m0, s46, 0xe000
	s_nop 0
	global_load_lds_dwordx4 v142, s[86:87]
	ds_read_b128 v[164:167], v230
	ds_read_b128 v[168:171], v230 offset:1024
	ds_read_b128 v[172:175], v230 offset:2048
	ds_read_b128 v[176:179], v230 offset:3072
	ds_read_b128 v[180:183], v231
	ds_read_b128 v[184:187], v231 offset:1024
	ds_read_b128 v[188:191], v231 offset:2048
	ds_read_b128 v[192:195], v231 offset:3072
	ds_read_b128 v[196:199], v160
	ds_read_b128 v[200:203], v160 offset:1024
	ds_read_b128 v[204:207], v160 offset:2048
	ds_read_b128 v[208:211], v160 offset:3072
	ds_read_b128 v[212:215], v160 offset:4096
	ds_read_b128 v[216:219], v160 offset:5120
	ds_read_b128 v[220:223], v160 offset:6144
	ds_read_b128 v[224:227], v160 offset:7168
	s_waitcnt vmcnt(8)
	s_waitcnt lgkmcnt(0)
	s_setprio 1
	s_barrier
	v_mfma_f32_16x16x32_bf16 v[122:125], v[164:167], v[196:199], v[122:125]
	v_mfma_f32_16x16x32_bf16 v[118:121], v[172:175], v[196:199], v[118:121]
	v_mfma_f32_16x16x32_bf16 v[110:113], v[164:167], v[204:207], v[110:113]
	v_mfma_f32_16x16x32_bf16 v[102:105], v[172:175], v[204:207], v[102:105]
	v_mfma_f32_16x16x32_bf16 v[94:97], v[164:167], v[212:215], v[94:97]
	v_mfma_f32_16x16x32_bf16 v[86:89], v[172:175], v[212:215], v[86:89]
	v_mfma_f32_16x16x32_bf16 v[78:81], v[164:167], v[220:223], v[78:81]
	v_mfma_f32_16x16x32_bf16 v[70:73], v[172:175], v[220:223], v[70:73]
	v_mfma_f32_16x16x32_bf16 v[122:125], v[168:171], v[200:203], v[122:125]
	v_mfma_f32_16x16x32_bf16 v[118:121], v[176:179], v[200:203], v[118:121]
	v_mfma_f32_16x16x32_bf16 v[110:113], v[168:171], v[208:211], v[110:113]
	v_mfma_f32_16x16x32_bf16 v[102:105], v[176:179], v[208:211], v[102:105]
	v_mfma_f32_16x16x32_bf16 v[94:97], v[168:171], v[216:219], v[94:97]
	v_mfma_f32_16x16x32_bf16 v[86:89], v[176:179], v[216:219], v[86:89]
	v_mfma_f32_16x16x32_bf16 v[78:81], v[168:171], v[224:227], v[78:81]
	v_mfma_f32_16x16x32_bf16 v[70:73], v[176:179], v[224:227], v[70:73]
	s_setprio 0
	s_setprio 1
	v_mfma_f32_16x16x32_bf16 v[126:129], v[180:183], v[196:199], v[126:129]
	v_mfma_f32_16x16x32_bf16 v[114:117], v[188:191], v[196:199], v[114:117]
	v_mfma_f32_16x16x32_bf16 v[106:109], v[180:183], v[204:207], v[106:109]
	v_mfma_f32_16x16x32_bf16 v[98:101], v[188:191], v[204:207], v[98:101]
	v_mfma_f32_16x16x32_bf16 v[90:93], v[180:183], v[212:215], v[90:93]
	v_mfma_f32_16x16x32_bf16 v[82:85], v[188:191], v[212:215], v[82:85]
	v_mfma_f32_16x16x32_bf16 v[74:77], v[180:183], v[220:223], v[74:77]
	v_mfma_f32_16x16x32_bf16 v[66:69], v[188:191], v[220:223], v[66:69]
	v_mfma_f32_16x16x32_bf16 v[126:129], v[184:187], v[200:203], v[126:129]
	v_mfma_f32_16x16x32_bf16 v[114:117], v[192:195], v[200:203], v[114:117]
	v_mfma_f32_16x16x32_bf16 v[106:109], v[184:187], v[208:211], v[106:109]
	v_mfma_f32_16x16x32_bf16 v[98:101], v[192:195], v[208:211], v[98:101]
	v_mfma_f32_16x16x32_bf16 v[90:93], v[184:187], v[216:219], v[90:93]
	v_mfma_f32_16x16x32_bf16 v[82:85], v[192:195], v[216:219], v[82:85]
	v_mfma_f32_16x16x32_bf16 v[74:77], v[184:187], v[224:227], v[74:77]
	v_mfma_f32_16x16x32_bf16 v[66:69], v[192:195], v[224:227], v[66:69]
	s_barrier
	s_setprio 0
	s_add_u32 s98, s96, 0xb0000
	s_addc_u32 s99, s97, 0
	s_add_i32 s6, s67, s23
	s_mov_b32 m0, s6
	s_nop 0
	global_load_lds_dwordx4 v132, s[96:97]
	s_add_i32 m0, s6, 0x2000
	s_add_i32 s6, s68, s23
	global_load_lds_dwordx4 v136, s[96:97]
	s_mov_b32 m0, s6
	s_nop 0
	global_load_lds_dwordx4 v132, s[98:99]
	s_add_i32 m0, s6, 0x2000
	s_nop 0
	global_load_lds_dwordx4 v136, s[98:99]
	s_mov_b32 m0, s46
	s_nop 0
	global_load_lds_dwordx4 v130, s[94:95]
	s_mov_b32 m0, s47
	s_nop 0
	global_load_lds_dwordx4 v134, s[94:95]
	ds_read_b128 v[196:199], v160 offset:16384
	ds_read_b128 v[200:203], v160 offset:17408
	ds_read_b128 v[204:207], v160 offset:18432
	ds_read_b128 v[208:211], v160 offset:19456
	ds_read_b128 v[212:215], v160 offset:20480
	ds_read_b128 v[216:219], v160 offset:21504
	ds_read_b128 v[220:223], v160 offset:22528
	ds_read_b128 v[224:227], v160 offset:23552
	s_waitcnt vmcnt(8)
	s_waitcnt lgkmcnt(0)
	s_setprio 1
	s_barrier
	v_mfma_f32_16x16x32_bf16 v[62:65], v[164:167], v[196:199], v[62:65]
	v_mfma_f32_16x16x32_bf16 v[54:57], v[172:175], v[196:199], v[54:57]
	v_mfma_f32_16x16x32_bf16 v[46:49], v[164:167], v[204:207], v[46:49]
	v_mfma_f32_16x16x32_bf16 v[38:41], v[172:175], v[204:207], v[38:41]
	v_mfma_f32_16x16x32_bf16 v[30:33], v[164:167], v[212:215], v[30:33]
	v_mfma_f32_16x16x32_bf16 v[22:25], v[172:175], v[212:215], v[22:25]
	v_mfma_f32_16x16x32_bf16 v[14:17], v[164:167], v[220:223], v[14:17]
	v_mfma_f32_16x16x32_bf16 v[6:9], v[172:175], v[220:223], v[6:9]
	v_mfma_f32_16x16x32_bf16 v[62:65], v[168:171], v[200:203], v[62:65]
	v_mfma_f32_16x16x32_bf16 v[54:57], v[176:179], v[200:203], v[54:57]
	v_mfma_f32_16x16x32_bf16 v[46:49], v[168:171], v[208:211], v[46:49]
	v_mfma_f32_16x16x32_bf16 v[38:41], v[176:179], v[208:211], v[38:41]
	v_mfma_f32_16x16x32_bf16 v[30:33], v[168:171], v[216:219], v[30:33]
	v_mfma_f32_16x16x32_bf16 v[22:25], v[176:179], v[216:219], v[22:25]
	v_mfma_f32_16x16x32_bf16 v[14:17], v[168:171], v[224:227], v[14:17]
	v_mfma_f32_16x16x32_bf16 v[6:9], v[176:179], v[224:227], v[6:9]
	s_setprio 0
	s_setprio 1
	v_mfma_f32_16x16x32_bf16 v[58:61], v[180:183], v[196:199], v[58:61]
	v_mfma_f32_16x16x32_bf16 v[50:53], v[188:191], v[196:199], v[50:53]
	v_mfma_f32_16x16x32_bf16 v[42:45], v[180:183], v[204:207], v[42:45]
	v_mfma_f32_16x16x32_bf16 v[34:37], v[188:191], v[204:207], v[34:37]
	v_mfma_f32_16x16x32_bf16 v[26:29], v[180:183], v[212:215], v[26:29]
	v_mfma_f32_16x16x32_bf16 v[18:21], v[188:191], v[212:215], v[18:21]
	v_mfma_f32_16x16x32_bf16 v[10:13], v[180:183], v[220:223], v[10:13]
	v_mfma_f32_16x16x32_bf16 v[2:5], v[188:191], v[220:223], v[2:5]
	v_mfma_f32_16x16x32_bf16 v[58:61], v[184:187], v[200:203], v[58:61]
	v_mfma_f32_16x16x32_bf16 v[50:53], v[192:195], v[200:203], v[50:53]
	v_mfma_f32_16x16x32_bf16 v[42:45], v[184:187], v[208:211], v[42:45]
	v_mfma_f32_16x16x32_bf16 v[34:37], v[192:195], v[208:211], v[34:37]
	v_mfma_f32_16x16x32_bf16 v[26:29], v[184:187], v[216:219], v[26:29]
	v_mfma_f32_16x16x32_bf16 v[18:21], v[192:195], v[216:219], v[18:21]
	v_mfma_f32_16x16x32_bf16 v[10:13], v[184:187], v[224:227], v[10:13]
	v_mfma_f32_16x16x32_bf16 v[2:5], v[192:195], v[224:227], v[2:5]
	s_barrier
	s_setprio 0
	s_add_u32 s98, s94, 0xb0000
	s_addc_u32 s99, s95, 0
	s_add_i32 s6, 0, 0x18000
	s_add_i32 s29, 0, 0x1c000
	s_mov_b32 m0, s48
	s_nop 0
	global_load_lds_dwordx4 v130, s[98:99]
	s_mov_b32 m0, s49
	s_nop 0
	global_load_lds_dwordx4 v134, s[98:99]
	ds_read_b128 v[164:167], v232
	ds_read_b128 v[168:171], v232 offset:1024
	ds_read_b128 v[172:175], v232 offset:2048
	ds_read_b128 v[176:179], v232 offset:3072
	ds_read_b128 v[180:183], v233
	ds_read_b128 v[184:187], v233 offset:1024
	ds_read_b128 v[188:191], v233 offset:2048
	ds_read_b128 v[192:195], v233 offset:3072
	ds_read_b128 v[196:199], v160 offset:32768
	ds_read_b128 v[200:203], v160 offset:33792
	ds_read_b128 v[204:207], v160 offset:34816
	ds_read_b128 v[208:211], v160 offset:35840
	ds_read_b128 v[212:215], v160 offset:36864
	ds_read_b128 v[216:219], v160 offset:37888
	ds_read_b128 v[220:223], v160 offset:38912
	ds_read_b128 v[224:227], v160 offset:39936
	s_waitcnt vmcnt(8)
	s_waitcnt lgkmcnt(0)
	s_setprio 1
	s_barrier
	v_mfma_f32_16x16x32_bf16 v[122:125], v[164:167], v[196:199], v[122:125]
	v_mfma_f32_16x16x32_bf16 v[118:121], v[172:175], v[196:199], v[118:121]
	v_mfma_f32_16x16x32_bf16 v[110:113], v[164:167], v[204:207], v[110:113]
	v_mfma_f32_16x16x32_bf16 v[102:105], v[172:175], v[204:207], v[102:105]
	v_mfma_f32_16x16x32_bf16 v[94:97], v[164:167], v[212:215], v[94:97]
	v_mfma_f32_16x16x32_bf16 v[86:89], v[172:175], v[212:215], v[86:89]
	v_mfma_f32_16x16x32_bf16 v[78:81], v[164:167], v[220:223], v[78:81]
	v_mfma_f32_16x16x32_bf16 v[70:73], v[172:175], v[220:223], v[70:73]
	v_mfma_f32_16x16x32_bf16 v[122:125], v[168:171], v[200:203], v[122:125]
	v_mfma_f32_16x16x32_bf16 v[118:121], v[176:179], v[200:203], v[118:121]
	v_mfma_f32_16x16x32_bf16 v[110:113], v[168:171], v[208:211], v[110:113]
	v_mfma_f32_16x16x32_bf16 v[102:105], v[176:179], v[208:211], v[102:105]
	v_mfma_f32_16x16x32_bf16 v[94:97], v[168:171], v[216:219], v[94:97]
	v_mfma_f32_16x16x32_bf16 v[86:89], v[176:179], v[216:219], v[86:89]
	v_mfma_f32_16x16x32_bf16 v[78:81], v[168:171], v[224:227], v[78:81]
	v_mfma_f32_16x16x32_bf16 v[70:73], v[176:179], v[224:227], v[70:73]
	s_setprio 0
	s_setprio 1
	v_mfma_f32_16x16x32_bf16 v[126:129], v[180:183], v[196:199], v[126:129]
	v_mfma_f32_16x16x32_bf16 v[114:117], v[188:191], v[196:199], v[114:117]
	v_mfma_f32_16x16x32_bf16 v[106:109], v[180:183], v[204:207], v[106:109]
	v_mfma_f32_16x16x32_bf16 v[98:101], v[188:191], v[204:207], v[98:101]
	v_mfma_f32_16x16x32_bf16 v[90:93], v[180:183], v[212:215], v[90:93]
	v_mfma_f32_16x16x32_bf16 v[82:85], v[188:191], v[212:215], v[82:85]
	v_mfma_f32_16x16x32_bf16 v[74:77], v[180:183], v[220:223], v[74:77]
	v_mfma_f32_16x16x32_bf16 v[66:69], v[188:191], v[220:223], v[66:69]
	v_mfma_f32_16x16x32_bf16 v[126:129], v[184:187], v[200:203], v[126:129]
	v_mfma_f32_16x16x32_bf16 v[114:117], v[192:195], v[200:203], v[114:117]
	v_mfma_f32_16x16x32_bf16 v[106:109], v[184:187], v[208:211], v[106:109]
	v_mfma_f32_16x16x32_bf16 v[98:101], v[192:195], v[208:211], v[98:101]
	v_mfma_f32_16x16x32_bf16 v[90:93], v[184:187], v[216:219], v[90:93]
	v_mfma_f32_16x16x32_bf16 v[82:85], v[192:195], v[216:219], v[82:85]
	v_mfma_f32_16x16x32_bf16 v[74:77], v[184:187], v[224:227], v[74:77]
	v_mfma_f32_16x16x32_bf16 v[66:69], v[192:195], v[224:227], v[66:69]
	s_barrier
	s_setprio 0
	s_add_u32 s96, s96, 0x80
	s_addc_u32 s97, s97, 0
	s_add_u32 s98, s96, 0xb0000
	s_addc_u32 s99, s97, 0
	s_add_u32 s94, s94, 0x80
	s_addc_u32 s95, s95, 0
	s_add_i32 s6, s6, s23
	s_mov_b32 m0, s6
	s_nop 0
	global_load_lds_dwordx4 v132, s[96:97]
	s_add_i32 m0, s6, 0x2000
	s_add_i32 s6, s29, s23
	global_load_lds_dwordx4 v136, s[96:97]
	s_mov_b32 m0, s6
	s_nop 0
	global_load_lds_dwordx4 v132, s[98:99]
	s_add_i32 m0, s6, 0x2000
	s_nop 0
	global_load_lds_dwordx4 v136, s[98:99]
	s_mov_b32 m0, s59
	s_nop 0
	global_load_lds_dwordx4 v130, s[94:95]
	s_mov_b32 m0, s60
	s_nop 0
	global_load_lds_dwordx4 v134, s[94:95]
	ds_read_b128 v[196:199], v160 offset:49152
	ds_read_b128 v[200:203], v160 offset:50176
	ds_read_b128 v[204:207], v160 offset:51200
	ds_read_b128 v[208:211], v160 offset:52224
	ds_read_b128 v[212:215], v160 offset:53248
	ds_read_b128 v[216:219], v160 offset:54272
	ds_read_b128 v[220:223], v160 offset:55296
	ds_read_b128 v[224:227], v160 offset:56320
	s_waitcnt vmcnt(8)
	s_waitcnt lgkmcnt(0)
	s_setprio 1
	s_barrier
	v_mfma_f32_16x16x32_bf16 v[62:65], v[164:167], v[196:199], v[62:65]
	v_mfma_f32_16x16x32_bf16 v[54:57], v[172:175], v[196:199], v[54:57]
	v_mfma_f32_16x16x32_bf16 v[46:49], v[164:167], v[204:207], v[46:49]
	v_mfma_f32_16x16x32_bf16 v[38:41], v[172:175], v[204:207], v[38:41]
	v_mfma_f32_16x16x32_bf16 v[30:33], v[164:167], v[212:215], v[30:33]
	v_mfma_f32_16x16x32_bf16 v[22:25], v[172:175], v[212:215], v[22:25]
	v_mfma_f32_16x16x32_bf16 v[14:17], v[164:167], v[220:223], v[14:17]
	v_mfma_f32_16x16x32_bf16 v[6:9], v[172:175], v[220:223], v[6:9]
	v_mfma_f32_16x16x32_bf16 v[62:65], v[168:171], v[200:203], v[62:65]
	v_mfma_f32_16x16x32_bf16 v[54:57], v[176:179], v[200:203], v[54:57]
	v_mfma_f32_16x16x32_bf16 v[46:49], v[168:171], v[208:211], v[46:49]
	v_mfma_f32_16x16x32_bf16 v[38:41], v[176:179], v[208:211], v[38:41]
	v_mfma_f32_16x16x32_bf16 v[30:33], v[168:171], v[216:219], v[30:33]
	v_mfma_f32_16x16x32_bf16 v[22:25], v[176:179], v[216:219], v[22:25]
	v_mfma_f32_16x16x32_bf16 v[14:17], v[168:171], v[224:227], v[14:17]
	v_mfma_f32_16x16x32_bf16 v[6:9], v[176:179], v[224:227], v[6:9]
	s_setprio 0
	s_setprio 1
	v_mfma_f32_16x16x32_bf16 v[58:61], v[180:183], v[196:199], v[58:61]
	v_mfma_f32_16x16x32_bf16 v[50:53], v[188:191], v[196:199], v[50:53]
	v_mfma_f32_16x16x32_bf16 v[42:45], v[180:183], v[204:207], v[42:45]
	v_mfma_f32_16x16x32_bf16 v[34:37], v[188:191], v[204:207], v[34:37]
	v_mfma_f32_16x16x32_bf16 v[26:29], v[180:183], v[212:215], v[26:29]
	v_mfma_f32_16x16x32_bf16 v[18:21], v[188:191], v[212:215], v[18:21]
	v_mfma_f32_16x16x32_bf16 v[10:13], v[180:183], v[220:223], v[10:13]
	v_mfma_f32_16x16x32_bf16 v[2:5], v[188:191], v[220:223], v[2:5]
	v_mfma_f32_16x16x32_bf16 v[58:61], v[184:187], v[200:203], v[58:61]
	v_mfma_f32_16x16x32_bf16 v[50:53], v[192:195], v[200:203], v[50:53]
	v_mfma_f32_16x16x32_bf16 v[42:45], v[184:187], v[208:211], v[42:45]
	v_mfma_f32_16x16x32_bf16 v[34:37], v[192:195], v[208:211], v[34:37]
	v_mfma_f32_16x16x32_bf16 v[26:29], v[184:187], v[216:219], v[26:29]
	v_mfma_f32_16x16x32_bf16 v[18:21], v[192:195], v[216:219], v[18:21]
	v_mfma_f32_16x16x32_bf16 v[10:13], v[184:187], v[224:227], v[10:13]
	v_mfma_f32_16x16x32_bf16 v[2:5], v[192:195], v[224:227], v[2:5]
	s_barrier
	s_setprio 0
	s_mov_b32 s6, s7
	s_add_u32 s88, s88, 0x100
	s_addc_u32 s89, s89, 0
	s_add_u32 s86, s86, 0x100
	s_addc_u32 s87, s87, 0
	s_cmp_ge_i32 s7, s101
	s_cbranch_scc0 .LBB0_1080

.LBB0_1390:
	v_cmp_gt_i32_e32 vcc, 1, v156
	s_cbranch_vccnz .LBB0_1452
	v_lshl_add_u64 v[152:153], v[2:3], 0, s[20:21]
	v_add_u32_e32 v138, -2, v156
	s_mov_b32 s6, 0
	s_nop 0
	v_readfirstlane_b32 s86, v150
	v_readfirstlane_b32 s87, v151
	v_readfirstlane_b32 s88, v152
	v_readfirstlane_b32 s89, v153
	v_readfirstlane_b32 s90, v146
	v_readfirstlane_b32 s91, v147
	v_readfirstlane_b32 s92, v148
	v_readfirstlane_b32 s93, v149
	v_readfirstlane_b32 s100, v138
	v_readfirstlane_b32 s101, v156
	v_add_u32_e32 v230, s67, v141
	v_add_u32_e32 v231, s70, v141
	v_add_u32_e32 v232, 0x18000, v141
	v_add_u32_e32 v233, 0x1c000, v141
	s_add_u32 s98, s86, 0x100
	s_addc_u32 s99, s87, 0
	s_cmp_eq_u32 s6, s100
	s_cselect_b64 s[94:95], s[90:91], s[98:99]
	s_cselect_b64 s[96:97], s[92:93], s[88:89]
	s_add_i32 s7, s6, 2
	s_nop 0
	s_add_i32 m0, s46, 0xc000
	s_nop 0
	global_load_lds_dwordx4 v144, s[86:87]
	s_add_i32 m0, s46, 0xe000
	s_nop 0
	global_load_lds_dwordx4 v142, s[86:87]
	ds_read_b128 v[164:167], v230
	ds_read_b128 v[168:171], v230 offset:1024
	ds_read_b128 v[172:175], v230 offset:2048
	ds_read_b128 v[176:179], v230 offset:3072
	ds_read_b128 v[180:183], v231
	ds_read_b128 v[184:187], v231 offset:1024
	ds_read_b128 v[188:191], v231 offset:2048
	ds_read_b128 v[192:195], v231 offset:3072
	ds_read_b128 v[196:199], v160
	ds_read_b128 v[200:203], v160 offset:1024
	ds_read_b128 v[204:207], v160 offset:2048
	ds_read_b128 v[208:211], v160 offset:3072
	ds_read_b128 v[212:215], v160 offset:4096
	ds_read_b128 v[216:219], v160 offset:5120
	ds_read_b128 v[220:223], v160 offset:6144
	ds_read_b128 v[224:227], v160 offset:7168
	s_waitcnt vmcnt(8)
	s_waitcnt lgkmcnt(0)
	s_setprio 1
	s_barrier
	v_mfma_f32_16x16x32_bf16 v[122:125], v[164:167], v[196:199], 0
	v_mfma_f32_16x16x32_bf16 v[118:121], v[172:175], v[196:199], 0
	v_mfma_f32_16x16x32_bf16 v[110:113], v[164:167], v[204:207], 0
	v_mfma_f32_16x16x32_bf16 v[102:105], v[172:175], v[204:207], 0
	v_mfma_f32_16x16x32_bf16 v[94:97], v[164:167], v[212:215], 0
	v_mfma_f32_16x16x32_bf16 v[86:89], v[172:175], v[212:215], 0
	v_mfma_f32_16x16x32_bf16 v[78:81], v[164:167], v[220:223], 0
	v_mfma_f32_16x16x32_bf16 v[70:73], v[172:175], v[220:223], 0
	v_mfma_f32_16x16x32_bf16 v[122:125], v[168:171], v[200:203], v[122:125]
	v_mfma_f32_16x16x32_bf16 v[118:121], v[176:179], v[200:203], v[118:121]
	v_mfma_f32_16x16x32_bf16 v[110:113], v[168:171], v[208:211], v[110:113]
	v_mfma_f32_16x16x32_bf16 v[102:105], v[176:179], v[208:211], v[102:105]
	v_mfma_f32_16x16x32_bf16 v[94:97], v[168:171], v[216:219], v[94:97]
	v_mfma_f32_16x16x32_bf16 v[86:89], v[176:179], v[216:219], v[86:89]
	v_mfma_f32_16x16x32_bf16 v[78:81], v[168:171], v[224:227], v[78:81]
	v_mfma_f32_16x16x32_bf16 v[70:73], v[176:179], v[224:227], v[70:73]
	s_setprio 0
	s_setprio 1
	v_mfma_f32_16x16x32_bf16 v[126:129], v[180:183], v[196:199], 0
	v_mfma_f32_16x16x32_bf16 v[114:117], v[188:191], v[196:199], 0
	v_mfma_f32_16x16x32_bf16 v[106:109], v[180:183], v[204:207], 0
	v_mfma_f32_16x16x32_bf16 v[98:101], v[188:191], v[204:207], 0
	v_mfma_f32_16x16x32_bf16 v[90:93], v[180:183], v[212:215], 0
	v_mfma_f32_16x16x32_bf16 v[82:85], v[188:191], v[212:215], 0
	v_mfma_f32_16x16x32_bf16 v[74:77], v[180:183], v[220:223], 0
	v_mfma_f32_16x16x32_bf16 v[66:69], v[188:191], v[220:223], 0
	v_mfma_f32_16x16x32_bf16 v[126:129], v[184:187], v[200:203], v[126:129]
	v_mfma_f32_16x16x32_bf16 v[114:117], v[192:195], v[200:203], v[114:117]
	v_mfma_f32_16x16x32_bf16 v[106:109], v[184:187], v[208:211], v[106:109]
	v_mfma_f32_16x16x32_bf16 v[98:101], v[192:195], v[208:211], v[98:101]
	v_mfma_f32_16x16x32_bf16 v[90:93], v[184:187], v[216:219], v[90:93]
	v_mfma_f32_16x16x32_bf16 v[82:85], v[192:195], v[216:219], v[82:85]
	v_mfma_f32_16x16x32_bf16 v[74:77], v[184:187], v[224:227], v[74:77]
	v_mfma_f32_16x16x32_bf16 v[66:69], v[192:195], v[224:227], v[66:69]
	s_barrier
	s_setprio 0
	s_add_u32 s98, s96, 0xb0000
	s_addc_u32 s99, s97, 0
	s_add_i32 s6, s67, s23
	s_mov_b32 m0, s6
	s_nop 0
	global_load_lds_dwordx4 v132, s[96:97]
	s_add_i32 m0, s6, 0x2000
	s_add_i32 s6, s70, s23
	global_load_lds_dwordx4 v136, s[96:97]
	s_mov_b32 m0, s6
	s_nop 0
	global_load_lds_dwordx4 v132, s[98:99]
	s_add_i32 m0, s6, 0x2000
	s_nop 0
	global_load_lds_dwordx4 v136, s[98:99]
	s_mov_b32 m0, s46
	s_nop 0
	global_load_lds_dwordx4 v130, s[94:95]
	s_mov_b32 m0, s47
	s_nop 0
	global_load_lds_dwordx4 v134, s[94:95]
	ds_read_b128 v[196:199], v160 offset:16384
	ds_read_b128 v[200:203], v160 offset:17408
	ds_read_b128 v[204:207], v160 offset:18432
	ds_read_b128 v[208:211], v160 offset:19456
	ds_read_b128 v[212:215], v160 offset:20480
	ds_read_b128 v[216:219], v160 offset:21504
	ds_read_b128 v[220:223], v160 offset:22528
	ds_read_b128 v[224:227], v160 offset:23552
	s_waitcnt vmcnt(8)
	s_waitcnt lgkmcnt(0)
	s_setprio 1
	s_barrier
	v_mfma_f32_16x16x32_bf16 v[62:65], v[164:167], v[196:199], 0
	v_mfma_f32_16x16x32_bf16 v[54:57], v[172:175], v[196:199], 0
	v_mfma_f32_16x16x32_bf16 v[46:49], v[164:167], v[204:207], 0
	v_mfma_f32_16x16x32_bf16 v[38:41], v[172:175], v[204:207], 0
	v_mfma_f32_16x16x32_bf16 v[30:33], v[164:167], v[212:215], 0
	v_mfma_f32_16x16x32_bf16 v[22:25], v[172:175], v[212:215], 0
	v_mfma_f32_16x16x32_bf16 v[14:17], v[164:167], v[220:223], 0
	v_mfma_f32_16x16x32_bf16 v[6:9], v[172:175], v[220:223], 0
	v_mfma_f32_16x16x32_bf16 v[62:65], v[168:171], v[200:203], v[62:65]
	v_mfma_f32_16x16x32_bf16 v[54:57], v[176:179], v[200:203], v[54:57]
	v_mfma_f32_16x16x32_bf16 v[46:49], v[168:171], v[208:211], v[46:49]
	v_mfma_f32_16x16x32_bf16 v[38:41], v[176:179], v[208:211], v[38:41]
	v_mfma_f32_16x16x32_bf16 v[30:33], v[168:171], v[216:219], v[30:33]
	v_mfma_f32_16x16x32_bf16 v[22:25], v[176:179], v[216:219], v[22:25]
	v_mfma_f32_16x16x32_bf16 v[14:17], v[168:171], v[224:227], v[14:17]
	v_mfma_f32_16x16x32_bf16 v[6:9], v[176:179], v[224:227], v[6:9]
	s_setprio 0
	s_setprio 1
	v_mfma_f32_16x16x32_bf16 v[58:61], v[180:183], v[196:199], 0
	v_mfma_f32_16x16x32_bf16 v[50:53], v[188:191], v[196:199], 0
	v_mfma_f32_16x16x32_bf16 v[42:45], v[180:183], v[204:207], 0
	v_mfma_f32_16x16x32_bf16 v[34:37], v[188:191], v[204:207], 0
	v_mfma_f32_16x16x32_bf16 v[26:29], v[180:183], v[212:215], 0
	v_mfma_f32_16x16x32_bf16 v[18:21], v[188:191], v[212:215], 0
	v_mfma_f32_16x16x32_bf16 v[10:13], v[180:183], v[220:223], 0
	v_mfma_f32_16x16x32_bf16 v[2:5], v[188:191], v[220:223], 0
	v_mfma_f32_16x16x32_bf16 v[58:61], v[184:187], v[200:203], v[58:61]
	v_mfma_f32_16x16x32_bf16 v[50:53], v[192:195], v[200:203], v[50:53]
	v_mfma_f32_16x16x32_bf16 v[42:45], v[184:187], v[208:211], v[42:45]
	v_mfma_f32_16x16x32_bf16 v[34:37], v[192:195], v[208:211], v[34:37]
	v_mfma_f32_16x16x32_bf16 v[26:29], v[184:187], v[216:219], v[26:29]
	v_mfma_f32_16x16x32_bf16 v[18:21], v[192:195], v[216:219], v[18:21]
	v_mfma_f32_16x16x32_bf16 v[10:13], v[184:187], v[224:227], v[10:13]
	v_mfma_f32_16x16x32_bf16 v[2:5], v[192:195], v[224:227], v[2:5]
	s_barrier
	s_setprio 0
	s_add_u32 s98, s94, 0xb0000
	s_addc_u32 s99, s95, 0
	s_add_i32 s6, 0, 0x18000
	s_add_i32 s29, 0, 0x1c000
	s_mov_b32 m0, s48
	s_nop 0
	global_load_lds_dwordx4 v130, s[98:99]
	s_mov_b32 m0, s49
	s_nop 0
	global_load_lds_dwordx4 v134, s[98:99]
	ds_read_b128 v[164:167], v232
	ds_read_b128 v[168:171], v232 offset:1024
	ds_read_b128 v[172:175], v232 offset:2048
	ds_read_b128 v[176:179], v232 offset:3072
	ds_read_b128 v[180:183], v233
	ds_read_b128 v[184:187], v233 offset:1024
	ds_read_b128 v[188:191], v233 offset:2048
	ds_read_b128 v[192:195], v233 offset:3072
	ds_read_b128 v[196:199], v160 offset:32768
	ds_read_b128 v[200:203], v160 offset:33792
	ds_read_b128 v[204:207], v160 offset:34816
	ds_read_b128 v[208:211], v160 offset:35840
	ds_read_b128 v[212:215], v160 offset:36864
	ds_read_b128 v[216:219], v160 offset:37888
	ds_read_b128 v[220:223], v160 offset:38912
	ds_read_b128 v[224:227], v160 offset:39936
	s_waitcnt vmcnt(8)
	s_waitcnt lgkmcnt(0)
	s_setprio 1
	s_barrier
	v_mfma_f32_16x16x32_bf16 v[122:125], v[164:167], v[196:199], v[122:125]
	v_mfma_f32_16x16x32_bf16 v[118:121], v[172:175], v[196:199], v[118:121]
	v_mfma_f32_16x16x32_bf16 v[110:113], v[164:167], v[204:207], v[110:113]
	v_mfma_f32_16x16x32_bf16 v[102:105], v[172:175], v[204:207], v[102:105]
	v_mfma_f32_16x16x32_bf16 v[94:97], v[164:167], v[212:215], v[94:97]
	v_mfma_f32_16x16x32_bf16 v[86:89], v[172:175], v[212:215], v[86:89]
	v_mfma_f32_16x16x32_bf16 v[78:81], v[164:167], v[220:223], v[78:81]
	v_mfma_f32_16x16x32_bf16 v[70:73], v[172:175], v[220:223], v[70:73]
	v_mfma_f32_16x16x32_bf16 v[122:125], v[168:171], v[200:203], v[122:125]
	v_mfma_f32_16x16x32_bf16 v[118:121], v[176:179], v[200:203], v[118:121]
	v_mfma_f32_16x16x32_bf16 v[110:113], v[168:171], v[208:211], v[110:113]
	v_mfma_f32_16x16x32_bf16 v[102:105], v[176:179], v[208:211], v[102:105]
	v_mfma_f32_16x16x32_bf16 v[94:97], v[168:171], v[216:219], v[94:97]
	v_mfma_f32_16x16x32_bf16 v[86:89], v[176:179], v[216:219], v[86:89]
	v_mfma_f32_16x16x32_bf16 v[78:81], v[168:171], v[224:227], v[78:81]
	v_mfma_f32_16x16x32_bf16 v[70:73], v[176:179], v[224:227], v[70:73]
	s_setprio 0
	s_setprio 1
	v_mfma_f32_16x16x32_bf16 v[126:129], v[180:183], v[196:199], v[126:129]
	v_mfma_f32_16x16x32_bf16 v[114:117], v[188:191], v[196:199], v[114:117]
	v_mfma_f32_16x16x32_bf16 v[106:109], v[180:183], v[204:207], v[106:109]
	v_mfma_f32_16x16x32_bf16 v[98:101], v[188:191], v[204:207], v[98:101]
	v_mfma_f32_16x16x32_bf16 v[90:93], v[180:183], v[212:215], v[90:93]
	v_mfma_f32_16x16x32_bf16 v[82:85], v[188:191], v[212:215], v[82:85]
	v_mfma_f32_16x16x32_bf16 v[74:77], v[180:183], v[220:223], v[74:77]
	v_mfma_f32_16x16x32_bf16 v[66:69], v[188:191], v[220:223], v[66:69]
	v_mfma_f32_16x16x32_bf16 v[126:129], v[184:187], v[200:203], v[126:129]
	v_mfma_f32_16x16x32_bf16 v[114:117], v[192:195], v[200:203], v[114:117]
	v_mfma_f32_16x16x32_bf16 v[106:109], v[184:187], v[208:211], v[106:109]
	v_mfma_f32_16x16x32_bf16 v[98:101], v[192:195], v[208:211], v[98:101]
	v_mfma_f32_16x16x32_bf16 v[90:93], v[184:187], v[216:219], v[90:93]
	v_mfma_f32_16x16x32_bf16 v[82:85], v[192:195], v[216:219], v[82:85]
	v_mfma_f32_16x16x32_bf16 v[74:77], v[184:187], v[224:227], v[74:77]
	v_mfma_f32_16x16x32_bf16 v[66:69], v[192:195], v[224:227], v[66:69]
	s_barrier
	s_setprio 0
	s_add_u32 s96, s96, 0x80
	s_addc_u32 s97, s97, 0
	s_add_u32 s98, s96, 0xb0000
	s_addc_u32 s99, s97, 0
	s_add_u32 s94, s94, 0x80
	s_addc_u32 s95, s95, 0
	s_add_i32 s6, s6, s23
	s_mov_b32 m0, s6
	s_nop 0
	global_load_lds_dwordx4 v132, s[96:97]
	s_add_i32 m0, s6, 0x2000
	s_add_i32 s6, s29, s23
	global_load_lds_dwordx4 v136, s[96:97]
	s_mov_b32 m0, s6
	s_nop 0
	global_load_lds_dwordx4 v132, s[98:99]
	s_add_i32 m0, s6, 0x2000
	s_nop 0
	global_load_lds_dwordx4 v136, s[98:99]
	s_mov_b32 m0, s59
	s_nop 0
	global_load_lds_dwordx4 v130, s[94:95]
	s_mov_b32 m0, s60
	s_nop 0
	global_load_lds_dwordx4 v134, s[94:95]
	ds_read_b128 v[196:199], v160 offset:49152
	ds_read_b128 v[200:203], v160 offset:50176
	ds_read_b128 v[204:207], v160 offset:51200
	ds_read_b128 v[208:211], v160 offset:52224
	ds_read_b128 v[212:215], v160 offset:53248
	ds_read_b128 v[216:219], v160 offset:54272
	ds_read_b128 v[220:223], v160 offset:55296
	ds_read_b128 v[224:227], v160 offset:56320
	s_waitcnt vmcnt(8)
	s_waitcnt lgkmcnt(0)
	s_setprio 1
	s_barrier
	v_mfma_f32_16x16x32_bf16 v[62:65], v[164:167], v[196:199], v[62:65]
	v_mfma_f32_16x16x32_bf16 v[54:57], v[172:175], v[196:199], v[54:57]
	v_mfma_f32_16x16x32_bf16 v[46:49], v[164:167], v[204:207], v[46:49]
	v_mfma_f32_16x16x32_bf16 v[38:41], v[172:175], v[204:207], v[38:41]
	v_mfma_f32_16x16x32_bf16 v[30:33], v[164:167], v[212:215], v[30:33]
	v_mfma_f32_16x16x32_bf16 v[22:25], v[172:175], v[212:215], v[22:25]
	v_mfma_f32_16x16x32_bf16 v[14:17], v[164:167], v[220:223], v[14:17]
	v_mfma_f32_16x16x32_bf16 v[6:9], v[172:175], v[220:223], v[6:9]
	v_mfma_f32_16x16x32_bf16 v[62:65], v[168:171], v[200:203], v[62:65]
	v_mfma_f32_16x16x32_bf16 v[54:57], v[176:179], v[200:203], v[54:57]
	v_mfma_f32_16x16x32_bf16 v[46:49], v[168:171], v[208:211], v[46:49]
	v_mfma_f32_16x16x32_bf16 v[38:41], v[176:179], v[208:211], v[38:41]
	v_mfma_f32_16x16x32_bf16 v[30:33], v[168:171], v[216:219], v[30:33]
	v_mfma_f32_16x16x32_bf16 v[22:25], v[176:179], v[216:219], v[22:25]
	v_mfma_f32_16x16x32_bf16 v[14:17], v[168:171], v[224:227], v[14:17]
	v_mfma_f32_16x16x32_bf16 v[6:9], v[176:179], v[224:227], v[6:9]
	s_setprio 0
	s_setprio 1
	v_mfma_f32_16x16x32_bf16 v[58:61], v[180:183], v[196:199], v[58:61]
	v_mfma_f32_16x16x32_bf16 v[50:53], v[188:191], v[196:199], v[50:53]
	v_mfma_f32_16x16x32_bf16 v[42:45], v[180:183], v[204:207], v[42:45]
	v_mfma_f32_16x16x32_bf16 v[34:37], v[188:191], v[204:207], v[34:37]
	v_mfma_f32_16x16x32_bf16 v[26:29], v[180:183], v[212:215], v[26:29]
	v_mfma_f32_16x16x32_bf16 v[18:21], v[188:191], v[212:215], v[18:21]
	v_mfma_f32_16x16x32_bf16 v[10:13], v[180:183], v[220:223], v[10:13]
	v_mfma_f32_16x16x32_bf16 v[2:5], v[188:191], v[220:223], v[2:5]
	v_mfma_f32_16x16x32_bf16 v[58:61], v[184:187], v[200:203], v[58:61]
	v_mfma_f32_16x16x32_bf16 v[50:53], v[192:195], v[200:203], v[50:53]
	v_mfma_f32_16x16x32_bf16 v[42:45], v[184:187], v[208:211], v[42:45]
	v_mfma_f32_16x16x32_bf16 v[34:37], v[192:195], v[208:211], v[34:37]
	v_mfma_f32_16x16x32_bf16 v[26:29], v[184:187], v[216:219], v[26:29]
	v_mfma_f32_16x16x32_bf16 v[18:21], v[192:195], v[216:219], v[18:21]
	v_mfma_f32_16x16x32_bf16 v[10:13], v[184:187], v[224:227], v[10:13]
	v_mfma_f32_16x16x32_bf16 v[2:5], v[192:195], v[224:227], v[2:5]
	s_barrier
	s_setprio 0
	s_mov_b32 s6, s7
	s_add_u32 s88, s88, 0x100
	s_addc_u32 s89, s89, 0
	s_add_u32 s86, s86, 0x100
	s_addc_u32 s87, s87, 0
	s_cmp_ge_i32 s7, s101
	s_cbranch_scc1 .Lmy_kexit_7
.LBB0_1392:
	s_add_u32 s98, s86, 0x100
	s_addc_u32 s99, s87, 0
	s_cmp_eq_u32 s6, s100
	s_cselect_b64 s[94:95], s[90:91], s[98:99]
	s_cselect_b64 s[96:97], s[92:93], s[88:89]
	s_add_i32 s7, s6, 2
	s_nop 0
	s_add_i32 m0, s46, 0xc000
	s_nop 0
	global_load_lds_dwordx4 v144, s[86:87]
	s_add_i32 m0, s46, 0xe000
	s_nop 0
	global_load_lds_dwordx4 v142, s[86:87]
	ds_read_b128 v[164:167], v230
	ds_read_b128 v[168:171], v230 offset:1024
	ds_read_b128 v[172:175], v230 offset:2048
	ds_read_b128 v[176:179], v230 offset:3072
	ds_read_b128 v[180:183], v231
	ds_read_b128 v[184:187], v231 offset:1024
	ds_read_b128 v[188:191], v231 offset:2048
	ds_read_b128 v[192:195], v231 offset:3072
	ds_read_b128 v[196:199], v160
	ds_read_b128 v[200:203], v160 offset:1024
	ds_read_b128 v[204:207], v160 offset:2048
	ds_read_b128 v[208:211], v160 offset:3072
	ds_read_b128 v[212:215], v160 offset:4096
	ds_read_b128 v[216:219], v160 offset:5120
	ds_read_b128 v[220:223], v160 offset:6144
	ds_read_b128 v[224:227], v160 offset:7168
	s_waitcnt vmcnt(8)
	s_waitcnt lgkmcnt(0)
	s_setprio 1
	s_barrier
	v_mfma_f32_16x16x32_bf16 v[122:125], v[164:167], v[196:199], v[122:125]
	v_mfma_f32_16x16x32_bf16 v[118:121], v[172:175], v[196:199], v[118:121]
	v_mfma_f32_16x16x32_bf16 v[110:113], v[164:167], v[204:207], v[110:113]
	v_mfma_f32_16x16x32_bf16 v[102:105], v[172:175], v[204:207], v[102:105]
	v_mfma_f32_16x16x32_bf16 v[94:97], v[164:167], v[212:215], v[94:97]
	v_mfma_f32_16x16x32_bf16 v[86:89], v[172:175], v[212:215], v[86:89]
	v_mfma_f32_16x16x32_bf16 v[78:81], v[164:167], v[220:223], v[78:81]
	v_mfma_f32_16x16x32_bf16 v[70:73], v[172:175], v[220:223], v[70:73]
	v_mfma_f32_16x16x32_bf16 v[122:125], v[168:171], v[200:203], v[122:125]
	v_mfma_f32_16x16x32_bf16 v[118:121], v[176:179], v[200:203], v[118:121]
	v_mfma_f32_16x16x32_bf16 v[110:113], v[168:171], v[208:211], v[110:113]
	v_mfma_f32_16x16x32_bf16 v[102:105], v[176:179], v[208:211], v[102:105]
	v_mfma_f32_16x16x32_bf16 v[94:97], v[168:171], v[216:219], v[94:97]
	v_mfma_f32_16x16x32_bf16 v[86:89], v[176:179], v[216:219], v[86:89]
	v_mfma_f32_16x16x32_bf16 v[78:81], v[168:171], v[224:227], v[78:81]
	v_mfma_f32_16x16x32_bf16 v[70:73], v[176:179], v[224:227], v[70:73]
	s_setprio 0
	s_setprio 1
	v_mfma_f32_16x16x32_bf16 v[126:129], v[180:183], v[196:199], v[126:129]
	v_mfma_f32_16x16x32_bf16 v[114:117], v[188:191], v[196:199], v[114:117]
	v_mfma_f32_16x16x32_bf16 v[106:109], v[180:183], v[204:207], v[106:109]
	v_mfma_f32_16x16x32_bf16 v[98:101], v[188:191], v[204:207], v[98:101]
	v_mfma_f32_16x16x32_bf16 v[90:93], v[180:183], v[212:215], v[90:93]
	v_mfma_f32_16x16x32_bf16 v[82:85], v[188:191], v[212:215], v[82:85]
	v_mfma_f32_16x16x32_bf16 v[74:77], v[180:183], v[220:223], v[74:77]
	v_mfma_f32_16x16x32_bf16 v[66:69], v[188:191], v[220:223], v[66:69]
	v_mfma_f32_16x16x32_bf16 v[126:129], v[184:187], v[200:203], v[126:129]
	v_mfma_f32_16x16x32_bf16 v[114:117], v[192:195], v[200:203], v[114:117]
	v_mfma_f32_16x16x32_bf16 v[106:109], v[184:187], v[208:211], v[106:109]
	v_mfma_f32_16x16x32_bf16 v[98:101], v[192:195], v[208:211], v[98:101]
	v_mfma_f32_16x16x32_bf16 v[90:93], v[184:187], v[216:219], v[90:93]
	v_mfma_f32_16x16x32_bf16 v[82:85], v[192:195], v[216:219], v[82:85]
	v_mfma_f32_16x16x32_bf16 v[74:77], v[184:187], v[224:227], v[74:77]
	v_mfma_f32_16x16x32_bf16 v[66:69], v[192:195], v[224:227], v[66:69]
	s_barrier
	s_setprio 0
	s_add_u32 s98, s96, 0xb0000
	s_addc_u32 s99, s97, 0
	s_add_i32 s6, s67, s23
	s_mov_b32 m0, s6
	s_nop 0
	global_load_lds_dwordx4 v132, s[96:97]
	s_add_i32 m0, s6, 0x2000
	s_add_i32 s6, s70, s23
	global_load_lds_dwordx4 v136, s[96:97]
	s_mov_b32 m0, s6
	s_nop 0
	global_load_lds_dwordx4 v132, s[98:99]
	s_add_i32 m0, s6, 0x2000
	s_nop 0
	global_load_lds_dwordx4 v136, s[98:99]
	s_mov_b32 m0, s46
	s_nop 0
	global_load_lds_dwordx4 v130, s[94:95]
	s_mov_b32 m0, s47
	s_nop 0
	global_load_lds_dwordx4 v134, s[94:95]
	ds_read_b128 v[196:199], v160 offset:16384
	ds_read_b128 v[200:203], v160 offset:17408
	ds_read_b128 v[204:207], v160 offset:18432
	ds_read_b128 v[208:211], v160 offset:19456
	ds_read_b128 v[212:215], v160 offset:20480
	ds_read_b128 v[216:219], v160 offset:21504
	ds_read_b128 v[220:223], v160 offset:22528
	ds_read_b128 v[224:227], v160 offset:23552
	s_waitcnt vmcnt(8)
	s_waitcnt lgkmcnt(0)
	s_setprio 1
	s_barrier
	v_mfma_f32_16x16x32_bf16 v[62:65], v[164:167], v[196:199], v[62:65]
	v_mfma_f32_16x16x32_bf16 v[54:57], v[172:175], v[196:199], v[54:57]
	v_mfma_f32_16x16x32_bf16 v[46:49], v[164:167], v[204:207], v[46:49]
	v_mfma_f32_16x16x32_bf16 v[38:41], v[172:175], v[204:207], v[38:41]
	v_mfma_f32_16x16x32_bf16 v[30:33], v[164:167], v[212:215], v[30:33]
	v_mfma_f32_16x16x32_bf16 v[22:25], v[172:175], v[212:215], v[22:25]
	v_mfma_f32_16x16x32_bf16 v[14:17], v[164:167], v[220:223], v[14:17]
	v_mfma_f32_16x16x32_bf16 v[6:9], v[172:175], v[220:223], v[6:9]
	v_mfma_f32_16x16x32_bf16 v[62:65], v[168:171], v[200:203], v[62:65]
	v_mfma_f32_16x16x32_bf16 v[54:57], v[176:179], v[200:203], v[54:57]
	v_mfma_f32_16x16x32_bf16 v[46:49], v[168:171], v[208:211], v[46:49]
	v_mfma_f32_16x16x32_bf16 v[38:41], v[176:179], v[208:211], v[38:41]
	v_mfma_f32_16x16x32_bf16 v[30:33], v[168:171], v[216:219], v[30:33]
	v_mfma_f32_16x16x32_bf16 v[22:25], v[176:179], v[216:219], v[22:25]
	v_mfma_f32_16x16x32_bf16 v[14:17], v[168:171], v[224:227], v[14:17]
	v_mfma_f32_16x16x32_bf16 v[6:9], v[176:179], v[224:227], v[6:9]
	s_setprio 0
	s_setprio 1
	v_mfma_f32_16x16x32_bf16 v[58:61], v[180:183], v[196:199], v[58:61]
	v_mfma_f32_16x16x32_bf16 v[50:53], v[188:191], v[196:199], v[50:53]
	v_mfma_f32_16x16x32_bf16 v[42:45], v[180:183], v[204:207], v[42:45]
	v_mfma_f32_16x16x32_bf16 v[34:37], v[188:191], v[204:207], v[34:37]
	v_mfma_f32_16x16x32_bf16 v[26:29], v[180:183], v[212:215], v[26:29]
	v_mfma_f32_16x16x32_bf16 v[18:21], v[188:191], v[212:215], v[18:21]
	v_mfma_f32_16x16x32_bf16 v[10:13], v[180:183], v[220:223], v[10:13]
	v_mfma_f32_16x16x32_bf16 v[2:5], v[188:191], v[220:223], v[2:5]
	v_mfma_f32_16x16x32_bf16 v[58:61], v[184:187], v[200:203], v[58:61]
	v_mfma_f32_16x16x32_bf16 v[50:53], v[192:195], v[200:203], v[50:53]
	v_mfma_f32_16x16x32_bf16 v[42:45], v[184:187], v[208:211], v[42:45]
	v_mfma_f32_16x16x32_bf16 v[34:37], v[192:195], v[208:211], v[34:37]
	v_mfma_f32_16x16x32_bf16 v[26:29], v[184:187], v[216:219], v[26:29]
	v_mfma_f32_16x16x32_bf16 v[18:21], v[192:195], v[216:219], v[18:21]
	v_mfma_f32_16x16x32_bf16 v[10:13], v[184:187], v[224:227], v[10:13]
	v_mfma_f32_16x16x32_bf16 v[2:5], v[192:195], v[224:227], v[2:5]
	s_barrier
	s_setprio 0
	s_add_u32 s98, s94, 0xb0000
	s_addc_u32 s99, s95, 0
	s_add_i32 s6, 0, 0x18000
	s_add_i32 s29, 0, 0x1c000
	s_mov_b32 m0, s48
	s_nop 0
	global_load_lds_dwordx4 v130, s[98:99]
	s_mov_b32 m0, s49
	s_nop 0
	global_load_lds_dwordx4 v134, s[98:99]
	ds_read_b128 v[164:167], v232
	ds_read_b128 v[168:171], v232 offset:1024
	ds_read_b128 v[172:175], v232 offset:2048
	ds_read_b128 v[176:179], v232 offset:3072
	ds_read_b128 v[180:183], v233
	ds_read_b128 v[184:187], v233 offset:1024
	ds_read_b128 v[188:191], v233 offset:2048
	ds_read_b128 v[192:195], v233 offset:3072
	ds_read_b128 v[196:199], v160 offset:32768
	ds_read_b128 v[200:203], v160 offset:33792
	ds_read_b128 v[204:207], v160 offset:34816
	ds_read_b128 v[208:211], v160 offset:35840
	ds_read_b128 v[212:215], v160 offset:36864
	ds_read_b128 v[216:219], v160 offset:37888
	ds_read_b128 v[220:223], v160 offset:38912
	ds_read_b128 v[224:227], v160 offset:39936
	s_waitcnt vmcnt(8)
	s_waitcnt lgkmcnt(0)
	s_setprio 1
	s_barrier
	v_mfma_f32_16x16x32_bf16 v[122:125], v[164:167], v[196:199], v[122:125]
	v_mfma_f32_16x16x32_bf16 v[118:121], v[172:175], v[196:199], v[118:121]
	v_mfma_f32_16x16x32_bf16 v[110:113], v[164:167], v[204:207], v[110:113]
	v_mfma_f32_16x16x32_bf16 v[102:105], v[172:175], v[204:207], v[102:105]
	v_mfma_f32_16x16x32_bf16 v[94:97], v[164:167], v[212:215], v[94:97]
	v_mfma_f32_16x16x32_bf16 v[86:89], v[172:175], v[212:215], v[86:89]
	v_mfma_f32_16x16x32_bf16 v[78:81], v[164:167], v[220:223], v[78:81]
	v_mfma_f32_16x16x32_bf16 v[70:73], v[172:175], v[220:223], v[70:73]
	v_mfma_f32_16x16x32_bf16 v[122:125], v[168:171], v[200:203], v[122:125]
	v_mfma_f32_16x16x32_bf16 v[118:121], v[176:179], v[200:203], v[118:121]
	v_mfma_f32_16x16x32_bf16 v[110:113], v[168:171], v[208:211], v[110:113]
	v_mfma_f32_16x16x32_bf16 v[102:105], v[176:179], v[208:211], v[102:105]
	v_mfma_f32_16x16x32_bf16 v[94:97], v[168:171], v[216:219], v[94:97]
	v_mfma_f32_16x16x32_bf16 v[86:89], v[176:179], v[216:219], v[86:89]
	v_mfma_f32_16x16x32_bf16 v[78:81], v[168:171], v[224:227], v[78:81]
	v_mfma_f32_16x16x32_bf16 v[70:73], v[176:179], v[224:227], v[70:73]
	s_setprio 0
	s_setprio 1
	v_mfma_f32_16x16x32_bf16 v[126:129], v[180:183], v[196:199], v[126:129]
	v_mfma_f32_16x16x32_bf16 v[114:117], v[188:191], v[196:199], v[114:117]
	v_mfma_f32_16x16x32_bf16 v[106:109], v[180:183], v[204:207], v[106:109]
	v_mfma_f32_16x16x32_bf16 v[98:101], v[188:191], v[204:207], v[98:101]
	v_mfma_f32_16x16x32_bf16 v[90:93], v[180:183], v[212:215], v[90:93]
	v_mfma_f32_16x16x32_bf16 v[82:85], v[188:191], v[212:215], v[82:85]
	v_mfma_f32_16x16x32_bf16 v[74:77], v[180:183], v[220:223], v[74:77]
	v_mfma_f32_16x16x32_bf16 v[66:69], v[188:191], v[220:223], v[66:69]
	v_mfma_f32_16x16x32_bf16 v[126:129], v[184:187], v[200:203], v[126:129]
	v_mfma_f32_16x16x32_bf16 v[114:117], v[192:195], v[200:203], v[114:117]
	v_mfma_f32_16x16x32_bf16 v[106:109], v[184:187], v[208:211], v[106:109]
	v_mfma_f32_16x16x32_bf16 v[98:101], v[192:195], v[208:211], v[98:101]
	v_mfma_f32_16x16x32_bf16 v[90:93], v[184:187], v[216:219], v[90:93]
	v_mfma_f32_16x16x32_bf16 v[82:85], v[192:195], v[216:219], v[82:85]
	v_mfma_f32_16x16x32_bf16 v[74:77], v[184:187], v[224:227], v[74:77]
	v_mfma_f32_16x16x32_bf16 v[66:69], v[192:195], v[224:227], v[66:69]
	s_barrier
	s_setprio 0
	s_add_u32 s96, s96, 0x80
	s_addc_u32 s97, s97, 0
	s_add_u32 s98, s96, 0xb0000
	s_addc_u32 s99, s97, 0
	s_add_u32 s94, s94, 0x80
	s_addc_u32 s95, s95, 0
	s_add_i32 s6, s6, s23
	s_mov_b32 m0, s6
	s_nop 0
	global_load_lds_dwordx4 v132, s[96:97]
	s_add_i32 m0, s6, 0x2000
	s_add_i32 s6, s29, s23
	global_load_lds_dwordx4 v136, s[96:97]
	s_mov_b32 m0, s6
	s_nop 0
	global_load_lds_dwordx4 v132, s[98:99]
	s_add_i32 m0, s6, 0x2000
	s_nop 0
	global_load_lds_dwordx4 v136, s[98:99]
	s_mov_b32 m0, s59
	s_nop 0
	global_load_lds_dwordx4 v130, s[94:95]
	s_mov_b32 m0, s60
	s_nop 0
	global_load_lds_dwordx4 v134, s[94:95]
	ds_read_b128 v[196:199], v160 offset:49152
	ds_read_b128 v[200:203], v160 offset:50176
	ds_read_b128 v[204:207], v160 offset:51200
	ds_read_b128 v[208:211], v160 offset:52224
	ds_read_b128 v[212:215], v160 offset:53248
	ds_read_b128 v[216:219], v160 offset:54272
	ds_read_b128 v[220:223], v160 offset:55296
	ds_read_b128 v[224:227], v160 offset:56320
	s_waitcnt vmcnt(8)
	s_waitcnt lgkmcnt(0)
	s_setprio 1
	s_barrier
	v_mfma_f32_16x16x32_bf16 v[62:65], v[164:167], v[196:199], v[62:65]
	v_mfma_f32_16x16x32_bf16 v[54:57], v[172:175], v[196:199], v[54:57]
	v_mfma_f32_16x16x32_bf16 v[46:49], v[164:167], v[204:207], v[46:49]
	v_mfma_f32_16x16x32_bf16 v[38:41], v[172:175], v[204:207], v[38:41]
	v_mfma_f32_16x16x32_bf16 v[30:33], v[164:167], v[212:215], v[30:33]
	v_mfma_f32_16x16x32_bf16 v[22:25], v[172:175], v[212:215], v[22:25]
	v_mfma_f32_16x16x32_bf16 v[14:17], v[164:167], v[220:223], v[14:17]
	v_mfma_f32_16x16x32_bf16 v[6:9], v[172:175], v[220:223], v[6:9]
	v_mfma_f32_16x16x32_bf16 v[62:65], v[168:171], v[200:203], v[62:65]
	v_mfma_f32_16x16x32_bf16 v[54:57], v[176:179], v[200:203], v[54:57]
	v_mfma_f32_16x16x32_bf16 v[46:49], v[168:171], v[208:211], v[46:49]
	v_mfma_f32_16x16x32_bf16 v[38:41], v[176:179], v[208:211], v[38:41]
	v_mfma_f32_16x16x32_bf16 v[30:33], v[168:171], v[216:219], v[30:33]
	v_mfma_f32_16x16x32_bf16 v[22:25], v[176:179], v[216:219], v[22:25]
	v_mfma_f32_16x16x32_bf16 v[14:17], v[168:171], v[224:227], v[14:17]
	v_mfma_f32_16x16x32_bf16 v[6:9], v[176:179], v[224:227], v[6:9]
	s_setprio 0
	s_setprio 1
	v_mfma_f32_16x16x32_bf16 v[58:61], v[180:183], v[196:199], v[58:61]
	v_mfma_f32_16x16x32_bf16 v[50:53], v[188:191], v[196:199], v[50:53]
	v_mfma_f32_16x16x32_bf16 v[42:45], v[180:183], v[204:207], v[42:45]
	v_mfma_f32_16x16x32_bf16 v[34:37], v[188:191], v[204:207], v[34:37]
	v_mfma_f32_16x16x32_bf16 v[26:29], v[180:183], v[212:215], v[26:29]
	v_mfma_f32_16x16x32_bf16 v[18:21], v[188:191], v[212:215], v[18:21]
	v_mfma_f32_16x16x32_bf16 v[10:13], v[180:183], v[220:223], v[10:13]
	v_mfma_f32_16x16x32_bf16 v[2:5], v[188:191], v[220:223], v[2:5]
	v_mfma_f32_16x16x32_bf16 v[58:61], v[184:187], v[200:203], v[58:61]
	v_mfma_f32_16x16x32_bf16 v[50:53], v[192:195], v[200:203], v[50:53]
	v_mfma_f32_16x16x32_bf16 v[42:45], v[184:187], v[208:211], v[42:45]
	v_mfma_f32_16x16x32_bf16 v[34:37], v[192:195], v[208:211], v[34:37]
	v_mfma_f32_16x16x32_bf16 v[26:29], v[184:187], v[216:219], v[26:29]
	v_mfma_f32_16x16x32_bf16 v[18:21], v[192:195], v[216:219], v[18:21]
	v_mfma_f32_16x16x32_bf16 v[10:13], v[184:187], v[224:227], v[10:13]
	v_mfma_f32_16x16x32_bf16 v[2:5], v[192:195], v[224:227], v[2:5]
	s_barrier
	s_setprio 0
	s_mov_b32 s6, s7
	s_add_u32 s88, s88, 0x100
	s_addc_u32 s89, s89, 0
	s_add_u32 s86, s86, 0x100
	s_addc_u32 s87, s87, 0
	s_cmp_ge_i32 s7, s101
	s_cbranch_scc0 .LBB0_1392

.LBB0_1571:
	v_cmp_gt_i32_e32 vcc, 1, v141
	s_cbranch_vccnz .LBB0_1633
	v_lshl_add_u64 v[154:155], v[2:3], 0, s[18:19]
	v_add_u32_e32 v138, -2, v141
	v_lshl_add_u64 v[152:153], v[4:5], 0, s[22:23]
	s_mov_b32 s7, 0
	s_nop 0
	v_readfirstlane_b32 s86, v154
	v_readfirstlane_b32 s87, v155
	v_readfirstlane_b32 s88, v152
	v_readfirstlane_b32 s89, v153
	v_readfirstlane_b32 s90, v148
	v_readfirstlane_b32 s91, v149
	v_readfirstlane_b32 s92, v150
	v_readfirstlane_b32 s93, v151
	v_readfirstlane_b32 s100, v138
	v_readfirstlane_b32 s101, v141
	v_add_u32_e32 v230, s71, v160
	v_add_u32_e32 v231, s72, v160
	v_add_u32_e32 v232, 0x18000, v160
	v_add_u32_e32 v233, 0x1c000, v160
	s_add_u32 s98, s86, 0xfffc0080
	s_addc_u32 s99, s87, -1
	s_cmp_eq_u32 s7, s100
	s_cselect_b64 s[94:95], s[90:91], s[98:99]
	s_cselect_b64 s[96:97], s[92:93], s[88:89]
	s_add_i32 s47, s7, 2
	s_nop 0
	s_mov_b32 m0, s74
	s_nop 0
	global_load_lds_dwordx4 v144, s[86:87]
	s_mov_b32 m0, s75
	s_nop 0
	global_load_lds_dwordx4 v142, s[86:87]
	ds_read_b128 v[156:159], v230
	ds_read_b128 v[166:169], v230 offset:1024
	ds_read_b128 v[170:173], v230 offset:2048
	ds_read_b128 v[174:177], v230 offset:3072
	ds_read_b128 v[178:181], v231
	ds_read_b128 v[182:185], v231 offset:1024
	ds_read_b128 v[186:189], v231 offset:2048
	ds_read_b128 v[190:193], v231 offset:3072
	ds_read_b128 v[194:197], v163
	ds_read_b128 v[198:201], v163 offset:1024
	ds_read_b128 v[202:205], v163 offset:2048
	ds_read_b128 v[206:209], v163 offset:3072
	ds_read_b128 v[210:213], v163 offset:4096
	ds_read_b128 v[214:217], v163 offset:5120
	ds_read_b128 v[218:221], v163 offset:6144
	ds_read_b128 v[222:225], v163 offset:7168
	s_waitcnt vmcnt(8)
	s_waitcnt lgkmcnt(0)
	s_setprio 1
	s_barrier
	v_mfma_f32_16x16x32_bf16 v[122:125], v[156:159], v[194:197], 0
	v_mfma_f32_16x16x32_bf16 v[118:121], v[170:173], v[194:197], 0
	v_mfma_f32_16x16x32_bf16 v[110:113], v[156:159], v[202:205], 0
	v_mfma_f32_16x16x32_bf16 v[102:105], v[170:173], v[202:205], 0
	v_mfma_f32_16x16x32_bf16 v[94:97], v[156:159], v[210:213], 0
	v_mfma_f32_16x16x32_bf16 v[86:89], v[170:173], v[210:213], 0
	v_mfma_f32_16x16x32_bf16 v[78:81], v[156:159], v[218:221], 0
	v_mfma_f32_16x16x32_bf16 v[70:73], v[170:173], v[218:221], 0
	v_mfma_f32_16x16x32_bf16 v[122:125], v[166:169], v[198:201], v[122:125]
	v_mfma_f32_16x16x32_bf16 v[118:121], v[174:177], v[198:201], v[118:121]
	v_mfma_f32_16x16x32_bf16 v[110:113], v[166:169], v[206:209], v[110:113]
	v_mfma_f32_16x16x32_bf16 v[102:105], v[174:177], v[206:209], v[102:105]
	v_mfma_f32_16x16x32_bf16 v[94:97], v[166:169], v[214:217], v[94:97]
	v_mfma_f32_16x16x32_bf16 v[86:89], v[174:177], v[214:217], v[86:89]
	v_mfma_f32_16x16x32_bf16 v[78:81], v[166:169], v[222:225], v[78:81]
	v_mfma_f32_16x16x32_bf16 v[70:73], v[174:177], v[222:225], v[70:73]
	s_setprio 0
	s_setprio 1
	v_mfma_f32_16x16x32_bf16 v[126:129], v[178:181], v[194:197], 0
	v_mfma_f32_16x16x32_bf16 v[114:117], v[186:189], v[194:197], 0
	v_mfma_f32_16x16x32_bf16 v[106:109], v[178:181], v[202:205], 0
	v_mfma_f32_16x16x32_bf16 v[98:101], v[186:189], v[202:205], 0
	v_mfma_f32_16x16x32_bf16 v[90:93], v[178:181], v[210:213], 0
	v_mfma_f32_16x16x32_bf16 v[82:85], v[186:189], v[210:213], 0
	v_mfma_f32_16x16x32_bf16 v[74:77], v[178:181], v[218:221], 0
	v_mfma_f32_16x16x32_bf16 v[66:69], v[186:189], v[218:221], 0
	v_mfma_f32_16x16x32_bf16 v[126:129], v[182:185], v[198:201], v[126:129]
	v_mfma_f32_16x16x32_bf16 v[114:117], v[190:193], v[198:201], v[114:117]
	v_mfma_f32_16x16x32_bf16 v[106:109], v[182:185], v[206:209], v[106:109]
	v_mfma_f32_16x16x32_bf16 v[98:101], v[190:193], v[206:209], v[98:101]
	v_mfma_f32_16x16x32_bf16 v[90:93], v[182:185], v[214:217], v[90:93]
	v_mfma_f32_16x16x32_bf16 v[82:85], v[190:193], v[214:217], v[82:85]
	v_mfma_f32_16x16x32_bf16 v[74:77], v[182:185], v[222:225], v[74:77]
	v_mfma_f32_16x16x32_bf16 v[66:69], v[190:193], v[222:225], v[66:69]
	s_barrier
	s_setprio 0
	s_add_u32 s98, s96, 0x40000
	s_addc_u32 s99, s97, 0
	s_add_i32 s7, s71, s29
	s_mov_b32 m0, s7
	s_nop 0
	global_load_lds_dwordx4 v132, s[96:97]
	s_add_i32 m0, s7, 0x2000
	s_add_i32 s7, s72, s29
	global_load_lds_dwordx4 v136, s[96:97]
	s_mov_b32 m0, s7
	s_nop 0
	global_load_lds_dwordx4 v132, s[98:99]
	s_add_i32 m0, s7, 0x2000
	s_nop 0
	global_load_lds_dwordx4 v136, s[98:99]
	s_mov_b32 m0, s51
	s_nop 0
	global_load_lds_dwordx4 v130, s[94:95]
	s_mov_b32 m0, s60
	s_nop 0
	global_load_lds_dwordx4 v134, s[94:95]
	ds_read_b128 v[194:197], v163 offset:16384
	ds_read_b128 v[198:201], v163 offset:17408
	ds_read_b128 v[202:205], v163 offset:18432
	ds_read_b128 v[206:209], v163 offset:19456
	ds_read_b128 v[210:213], v163 offset:20480
	ds_read_b128 v[214:217], v163 offset:21504
	ds_read_b128 v[218:221], v163 offset:22528
	ds_read_b128 v[222:225], v163 offset:23552
	s_waitcnt vmcnt(8)
	s_waitcnt lgkmcnt(0)
	s_setprio 1
	s_barrier
	v_mfma_f32_16x16x32_bf16 v[62:65], v[156:159], v[194:197], 0
	v_mfma_f32_16x16x32_bf16 v[54:57], v[170:173], v[194:197], 0
	v_mfma_f32_16x16x32_bf16 v[46:49], v[156:159], v[202:205], 0
	v_mfma_f32_16x16x32_bf16 v[38:41], v[170:173], v[202:205], 0
	v_mfma_f32_16x16x32_bf16 v[30:33], v[156:159], v[210:213], 0
	v_mfma_f32_16x16x32_bf16 v[22:25], v[170:173], v[210:213], 0
	v_mfma_f32_16x16x32_bf16 v[14:17], v[156:159], v[218:221], 0
	v_mfma_f32_16x16x32_bf16 v[6:9], v[170:173], v[218:221], 0
	v_mfma_f32_16x16x32_bf16 v[62:65], v[166:169], v[198:201], v[62:65]
	v_mfma_f32_16x16x32_bf16 v[54:57], v[174:177], v[198:201], v[54:57]
	v_mfma_f32_16x16x32_bf16 v[46:49], v[166:169], v[206:209], v[46:49]
	v_mfma_f32_16x16x32_bf16 v[38:41], v[174:177], v[206:209], v[38:41]
	v_mfma_f32_16x16x32_bf16 v[30:33], v[166:169], v[214:217], v[30:33]
	v_mfma_f32_16x16x32_bf16 v[22:25], v[174:177], v[214:217], v[22:25]
	v_mfma_f32_16x16x32_bf16 v[14:17], v[166:169], v[222:225], v[14:17]
	v_mfma_f32_16x16x32_bf16 v[6:9], v[174:177], v[222:225], v[6:9]
	s_setprio 0
	s_setprio 1
	v_mfma_f32_16x16x32_bf16 v[58:61], v[178:181], v[194:197], 0
	v_mfma_f32_16x16x32_bf16 v[50:53], v[186:189], v[194:197], 0
	v_mfma_f32_16x16x32_bf16 v[42:45], v[178:181], v[202:205], 0
	v_mfma_f32_16x16x32_bf16 v[34:37], v[186:189], v[202:205], 0
	v_mfma_f32_16x16x32_bf16 v[26:29], v[178:181], v[210:213], 0
	v_mfma_f32_16x16x32_bf16 v[18:21], v[186:189], v[210:213], 0
	v_mfma_f32_16x16x32_bf16 v[10:13], v[178:181], v[218:221], 0
	v_mfma_f32_16x16x32_bf16 v[2:5], v[186:189], v[218:221], 0
	v_mfma_f32_16x16x32_bf16 v[58:61], v[182:185], v[198:201], v[58:61]
	v_mfma_f32_16x16x32_bf16 v[50:53], v[190:193], v[198:201], v[50:53]
	v_mfma_f32_16x16x32_bf16 v[42:45], v[182:185], v[206:209], v[42:45]
	v_mfma_f32_16x16x32_bf16 v[34:37], v[190:193], v[206:209], v[34:37]
	v_mfma_f32_16x16x32_bf16 v[26:29], v[182:185], v[214:217], v[26:29]
	v_mfma_f32_16x16x32_bf16 v[18:21], v[190:193], v[214:217], v[18:21]
	v_mfma_f32_16x16x32_bf16 v[10:13], v[182:185], v[222:225], v[10:13]
	v_mfma_f32_16x16x32_bf16 v[2:5], v[190:193], v[222:225], v[2:5]
	s_barrier
	s_setprio 0
	s_add_u32 s98, s94, 0x40000
	s_addc_u32 s99, s95, 0
	s_add_i32 s7, 0, 0x18000
	s_add_i32 s49, 0, 0x1c000
	s_mov_b32 m0, s61
	s_nop 0
	global_load_lds_dwordx4 v130, s[98:99]
	s_mov_b32 m0, s62
	s_nop 0
	global_load_lds_dwordx4 v134, s[98:99]
	ds_read_b128 v[156:159], v232
	ds_read_b128 v[166:169], v232 offset:1024
	ds_read_b128 v[170:173], v232 offset:2048
	ds_read_b128 v[174:177], v232 offset:3072
	ds_read_b128 v[178:181], v233
	ds_read_b128 v[182:185], v233 offset:1024
	ds_read_b128 v[186:189], v233 offset:2048
	ds_read_b128 v[190:193], v233 offset:3072
	ds_read_b128 v[194:197], v163 offset:32768
	ds_read_b128 v[198:201], v163 offset:33792
	ds_read_b128 v[202:205], v163 offset:34816
	ds_read_b128 v[206:209], v163 offset:35840
	ds_read_b128 v[210:213], v163 offset:36864
	ds_read_b128 v[214:217], v163 offset:37888
	ds_read_b128 v[218:221], v163 offset:38912
	ds_read_b128 v[222:225], v163 offset:39936
	s_waitcnt vmcnt(8)
	s_waitcnt lgkmcnt(0)
	s_setprio 1
	s_barrier
	v_mfma_f32_16x16x32_bf16 v[122:125], v[156:159], v[194:197], v[122:125]
	v_mfma_f32_16x16x32_bf16 v[118:121], v[170:173], v[194:197], v[118:121]
	v_mfma_f32_16x16x32_bf16 v[110:113], v[156:159], v[202:205], v[110:113]
	v_mfma_f32_16x16x32_bf16 v[102:105], v[170:173], v[202:205], v[102:105]
	v_mfma_f32_16x16x32_bf16 v[94:97], v[156:159], v[210:213], v[94:97]
	v_mfma_f32_16x16x32_bf16 v[86:89], v[170:173], v[210:213], v[86:89]
	v_mfma_f32_16x16x32_bf16 v[78:81], v[156:159], v[218:221], v[78:81]
	v_mfma_f32_16x16x32_bf16 v[70:73], v[170:173], v[218:221], v[70:73]
	v_mfma_f32_16x16x32_bf16 v[122:125], v[166:169], v[198:201], v[122:125]
	v_mfma_f32_16x16x32_bf16 v[118:121], v[174:177], v[198:201], v[118:121]
	v_mfma_f32_16x16x32_bf16 v[110:113], v[166:169], v[206:209], v[110:113]
	v_mfma_f32_16x16x32_bf16 v[102:105], v[174:177], v[206:209], v[102:105]
	v_mfma_f32_16x16x32_bf16 v[94:97], v[166:169], v[214:217], v[94:97]
	v_mfma_f32_16x16x32_bf16 v[86:89], v[174:177], v[214:217], v[86:89]
	v_mfma_f32_16x16x32_bf16 v[78:81], v[166:169], v[222:225], v[78:81]
	v_mfma_f32_16x16x32_bf16 v[70:73], v[174:177], v[222:225], v[70:73]
	s_setprio 0
	s_setprio 1
	v_mfma_f32_16x16x32_bf16 v[126:129], v[178:181], v[194:197], v[126:129]
	v_mfma_f32_16x16x32_bf16 v[114:117], v[186:189], v[194:197], v[114:117]
	v_mfma_f32_16x16x32_bf16 v[106:109], v[178:181], v[202:205], v[106:109]
	v_mfma_f32_16x16x32_bf16 v[98:101], v[186:189], v[202:205], v[98:101]
	v_mfma_f32_16x16x32_bf16 v[90:93], v[178:181], v[210:213], v[90:93]
	v_mfma_f32_16x16x32_bf16 v[82:85], v[186:189], v[210:213], v[82:85]
	v_mfma_f32_16x16x32_bf16 v[74:77], v[178:181], v[218:221], v[74:77]
	v_mfma_f32_16x16x32_bf16 v[66:69], v[186:189], v[218:221], v[66:69]
	v_mfma_f32_16x16x32_bf16 v[126:129], v[182:185], v[198:201], v[126:129]
	v_mfma_f32_16x16x32_bf16 v[114:117], v[190:193], v[198:201], v[114:117]
	v_mfma_f32_16x16x32_bf16 v[106:109], v[182:185], v[206:209], v[106:109]
	v_mfma_f32_16x16x32_bf16 v[98:101], v[190:193], v[206:209], v[98:101]
	v_mfma_f32_16x16x32_bf16 v[90:93], v[182:185], v[214:217], v[90:93]
	v_mfma_f32_16x16x32_bf16 v[82:85], v[190:193], v[214:217], v[82:85]
	v_mfma_f32_16x16x32_bf16 v[74:77], v[182:185], v[222:225], v[74:77]
	v_mfma_f32_16x16x32_bf16 v[66:69], v[190:193], v[222:225], v[66:69]
	s_barrier
	s_setprio 0
	s_add_u32 s96, s96, 0x80
	s_addc_u32 s97, s97, 0
	s_add_u32 s98, s96, 0x40000
	s_addc_u32 s99, s97, 0
	s_add_u32 s94, s94, 0x80
	s_addc_u32 s95, s95, 0
	s_add_i32 s7, s7, s29
	s_mov_b32 m0, s7
	s_nop 0
	global_load_lds_dwordx4 v132, s[96:97]
	s_add_i32 m0, s7, 0x2000
	s_add_i32 s7, s49, s29
	global_load_lds_dwordx4 v136, s[96:97]
	s_mov_b32 m0, s7
	s_nop 0
	global_load_lds_dwordx4 v132, s[98:99]
	s_add_i32 m0, s7, 0x2000
	s_nop 0
	global_load_lds_dwordx4 v136, s[98:99]
	s_mov_b32 m0, s63
	s_nop 0
	global_load_lds_dwordx4 v130, s[94:95]
	s_mov_b32 m0, s64
	s_nop 0
	global_load_lds_dwordx4 v134, s[94:95]
	ds_read_b128 v[194:197], v163 offset:49152
	ds_read_b128 v[198:201], v163 offset:50176
	ds_read_b128 v[202:205], v163 offset:51200
	ds_read_b128 v[206:209], v163 offset:52224
	ds_read_b128 v[210:213], v163 offset:53248
	ds_read_b128 v[214:217], v163 offset:54272
	ds_read_b128 v[218:221], v163 offset:55296
	ds_read_b128 v[222:225], v163 offset:56320
	s_waitcnt vmcnt(8)
	s_waitcnt lgkmcnt(0)
	s_setprio 1
	s_barrier
	v_mfma_f32_16x16x32_bf16 v[62:65], v[156:159], v[194:197], v[62:65]
	v_mfma_f32_16x16x32_bf16 v[54:57], v[170:173], v[194:197], v[54:57]
	v_mfma_f32_16x16x32_bf16 v[46:49], v[156:159], v[202:205], v[46:49]
	v_mfma_f32_16x16x32_bf16 v[38:41], v[170:173], v[202:205], v[38:41]
	v_mfma_f32_16x16x32_bf16 v[30:33], v[156:159], v[210:213], v[30:33]
	v_mfma_f32_16x16x32_bf16 v[22:25], v[170:173], v[210:213], v[22:25]
	v_mfma_f32_16x16x32_bf16 v[14:17], v[156:159], v[218:221], v[14:17]
	v_mfma_f32_16x16x32_bf16 v[6:9], v[170:173], v[218:221], v[6:9]
	v_mfma_f32_16x16x32_bf16 v[62:65], v[166:169], v[198:201], v[62:65]
	v_mfma_f32_16x16x32_bf16 v[54:57], v[174:177], v[198:201], v[54:57]
	v_mfma_f32_16x16x32_bf16 v[46:49], v[166:169], v[206:209], v[46:49]
	v_mfma_f32_16x16x32_bf16 v[38:41], v[174:177], v[206:209], v[38:41]
	v_mfma_f32_16x16x32_bf16 v[30:33], v[166:169], v[214:217], v[30:33]
	v_mfma_f32_16x16x32_bf16 v[22:25], v[174:177], v[214:217], v[22:25]
	v_mfma_f32_16x16x32_bf16 v[14:17], v[166:169], v[222:225], v[14:17]
	v_mfma_f32_16x16x32_bf16 v[6:9], v[174:177], v[222:225], v[6:9]
	s_setprio 0
	s_setprio 1
	v_mfma_f32_16x16x32_bf16 v[58:61], v[178:181], v[194:197], v[58:61]
	v_mfma_f32_16x16x32_bf16 v[50:53], v[186:189], v[194:197], v[50:53]
	v_mfma_f32_16x16x32_bf16 v[42:45], v[178:181], v[202:205], v[42:45]
	v_mfma_f32_16x16x32_bf16 v[34:37], v[186:189], v[202:205], v[34:37]
	v_mfma_f32_16x16x32_bf16 v[26:29], v[178:181], v[210:213], v[26:29]
	v_mfma_f32_16x16x32_bf16 v[18:21], v[186:189], v[210:213], v[18:21]
	v_mfma_f32_16x16x32_bf16 v[10:13], v[178:181], v[218:221], v[10:13]
	v_mfma_f32_16x16x32_bf16 v[2:5], v[186:189], v[218:221], v[2:5]
	v_mfma_f32_16x16x32_bf16 v[58:61], v[182:185], v[198:201], v[58:61]
	v_mfma_f32_16x16x32_bf16 v[50:53], v[190:193], v[198:201], v[50:53]
	v_mfma_f32_16x16x32_bf16 v[42:45], v[182:185], v[206:209], v[42:45]
	v_mfma_f32_16x16x32_bf16 v[34:37], v[190:193], v[206:209], v[34:37]
	v_mfma_f32_16x16x32_bf16 v[26:29], v[182:185], v[214:217], v[26:29]
	v_mfma_f32_16x16x32_bf16 v[18:21], v[190:193], v[214:217], v[18:21]
	v_mfma_f32_16x16x32_bf16 v[10:13], v[182:185], v[222:225], v[10:13]
	v_mfma_f32_16x16x32_bf16 v[2:5], v[190:193], v[222:225], v[2:5]
	s_barrier
	s_setprio 0
	s_mov_b32 s7, s47
	s_add_u32 s88, s88, 0x100
	s_addc_u32 s89, s89, 0
	s_add_u32 s86, s86, 0x100
	s_addc_u32 s87, s87, 0
	s_cmp_ge_i32 s47, s101
	s_cbranch_scc1 .Lmy_kexit_8
.LBB0_1573:
	s_add_u32 s98, s86, 0xfffc0080
	s_addc_u32 s99, s87, -1
	s_cmp_eq_u32 s7, s100
	s_cselect_b64 s[94:95], s[90:91], s[98:99]
	s_cselect_b64 s[96:97], s[92:93], s[88:89]
	s_add_i32 s47, s7, 2
	s_nop 0
	s_mov_b32 m0, s74
	s_nop 0
	global_load_lds_dwordx4 v144, s[86:87]
	s_mov_b32 m0, s75
	s_nop 0
	global_load_lds_dwordx4 v142, s[86:87]
	ds_read_b128 v[156:159], v230
	ds_read_b128 v[166:169], v230 offset:1024
	ds_read_b128 v[170:173], v230 offset:2048
	ds_read_b128 v[174:177], v230 offset:3072
	ds_read_b128 v[178:181], v231
	ds_read_b128 v[182:185], v231 offset:1024
	ds_read_b128 v[186:189], v231 offset:2048
	ds_read_b128 v[190:193], v231 offset:3072
	ds_read_b128 v[194:197], v163
	ds_read_b128 v[198:201], v163 offset:1024
	ds_read_b128 v[202:205], v163 offset:2048
	ds_read_b128 v[206:209], v163 offset:3072
	ds_read_b128 v[210:213], v163 offset:4096
	ds_read_b128 v[214:217], v163 offset:5120
	ds_read_b128 v[218:221], v163 offset:6144
	ds_read_b128 v[222:225], v163 offset:7168
	s_waitcnt vmcnt(8)
	s_waitcnt lgkmcnt(0)
	s_setprio 1
	s_barrier
	v_mfma_f32_16x16x32_bf16 v[122:125], v[156:159], v[194:197], v[122:125]
	v_mfma_f32_16x16x32_bf16 v[118:121], v[170:173], v[194:197], v[118:121]
	v_mfma_f32_16x16x32_bf16 v[110:113], v[156:159], v[202:205], v[110:113]
	v_mfma_f32_16x16x32_bf16 v[102:105], v[170:173], v[202:205], v[102:105]
	v_mfma_f32_16x16x32_bf16 v[94:97], v[156:159], v[210:213], v[94:97]
	v_mfma_f32_16x16x32_bf16 v[86:89], v[170:173], v[210:213], v[86:89]
	v_mfma_f32_16x16x32_bf16 v[78:81], v[156:159], v[218:221], v[78:81]
	v_mfma_f32_16x16x32_bf16 v[70:73], v[170:173], v[218:221], v[70:73]
	v_mfma_f32_16x16x32_bf16 v[122:125], v[166:169], v[198:201], v[122:125]
	v_mfma_f32_16x16x32_bf16 v[118:121], v[174:177], v[198:201], v[118:121]
	v_mfma_f32_16x16x32_bf16 v[110:113], v[166:169], v[206:209], v[110:113]
	v_mfma_f32_16x16x32_bf16 v[102:105], v[174:177], v[206:209], v[102:105]
	v_mfma_f32_16x16x32_bf16 v[94:97], v[166:169], v[214:217], v[94:97]
	v_mfma_f32_16x16x32_bf16 v[86:89], v[174:177], v[214:217], v[86:89]
	v_mfma_f32_16x16x32_bf16 v[78:81], v[166:169], v[222:225], v[78:81]
	v_mfma_f32_16x16x32_bf16 v[70:73], v[174:177], v[222:225], v[70:73]
	s_setprio 0
	s_setprio 1
	v_mfma_f32_16x16x32_bf16 v[126:129], v[178:181], v[194:197], v[126:129]
	v_mfma_f32_16x16x32_bf16 v[114:117], v[186:189], v[194:197], v[114:117]
	v_mfma_f32_16x16x32_bf16 v[106:109], v[178:181], v[202:205], v[106:109]
	v_mfma_f32_16x16x32_bf16 v[98:101], v[186:189], v[202:205], v[98:101]
	v_mfma_f32_16x16x32_bf16 v[90:93], v[178:181], v[210:213], v[90:93]
	v_mfma_f32_16x16x32_bf16 v[82:85], v[186:189], v[210:213], v[82:85]
	v_mfma_f32_16x16x32_bf16 v[74:77], v[178:181], v[218:221], v[74:77]
	v_mfma_f32_16x16x32_bf16 v[66:69], v[186:189], v[218:221], v[66:69]
	v_mfma_f32_16x16x32_bf16 v[126:129], v[182:185], v[198:201], v[126:129]
	v_mfma_f32_16x16x32_bf16 v[114:117], v[190:193], v[198:201], v[114:117]
	v_mfma_f32_16x16x32_bf16 v[106:109], v[182:185], v[206:209], v[106:109]
	v_mfma_f32_16x16x32_bf16 v[98:101], v[190:193], v[206:209], v[98:101]
	v_mfma_f32_16x16x32_bf16 v[90:93], v[182:185], v[214:217], v[90:93]
	v_mfma_f32_16x16x32_bf16 v[82:85], v[190:193], v[214:217], v[82:85]
	v_mfma_f32_16x16x32_bf16 v[74:77], v[182:185], v[222:225], v[74:77]
	v_mfma_f32_16x16x32_bf16 v[66:69], v[190:193], v[222:225], v[66:69]
	s_barrier
	s_setprio 0
	s_add_u32 s98, s96, 0x40000
	s_addc_u32 s99, s97, 0
	s_add_i32 s7, s71, s29
	s_mov_b32 m0, s7
	s_nop 0
	global_load_lds_dwordx4 v132, s[96:97]
	s_add_i32 m0, s7, 0x2000
	s_add_i32 s7, s72, s29
	global_load_lds_dwordx4 v136, s[96:97]
	s_mov_b32 m0, s7
	s_nop 0
	global_load_lds_dwordx4 v132, s[98:99]
	s_add_i32 m0, s7, 0x2000
	s_nop 0
	global_load_lds_dwordx4 v136, s[98:99]
	s_mov_b32 m0, s51
	s_nop 0
	global_load_lds_dwordx4 v130, s[94:95]
	s_mov_b32 m0, s60
	s_nop 0
	global_load_lds_dwordx4 v134, s[94:95]
	ds_read_b128 v[194:197], v163 offset:16384
	ds_read_b128 v[198:201], v163 offset:17408
	ds_read_b128 v[202:205], v163 offset:18432
	ds_read_b128 v[206:209], v163 offset:19456
	ds_read_b128 v[210:213], v163 offset:20480
	ds_read_b128 v[214:217], v163 offset:21504
	ds_read_b128 v[218:221], v163 offset:22528
	ds_read_b128 v[222:225], v163 offset:23552
	s_waitcnt vmcnt(8)
	s_waitcnt lgkmcnt(0)
	s_setprio 1
	s_barrier
	v_mfma_f32_16x16x32_bf16 v[62:65], v[156:159], v[194:197], v[62:65]
	v_mfma_f32_16x16x32_bf16 v[54:57], v[170:173], v[194:197], v[54:57]
	v_mfma_f32_16x16x32_bf16 v[46:49], v[156:159], v[202:205], v[46:49]
	v_mfma_f32_16x16x32_bf16 v[38:41], v[170:173], v[202:205], v[38:41]
	v_mfma_f32_16x16x32_bf16 v[30:33], v[156:159], v[210:213], v[30:33]
	v_mfma_f32_16x16x32_bf16 v[22:25], v[170:173], v[210:213], v[22:25]
	v_mfma_f32_16x16x32_bf16 v[14:17], v[156:159], v[218:221], v[14:17]
	v_mfma_f32_16x16x32_bf16 v[6:9], v[170:173], v[218:221], v[6:9]
	v_mfma_f32_16x16x32_bf16 v[62:65], v[166:169], v[198:201], v[62:65]
	v_mfma_f32_16x16x32_bf16 v[54:57], v[174:177], v[198:201], v[54:57]
	v_mfma_f32_16x16x32_bf16 v[46:49], v[166:169], v[206:209], v[46:49]
	v_mfma_f32_16x16x32_bf16 v[38:41], v[174:177], v[206:209], v[38:41]
	v_mfma_f32_16x16x32_bf16 v[30:33], v[166:169], v[214:217], v[30:33]
	v_mfma_f32_16x16x32_bf16 v[22:25], v[174:177], v[214:217], v[22:25]
	v_mfma_f32_16x16x32_bf16 v[14:17], v[166:169], v[222:225], v[14:17]
	v_mfma_f32_16x16x32_bf16 v[6:9], v[174:177], v[222:225], v[6:9]
	s_setprio 0
	s_setprio 1
	v_mfma_f32_16x16x32_bf16 v[58:61], v[178:181], v[194:197], v[58:61]
	v_mfma_f32_16x16x32_bf16 v[50:53], v[186:189], v[194:197], v[50:53]
	v_mfma_f32_16x16x32_bf16 v[42:45], v[178:181], v[202:205], v[42:45]
	v_mfma_f32_16x16x32_bf16 v[34:37], v[186:189], v[202:205], v[34:37]
	v_mfma_f32_16x16x32_bf16 v[26:29], v[178:181], v[210:213], v[26:29]
	v_mfma_f32_16x16x32_bf16 v[18:21], v[186:189], v[210:213], v[18:21]
	v_mfma_f32_16x16x32_bf16 v[10:13], v[178:181], v[218:221], v[10:13]
	v_mfma_f32_16x16x32_bf16 v[2:5], v[186:189], v[218:221], v[2:5]
	v_mfma_f32_16x16x32_bf16 v[58:61], v[182:185], v[198:201], v[58:61]
	v_mfma_f32_16x16x32_bf16 v[50:53], v[190:193], v[198:201], v[50:53]
	v_mfma_f32_16x16x32_bf16 v[42:45], v[182:185], v[206:209], v[42:45]
	v_mfma_f32_16x16x32_bf16 v[34:37], v[190:193], v[206:209], v[34:37]
	v_mfma_f32_16x16x32_bf16 v[26:29], v[182:185], v[214:217], v[26:29]
	v_mfma_f32_16x16x32_bf16 v[18:21], v[190:193], v[214:217], v[18:21]
	v_mfma_f32_16x16x32_bf16 v[10:13], v[182:185], v[222:225], v[10:13]
	v_mfma_f32_16x16x32_bf16 v[2:5], v[190:193], v[222:225], v[2:5]
	s_barrier
	s_setprio 0
	s_add_u32 s98, s94, 0x40000
	s_addc_u32 s99, s95, 0
	s_add_i32 s7, 0, 0x18000
	s_add_i32 s49, 0, 0x1c000
	s_mov_b32 m0, s61
	s_nop 0
	global_load_lds_dwordx4 v130, s[98:99]
	s_mov_b32 m0, s62
	s_nop 0
	global_load_lds_dwordx4 v134, s[98:99]
	ds_read_b128 v[156:159], v232
	ds_read_b128 v[166:169], v232 offset:1024
	ds_read_b128 v[170:173], v232 offset:2048
	ds_read_b128 v[174:177], v232 offset:3072
	ds_read_b128 v[178:181], v233
	ds_read_b128 v[182:185], v233 offset:1024
	ds_read_b128 v[186:189], v233 offset:2048
	ds_read_b128 v[190:193], v233 offset:3072
	ds_read_b128 v[194:197], v163 offset:32768
	ds_read_b128 v[198:201], v163 offset:33792
	ds_read_b128 v[202:205], v163 offset:34816
	ds_read_b128 v[206:209], v163 offset:35840
	ds_read_b128 v[210:213], v163 offset:36864
	ds_read_b128 v[214:217], v163 offset:37888
	ds_read_b128 v[218:221], v163 offset:38912
	ds_read_b128 v[222:225], v163 offset:39936
	s_waitcnt vmcnt(8)
	s_waitcnt lgkmcnt(0)
	s_setprio 1
	s_barrier
	v_mfma_f32_16x16x32_bf16 v[122:125], v[156:159], v[194:197], v[122:125]
	v_mfma_f32_16x16x32_bf16 v[118:121], v[170:173], v[194:197], v[118:121]
	v_mfma_f32_16x16x32_bf16 v[110:113], v[156:159], v[202:205], v[110:113]
	v_mfma_f32_16x16x32_bf16 v[102:105], v[170:173], v[202:205], v[102:105]
	v_mfma_f32_16x16x32_bf16 v[94:97], v[156:159], v[210:213], v[94:97]
	v_mfma_f32_16x16x32_bf16 v[86:89], v[170:173], v[210:213], v[86:89]
	v_mfma_f32_16x16x32_bf16 v[78:81], v[156:159], v[218:221], v[78:81]
	v_mfma_f32_16x16x32_bf16 v[70:73], v[170:173], v[218:221], v[70:73]
	v_mfma_f32_16x16x32_bf16 v[122:125], v[166:169], v[198:201], v[122:125]
	v_mfma_f32_16x16x32_bf16 v[118:121], v[174:177], v[198:201], v[118:121]
	v_mfma_f32_16x16x32_bf16 v[110:113], v[166:169], v[206:209], v[110:113]
	v_mfma_f32_16x16x32_bf16 v[102:105], v[174:177], v[206:209], v[102:105]
	v_mfma_f32_16x16x32_bf16 v[94:97], v[166:169], v[214:217], v[94:97]
	v_mfma_f32_16x16x32_bf16 v[86:89], v[174:177], v[214:217], v[86:89]
	v_mfma_f32_16x16x32_bf16 v[78:81], v[166:169], v[222:225], v[78:81]
	v_mfma_f32_16x16x32_bf16 v[70:73], v[174:177], v[222:225], v[70:73]
	s_setprio 0
	s_setprio 1
	v_mfma_f32_16x16x32_bf16 v[126:129], v[178:181], v[194:197], v[126:129]
	v_mfma_f32_16x16x32_bf16 v[114:117], v[186:189], v[194:197], v[114:117]
	v_mfma_f32_16x16x32_bf16 v[106:109], v[178:181], v[202:205], v[106:109]
	v_mfma_f32_16x16x32_bf16 v[98:101], v[186:189], v[202:205], v[98:101]
	v_mfma_f32_16x16x32_bf16 v[90:93], v[178:181], v[210:213], v[90:93]
	v_mfma_f32_16x16x32_bf16 v[82:85], v[186:189], v[210:213], v[82:85]
	v_mfma_f32_16x16x32_bf16 v[74:77], v[178:181], v[218:221], v[74:77]
	v_mfma_f32_16x16x32_bf16 v[66:69], v[186:189], v[218:221], v[66:69]
	v_mfma_f32_16x16x32_bf16 v[126:129], v[182:185], v[198:201], v[126:129]
	v_mfma_f32_16x16x32_bf16 v[114:117], v[190:193], v[198:201], v[114:117]
	v_mfma_f32_16x16x32_bf16 v[106:109], v[182:185], v[206:209], v[106:109]
	v_mfma_f32_16x16x32_bf16 v[98:101], v[190:193], v[206:209], v[98:101]
	v_mfma_f32_16x16x32_bf16 v[90:93], v[182:185], v[214:217], v[90:93]
	v_mfma_f32_16x16x32_bf16 v[82:85], v[190:193], v[214:217], v[82:85]
	v_mfma_f32_16x16x32_bf16 v[74:77], v[182:185], v[222:225], v[74:77]
	v_mfma_f32_16x16x32_bf16 v[66:69], v[190:193], v[222:225], v[66:69]
	s_barrier
	s_setprio 0
	s_add_u32 s96, s96, 0x80
	s_addc_u32 s97, s97, 0
	s_add_u32 s98, s96, 0x40000
	s_addc_u32 s99, s97, 0
	s_add_u32 s94, s94, 0x80
	s_addc_u32 s95, s95, 0
	s_add_i32 s7, s7, s29
	s_mov_b32 m0, s7
	s_nop 0
	global_load_lds_dwordx4 v132, s[96:97]
	s_add_i32 m0, s7, 0x2000
	s_add_i32 s7, s49, s29
	global_load_lds_dwordx4 v136, s[96:97]
	s_mov_b32 m0, s7
	s_nop 0
	global_load_lds_dwordx4 v132, s[98:99]
	s_add_i32 m0, s7, 0x2000
	s_nop 0
	global_load_lds_dwordx4 v136, s[98:99]
	s_mov_b32 m0, s63
	s_nop 0
	global_load_lds_dwordx4 v130, s[94:95]
	s_mov_b32 m0, s64
	s_nop 0
	global_load_lds_dwordx4 v134, s[94:95]
	ds_read_b128 v[194:197], v163 offset:49152
	ds_read_b128 v[198:201], v163 offset:50176
	ds_read_b128 v[202:205], v163 offset:51200
	ds_read_b128 v[206:209], v163 offset:52224
	ds_read_b128 v[210:213], v163 offset:53248
	ds_read_b128 v[214:217], v163 offset:54272
	ds_read_b128 v[218:221], v163 offset:55296
	ds_read_b128 v[222:225], v163 offset:56320
	s_waitcnt vmcnt(8)
	s_waitcnt lgkmcnt(0)
	s_setprio 1
	s_barrier
	v_mfma_f32_16x16x32_bf16 v[62:65], v[156:159], v[194:197], v[62:65]
	v_mfma_f32_16x16x32_bf16 v[54:57], v[170:173], v[194:197], v[54:57]
	v_mfma_f32_16x16x32_bf16 v[46:49], v[156:159], v[202:205], v[46:49]
	v_mfma_f32_16x16x32_bf16 v[38:41], v[170:173], v[202:205], v[38:41]
	v_mfma_f32_16x16x32_bf16 v[30:33], v[156:159], v[210:213], v[30:33]
	v_mfma_f32_16x16x32_bf16 v[22:25], v[170:173], v[210:213], v[22:25]
	v_mfma_f32_16x16x32_bf16 v[14:17], v[156:159], v[218:221], v[14:17]
	v_mfma_f32_16x16x32_bf16 v[6:9], v[170:173], v[218:221], v[6:9]
	v_mfma_f32_16x16x32_bf16 v[62:65], v[166:169], v[198:201], v[62:65]
	v_mfma_f32_16x16x32_bf16 v[54:57], v[174:177], v[198:201], v[54:57]
	v_mfma_f32_16x16x32_bf16 v[46:49], v[166:169], v[206:209], v[46:49]
	v_mfma_f32_16x16x32_bf16 v[38:41], v[174:177], v[206:209], v[38:41]
	v_mfma_f32_16x16x32_bf16 v[30:33], v[166:169], v[214:217], v[30:33]
	v_mfma_f32_16x16x32_bf16 v[22:25], v[174:177], v[214:217], v[22:25]
	v_mfma_f32_16x16x32_bf16 v[14:17], v[166:169], v[222:225], v[14:17]
	v_mfma_f32_16x16x32_bf16 v[6:9], v[174:177], v[222:225], v[6:9]
	s_setprio 0
	s_setprio 1
	v_mfma_f32_16x16x32_bf16 v[58:61], v[178:181], v[194:197], v[58:61]
	v_mfma_f32_16x16x32_bf16 v[50:53], v[186:189], v[194:197], v[50:53]
	v_mfma_f32_16x16x32_bf16 v[42:45], v[178:181], v[202:205], v[42:45]
	v_mfma_f32_16x16x32_bf16 v[34:37], v[186:189], v[202:205], v[34:37]
	v_mfma_f32_16x16x32_bf16 v[26:29], v[178:181], v[210:213], v[26:29]
	v_mfma_f32_16x16x32_bf16 v[18:21], v[186:189], v[210:213], v[18:21]
	v_mfma_f32_16x16x32_bf16 v[10:13], v[178:181], v[218:221], v[10:13]
	v_mfma_f32_16x16x32_bf16 v[2:5], v[186:189], v[218:221], v[2:5]
	v_mfma_f32_16x16x32_bf16 v[58:61], v[182:185], v[198:201], v[58:61]
	v_mfma_f32_16x16x32_bf16 v[50:53], v[190:193], v[198:201], v[50:53]
	v_mfma_f32_16x16x32_bf16 v[42:45], v[182:185], v[206:209], v[42:45]
	v_mfma_f32_16x16x32_bf16 v[34:37], v[190:193], v[206:209], v[34:37]
	v_mfma_f32_16x16x32_bf16 v[26:29], v[182:185], v[214:217], v[26:29]
	v_mfma_f32_16x16x32_bf16 v[18:21], v[190:193], v[214:217], v[18:21]
	v_mfma_f32_16x16x32_bf16 v[10:13], v[182:185], v[222:225], v[10:13]
	v_mfma_f32_16x16x32_bf16 v[2:5], v[190:193], v[222:225], v[2:5]
	s_barrier
	s_setprio 0
	s_mov_b32 s7, s47
	s_add_u32 s88, s88, 0x100
	s_addc_u32 s89, s89, 0
	s_add_u32 s86, s86, 0x100
	s_addc_u32 s87, s87, 0
	s_cmp_ge_i32 s47, s101
	s_cbranch_scc0 .LBB0_1573

.LBB0_1761:
	v_cmp_gt_i32_e32 vcc, 1, v138
	s_cbranch_vccnz .LBB0_1823
	v_lshl_add_u64 v[152:153], v[2:3], 0, s[14:15]
	v_add_u32_e32 v154, -2, v138
	s_waitcnt lgkmcnt(0)
	v_lshl_add_u64 v[150:151], v[4:5], 0, s[18:19]
	s_mov_b32 s5, 0
	s_nop 0
	v_readfirstlane_b32 s86, v152
	v_readfirstlane_b32 s87, v153
	v_readfirstlane_b32 s88, v150
	v_readfirstlane_b32 s89, v151
	v_readfirstlane_b32 s90, v146
	v_readfirstlane_b32 s91, v147
	v_readfirstlane_b32 s92, v148
	v_readfirstlane_b32 s93, v149
	v_readfirstlane_b32 s100, v154
	v_readfirstlane_b32 s101, v138
	v_add_u32_e32 v230, s74, v141
	v_add_u32_e32 v231, s75, v141
	v_add_u32_e32 v232, 0x18000, v141
	v_add_u32_e32 v233, 0x1c000, v141
	s_add_u32 s98, s86, 0xfffc0080
	s_addc_u32 s99, s87, -1
	s_cmp_eq_u32 s5, s100
	s_cselect_b64 s[94:95], s[90:91], s[98:99]
	s_cselect_b64 s[96:97], s[92:93], s[88:89]
	s_add_i32 s29, s5, 2
	s_nop 0
	s_add_i32 m0, s47, 0xc000
	s_nop 0
	global_load_lds_dwordx4 v144, s[86:87]
	s_add_i32 m0, s47, 0xe000
	s_nop 0
	global_load_lds_dwordx4 v142, s[86:87]
	ds_read_b128 v[164:167], v230
	ds_read_b128 v[168:171], v230 offset:1024
	ds_read_b128 v[172:175], v230 offset:2048
	ds_read_b128 v[176:179], v230 offset:3072
	ds_read_b128 v[180:183], v231
	ds_read_b128 v[184:187], v231 offset:1024
	ds_read_b128 v[188:191], v231 offset:2048
	ds_read_b128 v[192:195], v231 offset:3072
	ds_read_b128 v[196:199], v160
	ds_read_b128 v[200:203], v160 offset:1024
	ds_read_b128 v[204:207], v160 offset:2048
	ds_read_b128 v[208:211], v160 offset:3072
	ds_read_b128 v[212:215], v160 offset:4096
	ds_read_b128 v[216:219], v160 offset:5120
	ds_read_b128 v[220:223], v160 offset:6144
	ds_read_b128 v[224:227], v160 offset:7168
	s_waitcnt vmcnt(8)
	s_waitcnt lgkmcnt(0)
	s_setprio 1
	s_barrier
	v_mfma_f32_16x16x32_bf16 v[122:125], v[164:167], v[196:199], 0
	v_mfma_f32_16x16x32_bf16 v[118:121], v[172:175], v[196:199], 0
	v_mfma_f32_16x16x32_bf16 v[110:113], v[164:167], v[204:207], 0
	v_mfma_f32_16x16x32_bf16 v[102:105], v[172:175], v[204:207], 0
	v_mfma_f32_16x16x32_bf16 v[94:97], v[164:167], v[212:215], 0
	v_mfma_f32_16x16x32_bf16 v[86:89], v[172:175], v[212:215], 0
	v_mfma_f32_16x16x32_bf16 v[78:81], v[164:167], v[220:223], 0
	v_mfma_f32_16x16x32_bf16 v[70:73], v[172:175], v[220:223], 0
	v_mfma_f32_16x16x32_bf16 v[122:125], v[168:171], v[200:203], v[122:125]
	v_mfma_f32_16x16x32_bf16 v[118:121], v[176:179], v[200:203], v[118:121]
	v_mfma_f32_16x16x32_bf16 v[110:113], v[168:171], v[208:211], v[110:113]
	v_mfma_f32_16x16x32_bf16 v[102:105], v[176:179], v[208:211], v[102:105]
	v_mfma_f32_16x16x32_bf16 v[94:97], v[168:171], v[216:219], v[94:97]
	v_mfma_f32_16x16x32_bf16 v[86:89], v[176:179], v[216:219], v[86:89]
	v_mfma_f32_16x16x32_bf16 v[78:81], v[168:171], v[224:227], v[78:81]
	v_mfma_f32_16x16x32_bf16 v[70:73], v[176:179], v[224:227], v[70:73]
	s_setprio 0
	s_setprio 1
	v_mfma_f32_16x16x32_bf16 v[126:129], v[180:183], v[196:199], 0
	v_mfma_f32_16x16x32_bf16 v[114:117], v[188:191], v[196:199], 0
	v_mfma_f32_16x16x32_bf16 v[106:109], v[180:183], v[204:207], 0
	v_mfma_f32_16x16x32_bf16 v[98:101], v[188:191], v[204:207], 0
	v_mfma_f32_16x16x32_bf16 v[90:93], v[180:183], v[212:215], 0
	v_mfma_f32_16x16x32_bf16 v[82:85], v[188:191], v[212:215], 0
	v_mfma_f32_16x16x32_bf16 v[74:77], v[180:183], v[220:223], 0
	v_mfma_f32_16x16x32_bf16 v[66:69], v[188:191], v[220:223], 0
	v_mfma_f32_16x16x32_bf16 v[126:129], v[184:187], v[200:203], v[126:129]
	v_mfma_f32_16x16x32_bf16 v[114:117], v[192:195], v[200:203], v[114:117]
	v_mfma_f32_16x16x32_bf16 v[106:109], v[184:187], v[208:211], v[106:109]
	v_mfma_f32_16x16x32_bf16 v[98:101], v[192:195], v[208:211], v[98:101]
	v_mfma_f32_16x16x32_bf16 v[90:93], v[184:187], v[216:219], v[90:93]
	v_mfma_f32_16x16x32_bf16 v[82:85], v[192:195], v[216:219], v[82:85]
	v_mfma_f32_16x16x32_bf16 v[74:77], v[184:187], v[224:227], v[74:77]
	v_mfma_f32_16x16x32_bf16 v[66:69], v[192:195], v[224:227], v[66:69]
	s_barrier
	s_setprio 0
	s_add_u32 s98, s96, 0x40000
	s_addc_u32 s99, s97, 0
	s_add_i32 s5, s74, s23
	s_mov_b32 m0, s5
	s_nop 0
	global_load_lds_dwordx4 v132, s[96:97]
	s_add_i32 m0, s5, 0x2000
	s_add_i32 s5, s75, s23
	global_load_lds_dwordx4 v136, s[96:97]
	s_mov_b32 m0, s5
	s_nop 0
	global_load_lds_dwordx4 v132, s[98:99]
	s_add_i32 m0, s5, 0x2000
	s_nop 0
	global_load_lds_dwordx4 v136, s[98:99]
	s_mov_b32 m0, s47
	s_nop 0
	global_load_lds_dwordx4 v130, s[94:95]
	s_mov_b32 m0, s56
	s_nop 0
	global_load_lds_dwordx4 v134, s[94:95]
	ds_read_b128 v[196:199], v160 offset:16384
	ds_read_b128 v[200:203], v160 offset:17408
	ds_read_b128 v[204:207], v160 offset:18432
	ds_read_b128 v[208:211], v160 offset:19456
	ds_read_b128 v[212:215], v160 offset:20480
	ds_read_b128 v[216:219], v160 offset:21504
	ds_read_b128 v[220:223], v160 offset:22528
	ds_read_b128 v[224:227], v160 offset:23552
	s_waitcnt vmcnt(8)
	s_waitcnt lgkmcnt(0)
	s_setprio 1
	s_barrier
	v_mfma_f32_16x16x32_bf16 v[62:65], v[164:167], v[196:199], 0
	v_mfma_f32_16x16x32_bf16 v[54:57], v[172:175], v[196:199], 0
	v_mfma_f32_16x16x32_bf16 v[46:49], v[164:167], v[204:207], 0
	v_mfma_f32_16x16x32_bf16 v[38:41], v[172:175], v[204:207], 0
	v_mfma_f32_16x16x32_bf16 v[30:33], v[164:167], v[212:215], 0
	v_mfma_f32_16x16x32_bf16 v[22:25], v[172:175], v[212:215], 0
	v_mfma_f32_16x16x32_bf16 v[14:17], v[164:167], v[220:223], 0
	v_mfma_f32_16x16x32_bf16 v[6:9], v[172:175], v[220:223], 0
	v_mfma_f32_16x16x32_bf16 v[62:65], v[168:171], v[200:203], v[62:65]
	v_mfma_f32_16x16x32_bf16 v[54:57], v[176:179], v[200:203], v[54:57]
	v_mfma_f32_16x16x32_bf16 v[46:49], v[168:171], v[208:211], v[46:49]
	v_mfma_f32_16x16x32_bf16 v[38:41], v[176:179], v[208:211], v[38:41]
	v_mfma_f32_16x16x32_bf16 v[30:33], v[168:171], v[216:219], v[30:33]
	v_mfma_f32_16x16x32_bf16 v[22:25], v[176:179], v[216:219], v[22:25]
	v_mfma_f32_16x16x32_bf16 v[14:17], v[168:171], v[224:227], v[14:17]
	v_mfma_f32_16x16x32_bf16 v[6:9], v[176:179], v[224:227], v[6:9]
	s_setprio 0
	s_setprio 1
	v_mfma_f32_16x16x32_bf16 v[58:61], v[180:183], v[196:199], 0
	v_mfma_f32_16x16x32_bf16 v[50:53], v[188:191], v[196:199], 0
	v_mfma_f32_16x16x32_bf16 v[42:45], v[180:183], v[204:207], 0
	v_mfma_f32_16x16x32_bf16 v[34:37], v[188:191], v[204:207], 0
	v_mfma_f32_16x16x32_bf16 v[26:29], v[180:183], v[212:215], 0
	v_mfma_f32_16x16x32_bf16 v[18:21], v[188:191], v[212:215], 0
	v_mfma_f32_16x16x32_bf16 v[10:13], v[180:183], v[220:223], 0
	v_mfma_f32_16x16x32_bf16 v[2:5], v[188:191], v[220:223], 0
	v_mfma_f32_16x16x32_bf16 v[58:61], v[184:187], v[200:203], v[58:61]
	v_mfma_f32_16x16x32_bf16 v[50:53], v[192:195], v[200:203], v[50:53]
	v_mfma_f32_16x16x32_bf16 v[42:45], v[184:187], v[208:211], v[42:45]
	v_mfma_f32_16x16x32_bf16 v[34:37], v[192:195], v[208:211], v[34:37]
	v_mfma_f32_16x16x32_bf16 v[26:29], v[184:187], v[216:219], v[26:29]
	v_mfma_f32_16x16x32_bf16 v[18:21], v[192:195], v[216:219], v[18:21]
	v_mfma_f32_16x16x32_bf16 v[10:13], v[184:187], v[224:227], v[10:13]
	v_mfma_f32_16x16x32_bf16 v[2:5], v[192:195], v[224:227], v[2:5]
	s_barrier
	s_setprio 0
	s_add_u32 s98, s94, 0x40000
	s_addc_u32 s99, s95, 0
	s_add_i32 s5, 0, 0x18000
	s_add_i32 s45, 0, 0x1c000
	s_mov_b32 m0, s57
	s_nop 0
	global_load_lds_dwordx4 v130, s[98:99]
	s_mov_b32 m0, s58
	s_nop 0
	global_load_lds_dwordx4 v134, s[98:99]
	ds_read_b128 v[164:167], v232
	ds_read_b128 v[168:171], v232 offset:1024
	ds_read_b128 v[172:175], v232 offset:2048
	ds_read_b128 v[176:179], v232 offset:3072
	ds_read_b128 v[180:183], v233
	ds_read_b128 v[184:187], v233 offset:1024
	ds_read_b128 v[188:191], v233 offset:2048
	ds_read_b128 v[192:195], v233 offset:3072
	ds_read_b128 v[196:199], v160 offset:32768
	ds_read_b128 v[200:203], v160 offset:33792
	ds_read_b128 v[204:207], v160 offset:34816
	ds_read_b128 v[208:211], v160 offset:35840
	ds_read_b128 v[212:215], v160 offset:36864
	ds_read_b128 v[216:219], v160 offset:37888
	ds_read_b128 v[220:223], v160 offset:38912
	ds_read_b128 v[224:227], v160 offset:39936
	s_waitcnt vmcnt(8)
	s_waitcnt lgkmcnt(0)
	s_setprio 1
	s_barrier
	v_mfma_f32_16x16x32_bf16 v[122:125], v[164:167], v[196:199], v[122:125]
	v_mfma_f32_16x16x32_bf16 v[118:121], v[172:175], v[196:199], v[118:121]
	v_mfma_f32_16x16x32_bf16 v[110:113], v[164:167], v[204:207], v[110:113]
	v_mfma_f32_16x16x32_bf16 v[102:105], v[172:175], v[204:207], v[102:105]
	v_mfma_f32_16x16x32_bf16 v[94:97], v[164:167], v[212:215], v[94:97]
	v_mfma_f32_16x16x32_bf16 v[86:89], v[172:175], v[212:215], v[86:89]
	v_mfma_f32_16x16x32_bf16 v[78:81], v[164:167], v[220:223], v[78:81]
	v_mfma_f32_16x16x32_bf16 v[70:73], v[172:175], v[220:223], v[70:73]
	v_mfma_f32_16x16x32_bf16 v[122:125], v[168:171], v[200:203], v[122:125]
	v_mfma_f32_16x16x32_bf16 v[118:121], v[176:179], v[200:203], v[118:121]
	v_mfma_f32_16x16x32_bf16 v[110:113], v[168:171], v[208:211], v[110:113]
	v_mfma_f32_16x16x32_bf16 v[102:105], v[176:179], v[208:211], v[102:105]
	v_mfma_f32_16x16x32_bf16 v[94:97], v[168:171], v[216:219], v[94:97]
	v_mfma_f32_16x16x32_bf16 v[86:89], v[176:179], v[216:219], v[86:89]
	v_mfma_f32_16x16x32_bf16 v[78:81], v[168:171], v[224:227], v[78:81]
	v_mfma_f32_16x16x32_bf16 v[70:73], v[176:179], v[224:227], v[70:73]
	s_setprio 0
	s_setprio 1
	v_mfma_f32_16x16x32_bf16 v[126:129], v[180:183], v[196:199], v[126:129]
	v_mfma_f32_16x16x32_bf16 v[114:117], v[188:191], v[196:199], v[114:117]
	v_mfma_f32_16x16x32_bf16 v[106:109], v[180:183], v[204:207], v[106:109]
	v_mfma_f32_16x16x32_bf16 v[98:101], v[188:191], v[204:207], v[98:101]
	v_mfma_f32_16x16x32_bf16 v[90:93], v[180:183], v[212:215], v[90:93]
	v_mfma_f32_16x16x32_bf16 v[82:85], v[188:191], v[212:215], v[82:85]
	v_mfma_f32_16x16x32_bf16 v[74:77], v[180:183], v[220:223], v[74:77]
	v_mfma_f32_16x16x32_bf16 v[66:69], v[188:191], v[220:223], v[66:69]
	v_mfma_f32_16x16x32_bf16 v[126:129], v[184:187], v[200:203], v[126:129]
	v_mfma_f32_16x16x32_bf16 v[114:117], v[192:195], v[200:203], v[114:117]
	v_mfma_f32_16x16x32_bf16 v[106:109], v[184:187], v[208:211], v[106:109]
	v_mfma_f32_16x16x32_bf16 v[98:101], v[192:195], v[208:211], v[98:101]
	v_mfma_f32_16x16x32_bf16 v[90:93], v[184:187], v[216:219], v[90:93]
	v_mfma_f32_16x16x32_bf16 v[82:85], v[192:195], v[216:219], v[82:85]
	v_mfma_f32_16x16x32_bf16 v[74:77], v[184:187], v[224:227], v[74:77]
	v_mfma_f32_16x16x32_bf16 v[66:69], v[192:195], v[224:227], v[66:69]
	s_barrier
	s_setprio 0
	s_add_u32 s96, s96, 0x80
	s_addc_u32 s97, s97, 0
	s_add_u32 s98, s96, 0x40000
	s_addc_u32 s99, s97, 0
	s_add_u32 s94, s94, 0x80
	s_addc_u32 s95, s95, 0
	s_add_i32 s5, s5, s23
	s_mov_b32 m0, s5
	s_nop 0
	global_load_lds_dwordx4 v132, s[96:97]
	s_add_i32 m0, s5, 0x2000
	s_add_i32 s5, s45, s23
	global_load_lds_dwordx4 v136, s[96:97]
	s_mov_b32 m0, s5
	s_nop 0
	global_load_lds_dwordx4 v132, s[98:99]
	s_add_i32 m0, s5, 0x2000
	s_nop 0
	global_load_lds_dwordx4 v136, s[98:99]
	s_mov_b32 m0, s64
	s_nop 0
	global_load_lds_dwordx4 v130, s[94:95]
	s_mov_b32 m0, s65
	s_nop 0
	global_load_lds_dwordx4 v134, s[94:95]
	ds_read_b128 v[196:199], v160 offset:49152
	ds_read_b128 v[200:203], v160 offset:50176
	ds_read_b128 v[204:207], v160 offset:51200
	ds_read_b128 v[208:211], v160 offset:52224
	ds_read_b128 v[212:215], v160 offset:53248
	ds_read_b128 v[216:219], v160 offset:54272
	ds_read_b128 v[220:223], v160 offset:55296
	ds_read_b128 v[224:227], v160 offset:56320
	s_waitcnt vmcnt(8)
	s_waitcnt lgkmcnt(0)
	s_setprio 1
	s_barrier
	v_mfma_f32_16x16x32_bf16 v[62:65], v[164:167], v[196:199], v[62:65]
	v_mfma_f32_16x16x32_bf16 v[54:57], v[172:175], v[196:199], v[54:57]
	v_mfma_f32_16x16x32_bf16 v[46:49], v[164:167], v[204:207], v[46:49]
	v_mfma_f32_16x16x32_bf16 v[38:41], v[172:175], v[204:207], v[38:41]
	v_mfma_f32_16x16x32_bf16 v[30:33], v[164:167], v[212:215], v[30:33]
	v_mfma_f32_16x16x32_bf16 v[22:25], v[172:175], v[212:215], v[22:25]
	v_mfma_f32_16x16x32_bf16 v[14:17], v[164:167], v[220:223], v[14:17]
	v_mfma_f32_16x16x32_bf16 v[6:9], v[172:175], v[220:223], v[6:9]
	v_mfma_f32_16x16x32_bf16 v[62:65], v[168:171], v[200:203], v[62:65]
	v_mfma_f32_16x16x32_bf16 v[54:57], v[176:179], v[200:203], v[54:57]
	v_mfma_f32_16x16x32_bf16 v[46:49], v[168:171], v[208:211], v[46:49]
	v_mfma_f32_16x16x32_bf16 v[38:41], v[176:179], v[208:211], v[38:41]
	v_mfma_f32_16x16x32_bf16 v[30:33], v[168:171], v[216:219], v[30:33]
	v_mfma_f32_16x16x32_bf16 v[22:25], v[176:179], v[216:219], v[22:25]
	v_mfma_f32_16x16x32_bf16 v[14:17], v[168:171], v[224:227], v[14:17]
	v_mfma_f32_16x16x32_bf16 v[6:9], v[176:179], v[224:227], v[6:9]
	s_setprio 0
	s_setprio 1
	v_mfma_f32_16x16x32_bf16 v[58:61], v[180:183], v[196:199], v[58:61]
	v_mfma_f32_16x16x32_bf16 v[50:53], v[188:191], v[196:199], v[50:53]
	v_mfma_f32_16x16x32_bf16 v[42:45], v[180:183], v[204:207], v[42:45]
	v_mfma_f32_16x16x32_bf16 v[34:37], v[188:191], v[204:207], v[34:37]
	v_mfma_f32_16x16x32_bf16 v[26:29], v[180:183], v[212:215], v[26:29]
	v_mfma_f32_16x16x32_bf16 v[18:21], v[188:191], v[212:215], v[18:21]
	v_mfma_f32_16x16x32_bf16 v[10:13], v[180:183], v[220:223], v[10:13]
	v_mfma_f32_16x16x32_bf16 v[2:5], v[188:191], v[220:223], v[2:5]
	v_mfma_f32_16x16x32_bf16 v[58:61], v[184:187], v[200:203], v[58:61]
	v_mfma_f32_16x16x32_bf16 v[50:53], v[192:195], v[200:203], v[50:53]
	v_mfma_f32_16x16x32_bf16 v[42:45], v[184:187], v[208:211], v[42:45]
	v_mfma_f32_16x16x32_bf16 v[34:37], v[192:195], v[208:211], v[34:37]
	v_mfma_f32_16x16x32_bf16 v[26:29], v[184:187], v[216:219], v[26:29]
	v_mfma_f32_16x16x32_bf16 v[18:21], v[192:195], v[216:219], v[18:21]
	v_mfma_f32_16x16x32_bf16 v[10:13], v[184:187], v[224:227], v[10:13]
	v_mfma_f32_16x16x32_bf16 v[2:5], v[192:195], v[224:227], v[2:5]
	s_barrier
	s_setprio 0
	s_mov_b32 s5, s29
	s_add_u32 s88, s88, 0x100
	s_addc_u32 s89, s89, 0
	s_add_u32 s86, s86, 0x100
	s_addc_u32 s87, s87, 0
	s_cmp_ge_i32 s29, s101
	s_cbranch_scc1 .Lmy_kexit_9
.LBB0_1763:
	s_add_u32 s98, s86, 0xfffc0080
	s_addc_u32 s99, s87, -1
	s_cmp_eq_u32 s5, s100
	s_cselect_b64 s[94:95], s[90:91], s[98:99]
	s_cselect_b64 s[96:97], s[92:93], s[88:89]
	s_add_i32 s29, s5, 2
	s_nop 0
	s_add_i32 m0, s47, 0xc000
	s_nop 0
	global_load_lds_dwordx4 v144, s[86:87]
	s_add_i32 m0, s47, 0xe000
	s_nop 0
	global_load_lds_dwordx4 v142, s[86:87]
	ds_read_b128 v[164:167], v230
	ds_read_b128 v[168:171], v230 offset:1024
	ds_read_b128 v[172:175], v230 offset:2048
	ds_read_b128 v[176:179], v230 offset:3072
	ds_read_b128 v[180:183], v231
	ds_read_b128 v[184:187], v231 offset:1024
	ds_read_b128 v[188:191], v231 offset:2048
	ds_read_b128 v[192:195], v231 offset:3072
	ds_read_b128 v[196:199], v160
	ds_read_b128 v[200:203], v160 offset:1024
	ds_read_b128 v[204:207], v160 offset:2048
	ds_read_b128 v[208:211], v160 offset:3072
	ds_read_b128 v[212:215], v160 offset:4096
	ds_read_b128 v[216:219], v160 offset:5120
	ds_read_b128 v[220:223], v160 offset:6144
	ds_read_b128 v[224:227], v160 offset:7168
	s_waitcnt vmcnt(8)
	s_waitcnt lgkmcnt(0)
	s_setprio 1
	s_barrier
	v_mfma_f32_16x16x32_bf16 v[122:125], v[164:167], v[196:199], v[122:125]
	v_mfma_f32_16x16x32_bf16 v[118:121], v[172:175], v[196:199], v[118:121]
	v_mfma_f32_16x16x32_bf16 v[110:113], v[164:167], v[204:207], v[110:113]
	v_mfma_f32_16x16x32_bf16 v[102:105], v[172:175], v[204:207], v[102:105]
	v_mfma_f32_16x16x32_bf16 v[94:97], v[164:167], v[212:215], v[94:97]
	v_mfma_f32_16x16x32_bf16 v[86:89], v[172:175], v[212:215], v[86:89]
	v_mfma_f32_16x16x32_bf16 v[78:81], v[164:167], v[220:223], v[78:81]
	v_mfma_f32_16x16x32_bf16 v[70:73], v[172:175], v[220:223], v[70:73]
	v_mfma_f32_16x16x32_bf16 v[122:125], v[168:171], v[200:203], v[122:125]
	v_mfma_f32_16x16x32_bf16 v[118:121], v[176:179], v[200:203], v[118:121]
	v_mfma_f32_16x16x32_bf16 v[110:113], v[168:171], v[208:211], v[110:113]
	v_mfma_f32_16x16x32_bf16 v[102:105], v[176:179], v[208:211], v[102:105]
	v_mfma_f32_16x16x32_bf16 v[94:97], v[168:171], v[216:219], v[94:97]
	v_mfma_f32_16x16x32_bf16 v[86:89], v[176:179], v[216:219], v[86:89]
	v_mfma_f32_16x16x32_bf16 v[78:81], v[168:171], v[224:227], v[78:81]
	v_mfma_f32_16x16x32_bf16 v[70:73], v[176:179], v[224:227], v[70:73]
	s_setprio 0
	s_setprio 1
	v_mfma_f32_16x16x32_bf16 v[126:129], v[180:183], v[196:199], v[126:129]
	v_mfma_f32_16x16x32_bf16 v[114:117], v[188:191], v[196:199], v[114:117]
	v_mfma_f32_16x16x32_bf16 v[106:109], v[180:183], v[204:207], v[106:109]
	v_mfma_f32_16x16x32_bf16 v[98:101], v[188:191], v[204:207], v[98:101]
	v_mfma_f32_16x16x32_bf16 v[90:93], v[180:183], v[212:215], v[90:93]
	v_mfma_f32_16x16x32_bf16 v[82:85], v[188:191], v[212:215], v[82:85]
	v_mfma_f32_16x16x32_bf16 v[74:77], v[180:183], v[220:223], v[74:77]
	v_mfma_f32_16x16x32_bf16 v[66:69], v[188:191], v[220:223], v[66:69]
	v_mfma_f32_16x16x32_bf16 v[126:129], v[184:187], v[200:203], v[126:129]
	v_mfma_f32_16x16x32_bf16 v[114:117], v[192:195], v[200:203], v[114:117]
	v_mfma_f32_16x16x32_bf16 v[106:109], v[184:187], v[208:211], v[106:109]
	v_mfma_f32_16x16x32_bf16 v[98:101], v[192:195], v[208:211], v[98:101]
	v_mfma_f32_16x16x32_bf16 v[90:93], v[184:187], v[216:219], v[90:93]
	v_mfma_f32_16x16x32_bf16 v[82:85], v[192:195], v[216:219], v[82:85]
	v_mfma_f32_16x16x32_bf16 v[74:77], v[184:187], v[224:227], v[74:77]
	v_mfma_f32_16x16x32_bf16 v[66:69], v[192:195], v[224:227], v[66:69]
	s_barrier
	s_setprio 0
	s_add_u32 s98, s96, 0x40000
	s_addc_u32 s99, s97, 0
	s_add_i32 s5, s74, s23
	s_mov_b32 m0, s5
	s_nop 0
	global_load_lds_dwordx4 v132, s[96:97]
	s_add_i32 m0, s5, 0x2000
	s_add_i32 s5, s75, s23
	global_load_lds_dwordx4 v136, s[96:97]
	s_mov_b32 m0, s5
	s_nop 0
	global_load_lds_dwordx4 v132, s[98:99]
	s_add_i32 m0, s5, 0x2000
	s_nop 0
	global_load_lds_dwordx4 v136, s[98:99]
	s_mov_b32 m0, s47
	s_nop 0
	global_load_lds_dwordx4 v130, s[94:95]
	s_mov_b32 m0, s56
	s_nop 0
	global_load_lds_dwordx4 v134, s[94:95]
	ds_read_b128 v[196:199], v160 offset:16384
	ds_read_b128 v[200:203], v160 offset:17408
	ds_read_b128 v[204:207], v160 offset:18432
	ds_read_b128 v[208:211], v160 offset:19456
	ds_read_b128 v[212:215], v160 offset:20480
	ds_read_b128 v[216:219], v160 offset:21504
	ds_read_b128 v[220:223], v160 offset:22528
	ds_read_b128 v[224:227], v160 offset:23552
	s_waitcnt vmcnt(8)
	s_waitcnt lgkmcnt(0)
	s_setprio 1
	s_barrier
	v_mfma_f32_16x16x32_bf16 v[62:65], v[164:167], v[196:199], v[62:65]
	v_mfma_f32_16x16x32_bf16 v[54:57], v[172:175], v[196:199], v[54:57]
	v_mfma_f32_16x16x32_bf16 v[46:49], v[164:167], v[204:207], v[46:49]
	v_mfma_f32_16x16x32_bf16 v[38:41], v[172:175], v[204:207], v[38:41]
	v_mfma_f32_16x16x32_bf16 v[30:33], v[164:167], v[212:215], v[30:33]
	v_mfma_f32_16x16x32_bf16 v[22:25], v[172:175], v[212:215], v[22:25]
	v_mfma_f32_16x16x32_bf16 v[14:17], v[164:167], v[220:223], v[14:17]
	v_mfma_f32_16x16x32_bf16 v[6:9], v[172:175], v[220:223], v[6:9]
	v_mfma_f32_16x16x32_bf16 v[62:65], v[168:171], v[200:203], v[62:65]
	v_mfma_f32_16x16x32_bf16 v[54:57], v[176:179], v[200:203], v[54:57]
	v_mfma_f32_16x16x32_bf16 v[46:49], v[168:171], v[208:211], v[46:49]
	v_mfma_f32_16x16x32_bf16 v[38:41], v[176:179], v[208:211], v[38:41]
	v_mfma_f32_16x16x32_bf16 v[30:33], v[168:171], v[216:219], v[30:33]
	v_mfma_f32_16x16x32_bf16 v[22:25], v[176:179], v[216:219], v[22:25]
	v_mfma_f32_16x16x32_bf16 v[14:17], v[168:171], v[224:227], v[14:17]
	v_mfma_f32_16x16x32_bf16 v[6:9], v[176:179], v[224:227], v[6:9]
	s_setprio 0
	s_setprio 1
	v_mfma_f32_16x16x32_bf16 v[58:61], v[180:183], v[196:199], v[58:61]
	v_mfma_f32_16x16x32_bf16 v[50:53], v[188:191], v[196:199], v[50:53]
	v_mfma_f32_16x16x32_bf16 v[42:45], v[180:183], v[204:207], v[42:45]
	v_mfma_f32_16x16x32_bf16 v[34:37], v[188:191], v[204:207], v[34:37]
	v_mfma_f32_16x16x32_bf16 v[26:29], v[180:183], v[212:215], v[26:29]
	v_mfma_f32_16x16x32_bf16 v[18:21], v[188:191], v[212:215], v[18:21]
	v_mfma_f32_16x16x32_bf16 v[10:13], v[180:183], v[220:223], v[10:13]
	v_mfma_f32_16x16x32_bf16 v[2:5], v[188:191], v[220:223], v[2:5]
	v_mfma_f32_16x16x32_bf16 v[58:61], v[184:187], v[200:203], v[58:61]
	v_mfma_f32_16x16x32_bf16 v[50:53], v[192:195], v[200:203], v[50:53]
	v_mfma_f32_16x16x32_bf16 v[42:45], v[184:187], v[208:211], v[42:45]
	v_mfma_f32_16x16x32_bf16 v[34:37], v[192:195], v[208:211], v[34:37]
	v_mfma_f32_16x16x32_bf16 v[26:29], v[184:187], v[216:219], v[26:29]
	v_mfma_f32_16x16x32_bf16 v[18:21], v[192:195], v[216:219], v[18:21]
	v_mfma_f32_16x16x32_bf16 v[10:13], v[184:187], v[224:227], v[10:13]
	v_mfma_f32_16x16x32_bf16 v[2:5], v[192:195], v[224:227], v[2:5]
	s_barrier
	s_setprio 0
	s_add_u32 s98, s94, 0x40000
	s_addc_u32 s99, s95, 0
	s_add_i32 s5, 0, 0x18000
	s_add_i32 s45, 0, 0x1c000
	s_mov_b32 m0, s57
	s_nop 0
	global_load_lds_dwordx4 v130, s[98:99]
	s_mov_b32 m0, s58
	s_nop 0
	global_load_lds_dwordx4 v134, s[98:99]
	ds_read_b128 v[164:167], v232
	ds_read_b128 v[168:171], v232 offset:1024
	ds_read_b128 v[172:175], v232 offset:2048
	ds_read_b128 v[176:179], v232 offset:3072
	ds_read_b128 v[180:183], v233
	ds_read_b128 v[184:187], v233 offset:1024
	ds_read_b128 v[188:191], v233 offset:2048
	ds_read_b128 v[192:195], v233 offset:3072
	ds_read_b128 v[196:199], v160 offset:32768
	ds_read_b128 v[200:203], v160 offset:33792
	ds_read_b128 v[204:207], v160 offset:34816
	ds_read_b128 v[208:211], v160 offset:35840
	ds_read_b128 v[212:215], v160 offset:36864
	ds_read_b128 v[216:219], v160 offset:37888
	ds_read_b128 v[220:223], v160 offset:38912
	ds_read_b128 v[224:227], v160 offset:39936
	s_waitcnt vmcnt(8)
	s_waitcnt lgkmcnt(0)
	s_setprio 1
	s_barrier
	v_mfma_f32_16x16x32_bf16 v[122:125], v[164:167], v[196:199], v[122:125]
	v_mfma_f32_16x16x32_bf16 v[118:121], v[172:175], v[196:199], v[118:121]
	v_mfma_f32_16x16x32_bf16 v[110:113], v[164:167], v[204:207], v[110:113]
	v_mfma_f32_16x16x32_bf16 v[102:105], v[172:175], v[204:207], v[102:105]
	v_mfma_f32_16x16x32_bf16 v[94:97], v[164:167], v[212:215], v[94:97]
	v_mfma_f32_16x16x32_bf16 v[86:89], v[172:175], v[212:215], v[86:89]
	v_mfma_f32_16x16x32_bf16 v[78:81], v[164:167], v[220:223], v[78:81]
	v_mfma_f32_16x16x32_bf16 v[70:73], v[172:175], v[220:223], v[70:73]
	v_mfma_f32_16x16x32_bf16 v[122:125], v[168:171], v[200:203], v[122:125]
	v_mfma_f32_16x16x32_bf16 v[118:121], v[176:179], v[200:203], v[118:121]
	v_mfma_f32_16x16x32_bf16 v[110:113], v[168:171], v[208:211], v[110:113]
	v_mfma_f32_16x16x32_bf16 v[102:105], v[176:179], v[208:211], v[102:105]
	v_mfma_f32_16x16x32_bf16 v[94:97], v[168:171], v[216:219], v[94:97]
	v_mfma_f32_16x16x32_bf16 v[86:89], v[176:179], v[216:219], v[86:89]
	v_mfma_f32_16x16x32_bf16 v[78:81], v[168:171], v[224:227], v[78:81]
	v_mfma_f32_16x16x32_bf16 v[70:73], v[176:179], v[224:227], v[70:73]
	s_setprio 0
	s_setprio 1
	v_mfma_f32_16x16x32_bf16 v[126:129], v[180:183], v[196:199], v[126:129]
	v_mfma_f32_16x16x32_bf16 v[114:117], v[188:191], v[196:199], v[114:117]
	v_mfma_f32_16x16x32_bf16 v[106:109], v[180:183], v[204:207], v[106:109]
	v_mfma_f32_16x16x32_bf16 v[98:101], v[188:191], v[204:207], v[98:101]
	v_mfma_f32_16x16x32_bf16 v[90:93], v[180:183], v[212:215], v[90:93]
	v_mfma_f32_16x16x32_bf16 v[82:85], v[188:191], v[212:215], v[82:85]
	v_mfma_f32_16x16x32_bf16 v[74:77], v[180:183], v[220:223], v[74:77]
	v_mfma_f32_16x16x32_bf16 v[66:69], v[188:191], v[220:223], v[66:69]
	v_mfma_f32_16x16x32_bf16 v[126:129], v[184:187], v[200:203], v[126:129]
	v_mfma_f32_16x16x32_bf16 v[114:117], v[192:195], v[200:203], v[114:117]
	v_mfma_f32_16x16x32_bf16 v[106:109], v[184:187], v[208:211], v[106:109]
	v_mfma_f32_16x16x32_bf16 v[98:101], v[192:195], v[208:211], v[98:101]
	v_mfma_f32_16x16x32_bf16 v[90:93], v[184:187], v[216:219], v[90:93]
	v_mfma_f32_16x16x32_bf16 v[82:85], v[192:195], v[216:219], v[82:85]
	v_mfma_f32_16x16x32_bf16 v[74:77], v[184:187], v[224:227], v[74:77]
	v_mfma_f32_16x16x32_bf16 v[66:69], v[192:195], v[224:227], v[66:69]
	s_barrier
	s_setprio 0
	s_add_u32 s96, s96, 0x80
	s_addc_u32 s97, s97, 0
	s_add_u32 s98, s96, 0x40000
	s_addc_u32 s99, s97, 0
	s_add_u32 s94, s94, 0x80
	s_addc_u32 s95, s95, 0
	s_add_i32 s5, s5, s23
	s_mov_b32 m0, s5
	s_nop 0
	global_load_lds_dwordx4 v132, s[96:97]
	s_add_i32 m0, s5, 0x2000
	s_add_i32 s5, s45, s23
	global_load_lds_dwordx4 v136, s[96:97]
	s_mov_b32 m0, s5
	s_nop 0
	global_load_lds_dwordx4 v132, s[98:99]
	s_add_i32 m0, s5, 0x2000
	s_nop 0
	global_load_lds_dwordx4 v136, s[98:99]
	s_mov_b32 m0, s64
	s_nop 0
	global_load_lds_dwordx4 v130, s[94:95]
	s_mov_b32 m0, s65
	s_nop 0
	global_load_lds_dwordx4 v134, s[94:95]
	ds_read_b128 v[196:199], v160 offset:49152
	ds_read_b128 v[200:203], v160 offset:50176
	ds_read_b128 v[204:207], v160 offset:51200
	ds_read_b128 v[208:211], v160 offset:52224
	ds_read_b128 v[212:215], v160 offset:53248
	ds_read_b128 v[216:219], v160 offset:54272
	ds_read_b128 v[220:223], v160 offset:55296
	ds_read_b128 v[224:227], v160 offset:56320
	s_waitcnt vmcnt(8)
	s_waitcnt lgkmcnt(0)
	s_setprio 1
	s_barrier
	v_mfma_f32_16x16x32_bf16 v[62:65], v[164:167], v[196:199], v[62:65]
	v_mfma_f32_16x16x32_bf16 v[54:57], v[172:175], v[196:199], v[54:57]
	v_mfma_f32_16x16x32_bf16 v[46:49], v[164:167], v[204:207], v[46:49]
	v_mfma_f32_16x16x32_bf16 v[38:41], v[172:175], v[204:207], v[38:41]
	v_mfma_f32_16x16x32_bf16 v[30:33], v[164:167], v[212:215], v[30:33]
	v_mfma_f32_16x16x32_bf16 v[22:25], v[172:175], v[212:215], v[22:25]
	v_mfma_f32_16x16x32_bf16 v[14:17], v[164:167], v[220:223], v[14:17]
	v_mfma_f32_16x16x32_bf16 v[6:9], v[172:175], v[220:223], v[6:9]
	v_mfma_f32_16x16x32_bf16 v[62:65], v[168:171], v[200:203], v[62:65]
	v_mfma_f32_16x16x32_bf16 v[54:57], v[176:179], v[200:203], v[54:57]
	v_mfma_f32_16x16x32_bf16 v[46:49], v[168:171], v[208:211], v[46:49]
	v_mfma_f32_16x16x32_bf16 v[38:41], v[176:179], v[208:211], v[38:41]
	v_mfma_f32_16x16x32_bf16 v[30:33], v[168:171], v[216:219], v[30:33]
	v_mfma_f32_16x16x32_bf16 v[22:25], v[176:179], v[216:219], v[22:25]
	v_mfma_f32_16x16x32_bf16 v[14:17], v[168:171], v[224:227], v[14:17]
	v_mfma_f32_16x16x32_bf16 v[6:9], v[176:179], v[224:227], v[6:9]
	s_setprio 0
	s_setprio 1
	v_mfma_f32_16x16x32_bf16 v[58:61], v[180:183], v[196:199], v[58:61]
	v_mfma_f32_16x16x32_bf16 v[50:53], v[188:191], v[196:199], v[50:53]
	v_mfma_f32_16x16x32_bf16 v[42:45], v[180:183], v[204:207], v[42:45]
	v_mfma_f32_16x16x32_bf16 v[34:37], v[188:191], v[204:207], v[34:37]
	v_mfma_f32_16x16x32_bf16 v[26:29], v[180:183], v[212:215], v[26:29]
	v_mfma_f32_16x16x32_bf16 v[18:21], v[188:191], v[212:215], v[18:21]
	v_mfma_f32_16x16x32_bf16 v[10:13], v[180:183], v[220:223], v[10:13]
	v_mfma_f32_16x16x32_bf16 v[2:5], v[188:191], v[220:223], v[2:5]
	v_mfma_f32_16x16x32_bf16 v[58:61], v[184:187], v[200:203], v[58:61]
	v_mfma_f32_16x16x32_bf16 v[50:53], v[192:195], v[200:203], v[50:53]
	v_mfma_f32_16x16x32_bf16 v[42:45], v[184:187], v[208:211], v[42:45]
	v_mfma_f32_16x16x32_bf16 v[34:37], v[192:195], v[208:211], v[34:37]
	v_mfma_f32_16x16x32_bf16 v[26:29], v[184:187], v[216:219], v[26:29]
	v_mfma_f32_16x16x32_bf16 v[18:21], v[192:195], v[216:219], v[18:21]
	v_mfma_f32_16x16x32_bf16 v[10:13], v[184:187], v[224:227], v[10:13]
	v_mfma_f32_16x16x32_bf16 v[2:5], v[192:195], v[224:227], v[2:5]
	s_barrier
	s_setprio 0
	s_mov_b32 s5, s29
	s_add_u32 s88, s88, 0x100
	s_addc_u32 s89, s89, 0
	s_add_u32 s86, s86, 0x100
	s_addc_u32 s87, s87, 0
	s_cmp_ge_i32 s29, s101
	s_cbranch_scc0 .LBB0_1763

.LBB0_1942:
	v_cmp_gt_i32_e32 vcc, 1, v138
	s_cbranch_vccnz .LBB0_2004
	v_lshl_add_u64 v[152:153], v[2:3], 0, s[16:17]
	v_add_u32_e32 v154, -2, v138
	s_waitcnt lgkmcnt(0)
	v_lshl_add_u64 v[150:151], v[4:5], 0, s[20:21]
	s_mov_b32 s5, 0
	s_nop 0
	v_readfirstlane_b32 s86, v152
	v_readfirstlane_b32 s87, v153
	v_readfirstlane_b32 s88, v150
	v_readfirstlane_b32 s89, v151
	v_readfirstlane_b32 s90, v146
	v_readfirstlane_b32 s91, v147
	v_readfirstlane_b32 s92, v148
	v_readfirstlane_b32 s93, v149
	v_readfirstlane_b32 s100, v154
	v_readfirstlane_b32 s101, v138
	v_add_u32_e32 v230, s72, v141
	v_add_u32_e32 v231, s73, v141
	v_add_u32_e32 v232, 0x18000, v141
	v_add_u32_e32 v233, 0x1c000, v141
	s_add_u32 s98, s86, 0xfffc0080
	s_addc_u32 s99, s87, -1
	s_cmp_eq_u32 s5, s100
	s_cselect_b64 s[94:95], s[90:91], s[98:99]
	s_cselect_b64 s[96:97], s[92:93], s[88:89]
	s_add_i32 s45, s5, 2
	s_nop 0
	s_mov_b32 m0, s74
	s_nop 0
	global_load_lds_dwordx4 v144, s[86:87]
	s_mov_b32 m0, s75
	s_nop 0
	global_load_lds_dwordx4 v142, s[86:87]
	ds_read_b128 v[164:167], v230
	ds_read_b128 v[168:171], v230 offset:1024
	ds_read_b128 v[172:175], v230 offset:2048
	ds_read_b128 v[176:179], v230 offset:3072
	ds_read_b128 v[180:183], v231
	ds_read_b128 v[184:187], v231 offset:1024
	ds_read_b128 v[188:191], v231 offset:2048
	ds_read_b128 v[192:195], v231 offset:3072
	ds_read_b128 v[196:199], v160
	ds_read_b128 v[200:203], v160 offset:1024
	ds_read_b128 v[204:207], v160 offset:2048
	ds_read_b128 v[208:211], v160 offset:3072
	ds_read_b128 v[212:215], v160 offset:4096
	ds_read_b128 v[216:219], v160 offset:5120
	ds_read_b128 v[220:223], v160 offset:6144
	ds_read_b128 v[224:227], v160 offset:7168
	s_waitcnt vmcnt(8)
	s_waitcnt lgkmcnt(0)
	s_setprio 1
	s_barrier
	v_mfma_f32_16x16x32_bf16 v[122:125], v[164:167], v[196:199], 0
	v_mfma_f32_16x16x32_bf16 v[118:121], v[172:175], v[196:199], 0
	v_mfma_f32_16x16x32_bf16 v[110:113], v[164:167], v[204:207], 0
	v_mfma_f32_16x16x32_bf16 v[102:105], v[172:175], v[204:207], 0
	v_mfma_f32_16x16x32_bf16 v[94:97], v[164:167], v[212:215], 0
	v_mfma_f32_16x16x32_bf16 v[86:89], v[172:175], v[212:215], 0
	v_mfma_f32_16x16x32_bf16 v[78:81], v[164:167], v[220:223], 0
	v_mfma_f32_16x16x32_bf16 v[70:73], v[172:175], v[220:223], 0
	v_mfma_f32_16x16x32_bf16 v[122:125], v[168:171], v[200:203], v[122:125]
	v_mfma_f32_16x16x32_bf16 v[118:121], v[176:179], v[200:203], v[118:121]
	v_mfma_f32_16x16x32_bf16 v[110:113], v[168:171], v[208:211], v[110:113]
	v_mfma_f32_16x16x32_bf16 v[102:105], v[176:179], v[208:211], v[102:105]
	v_mfma_f32_16x16x32_bf16 v[94:97], v[168:171], v[216:219], v[94:97]
	v_mfma_f32_16x16x32_bf16 v[86:89], v[176:179], v[216:219], v[86:89]
	v_mfma_f32_16x16x32_bf16 v[78:81], v[168:171], v[224:227], v[78:81]
	v_mfma_f32_16x16x32_bf16 v[70:73], v[176:179], v[224:227], v[70:73]
	s_setprio 0
	s_setprio 1
	v_mfma_f32_16x16x32_bf16 v[126:129], v[180:183], v[196:199], 0
	v_mfma_f32_16x16x32_bf16 v[114:117], v[188:191], v[196:199], 0
	v_mfma_f32_16x16x32_bf16 v[106:109], v[180:183], v[204:207], 0
	v_mfma_f32_16x16x32_bf16 v[98:101], v[188:191], v[204:207], 0
	v_mfma_f32_16x16x32_bf16 v[90:93], v[180:183], v[212:215], 0
	v_mfma_f32_16x16x32_bf16 v[82:85], v[188:191], v[212:215], 0
	v_mfma_f32_16x16x32_bf16 v[74:77], v[180:183], v[220:223], 0
	v_mfma_f32_16x16x32_bf16 v[66:69], v[188:191], v[220:223], 0
	v_mfma_f32_16x16x32_bf16 v[126:129], v[184:187], v[200:203], v[126:129]
	v_mfma_f32_16x16x32_bf16 v[114:117], v[192:195], v[200:203], v[114:117]
	v_mfma_f32_16x16x32_bf16 v[106:109], v[184:187], v[208:211], v[106:109]
	v_mfma_f32_16x16x32_bf16 v[98:101], v[192:195], v[208:211], v[98:101]
	v_mfma_f32_16x16x32_bf16 v[90:93], v[184:187], v[216:219], v[90:93]
	v_mfma_f32_16x16x32_bf16 v[82:85], v[192:195], v[216:219], v[82:85]
	v_mfma_f32_16x16x32_bf16 v[74:77], v[184:187], v[224:227], v[74:77]
	v_mfma_f32_16x16x32_bf16 v[66:69], v[192:195], v[224:227], v[66:69]
	s_barrier
	s_setprio 0
	s_add_u32 s98, s96, 0x40000
	s_addc_u32 s99, s97, 0
	s_mov_b32 m0, s76
	s_nop 0
	global_load_lds_dwordx4 v132, s[96:97]
	s_mov_b32 m0, s77
	s_add_i32 s5, s73, s25
	global_load_lds_dwordx4 v136, s[96:97]
	s_mov_b32 m0, s5
	s_nop 0
	global_load_lds_dwordx4 v132, s[98:99]
	s_add_i32 m0, s5, 0x2000
	s_nop 0
	global_load_lds_dwordx4 v136, s[98:99]
	s_mov_b32 m0, s49
	s_nop 0
	global_load_lds_dwordx4 v130, s[94:95]
	s_mov_b32 m0, s58
	s_nop 0
	global_load_lds_dwordx4 v134, s[94:95]
	ds_read_b128 v[196:199], v160 offset:16384
	ds_read_b128 v[200:203], v160 offset:17408
	ds_read_b128 v[204:207], v160 offset:18432
	ds_read_b128 v[208:211], v160 offset:19456
	ds_read_b128 v[212:215], v160 offset:20480
	ds_read_b128 v[216:219], v160 offset:21504
	ds_read_b128 v[220:223], v160 offset:22528
	ds_read_b128 v[224:227], v160 offset:23552
	s_waitcnt vmcnt(8)
	s_waitcnt lgkmcnt(0)
	s_setprio 1
	s_barrier
	v_mfma_f32_16x16x32_bf16 v[62:65], v[164:167], v[196:199], 0
	v_mfma_f32_16x16x32_bf16 v[54:57], v[172:175], v[196:199], 0
	v_mfma_f32_16x16x32_bf16 v[46:49], v[164:167], v[204:207], 0
	v_mfma_f32_16x16x32_bf16 v[38:41], v[172:175], v[204:207], 0
	v_mfma_f32_16x16x32_bf16 v[30:33], v[164:167], v[212:215], 0
	v_mfma_f32_16x16x32_bf16 v[22:25], v[172:175], v[212:215], 0
	v_mfma_f32_16x16x32_bf16 v[14:17], v[164:167], v[220:223], 0
	v_mfma_f32_16x16x32_bf16 v[6:9], v[172:175], v[220:223], 0
	v_mfma_f32_16x16x32_bf16 v[62:65], v[168:171], v[200:203], v[62:65]
	v_mfma_f32_16x16x32_bf16 v[54:57], v[176:179], v[200:203], v[54:57]
	v_mfma_f32_16x16x32_bf16 v[46:49], v[168:171], v[208:211], v[46:49]
	v_mfma_f32_16x16x32_bf16 v[38:41], v[176:179], v[208:211], v[38:41]
	v_mfma_f32_16x16x32_bf16 v[30:33], v[168:171], v[216:219], v[30:33]
	v_mfma_f32_16x16x32_bf16 v[22:25], v[176:179], v[216:219], v[22:25]
	v_mfma_f32_16x16x32_bf16 v[14:17], v[168:171], v[224:227], v[14:17]
	v_mfma_f32_16x16x32_bf16 v[6:9], v[176:179], v[224:227], v[6:9]
	s_setprio 0
	s_setprio 1
	v_mfma_f32_16x16x32_bf16 v[58:61], v[180:183], v[196:199], 0
	v_mfma_f32_16x16x32_bf16 v[50:53], v[188:191], v[196:199], 0
	v_mfma_f32_16x16x32_bf16 v[42:45], v[180:183], v[204:207], 0
	v_mfma_f32_16x16x32_bf16 v[34:37], v[188:191], v[204:207], 0
	v_mfma_f32_16x16x32_bf16 v[26:29], v[180:183], v[212:215], 0
	v_mfma_f32_16x16x32_bf16 v[18:21], v[188:191], v[212:215], 0
	v_mfma_f32_16x16x32_bf16 v[10:13], v[180:183], v[220:223], 0
	v_mfma_f32_16x16x32_bf16 v[2:5], v[188:191], v[220:223], 0
	v_mfma_f32_16x16x32_bf16 v[58:61], v[184:187], v[200:203], v[58:61]
	v_mfma_f32_16x16x32_bf16 v[50:53], v[192:195], v[200:203], v[50:53]
	v_mfma_f32_16x16x32_bf16 v[42:45], v[184:187], v[208:211], v[42:45]
	v_mfma_f32_16x16x32_bf16 v[34:37], v[192:195], v[208:211], v[34:37]
	v_mfma_f32_16x16x32_bf16 v[26:29], v[184:187], v[216:219], v[26:29]
	v_mfma_f32_16x16x32_bf16 v[18:21], v[192:195], v[216:219], v[18:21]
	v_mfma_f32_16x16x32_bf16 v[10:13], v[184:187], v[224:227], v[10:13]
	v_mfma_f32_16x16x32_bf16 v[2:5], v[192:195], v[224:227], v[2:5]
	s_barrier
	s_setprio 0
	s_add_u32 s98, s94, 0x40000
	s_addc_u32 s99, s95, 0
	s_add_i32 s5, 0, 0x18000
	s_add_i32 s47, 0, 0x1c000
	s_mov_b32 m0, s59
	s_nop 0
	global_load_lds_dwordx4 v130, s[98:99]
	s_mov_b32 m0, s60
	s_nop 0
	global_load_lds_dwordx4 v134, s[98:99]
	ds_read_b128 v[164:167], v232
	ds_read_b128 v[168:171], v232 offset:1024
	ds_read_b128 v[172:175], v232 offset:2048
	ds_read_b128 v[176:179], v232 offset:3072
	ds_read_b128 v[180:183], v233
	ds_read_b128 v[184:187], v233 offset:1024
	ds_read_b128 v[188:191], v233 offset:2048
	ds_read_b128 v[192:195], v233 offset:3072
	ds_read_b128 v[196:199], v160 offset:32768
	ds_read_b128 v[200:203], v160 offset:33792
	ds_read_b128 v[204:207], v160 offset:34816
	ds_read_b128 v[208:211], v160 offset:35840
	ds_read_b128 v[212:215], v160 offset:36864
	ds_read_b128 v[216:219], v160 offset:37888
	ds_read_b128 v[220:223], v160 offset:38912
	ds_read_b128 v[224:227], v160 offset:39936
	s_waitcnt vmcnt(8)
	s_waitcnt lgkmcnt(0)
	s_setprio 1
	s_barrier
	v_mfma_f32_16x16x32_bf16 v[122:125], v[164:167], v[196:199], v[122:125]
	v_mfma_f32_16x16x32_bf16 v[118:121], v[172:175], v[196:199], v[118:121]
	v_mfma_f32_16x16x32_bf16 v[110:113], v[164:167], v[204:207], v[110:113]
	v_mfma_f32_16x16x32_bf16 v[102:105], v[172:175], v[204:207], v[102:105]
	v_mfma_f32_16x16x32_bf16 v[94:97], v[164:167], v[212:215], v[94:97]
	v_mfma_f32_16x16x32_bf16 v[86:89], v[172:175], v[212:215], v[86:89]
	v_mfma_f32_16x16x32_bf16 v[78:81], v[164:167], v[220:223], v[78:81]
	v_mfma_f32_16x16x32_bf16 v[70:73], v[172:175], v[220:223], v[70:73]
	v_mfma_f32_16x16x32_bf16 v[122:125], v[168:171], v[200:203], v[122:125]
	v_mfma_f32_16x16x32_bf16 v[118:121], v[176:179], v[200:203], v[118:121]
	v_mfma_f32_16x16x32_bf16 v[110:113], v[168:171], v[208:211], v[110:113]
	v_mfma_f32_16x16x32_bf16 v[102:105], v[176:179], v[208:211], v[102:105]
	v_mfma_f32_16x16x32_bf16 v[94:97], v[168:171], v[216:219], v[94:97]
	v_mfma_f32_16x16x32_bf16 v[86:89], v[176:179], v[216:219], v[86:89]
	v_mfma_f32_16x16x32_bf16 v[78:81], v[168:171], v[224:227], v[78:81]
	v_mfma_f32_16x16x32_bf16 v[70:73], v[176:179], v[224:227], v[70:73]
	s_setprio 0
	s_setprio 1
	v_mfma_f32_16x16x32_bf16 v[126:129], v[180:183], v[196:199], v[126:129]
	v_mfma_f32_16x16x32_bf16 v[114:117], v[188:191], v[196:199], v[114:117]
	v_mfma_f32_16x16x32_bf16 v[106:109], v[180:183], v[204:207], v[106:109]
	v_mfma_f32_16x16x32_bf16 v[98:101], v[188:191], v[204:207], v[98:101]
	v_mfma_f32_16x16x32_bf16 v[90:93], v[180:183], v[212:215], v[90:93]
	v_mfma_f32_16x16x32_bf16 v[82:85], v[188:191], v[212:215], v[82:85]
	v_mfma_f32_16x16x32_bf16 v[74:77], v[180:183], v[220:223], v[74:77]
	v_mfma_f32_16x16x32_bf16 v[66:69], v[188:191], v[220:223], v[66:69]
	v_mfma_f32_16x16x32_bf16 v[126:129], v[184:187], v[200:203], v[126:129]
	v_mfma_f32_16x16x32_bf16 v[114:117], v[192:195], v[200:203], v[114:117]
	v_mfma_f32_16x16x32_bf16 v[106:109], v[184:187], v[208:211], v[106:109]
	v_mfma_f32_16x16x32_bf16 v[98:101], v[192:195], v[208:211], v[98:101]
	v_mfma_f32_16x16x32_bf16 v[90:93], v[184:187], v[216:219], v[90:93]
	v_mfma_f32_16x16x32_bf16 v[82:85], v[192:195], v[216:219], v[82:85]
	v_mfma_f32_16x16x32_bf16 v[74:77], v[184:187], v[224:227], v[74:77]
	v_mfma_f32_16x16x32_bf16 v[66:69], v[192:195], v[224:227], v[66:69]
	s_barrier
	s_setprio 0
	s_add_u32 s96, s96, 0x80
	s_addc_u32 s97, s97, 0
	s_add_u32 s98, s96, 0x40000
	s_addc_u32 s99, s97, 0
	s_add_u32 s94, s94, 0x80
	s_addc_u32 s95, s95, 0
	s_add_i32 s5, s5, s25
	s_mov_b32 m0, s5
	s_nop 0
	global_load_lds_dwordx4 v132, s[96:97]
	s_add_i32 m0, s5, 0x2000
	s_add_i32 s5, s47, s25
	global_load_lds_dwordx4 v136, s[96:97]
	s_mov_b32 m0, s5
	s_nop 0
	global_load_lds_dwordx4 v132, s[98:99]
	s_add_i32 m0, s5, 0x2000
	s_nop 0
	global_load_lds_dwordx4 v136, s[98:99]
	s_mov_b32 m0, s61
	s_nop 0
	global_load_lds_dwordx4 v130, s[94:95]
	s_mov_b32 m0, s62
	s_nop 0
	global_load_lds_dwordx4 v134, s[94:95]
	ds_read_b128 v[196:199], v160 offset:49152
	ds_read_b128 v[200:203], v160 offset:50176
	ds_read_b128 v[204:207], v160 offset:51200
	ds_read_b128 v[208:211], v160 offset:52224
	ds_read_b128 v[212:215], v160 offset:53248
	ds_read_b128 v[216:219], v160 offset:54272
	ds_read_b128 v[220:223], v160 offset:55296
	ds_read_b128 v[224:227], v160 offset:56320
	s_waitcnt vmcnt(8)
	s_waitcnt lgkmcnt(0)
	s_setprio 1
	s_barrier
	v_mfma_f32_16x16x32_bf16 v[62:65], v[164:167], v[196:199], v[62:65]
	v_mfma_f32_16x16x32_bf16 v[54:57], v[172:175], v[196:199], v[54:57]
	v_mfma_f32_16x16x32_bf16 v[46:49], v[164:167], v[204:207], v[46:49]
	v_mfma_f32_16x16x32_bf16 v[38:41], v[172:175], v[204:207], v[38:41]
	v_mfma_f32_16x16x32_bf16 v[30:33], v[164:167], v[212:215], v[30:33]
	v_mfma_f32_16x16x32_bf16 v[22:25], v[172:175], v[212:215], v[22:25]
	v_mfma_f32_16x16x32_bf16 v[14:17], v[164:167], v[220:223], v[14:17]
	v_mfma_f32_16x16x32_bf16 v[6:9], v[172:175], v[220:223], v[6:9]
	v_mfma_f32_16x16x32_bf16 v[62:65], v[168:171], v[200:203], v[62:65]
	v_mfma_f32_16x16x32_bf16 v[54:57], v[176:179], v[200:203], v[54:57]
	v_mfma_f32_16x16x32_bf16 v[46:49], v[168:171], v[208:211], v[46:49]
	v_mfma_f32_16x16x32_bf16 v[38:41], v[176:179], v[208:211], v[38:41]
	v_mfma_f32_16x16x32_bf16 v[30:33], v[168:171], v[216:219], v[30:33]
	v_mfma_f32_16x16x32_bf16 v[22:25], v[176:179], v[216:219], v[22:25]
	v_mfma_f32_16x16x32_bf16 v[14:17], v[168:171], v[224:227], v[14:17]
	v_mfma_f32_16x16x32_bf16 v[6:9], v[176:179], v[224:227], v[6:9]
	s_setprio 0
	s_setprio 1
	v_mfma_f32_16x16x32_bf16 v[58:61], v[180:183], v[196:199], v[58:61]
	v_mfma_f32_16x16x32_bf16 v[50:53], v[188:191], v[196:199], v[50:53]
	v_mfma_f32_16x16x32_bf16 v[42:45], v[180:183], v[204:207], v[42:45]
	v_mfma_f32_16x16x32_bf16 v[34:37], v[188:191], v[204:207], v[34:37]
	v_mfma_f32_16x16x32_bf16 v[26:29], v[180:183], v[212:215], v[26:29]
	v_mfma_f32_16x16x32_bf16 v[18:21], v[188:191], v[212:215], v[18:21]
	v_mfma_f32_16x16x32_bf16 v[10:13], v[180:183], v[220:223], v[10:13]
	v_mfma_f32_16x16x32_bf16 v[2:5], v[188:191], v[220:223], v[2:5]
	v_mfma_f32_16x16x32_bf16 v[58:61], v[184:187], v[200:203], v[58:61]
	v_mfma_f32_16x16x32_bf16 v[50:53], v[192:195], v[200:203], v[50:53]
	v_mfma_f32_16x16x32_bf16 v[42:45], v[184:187], v[208:211], v[42:45]
	v_mfma_f32_16x16x32_bf16 v[34:37], v[192:195], v[208:211], v[34:37]
	v_mfma_f32_16x16x32_bf16 v[26:29], v[184:187], v[216:219], v[26:29]
	v_mfma_f32_16x16x32_bf16 v[18:21], v[192:195], v[216:219], v[18:21]
	v_mfma_f32_16x16x32_bf16 v[10:13], v[184:187], v[224:227], v[10:13]
	v_mfma_f32_16x16x32_bf16 v[2:5], v[192:195], v[224:227], v[2:5]
	s_barrier
	s_setprio 0
	s_mov_b32 s5, s45
	s_add_u32 s88, s88, 0x100
	s_addc_u32 s89, s89, 0
	s_add_u32 s86, s86, 0x100
	s_addc_u32 s87, s87, 0
	s_cmp_ge_i32 s45, s101
	s_cbranch_scc1 .Lmy_kexit_10
.LBB0_1944:
	s_add_u32 s98, s86, 0xfffc0080
	s_addc_u32 s99, s87, -1
	s_cmp_eq_u32 s5, s100
	s_cselect_b64 s[94:95], s[90:91], s[98:99]
	s_cselect_b64 s[96:97], s[92:93], s[88:89]
	s_add_i32 s45, s5, 2
	s_nop 0
	s_mov_b32 m0, s74
	s_nop 0
	global_load_lds_dwordx4 v144, s[86:87]
	s_mov_b32 m0, s75
	s_nop 0
	global_load_lds_dwordx4 v142, s[86:87]
	ds_read_b128 v[164:167], v230
	ds_read_b128 v[168:171], v230 offset:1024
	ds_read_b128 v[172:175], v230 offset:2048
	ds_read_b128 v[176:179], v230 offset:3072
	ds_read_b128 v[180:183], v231
	ds_read_b128 v[184:187], v231 offset:1024
	ds_read_b128 v[188:191], v231 offset:2048
	ds_read_b128 v[192:195], v231 offset:3072
	ds_read_b128 v[196:199], v160
	ds_read_b128 v[200:203], v160 offset:1024
	ds_read_b128 v[204:207], v160 offset:2048
	ds_read_b128 v[208:211], v160 offset:3072
	ds_read_b128 v[212:215], v160 offset:4096
	ds_read_b128 v[216:219], v160 offset:5120
	ds_read_b128 v[220:223], v160 offset:6144
	ds_read_b128 v[224:227], v160 offset:7168
	s_waitcnt vmcnt(8)
	s_waitcnt lgkmcnt(0)
	s_setprio 1
	s_barrier
	v_mfma_f32_16x16x32_bf16 v[122:125], v[164:167], v[196:199], v[122:125]
	v_mfma_f32_16x16x32_bf16 v[118:121], v[172:175], v[196:199], v[118:121]
	v_mfma_f32_16x16x32_bf16 v[110:113], v[164:167], v[204:207], v[110:113]
	v_mfma_f32_16x16x32_bf16 v[102:105], v[172:175], v[204:207], v[102:105]
	v_mfma_f32_16x16x32_bf16 v[94:97], v[164:167], v[212:215], v[94:97]
	v_mfma_f32_16x16x32_bf16 v[86:89], v[172:175], v[212:215], v[86:89]
	v_mfma_f32_16x16x32_bf16 v[78:81], v[164:167], v[220:223], v[78:81]
	v_mfma_f32_16x16x32_bf16 v[70:73], v[172:175], v[220:223], v[70:73]
	v_mfma_f32_16x16x32_bf16 v[122:125], v[168:171], v[200:203], v[122:125]
	v_mfma_f32_16x16x32_bf16 v[118:121], v[176:179], v[200:203], v[118:121]
	v_mfma_f32_16x16x32_bf16 v[110:113], v[168:171], v[208:211], v[110:113]
	v_mfma_f32_16x16x32_bf16 v[102:105], v[176:179], v[208:211], v[102:105]
	v_mfma_f32_16x16x32_bf16 v[94:97], v[168:171], v[216:219], v[94:97]
	v_mfma_f32_16x16x32_bf16 v[86:89], v[176:179], v[216:219], v[86:89]
	v_mfma_f32_16x16x32_bf16 v[78:81], v[168:171], v[224:227], v[78:81]
	v_mfma_f32_16x16x32_bf16 v[70:73], v[176:179], v[224:227], v[70:73]
	s_setprio 0
	s_setprio 1
	v_mfma_f32_16x16x32_bf16 v[126:129], v[180:183], v[196:199], v[126:129]
	v_mfma_f32_16x16x32_bf16 v[114:117], v[188:191], v[196:199], v[114:117]
	v_mfma_f32_16x16x32_bf16 v[106:109], v[180:183], v[204:207], v[106:109]
	v_mfma_f32_16x16x32_bf16 v[98:101], v[188:191], v[204:207], v[98:101]
	v_mfma_f32_16x16x32_bf16 v[90:93], v[180:183], v[212:215], v[90:93]
	v_mfma_f32_16x16x32_bf16 v[82:85], v[188:191], v[212:215], v[82:85]
	v_mfma_f32_16x16x32_bf16 v[74:77], v[180:183], v[220:223], v[74:77]
	v_mfma_f32_16x16x32_bf16 v[66:69], v[188:191], v[220:223], v[66:69]
	v_mfma_f32_16x16x32_bf16 v[126:129], v[184:187], v[200:203], v[126:129]
	v_mfma_f32_16x16x32_bf16 v[114:117], v[192:195], v[200:203], v[114:117]
	v_mfma_f32_16x16x32_bf16 v[106:109], v[184:187], v[208:211], v[106:109]
	v_mfma_f32_16x16x32_bf16 v[98:101], v[192:195], v[208:211], v[98:101]
	v_mfma_f32_16x16x32_bf16 v[90:93], v[184:187], v[216:219], v[90:93]
	v_mfma_f32_16x16x32_bf16 v[82:85], v[192:195], v[216:219], v[82:85]
	v_mfma_f32_16x16x32_bf16 v[74:77], v[184:187], v[224:227], v[74:77]
	v_mfma_f32_16x16x32_bf16 v[66:69], v[192:195], v[224:227], v[66:69]
	s_barrier
	s_setprio 0
	s_add_u32 s98, s96, 0x40000
	s_addc_u32 s99, s97, 0
	s_mov_b32 m0, s76
	s_nop 0
	global_load_lds_dwordx4 v132, s[96:97]
	s_mov_b32 m0, s77
	s_add_i32 s5, s73, s25
	global_load_lds_dwordx4 v136, s[96:97]
	s_mov_b32 m0, s5
	s_nop 0
	global_load_lds_dwordx4 v132, s[98:99]
	s_add_i32 m0, s5, 0x2000
	s_nop 0
	global_load_lds_dwordx4 v136, s[98:99]
	s_mov_b32 m0, s49
	s_nop 0
	global_load_lds_dwordx4 v130, s[94:95]
	s_mov_b32 m0, s58
	s_nop 0
	global_load_lds_dwordx4 v134, s[94:95]
	ds_read_b128 v[196:199], v160 offset:16384
	ds_read_b128 v[200:203], v160 offset:17408
	ds_read_b128 v[204:207], v160 offset:18432
	ds_read_b128 v[208:211], v160 offset:19456
	ds_read_b128 v[212:215], v160 offset:20480
	ds_read_b128 v[216:219], v160 offset:21504
	ds_read_b128 v[220:223], v160 offset:22528
	ds_read_b128 v[224:227], v160 offset:23552
	s_waitcnt vmcnt(8)
	s_waitcnt lgkmcnt(0)
	s_setprio 1
	s_barrier
	v_mfma_f32_16x16x32_bf16 v[62:65], v[164:167], v[196:199], v[62:65]
	v_mfma_f32_16x16x32_bf16 v[54:57], v[172:175], v[196:199], v[54:57]
	v_mfma_f32_16x16x32_bf16 v[46:49], v[164:167], v[204:207], v[46:49]
	v_mfma_f32_16x16x32_bf16 v[38:41], v[172:175], v[204:207], v[38:41]
	v_mfma_f32_16x16x32_bf16 v[30:33], v[164:167], v[212:215], v[30:33]
	v_mfma_f32_16x16x32_bf16 v[22:25], v[172:175], v[212:215], v[22:25]
	v_mfma_f32_16x16x32_bf16 v[14:17], v[164:167], v[220:223], v[14:17]
	v_mfma_f32_16x16x32_bf16 v[6:9], v[172:175], v[220:223], v[6:9]
	v_mfma_f32_16x16x32_bf16 v[62:65], v[168:171], v[200:203], v[62:65]
	v_mfma_f32_16x16x32_bf16 v[54:57], v[176:179], v[200:203], v[54:57]
	v_mfma_f32_16x16x32_bf16 v[46:49], v[168:171], v[208:211], v[46:49]
	v_mfma_f32_16x16x32_bf16 v[38:41], v[176:179], v[208:211], v[38:41]
	v_mfma_f32_16x16x32_bf16 v[30:33], v[168:171], v[216:219], v[30:33]
	v_mfma_f32_16x16x32_bf16 v[22:25], v[176:179], v[216:219], v[22:25]
	v_mfma_f32_16x16x32_bf16 v[14:17], v[168:171], v[224:227], v[14:17]
	v_mfma_f32_16x16x32_bf16 v[6:9], v[176:179], v[224:227], v[6:9]
	s_setprio 0
	s_setprio 1
	v_mfma_f32_16x16x32_bf16 v[58:61], v[180:183], v[196:199], v[58:61]
	v_mfma_f32_16x16x32_bf16 v[50:53], v[188:191], v[196:199], v[50:53]
	v_mfma_f32_16x16x32_bf16 v[42:45], v[180:183], v[204:207], v[42:45]
	v_mfma_f32_16x16x32_bf16 v[34:37], v[188:191], v[204:207], v[34:37]
	v_mfma_f32_16x16x32_bf16 v[26:29], v[180:183], v[212:215], v[26:29]
	v_mfma_f32_16x16x32_bf16 v[18:21], v[188:191], v[212:215], v[18:21]
	v_mfma_f32_16x16x32_bf16 v[10:13], v[180:183], v[220:223], v[10:13]
	v_mfma_f32_16x16x32_bf16 v[2:5], v[188:191], v[220:223], v[2:5]
	v_mfma_f32_16x16x32_bf16 v[58:61], v[184:187], v[200:203], v[58:61]
	v_mfma_f32_16x16x32_bf16 v[50:53], v[192:195], v[200:203], v[50:53]
	v_mfma_f32_16x16x32_bf16 v[42:45], v[184:187], v[208:211], v[42:45]
	v_mfma_f32_16x16x32_bf16 v[34:37], v[192:195], v[208:211], v[34:37]
	v_mfma_f32_16x16x32_bf16 v[26:29], v[184:187], v[216:219], v[26:29]
	v_mfma_f32_16x16x32_bf16 v[18:21], v[192:195], v[216:219], v[18:21]
	v_mfma_f32_16x16x32_bf16 v[10:13], v[184:187], v[224:227], v[10:13]
	v_mfma_f32_16x16x32_bf16 v[2:5], v[192:195], v[224:227], v[2:5]
	s_barrier
	s_setprio 0
	s_add_u32 s98, s94, 0x40000
	s_addc_u32 s99, s95, 0
	s_add_i32 s5, 0, 0x18000
	s_add_i32 s47, 0, 0x1c000
	s_mov_b32 m0, s59
	s_nop 0
	global_load_lds_dwordx4 v130, s[98:99]
	s_mov_b32 m0, s60
	s_nop 0
	global_load_lds_dwordx4 v134, s[98:99]
	ds_read_b128 v[164:167], v232
	ds_read_b128 v[168:171], v232 offset:1024
	ds_read_b128 v[172:175], v232 offset:2048
	ds_read_b128 v[176:179], v232 offset:3072
	ds_read_b128 v[180:183], v233
	ds_read_b128 v[184:187], v233 offset:1024
	ds_read_b128 v[188:191], v233 offset:2048
	ds_read_b128 v[192:195], v233 offset:3072
	ds_read_b128 v[196:199], v160 offset:32768
	ds_read_b128 v[200:203], v160 offset:33792
	ds_read_b128 v[204:207], v160 offset:34816
	ds_read_b128 v[208:211], v160 offset:35840
	ds_read_b128 v[212:215], v160 offset:36864
	ds_read_b128 v[216:219], v160 offset:37888
	ds_read_b128 v[220:223], v160 offset:38912
	ds_read_b128 v[224:227], v160 offset:39936
	s_waitcnt vmcnt(8)
	s_waitcnt lgkmcnt(0)
	s_setprio 1
	s_barrier
	v_mfma_f32_16x16x32_bf16 v[122:125], v[164:167], v[196:199], v[122:125]
	v_mfma_f32_16x16x32_bf16 v[118:121], v[172:175], v[196:199], v[118:121]
	v_mfma_f32_16x16x32_bf16 v[110:113], v[164:167], v[204:207], v[110:113]
	v_mfma_f32_16x16x32_bf16 v[102:105], v[172:175], v[204:207], v[102:105]
	v_mfma_f32_16x16x32_bf16 v[94:97], v[164:167], v[212:215], v[94:97]
	v_mfma_f32_16x16x32_bf16 v[86:89], v[172:175], v[212:215], v[86:89]
	v_mfma_f32_16x16x32_bf16 v[78:81], v[164:167], v[220:223], v[78:81]
	v_mfma_f32_16x16x32_bf16 v[70:73], v[172:175], v[220:223], v[70:73]
	v_mfma_f32_16x16x32_bf16 v[122:125], v[168:171], v[200:203], v[122:125]
	v_mfma_f32_16x16x32_bf16 v[118:121], v[176:179], v[200:203], v[118:121]
	v_mfma_f32_16x16x32_bf16 v[110:113], v[168:171], v[208:211], v[110:113]
	v_mfma_f32_16x16x32_bf16 v[102:105], v[176:179], v[208:211], v[102:105]
	v_mfma_f32_16x16x32_bf16 v[94:97], v[168:171], v[216:219], v[94:97]
	v_mfma_f32_16x16x32_bf16 v[86:89], v[176:179], v[216:219], v[86:89]
	v_mfma_f32_16x16x32_bf16 v[78:81], v[168:171], v[224:227], v[78:81]
	v_mfma_f32_16x16x32_bf16 v[70:73], v[176:179], v[224:227], v[70:73]
	s_setprio 0
	s_setprio 1
	v_mfma_f32_16x16x32_bf16 v[126:129], v[180:183], v[196:199], v[126:129]
	v_mfma_f32_16x16x32_bf16 v[114:117], v[188:191], v[196:199], v[114:117]
	v_mfma_f32_16x16x32_bf16 v[106:109], v[180:183], v[204:207], v[106:109]
	v_mfma_f32_16x16x32_bf16 v[98:101], v[188:191], v[204:207], v[98:101]
	v_mfma_f32_16x16x32_bf16 v[90:93], v[180:183], v[212:215], v[90:93]
	v_mfma_f32_16x16x32_bf16 v[82:85], v[188:191], v[212:215], v[82:85]
	v_mfma_f32_16x16x32_bf16 v[74:77], v[180:183], v[220:223], v[74:77]
	v_mfma_f32_16x16x32_bf16 v[66:69], v[188:191], v[220:223], v[66:69]
	v_mfma_f32_16x16x32_bf16 v[126:129], v[184:187], v[200:203], v[126:129]
	v_mfma_f32_16x16x32_bf16 v[114:117], v[192:195], v[200:203], v[114:117]
	v_mfma_f32_16x16x32_bf16 v[106:109], v[184:187], v[208:211], v[106:109]
	v_mfma_f32_16x16x32_bf16 v[98:101], v[192:195], v[208:211], v[98:101]
	v_mfma_f32_16x16x32_bf16 v[90:93], v[184:187], v[216:219], v[90:93]
	v_mfma_f32_16x16x32_bf16 v[82:85], v[192:195], v[216:219], v[82:85]
	v_mfma_f32_16x16x32_bf16 v[74:77], v[184:187], v[224:227], v[74:77]
	v_mfma_f32_16x16x32_bf16 v[66:69], v[192:195], v[224:227], v[66:69]
	s_barrier
	s_setprio 0
	s_add_u32 s96, s96, 0x80
	s_addc_u32 s97, s97, 0
	s_add_u32 s98, s96, 0x40000
	s_addc_u32 s99, s97, 0
	s_add_u32 s94, s94, 0x80
	s_addc_u32 s95, s95, 0
	s_add_i32 s5, s5, s25
	s_mov_b32 m0, s5
	s_nop 0
	global_load_lds_dwordx4 v132, s[96:97]
	s_add_i32 m0, s5, 0x2000
	s_add_i32 s5, s47, s25
	global_load_lds_dwordx4 v136, s[96:97]
	s_mov_b32 m0, s5
	s_nop 0
	global_load_lds_dwordx4 v132, s[98:99]
	s_add_i32 m0, s5, 0x2000
	s_nop 0
	global_load_lds_dwordx4 v136, s[98:99]
	s_mov_b32 m0, s61
	s_nop 0
	global_load_lds_dwordx4 v130, s[94:95]
	s_mov_b32 m0, s62
	s_nop 0
	global_load_lds_dwordx4 v134, s[94:95]
	ds_read_b128 v[196:199], v160 offset:49152
	ds_read_b128 v[200:203], v160 offset:50176
	ds_read_b128 v[204:207], v160 offset:51200
	ds_read_b128 v[208:211], v160 offset:52224
	ds_read_b128 v[212:215], v160 offset:53248
	ds_read_b128 v[216:219], v160 offset:54272
	ds_read_b128 v[220:223], v160 offset:55296
	ds_read_b128 v[224:227], v160 offset:56320
	s_waitcnt vmcnt(8)
	s_waitcnt lgkmcnt(0)
	s_setprio 1
	s_barrier
	v_mfma_f32_16x16x32_bf16 v[62:65], v[164:167], v[196:199], v[62:65]
	v_mfma_f32_16x16x32_bf16 v[54:57], v[172:175], v[196:199], v[54:57]
	v_mfma_f32_16x16x32_bf16 v[46:49], v[164:167], v[204:207], v[46:49]
	v_mfma_f32_16x16x32_bf16 v[38:41], v[172:175], v[204:207], v[38:41]
	v_mfma_f32_16x16x32_bf16 v[30:33], v[164:167], v[212:215], v[30:33]
	v_mfma_f32_16x16x32_bf16 v[22:25], v[172:175], v[212:215], v[22:25]
	v_mfma_f32_16x16x32_bf16 v[14:17], v[164:167], v[220:223], v[14:17]
	v_mfma_f32_16x16x32_bf16 v[6:9], v[172:175], v[220:223], v[6:9]
	v_mfma_f32_16x16x32_bf16 v[62:65], v[168:171], v[200:203], v[62:65]
	v_mfma_f32_16x16x32_bf16 v[54:57], v[176:179], v[200:203], v[54:57]
	v_mfma_f32_16x16x32_bf16 v[46:49], v[168:171], v[208:211], v[46:49]
	v_mfma_f32_16x16x32_bf16 v[38:41], v[176:179], v[208:211], v[38:41]
	v_mfma_f32_16x16x32_bf16 v[30:33], v[168:171], v[216:219], v[30:33]
	v_mfma_f32_16x16x32_bf16 v[22:25], v[176:179], v[216:219], v[22:25]
	v_mfma_f32_16x16x32_bf16 v[14:17], v[168:171], v[224:227], v[14:17]
	v_mfma_f32_16x16x32_bf16 v[6:9], v[176:179], v[224:227], v[6:9]
	s_setprio 0
	s_setprio 1
	v_mfma_f32_16x16x32_bf16 v[58:61], v[180:183], v[196:199], v[58:61]
	v_mfma_f32_16x16x32_bf16 v[50:53], v[188:191], v[196:199], v[50:53]
	v_mfma_f32_16x16x32_bf16 v[42:45], v[180:183], v[204:207], v[42:45]
	v_mfma_f32_16x16x32_bf16 v[34:37], v[188:191], v[204:207], v[34:37]
	v_mfma_f32_16x16x32_bf16 v[26:29], v[180:183], v[212:215], v[26:29]
	v_mfma_f32_16x16x32_bf16 v[18:21], v[188:191], v[212:215], v[18:21]
	v_mfma_f32_16x16x32_bf16 v[10:13], v[180:183], v[220:223], v[10:13]
	v_mfma_f32_16x16x32_bf16 v[2:5], v[188:191], v[220:223], v[2:5]
	v_mfma_f32_16x16x32_bf16 v[58:61], v[184:187], v[200:203], v[58:61]
	v_mfma_f32_16x16x32_bf16 v[50:53], v[192:195], v[200:203], v[50:53]
	v_mfma_f32_16x16x32_bf16 v[42:45], v[184:187], v[208:211], v[42:45]
	v_mfma_f32_16x16x32_bf16 v[34:37], v[192:195], v[208:211], v[34:37]
	v_mfma_f32_16x16x32_bf16 v[26:29], v[184:187], v[216:219], v[26:29]
	v_mfma_f32_16x16x32_bf16 v[18:21], v[192:195], v[216:219], v[18:21]
	v_mfma_f32_16x16x32_bf16 v[10:13], v[184:187], v[224:227], v[10:13]
	v_mfma_f32_16x16x32_bf16 v[2:5], v[192:195], v[224:227], v[2:5]
	s_barrier
	s_setprio 0
	s_mov_b32 s5, s45
	s_add_u32 s88, s88, 0x100
	s_addc_u32 s89, s89, 0
	s_add_u32 s86, s86, 0x100
	s_addc_u32 s87, s87, 0
	s_cmp_ge_i32 s45, s101
	s_cbranch_scc0 .LBB0_1944

.LBB0_2073:
	v_cmp_gt_i32_e32 vcc, 1, v156
	s_cbranch_vccnz .LBB0_2135
	v_lshl_add_u64 v[152:153], v[2:3], 0, s[18:19]
	v_add_u32_e32 v138, -2, v156
	s_mov_b32 s4, 0
	s_nop 0
	v_readfirstlane_b32 s86, v150
	v_readfirstlane_b32 s87, v151
	v_readfirstlane_b32 s88, v152
	v_readfirstlane_b32 s89, v153
	v_readfirstlane_b32 s90, v146
	v_readfirstlane_b32 s91, v147
	v_readfirstlane_b32 s92, v148
	v_readfirstlane_b32 s93, v149
	v_readfirstlane_b32 s100, v138
	v_readfirstlane_b32 s101, v156
	v_add_u32_e32 v230, s65, v141
	v_add_u32_e32 v231, s66, v141
	v_add_u32_e32 v232, 0x18000, v141
	v_add_u32_e32 v233, 0x1c000, v141
	s_add_u32 s98, s86, 0x100
	s_addc_u32 s99, s87, 0
	s_cmp_eq_u32 s4, s100
	s_cselect_b64 s[94:95], s[90:91], s[98:99]
	s_cselect_b64 s[96:97], s[92:93], s[88:89]
	s_add_i32 s5, s4, 2
	s_nop 0
	s_add_i32 m0, s44, 0xc000
	s_nop 0
	global_load_lds_dwordx4 v144, s[86:87]
	s_add_i32 m0, s44, 0xe000
	s_nop 0
	global_load_lds_dwordx4 v142, s[86:87]
	ds_read_b128 v[164:167], v230
	ds_read_b128 v[168:171], v230 offset:1024
	ds_read_b128 v[172:175], v230 offset:2048
	ds_read_b128 v[176:179], v230 offset:3072
	ds_read_b128 v[180:183], v231
	ds_read_b128 v[184:187], v231 offset:1024
	ds_read_b128 v[188:191], v231 offset:2048
	ds_read_b128 v[192:195], v231 offset:3072
	ds_read_b128 v[196:199], v160
	ds_read_b128 v[200:203], v160 offset:1024
	ds_read_b128 v[204:207], v160 offset:2048
	ds_read_b128 v[208:211], v160 offset:3072
	ds_read_b128 v[212:215], v160 offset:4096
	ds_read_b128 v[216:219], v160 offset:5120
	ds_read_b128 v[220:223], v160 offset:6144
	ds_read_b128 v[224:227], v160 offset:7168
	s_waitcnt vmcnt(8)
	s_waitcnt lgkmcnt(0)
	s_setprio 1
	s_barrier
	v_mfma_f32_16x16x32_bf16 v[122:125], v[164:167], v[196:199], 0
	v_mfma_f32_16x16x32_bf16 v[118:121], v[172:175], v[196:199], 0
	v_mfma_f32_16x16x32_bf16 v[110:113], v[164:167], v[204:207], 0
	v_mfma_f32_16x16x32_bf16 v[102:105], v[172:175], v[204:207], 0
	v_mfma_f32_16x16x32_bf16 v[94:97], v[164:167], v[212:215], 0
	v_mfma_f32_16x16x32_bf16 v[86:89], v[172:175], v[212:215], 0
	v_mfma_f32_16x16x32_bf16 v[78:81], v[164:167], v[220:223], 0
	v_mfma_f32_16x16x32_bf16 v[70:73], v[172:175], v[220:223], 0
	v_mfma_f32_16x16x32_bf16 v[122:125], v[168:171], v[200:203], v[122:125]
	v_mfma_f32_16x16x32_bf16 v[118:121], v[176:179], v[200:203], v[118:121]
	v_mfma_f32_16x16x32_bf16 v[110:113], v[168:171], v[208:211], v[110:113]
	v_mfma_f32_16x16x32_bf16 v[102:105], v[176:179], v[208:211], v[102:105]
	v_mfma_f32_16x16x32_bf16 v[94:97], v[168:171], v[216:219], v[94:97]
	v_mfma_f32_16x16x32_bf16 v[86:89], v[176:179], v[216:219], v[86:89]
	v_mfma_f32_16x16x32_bf16 v[78:81], v[168:171], v[224:227], v[78:81]
	v_mfma_f32_16x16x32_bf16 v[70:73], v[176:179], v[224:227], v[70:73]
	s_setprio 0
	s_setprio 1
	v_mfma_f32_16x16x32_bf16 v[126:129], v[180:183], v[196:199], 0
	v_mfma_f32_16x16x32_bf16 v[114:117], v[188:191], v[196:199], 0
	v_mfma_f32_16x16x32_bf16 v[106:109], v[180:183], v[204:207], 0
	v_mfma_f32_16x16x32_bf16 v[98:101], v[188:191], v[204:207], 0
	v_mfma_f32_16x16x32_bf16 v[90:93], v[180:183], v[212:215], 0
	v_mfma_f32_16x16x32_bf16 v[82:85], v[188:191], v[212:215], 0
	v_mfma_f32_16x16x32_bf16 v[74:77], v[180:183], v[220:223], 0
	v_mfma_f32_16x16x32_bf16 v[66:69], v[188:191], v[220:223], 0
	v_mfma_f32_16x16x32_bf16 v[126:129], v[184:187], v[200:203], v[126:129]
	v_mfma_f32_16x16x32_bf16 v[114:117], v[192:195], v[200:203], v[114:117]
	v_mfma_f32_16x16x32_bf16 v[106:109], v[184:187], v[208:211], v[106:109]
	v_mfma_f32_16x16x32_bf16 v[98:101], v[192:195], v[208:211], v[98:101]
	v_mfma_f32_16x16x32_bf16 v[90:93], v[184:187], v[216:219], v[90:93]
	v_mfma_f32_16x16x32_bf16 v[82:85], v[192:195], v[216:219], v[82:85]
	v_mfma_f32_16x16x32_bf16 v[74:77], v[184:187], v[224:227], v[74:77]
	v_mfma_f32_16x16x32_bf16 v[66:69], v[192:195], v[224:227], v[66:69]
	s_barrier
	s_setprio 0
	s_add_u32 s98, s96, 0xb0000
	s_addc_u32 s99, s97, 0
	s_add_i32 s4, s65, s21
	s_mov_b32 m0, s4
	s_nop 0
	global_load_lds_dwordx4 v132, s[96:97]
	s_add_i32 m0, s4, 0x2000
	s_add_i32 s4, s66, s21
	global_load_lds_dwordx4 v136, s[96:97]
	s_mov_b32 m0, s4
	s_nop 0
	global_load_lds_dwordx4 v132, s[98:99]
	s_add_i32 m0, s4, 0x2000
	s_nop 0
	global_load_lds_dwordx4 v136, s[98:99]
	s_mov_b32 m0, s44
	s_nop 0
	global_load_lds_dwordx4 v130, s[94:95]
	s_mov_b32 m0, s45
	s_nop 0
	global_load_lds_dwordx4 v134, s[94:95]
	ds_read_b128 v[196:199], v160 offset:16384
	ds_read_b128 v[200:203], v160 offset:17408
	ds_read_b128 v[204:207], v160 offset:18432
	ds_read_b128 v[208:211], v160 offset:19456
	ds_read_b128 v[212:215], v160 offset:20480
	ds_read_b128 v[216:219], v160 offset:21504
	ds_read_b128 v[220:223], v160 offset:22528
	ds_read_b128 v[224:227], v160 offset:23552
	s_waitcnt vmcnt(8)
	s_waitcnt lgkmcnt(0)
	s_setprio 1
	s_barrier
	v_mfma_f32_16x16x32_bf16 v[62:65], v[164:167], v[196:199], 0
	v_mfma_f32_16x16x32_bf16 v[54:57], v[172:175], v[196:199], 0
	v_mfma_f32_16x16x32_bf16 v[46:49], v[164:167], v[204:207], 0
	v_mfma_f32_16x16x32_bf16 v[38:41], v[172:175], v[204:207], 0
	v_mfma_f32_16x16x32_bf16 v[30:33], v[164:167], v[212:215], 0
	v_mfma_f32_16x16x32_bf16 v[22:25], v[172:175], v[212:215], 0
	v_mfma_f32_16x16x32_bf16 v[14:17], v[164:167], v[220:223], 0
	v_mfma_f32_16x16x32_bf16 v[6:9], v[172:175], v[220:223], 0
	v_mfma_f32_16x16x32_bf16 v[62:65], v[168:171], v[200:203], v[62:65]
	v_mfma_f32_16x16x32_bf16 v[54:57], v[176:179], v[200:203], v[54:57]
	v_mfma_f32_16x16x32_bf16 v[46:49], v[168:171], v[208:211], v[46:49]
	v_mfma_f32_16x16x32_bf16 v[38:41], v[176:179], v[208:211], v[38:41]
	v_mfma_f32_16x16x32_bf16 v[30:33], v[168:171], v[216:219], v[30:33]
	v_mfma_f32_16x16x32_bf16 v[22:25], v[176:179], v[216:219], v[22:25]
	v_mfma_f32_16x16x32_bf16 v[14:17], v[168:171], v[224:227], v[14:17]
	v_mfma_f32_16x16x32_bf16 v[6:9], v[176:179], v[224:227], v[6:9]
	s_setprio 0
	s_setprio 1
	v_mfma_f32_16x16x32_bf16 v[58:61], v[180:183], v[196:199], 0
	v_mfma_f32_16x16x32_bf16 v[50:53], v[188:191], v[196:199], 0
	v_mfma_f32_16x16x32_bf16 v[42:45], v[180:183], v[204:207], 0
	v_mfma_f32_16x16x32_bf16 v[34:37], v[188:191], v[204:207], 0
	v_mfma_f32_16x16x32_bf16 v[26:29], v[180:183], v[212:215], 0
	v_mfma_f32_16x16x32_bf16 v[18:21], v[188:191], v[212:215], 0
	v_mfma_f32_16x16x32_bf16 v[10:13], v[180:183], v[220:223], 0
	v_mfma_f32_16x16x32_bf16 v[2:5], v[188:191], v[220:223], 0
	v_mfma_f32_16x16x32_bf16 v[58:61], v[184:187], v[200:203], v[58:61]
	v_mfma_f32_16x16x32_bf16 v[50:53], v[192:195], v[200:203], v[50:53]
	v_mfma_f32_16x16x32_bf16 v[42:45], v[184:187], v[208:211], v[42:45]
	v_mfma_f32_16x16x32_bf16 v[34:37], v[192:195], v[208:211], v[34:37]
	v_mfma_f32_16x16x32_bf16 v[26:29], v[184:187], v[216:219], v[26:29]
	v_mfma_f32_16x16x32_bf16 v[18:21], v[192:195], v[216:219], v[18:21]
	v_mfma_f32_16x16x32_bf16 v[10:13], v[184:187], v[224:227], v[10:13]
	v_mfma_f32_16x16x32_bf16 v[2:5], v[192:195], v[224:227], v[2:5]
	s_barrier
	s_setprio 0
	s_add_u32 s98, s94, 0xb0000
	s_addc_u32 s99, s95, 0
	s_add_i32 s4, 0, 0x18000
	s_add_i32 s25, 0, 0x1c000
	s_mov_b32 m0, s46
	s_nop 0
	global_load_lds_dwordx4 v130, s[98:99]
	s_mov_b32 m0, s47
	s_nop 0
	global_load_lds_dwordx4 v134, s[98:99]
	ds_read_b128 v[164:167], v232
	ds_read_b128 v[168:171], v232 offset:1024
	ds_read_b128 v[172:175], v232 offset:2048
	ds_read_b128 v[176:179], v232 offset:3072
	ds_read_b128 v[180:183], v233
	ds_read_b128 v[184:187], v233 offset:1024
	ds_read_b128 v[188:191], v233 offset:2048
	ds_read_b128 v[192:195], v233 offset:3072
	ds_read_b128 v[196:199], v160 offset:32768
	ds_read_b128 v[200:203], v160 offset:33792
	ds_read_b128 v[204:207], v160 offset:34816
	ds_read_b128 v[208:211], v160 offset:35840
	ds_read_b128 v[212:215], v160 offset:36864
	ds_read_b128 v[216:219], v160 offset:37888
	ds_read_b128 v[220:223], v160 offset:38912
	ds_read_b128 v[224:227], v160 offset:39936
	s_waitcnt vmcnt(8)
	s_waitcnt lgkmcnt(0)
	s_setprio 1
	s_barrier
	v_mfma_f32_16x16x32_bf16 v[122:125], v[164:167], v[196:199], v[122:125]
	v_mfma_f32_16x16x32_bf16 v[118:121], v[172:175], v[196:199], v[118:121]
	v_mfma_f32_16x16x32_bf16 v[110:113], v[164:167], v[204:207], v[110:113]
	v_mfma_f32_16x16x32_bf16 v[102:105], v[172:175], v[204:207], v[102:105]
	v_mfma_f32_16x16x32_bf16 v[94:97], v[164:167], v[212:215], v[94:97]
	v_mfma_f32_16x16x32_bf16 v[86:89], v[172:175], v[212:215], v[86:89]
	v_mfma_f32_16x16x32_bf16 v[78:81], v[164:167], v[220:223], v[78:81]
	v_mfma_f32_16x16x32_bf16 v[70:73], v[172:175], v[220:223], v[70:73]
	v_mfma_f32_16x16x32_bf16 v[122:125], v[168:171], v[200:203], v[122:125]
	v_mfma_f32_16x16x32_bf16 v[118:121], v[176:179], v[200:203], v[118:121]
	v_mfma_f32_16x16x32_bf16 v[110:113], v[168:171], v[208:211], v[110:113]
	v_mfma_f32_16x16x32_bf16 v[102:105], v[176:179], v[208:211], v[102:105]
	v_mfma_f32_16x16x32_bf16 v[94:97], v[168:171], v[216:219], v[94:97]
	v_mfma_f32_16x16x32_bf16 v[86:89], v[176:179], v[216:219], v[86:89]
	v_mfma_f32_16x16x32_bf16 v[78:81], v[168:171], v[224:227], v[78:81]
	v_mfma_f32_16x16x32_bf16 v[70:73], v[176:179], v[224:227], v[70:73]
	s_setprio 0
	s_setprio 1
	v_mfma_f32_16x16x32_bf16 v[126:129], v[180:183], v[196:199], v[126:129]
	v_mfma_f32_16x16x32_bf16 v[114:117], v[188:191], v[196:199], v[114:117]
	v_mfma_f32_16x16x32_bf16 v[106:109], v[180:183], v[204:207], v[106:109]
	v_mfma_f32_16x16x32_bf16 v[98:101], v[188:191], v[204:207], v[98:101]
	v_mfma_f32_16x16x32_bf16 v[90:93], v[180:183], v[212:215], v[90:93]
	v_mfma_f32_16x16x32_bf16 v[82:85], v[188:191], v[212:215], v[82:85]
	v_mfma_f32_16x16x32_bf16 v[74:77], v[180:183], v[220:223], v[74:77]
	v_mfma_f32_16x16x32_bf16 v[66:69], v[188:191], v[220:223], v[66:69]
	v_mfma_f32_16x16x32_bf16 v[126:129], v[184:187], v[200:203], v[126:129]
	v_mfma_f32_16x16x32_bf16 v[114:117], v[192:195], v[200:203], v[114:117]
	v_mfma_f32_16x16x32_bf16 v[106:109], v[184:187], v[208:211], v[106:109]
	v_mfma_f32_16x16x32_bf16 v[98:101], v[192:195], v[208:211], v[98:101]
	v_mfma_f32_16x16x32_bf16 v[90:93], v[184:187], v[216:219], v[90:93]
	v_mfma_f32_16x16x32_bf16 v[82:85], v[192:195], v[216:219], v[82:85]
	v_mfma_f32_16x16x32_bf16 v[74:77], v[184:187], v[224:227], v[74:77]
	v_mfma_f32_16x16x32_bf16 v[66:69], v[192:195], v[224:227], v[66:69]
	s_barrier
	s_setprio 0
	s_add_u32 s96, s96, 0x80
	s_addc_u32 s97, s97, 0
	s_add_u32 s98, s96, 0xb0000
	s_addc_u32 s99, s97, 0
	s_add_u32 s94, s94, 0x80
	s_addc_u32 s95, s95, 0
	s_add_i32 s4, s4, s21
	s_mov_b32 m0, s4
	s_nop 0
	global_load_lds_dwordx4 v132, s[96:97]
	s_add_i32 m0, s4, 0x2000
	s_add_i32 s4, s25, s21
	global_load_lds_dwordx4 v136, s[96:97]
	s_mov_b32 m0, s4
	s_nop 0
	global_load_lds_dwordx4 v132, s[98:99]
	s_add_i32 m0, s4, 0x2000
	s_nop 0
	global_load_lds_dwordx4 v136, s[98:99]
	s_mov_b32 m0, s57
	s_nop 0
	global_load_lds_dwordx4 v130, s[94:95]
	s_mov_b32 m0, s58
	s_nop 0
	global_load_lds_dwordx4 v134, s[94:95]
	ds_read_b128 v[196:199], v160 offset:49152
	ds_read_b128 v[200:203], v160 offset:50176
	ds_read_b128 v[204:207], v160 offset:51200
	ds_read_b128 v[208:211], v160 offset:52224
	ds_read_b128 v[212:215], v160 offset:53248
	ds_read_b128 v[216:219], v160 offset:54272
	ds_read_b128 v[220:223], v160 offset:55296
	ds_read_b128 v[224:227], v160 offset:56320
	s_waitcnt vmcnt(8)
	s_waitcnt lgkmcnt(0)
	s_setprio 1
	s_barrier
	v_mfma_f32_16x16x32_bf16 v[62:65], v[164:167], v[196:199], v[62:65]
	v_mfma_f32_16x16x32_bf16 v[54:57], v[172:175], v[196:199], v[54:57]
	v_mfma_f32_16x16x32_bf16 v[46:49], v[164:167], v[204:207], v[46:49]
	v_mfma_f32_16x16x32_bf16 v[38:41], v[172:175], v[204:207], v[38:41]
	v_mfma_f32_16x16x32_bf16 v[30:33], v[164:167], v[212:215], v[30:33]
	v_mfma_f32_16x16x32_bf16 v[22:25], v[172:175], v[212:215], v[22:25]
	v_mfma_f32_16x16x32_bf16 v[14:17], v[164:167], v[220:223], v[14:17]
	v_mfma_f32_16x16x32_bf16 v[6:9], v[172:175], v[220:223], v[6:9]
	v_mfma_f32_16x16x32_bf16 v[62:65], v[168:171], v[200:203], v[62:65]
	v_mfma_f32_16x16x32_bf16 v[54:57], v[176:179], v[200:203], v[54:57]
	v_mfma_f32_16x16x32_bf16 v[46:49], v[168:171], v[208:211], v[46:49]
	v_mfma_f32_16x16x32_bf16 v[38:41], v[176:179], v[208:211], v[38:41]
	v_mfma_f32_16x16x32_bf16 v[30:33], v[168:171], v[216:219], v[30:33]
	v_mfma_f32_16x16x32_bf16 v[22:25], v[176:179], v[216:219], v[22:25]
	v_mfma_f32_16x16x32_bf16 v[14:17], v[168:171], v[224:227], v[14:17]
	v_mfma_f32_16x16x32_bf16 v[6:9], v[176:179], v[224:227], v[6:9]
	s_setprio 0
	s_setprio 1
	v_mfma_f32_16x16x32_bf16 v[58:61], v[180:183], v[196:199], v[58:61]
	v_mfma_f32_16x16x32_bf16 v[50:53], v[188:191], v[196:199], v[50:53]
	v_mfma_f32_16x16x32_bf16 v[42:45], v[180:183], v[204:207], v[42:45]
	v_mfma_f32_16x16x32_bf16 v[34:37], v[188:191], v[204:207], v[34:37]
	v_mfma_f32_16x16x32_bf16 v[26:29], v[180:183], v[212:215], v[26:29]
	v_mfma_f32_16x16x32_bf16 v[18:21], v[188:191], v[212:215], v[18:21]
	v_mfma_f32_16x16x32_bf16 v[10:13], v[180:183], v[220:223], v[10:13]
	v_mfma_f32_16x16x32_bf16 v[2:5], v[188:191], v[220:223], v[2:5]
	v_mfma_f32_16x16x32_bf16 v[58:61], v[184:187], v[200:203], v[58:61]
	v_mfma_f32_16x16x32_bf16 v[50:53], v[192:195], v[200:203], v[50:53]
	v_mfma_f32_16x16x32_bf16 v[42:45], v[184:187], v[208:211], v[42:45]
	v_mfma_f32_16x16x32_bf16 v[34:37], v[192:195], v[208:211], v[34:37]
	v_mfma_f32_16x16x32_bf16 v[26:29], v[184:187], v[216:219], v[26:29]
	v_mfma_f32_16x16x32_bf16 v[18:21], v[192:195], v[216:219], v[18:21]
	v_mfma_f32_16x16x32_bf16 v[10:13], v[184:187], v[224:227], v[10:13]
	v_mfma_f32_16x16x32_bf16 v[2:5], v[192:195], v[224:227], v[2:5]
	s_barrier
	s_setprio 0
	s_mov_b32 s4, s5
	s_add_u32 s88, s88, 0x100
	s_addc_u32 s89, s89, 0
	s_add_u32 s86, s86, 0x100
	s_addc_u32 s87, s87, 0
	s_cmp_ge_i32 s5, s101
	s_cbranch_scc1 .Lmy_kexit_11
.LBB0_2075:
	s_add_u32 s98, s86, 0x100
	s_addc_u32 s99, s87, 0
	s_cmp_eq_u32 s4, s100
	s_cselect_b64 s[94:95], s[90:91], s[98:99]
	s_cselect_b64 s[96:97], s[92:93], s[88:89]
	s_add_i32 s5, s4, 2
	s_nop 0
	s_add_i32 m0, s44, 0xc000
	s_nop 0
	global_load_lds_dwordx4 v144, s[86:87]
	s_add_i32 m0, s44, 0xe000
	s_nop 0
	global_load_lds_dwordx4 v142, s[86:87]
	ds_read_b128 v[164:167], v230
	ds_read_b128 v[168:171], v230 offset:1024
	ds_read_b128 v[172:175], v230 offset:2048
	ds_read_b128 v[176:179], v230 offset:3072
	ds_read_b128 v[180:183], v231
	ds_read_b128 v[184:187], v231 offset:1024
	ds_read_b128 v[188:191], v231 offset:2048
	ds_read_b128 v[192:195], v231 offset:3072
	ds_read_b128 v[196:199], v160
	ds_read_b128 v[200:203], v160 offset:1024
	ds_read_b128 v[204:207], v160 offset:2048
	ds_read_b128 v[208:211], v160 offset:3072
	ds_read_b128 v[212:215], v160 offset:4096
	ds_read_b128 v[216:219], v160 offset:5120
	ds_read_b128 v[220:223], v160 offset:6144
	ds_read_b128 v[224:227], v160 offset:7168
	s_waitcnt vmcnt(8)
	s_waitcnt lgkmcnt(0)
	s_setprio 1
	s_barrier
	v_mfma_f32_16x16x32_bf16 v[122:125], v[164:167], v[196:199], v[122:125]
	v_mfma_f32_16x16x32_bf16 v[118:121], v[172:175], v[196:199], v[118:121]
	v_mfma_f32_16x16x32_bf16 v[110:113], v[164:167], v[204:207], v[110:113]
	v_mfma_f32_16x16x32_bf16 v[102:105], v[172:175], v[204:207], v[102:105]
	v_mfma_f32_16x16x32_bf16 v[94:97], v[164:167], v[212:215], v[94:97]
	v_mfma_f32_16x16x32_bf16 v[86:89], v[172:175], v[212:215], v[86:89]
	v_mfma_f32_16x16x32_bf16 v[78:81], v[164:167], v[220:223], v[78:81]
	v_mfma_f32_16x16x32_bf16 v[70:73], v[172:175], v[220:223], v[70:73]
	v_mfma_f32_16x16x32_bf16 v[122:125], v[168:171], v[200:203], v[122:125]
	v_mfma_f32_16x16x32_bf16 v[118:121], v[176:179], v[200:203], v[118:121]
	v_mfma_f32_16x16x32_bf16 v[110:113], v[168:171], v[208:211], v[110:113]
	v_mfma_f32_16x16x32_bf16 v[102:105], v[176:179], v[208:211], v[102:105]
	v_mfma_f32_16x16x32_bf16 v[94:97], v[168:171], v[216:219], v[94:97]
	v_mfma_f32_16x16x32_bf16 v[86:89], v[176:179], v[216:219], v[86:89]
	v_mfma_f32_16x16x32_bf16 v[78:81], v[168:171], v[224:227], v[78:81]
	v_mfma_f32_16x16x32_bf16 v[70:73], v[176:179], v[224:227], v[70:73]
	s_setprio 0
	s_setprio 1
	v_mfma_f32_16x16x32_bf16 v[126:129], v[180:183], v[196:199], v[126:129]
	v_mfma_f32_16x16x32_bf16 v[114:117], v[188:191], v[196:199], v[114:117]
	v_mfma_f32_16x16x32_bf16 v[106:109], v[180:183], v[204:207], v[106:109]
	v_mfma_f32_16x16x32_bf16 v[98:101], v[188:191], v[204:207], v[98:101]
	v_mfma_f32_16x16x32_bf16 v[90:93], v[180:183], v[212:215], v[90:93]
	v_mfma_f32_16x16x32_bf16 v[82:85], v[188:191], v[212:215], v[82:85]
	v_mfma_f32_16x16x32_bf16 v[74:77], v[180:183], v[220:223], v[74:77]
	v_mfma_f32_16x16x32_bf16 v[66:69], v[188:191], v[220:223], v[66:69]
	v_mfma_f32_16x16x32_bf16 v[126:129], v[184:187], v[200:203], v[126:129]
	v_mfma_f32_16x16x32_bf16 v[114:117], v[192:195], v[200:203], v[114:117]
	v_mfma_f32_16x16x32_bf16 v[106:109], v[184:187], v[208:211], v[106:109]
	v_mfma_f32_16x16x32_bf16 v[98:101], v[192:195], v[208:211], v[98:101]
	v_mfma_f32_16x16x32_bf16 v[90:93], v[184:187], v[216:219], v[90:93]
	v_mfma_f32_16x16x32_bf16 v[82:85], v[192:195], v[216:219], v[82:85]
	v_mfma_f32_16x16x32_bf16 v[74:77], v[184:187], v[224:227], v[74:77]
	v_mfma_f32_16x16x32_bf16 v[66:69], v[192:195], v[224:227], v[66:69]
	s_barrier
	s_setprio 0
	s_add_u32 s98, s96, 0xb0000
	s_addc_u32 s99, s97, 0
	s_add_i32 s4, s65, s21
	s_mov_b32 m0, s4
	s_nop 0
	global_load_lds_dwordx4 v132, s[96:97]
	s_add_i32 m0, s4, 0x2000
	s_add_i32 s4, s66, s21
	global_load_lds_dwordx4 v136, s[96:97]
	s_mov_b32 m0, s4
	s_nop 0
	global_load_lds_dwordx4 v132, s[98:99]
	s_add_i32 m0, s4, 0x2000
	s_nop 0
	global_load_lds_dwordx4 v136, s[98:99]
	s_mov_b32 m0, s44
	s_nop 0
	global_load_lds_dwordx4 v130, s[94:95]
	s_mov_b32 m0, s45
	s_nop 0
	global_load_lds_dwordx4 v134, s[94:95]
	ds_read_b128 v[196:199], v160 offset:16384
	ds_read_b128 v[200:203], v160 offset:17408
	ds_read_b128 v[204:207], v160 offset:18432
	ds_read_b128 v[208:211], v160 offset:19456
	ds_read_b128 v[212:215], v160 offset:20480
	ds_read_b128 v[216:219], v160 offset:21504
	ds_read_b128 v[220:223], v160 offset:22528
	ds_read_b128 v[224:227], v160 offset:23552
	s_waitcnt vmcnt(8)
	s_waitcnt lgkmcnt(0)
	s_setprio 1
	s_barrier
	v_mfma_f32_16x16x32_bf16 v[62:65], v[164:167], v[196:199], v[62:65]
	v_mfma_f32_16x16x32_bf16 v[54:57], v[172:175], v[196:199], v[54:57]
	v_mfma_f32_16x16x32_bf16 v[46:49], v[164:167], v[204:207], v[46:49]
	v_mfma_f32_16x16x32_bf16 v[38:41], v[172:175], v[204:207], v[38:41]
	v_mfma_f32_16x16x32_bf16 v[30:33], v[164:167], v[212:215], v[30:33]
	v_mfma_f32_16x16x32_bf16 v[22:25], v[172:175], v[212:215], v[22:25]
	v_mfma_f32_16x16x32_bf16 v[14:17], v[164:167], v[220:223], v[14:17]
	v_mfma_f32_16x16x32_bf16 v[6:9], v[172:175], v[220:223], v[6:9]
	v_mfma_f32_16x16x32_bf16 v[62:65], v[168:171], v[200:203], v[62:65]
	v_mfma_f32_16x16x32_bf16 v[54:57], v[176:179], v[200:203], v[54:57]
	v_mfma_f32_16x16x32_bf16 v[46:49], v[168:171], v[208:211], v[46:49]
	v_mfma_f32_16x16x32_bf16 v[38:41], v[176:179], v[208:211], v[38:41]
	v_mfma_f32_16x16x32_bf16 v[30:33], v[168:171], v[216:219], v[30:33]
	v_mfma_f32_16x16x32_bf16 v[22:25], v[176:179], v[216:219], v[22:25]
	v_mfma_f32_16x16x32_bf16 v[14:17], v[168:171], v[224:227], v[14:17]
	v_mfma_f32_16x16x32_bf16 v[6:9], v[176:179], v[224:227], v[6:9]
	s_setprio 0
	s_setprio 1
	v_mfma_f32_16x16x32_bf16 v[58:61], v[180:183], v[196:199], v[58:61]
	v_mfma_f32_16x16x32_bf16 v[50:53], v[188:191], v[196:199], v[50:53]
	v_mfma_f32_16x16x32_bf16 v[42:45], v[180:183], v[204:207], v[42:45]
	v_mfma_f32_16x16x32_bf16 v[34:37], v[188:191], v[204:207], v[34:37]
	v_mfma_f32_16x16x32_bf16 v[26:29], v[180:183], v[212:215], v[26:29]
	v_mfma_f32_16x16x32_bf16 v[18:21], v[188:191], v[212:215], v[18:21]
	v_mfma_f32_16x16x32_bf16 v[10:13], v[180:183], v[220:223], v[10:13]
	v_mfma_f32_16x16x32_bf16 v[2:5], v[188:191], v[220:223], v[2:5]
	v_mfma_f32_16x16x32_bf16 v[58:61], v[184:187], v[200:203], v[58:61]
	v_mfma_f32_16x16x32_bf16 v[50:53], v[192:195], v[200:203], v[50:53]
	v_mfma_f32_16x16x32_bf16 v[42:45], v[184:187], v[208:211], v[42:45]
	v_mfma_f32_16x16x32_bf16 v[34:37], v[192:195], v[208:211], v[34:37]
	v_mfma_f32_16x16x32_bf16 v[26:29], v[184:187], v[216:219], v[26:29]
	v_mfma_f32_16x16x32_bf16 v[18:21], v[192:195], v[216:219], v[18:21]
	v_mfma_f32_16x16x32_bf16 v[10:13], v[184:187], v[224:227], v[10:13]
	v_mfma_f32_16x16x32_bf16 v[2:5], v[192:195], v[224:227], v[2:5]
	s_barrier
	s_setprio 0
	s_add_u32 s98, s94, 0xb0000
	s_addc_u32 s99, s95, 0
	s_add_i32 s4, 0, 0x18000
	s_add_i32 s25, 0, 0x1c000
	s_mov_b32 m0, s46
	s_nop 0
	global_load_lds_dwordx4 v130, s[98:99]
	s_mov_b32 m0, s47
	s_nop 0
	global_load_lds_dwordx4 v134, s[98:99]
	ds_read_b128 v[164:167], v232
	ds_read_b128 v[168:171], v232 offset:1024
	ds_read_b128 v[172:175], v232 offset:2048
	ds_read_b128 v[176:179], v232 offset:3072
	ds_read_b128 v[180:183], v233
	ds_read_b128 v[184:187], v233 offset:1024
	ds_read_b128 v[188:191], v233 offset:2048
	ds_read_b128 v[192:195], v233 offset:3072
	ds_read_b128 v[196:199], v160 offset:32768
	ds_read_b128 v[200:203], v160 offset:33792
	ds_read_b128 v[204:207], v160 offset:34816
	ds_read_b128 v[208:211], v160 offset:35840
	ds_read_b128 v[212:215], v160 offset:36864
	ds_read_b128 v[216:219], v160 offset:37888
	ds_read_b128 v[220:223], v160 offset:38912
	ds_read_b128 v[224:227], v160 offset:39936
	s_waitcnt vmcnt(8)
	s_waitcnt lgkmcnt(0)
	s_setprio 1
	s_barrier
	v_mfma_f32_16x16x32_bf16 v[122:125], v[164:167], v[196:199], v[122:125]
	v_mfma_f32_16x16x32_bf16 v[118:121], v[172:175], v[196:199], v[118:121]
	v_mfma_f32_16x16x32_bf16 v[110:113], v[164:167], v[204:207], v[110:113]
	v_mfma_f32_16x16x32_bf16 v[102:105], v[172:175], v[204:207], v[102:105]
	v_mfma_f32_16x16x32_bf16 v[94:97], v[164:167], v[212:215], v[94:97]
	v_mfma_f32_16x16x32_bf16 v[86:89], v[172:175], v[212:215], v[86:89]
	v_mfma_f32_16x16x32_bf16 v[78:81], v[164:167], v[220:223], v[78:81]
	v_mfma_f32_16x16x32_bf16 v[70:73], v[172:175], v[220:223], v[70:73]
	v_mfma_f32_16x16x32_bf16 v[122:125], v[168:171], v[200:203], v[122:125]
	v_mfma_f32_16x16x32_bf16 v[118:121], v[176:179], v[200:203], v[118:121]
	v_mfma_f32_16x16x32_bf16 v[110:113], v[168:171], v[208:211], v[110:113]
	v_mfma_f32_16x16x32_bf16 v[102:105], v[176:179], v[208:211], v[102:105]
	v_mfma_f32_16x16x32_bf16 v[94:97], v[168:171], v[216:219], v[94:97]
	v_mfma_f32_16x16x32_bf16 v[86:89], v[176:179], v[216:219], v[86:89]
	v_mfma_f32_16x16x32_bf16 v[78:81], v[168:171], v[224:227], v[78:81]
	v_mfma_f32_16x16x32_bf16 v[70:73], v[176:179], v[224:227], v[70:73]
	s_setprio 0
	s_setprio 1
	v_mfma_f32_16x16x32_bf16 v[126:129], v[180:183], v[196:199], v[126:129]
	v_mfma_f32_16x16x32_bf16 v[114:117], v[188:191], v[196:199], v[114:117]
	v_mfma_f32_16x16x32_bf16 v[106:109], v[180:183], v[204:207], v[106:109]
	v_mfma_f32_16x16x32_bf16 v[98:101], v[188:191], v[204:207], v[98:101]
	v_mfma_f32_16x16x32_bf16 v[90:93], v[180:183], v[212:215], v[90:93]
	v_mfma_f32_16x16x32_bf16 v[82:85], v[188:191], v[212:215], v[82:85]
	v_mfma_f32_16x16x32_bf16 v[74:77], v[180:183], v[220:223], v[74:77]
	v_mfma_f32_16x16x32_bf16 v[66:69], v[188:191], v[220:223], v[66:69]
	v_mfma_f32_16x16x32_bf16 v[126:129], v[184:187], v[200:203], v[126:129]
	v_mfma_f32_16x16x32_bf16 v[114:117], v[192:195], v[200:203], v[114:117]
	v_mfma_f32_16x16x32_bf16 v[106:109], v[184:187], v[208:211], v[106:109]
	v_mfma_f32_16x16x32_bf16 v[98:101], v[192:195], v[208:211], v[98:101]
	v_mfma_f32_16x16x32_bf16 v[90:93], v[184:187], v[216:219], v[90:93]
	v_mfma_f32_16x16x32_bf16 v[82:85], v[192:195], v[216:219], v[82:85]
	v_mfma_f32_16x16x32_bf16 v[74:77], v[184:187], v[224:227], v[74:77]
	v_mfma_f32_16x16x32_bf16 v[66:69], v[192:195], v[224:227], v[66:69]
	s_barrier
	s_setprio 0
	s_add_u32 s96, s96, 0x80
	s_addc_u32 s97, s97, 0
	s_add_u32 s98, s96, 0xb0000
	s_addc_u32 s99, s97, 0
	s_add_u32 s94, s94, 0x80
	s_addc_u32 s95, s95, 0
	s_add_i32 s4, s4, s21
	s_mov_b32 m0, s4
	s_nop 0
	global_load_lds_dwordx4 v132, s[96:97]
	s_add_i32 m0, s4, 0x2000
	s_add_i32 s4, s25, s21
	global_load_lds_dwordx4 v136, s[96:97]
	s_mov_b32 m0, s4
	s_nop 0
	global_load_lds_dwordx4 v132, s[98:99]
	s_add_i32 m0, s4, 0x2000
	s_nop 0
	global_load_lds_dwordx4 v136, s[98:99]
	s_mov_b32 m0, s57
	s_nop 0
	global_load_lds_dwordx4 v130, s[94:95]
	s_mov_b32 m0, s58
	s_nop 0
	global_load_lds_dwordx4 v134, s[94:95]
	ds_read_b128 v[196:199], v160 offset:49152
	ds_read_b128 v[200:203], v160 offset:50176
	ds_read_b128 v[204:207], v160 offset:51200
	ds_read_b128 v[208:211], v160 offset:52224
	ds_read_b128 v[212:215], v160 offset:53248
	ds_read_b128 v[216:219], v160 offset:54272
	ds_read_b128 v[220:223], v160 offset:55296
	ds_read_b128 v[224:227], v160 offset:56320
	s_waitcnt vmcnt(8)
	s_waitcnt lgkmcnt(0)
	s_setprio 1
	s_barrier
	v_mfma_f32_16x16x32_bf16 v[62:65], v[164:167], v[196:199], v[62:65]
	v_mfma_f32_16x16x32_bf16 v[54:57], v[172:175], v[196:199], v[54:57]
	v_mfma_f32_16x16x32_bf16 v[46:49], v[164:167], v[204:207], v[46:49]
	v_mfma_f32_16x16x32_bf16 v[38:41], v[172:175], v[204:207], v[38:41]
	v_mfma_f32_16x16x32_bf16 v[30:33], v[164:167], v[212:215], v[30:33]
	v_mfma_f32_16x16x32_bf16 v[22:25], v[172:175], v[212:215], v[22:25]
	v_mfma_f32_16x16x32_bf16 v[14:17], v[164:167], v[220:223], v[14:17]
	v_mfma_f32_16x16x32_bf16 v[6:9], v[172:175], v[220:223], v[6:9]
	v_mfma_f32_16x16x32_bf16 v[62:65], v[168:171], v[200:203], v[62:65]
	v_mfma_f32_16x16x32_bf16 v[54:57], v[176:179], v[200:203], v[54:57]
	v_mfma_f32_16x16x32_bf16 v[46:49], v[168:171], v[208:211], v[46:49]
	v_mfma_f32_16x16x32_bf16 v[38:41], v[176:179], v[208:211], v[38:41]
	v_mfma_f32_16x16x32_bf16 v[30:33], v[168:171], v[216:219], v[30:33]
	v_mfma_f32_16x16x32_bf16 v[22:25], v[176:179], v[216:219], v[22:25]
	v_mfma_f32_16x16x32_bf16 v[14:17], v[168:171], v[224:227], v[14:17]
	v_mfma_f32_16x16x32_bf16 v[6:9], v[176:179], v[224:227], v[6:9]
	s_setprio 0
	s_setprio 1
	v_mfma_f32_16x16x32_bf16 v[58:61], v[180:183], v[196:199], v[58:61]
	v_mfma_f32_16x16x32_bf16 v[50:53], v[188:191], v[196:199], v[50:53]
	v_mfma_f32_16x16x32_bf16 v[42:45], v[180:183], v[204:207], v[42:45]
	v_mfma_f32_16x16x32_bf16 v[34:37], v[188:191], v[204:207], v[34:37]
	v_mfma_f32_16x16x32_bf16 v[26:29], v[180:183], v[212:215], v[26:29]
	v_mfma_f32_16x16x32_bf16 v[18:21], v[188:191], v[212:215], v[18:21]
	v_mfma_f32_16x16x32_bf16 v[10:13], v[180:183], v[220:223], v[10:13]
	v_mfma_f32_16x16x32_bf16 v[2:5], v[188:191], v[220:223], v[2:5]
	v_mfma_f32_16x16x32_bf16 v[58:61], v[184:187], v[200:203], v[58:61]
	v_mfma_f32_16x16x32_bf16 v[50:53], v[192:195], v[200:203], v[50:53]
	v_mfma_f32_16x16x32_bf16 v[42:45], v[184:187], v[208:211], v[42:45]
	v_mfma_f32_16x16x32_bf16 v[34:37], v[192:195], v[208:211], v[34:37]
	v_mfma_f32_16x16x32_bf16 v[26:29], v[184:187], v[216:219], v[26:29]
	v_mfma_f32_16x16x32_bf16 v[18:21], v[192:195], v[216:219], v[18:21]
	v_mfma_f32_16x16x32_bf16 v[10:13], v[184:187], v[224:227], v[10:13]
	v_mfma_f32_16x16x32_bf16 v[2:5], v[192:195], v[224:227], v[2:5]
	s_barrier
	s_setprio 0
	s_mov_b32 s4, s5
	s_add_u32 s88, s88, 0x100
	s_addc_u32 s89, s89, 0
	s_add_u32 s86, s86, 0x100
	s_addc_u32 s87, s87, 0
	s_cmp_ge_i32 s5, s101
	s_cbranch_scc0 .LBB0_2075
